# GEMM main loops aligned to 2 KiB (4 KiB for the rotated in-proj loop) so no hot loop straddles a page wherever the object is loaded
# speedup vs baseline: 1.0155x; 1.0003x over previous
; template <class Sched, class Epi>
; __device__ __forceinline__ void gemm_phase(LAS unsigned char* lds, const Sched& S, const Epi& E, const int K, const int lda, const int ldb) {
;     ...
;         const bool has_next = S.next(ui + 1, nxt);
;         const char* nA = has_next ? nxt.A : cA; const char* nB = has_next ? nxt.B : cB;
;         const bool chalf = cur.half != 0;
;     ...
;         for (int a = 0; a < 2; ++a)
; #pragma unroll
;             for (int b = 0; b < 2; ++b)
; #pragma unroll
;                 for (int m = 0; m < 4; ++m)
; #pragma unroll
;                     for (int n = 0; n < 2; ++n) acc[a][b][m][n] = (f32x4){0.f, 0.f, 0.f, 0.f};
;         cur = nxt; cA = nA; cB = nB; ++ui;
.LBB0_391:
	s_cmp_eq_u32 s40, 0
	s_cselect_b64 s[36:37], -1, 0
	s_add_u32 s19, s38, 0x100
	s_addc_u32 s21, s39, 0
	v_mov_b32_e32 v4, v203
	v_mov_b32_e32 v5, v203
	s_add_u32 s38, s4, 0x80080
	v_mov_b32_e32 v2, v203
	v_mov_b32_e32 v3, v203
	v_mov_b32_e32 v66, 0
	v_mov_b64_e32 v[8:9], v[4:5]
	v_mov_b64_e32 v[20:21], v[4:5]
	v_mov_b64_e32 v[24:25], v[4:5]
	v_mov_b64_e32 v[36:37], v[4:5]
	v_mov_b64_e32 v[40:41], v[4:5]
	v_mov_b64_e32 v[52:53], v[4:5]
	v_mov_b64_e32 v[56:57], v[4:5]
	v_mov_b64_e32 v[12:13], v[4:5]
	v_mov_b64_e32 v[16:17], v[4:5]
	v_mov_b64_e32 v[28:29], v[4:5]
	v_mov_b64_e32 v[32:33], v[4:5]
	v_mov_b64_e32 v[44:45], v[4:5]
	v_mov_b64_e32 v[48:49], v[4:5]
	v_mov_b64_e32 v[60:61], v[4:5]
	v_mov_b64_e32 v[64:65], v[4:5]
	s_addc_u32 s39, s5, 0
	s_mov_b32 s27, -2
	v_cndmask_b32_e64 v232, 0, 1, s[36:37]
	v_mov_b64_e32 v[6:7], v[2:3]
	v_mov_b64_e32 v[18:19], v[2:3]
	v_mov_b64_e32 v[22:23], v[2:3]
	v_mov_b64_e32 v[34:35], v[2:3]
	v_mov_b64_e32 v[38:39], v[2:3]
	v_mov_b64_e32 v[50:51], v[2:3]
	v_mov_b64_e32 v[54:55], v[2:3]
	v_mov_b64_e32 v[10:11], v[2:3]
	v_mov_b64_e32 v[14:15], v[2:3]
	v_mov_b64_e32 v[26:27], v[2:3]
	v_mov_b64_e32 v[30:31], v[2:3]
	v_mov_b64_e32 v[42:43], v[2:3]
	v_mov_b64_e32 v[46:47], v[2:3]
	v_mov_b64_e32 v[58:59], v[2:3]
	v_mov_b64_e32 v[62:63], v[2:3]
	v_mov_b32_e32 v67, v66
	v_mov_b32_e32 v68, v66
	v_mov_b32_e32 v69, v66
	v_mov_b32_e32 v70, v66
	v_mov_b32_e32 v71, v66
	v_mov_b32_e32 v72, v66
	v_mov_b32_e32 v73, v66
	v_mov_b32_e32 v78, v66
	v_mov_b32_e32 v79, v66
	v_mov_b32_e32 v80, v66
	v_mov_b32_e32 v81, v66
	v_mov_b32_e32 v86, v66
	v_mov_b32_e32 v87, v66
	v_mov_b32_e32 v88, v66
	v_mov_b32_e32 v89, v66
	v_mov_b32_e32 v94, v66
	v_mov_b32_e32 v95, v66
	v_mov_b32_e32 v96, v66
	v_mov_b32_e32 v97, v66
	v_mov_b32_e32 v102, v66
	v_mov_b32_e32 v103, v66
	v_mov_b32_e32 v104, v66
	v_mov_b32_e32 v105, v66
	v_mov_b32_e32 v110, v66
	v_mov_b32_e32 v111, v66
	v_mov_b32_e32 v112, v66
	v_mov_b32_e32 v113, v66
	v_mov_b32_e32 v118, v66
	v_mov_b32_e32 v119, v66
	v_mov_b32_e32 v120, v66
	v_mov_b32_e32 v121, v66
	v_mov_b32_e32 v74, v66
	v_mov_b32_e32 v75, v66
	v_mov_b32_e32 v76, v66
	v_mov_b32_e32 v77, v66
	v_mov_b32_e32 v82, v66
	v_mov_b32_e32 v83, v66
	v_mov_b32_e32 v84, v66
	v_mov_b32_e32 v85, v66
	v_mov_b32_e32 v90, v66
	v_mov_b32_e32 v91, v66
	v_mov_b32_e32 v92, v66
	v_mov_b32_e32 v93, v66
	v_mov_b32_e32 v98, v66
	v_mov_b32_e32 v99, v66
	v_mov_b32_e32 v100, v66
	v_mov_b32_e32 v101, v66
	v_mov_b32_e32 v106, v66
	v_mov_b32_e32 v107, v66
	v_mov_b32_e32 v108, v66
	v_mov_b32_e32 v109, v66
	v_mov_b32_e32 v114, v66
	v_mov_b32_e32 v115, v66
	v_mov_b32_e32 v116, v66
	v_mov_b32_e32 v117, v66
	v_mov_b32_e32 v122, v66
	v_mov_b32_e32 v123, v66
	v_mov_b32_e32 v124, v66
	v_mov_b32_e32 v125, v66
	v_mov_b32_e32 v126, v66
	v_mov_b32_e32 v127, v66
	v_mov_b32_e32 v128, v66
	v_mov_b32_e32 v129, v66
	s_branch .LBB0_393
	.p2align 12

; #define PG8_STAGE(bufoff, gbase, voff) do { _Pragma("unroll") for (int _i = 0; _i < 2; ++_i) \
;         __builtin_amdgcn_global_load_lds((const unsigned*)((const char*)(gbase) + (voff)[_i]), (LAS unsigned*)(lds + (bufoff) + ldsw + _i * 8192), 16, 0, 0); } while (0)
; #define PG8_WAIT_V(n) asm volatile("s_waitcnt vmcnt(" #n ")" ::: "memory")
; #define PG8_BAR __builtin_amdgcn_s_barrier()
; template <class Sched, class Epi>
; __device__ __forceinline__ void gemm_phase(LAS unsigned char* lds, const Sched& S, const Epi& E, const int K, const int lda, const int ldb) {
;     ...
;     f32x4 acc[2][2][4][2];
; #pragma unroll
;     for (int a = 0; a < 2; ++a)
; #pragma unroll
;         for (int b = 0; b < 2; ++b)
; #pragma unroll
;             for (int m = 0; m < 4; ++m)
; #pragma unroll
;                 for (int n = 0; n < 2; ++n) acc[a][b][m][n] = (f32x4){0.f, 0.f, 0.f, 0.f};
;     ...
;     PG8_WAIT_V(4); PG8_BAR;
;     PG8_STAGE(PG8_SB(1, 0), cB + kstep, voffB); PG8_STAGE(PG8_SA(1, 0), cA + kstep, voffA); PG8_STAGE(PG8_SB(1, 1), cB + hstepB + kstep, voffB);
;     PG8_WAIT_V(6); PG8_BAR;
.LBB0_735:
	v_lshrrev_b32_e32 v18, 1, v13
	v_and_b32_e32 v142, 24, v18
	v_and_b32_e32 v17, 15, v13
	v_lshlrev_b32_e32 v18, 1, v142
	v_lshlrev_b32_e32 v13, 2, v13
	v_lshl_or_b32 v1, s10, 6, v17
	v_lshl_or_b32 v17, v17, 6, v18
	s_lshl_b32 s9, s10, 13
	v_and_b32_e32 v13, 32, v13
	v_bitop3_b32 v18, v17, s9, v13 bitop3:0xde
	s_lshl_b32 s9, s11, 5
	s_and_b32 s9, s9, 0x60
	s_mov_b64 s[16:17], 0x80
	s_lshl_b32 s10, s9, 7
	s_add_i32 m0, s1, 0x18000
	v_lshl_add_u64 v[8:9], v[8:9], 0, s[16:17]
	v_bitop3_b32 v13, v17, s10, v13 bitop3:0xde
	s_waitcnt vmcnt(4)
	s_barrier
	global_load_lds_dwordx4 v[8:9], off
	v_lshl_add_u64 v[6:7], v[6:7], 0, s[16:17]
	s_add_i32 m0, s1, 0x1a000
	s_add_i32 s10, s1, 0x8000
	s_add_i32 s11, s1, 0xa000
	global_load_lds_dwordx4 v[6:7], off
	v_lshl_add_u64 v[4:5], v[4:5], 0, s[16:17]
	s_mov_b32 m0, s10
	s_add_u32 s24, s14, 0x80080
	global_load_lds_dwordx4 v[4:5], off
	v_lshl_add_u64 v[2:3], v[2:3], 0, s[16:17]
	s_mov_b32 m0, s11
	s_addc_u32 s25, s15, 0
	global_load_lds_dwordx4 v[2:3], off
	s_add_i32 m0, s1, 0x1c000
	v_lshl_add_u64 v[2:3], s[24:25], 0, v[132:133]
	global_load_lds_dwordx4 v[2:3], off
	v_lshl_add_u64 v[2:3], s[24:25], 0, v[136:137]
	s_add_i32 m0, s1, 0x1e000
	s_add_u32 s20, s6, s20
	global_load_lds_dwordx4 v[2:3], off
	s_addc_u32 s21, s7, s21
	v_lshlrev_b32_e32 v2, 15, v14
	s_add_u32 s26, s20, 0x4a00100
	v_and_b32_e32 v2, 0xffff0000, v2
	s_addc_u32 s27, s21, 0
	v_lshl_add_u32 v2, v15, 12, v2
	v_and_b32_e32 v3, 1, v14
	v_lshl_or_b32 v2, v3, 6, v2
	s_add_u32 s18, s6, s18
	v_lshl_add_u32 v2, v16, 1, v2
	v_mov_b32_e32 v3, v133
	s_addc_u32 s19, s7, s19
	v_lshl_add_u64 v[2:3], s[18:19], 0, v[2:3]
	s_mov_b64 s[20:21], 0x29558080
	v_lshl_add_u64 v[138:139], v[2:3], 0, s[20:21]
	v_lshlrev_b32_e32 v2, 15, v10
	v_and_b32_e32 v2, 0xffff0000, v2
	v_lshl_add_u32 v2, v11, 12, v2
	v_and_b32_e32 v3, 1, v10
	v_lshl_or_b32 v2, v3, 6, v2
	s_waitcnt vmcnt(6)
	v_lshl_add_u32 v2, v12, 1, v2
	v_mov_b32_e32 v3, v133
	s_add_i32 s31, 16, 0x10000
	s_add_i32 s35, 16, 0x14000
	s_add_i32 s37, 16, 0x18000
	s_add_i32 s39, 16, 0x1c000
	v_lshl_add_u64 v[2:3], s[18:19], 0, v[2:3]
	v_add_u32_e32 v143, s31, v13
	v_add_u32_e32 v145, s35, v13
	s_add_i32 s31, s31, s22
	s_add_i32 s35, s35, s22
	v_add_u32_e32 v146, s37, v13
	v_add_u32_e32 v147, s39, v13
	s_add_i32 s37, s37, s22
	s_add_i32 s39, s39, s22
	v_lshl_add_u64 v[140:141], v[2:3], 0, s[20:21]
	s_mov_b32 s28, -2
	s_mov_b64 s[20:21], 0
	v_add_u32_e32 v144, 16, v18
	s_add_i32 s29, s1, 0xc000
	s_add_i32 s30, s1, 0xe000
	s_add_i32 s34, s31, 0x2000
	s_add_i32 s36, s35, 0x2000
	s_add_i32 s38, s37, 0x2000
	s_add_i32 s40, s39, 0x2000
	v_mov_b32_e32 v2, v133
	v_mov_b32_e32 v3, v133
	v_mov_b32_e32 v4, v133
	v_mov_b32_e32 v5, v133
	v_mov_b32_e32 v6, v133
	v_mov_b32_e32 v7, v133
	v_mov_b32_e32 v8, v133
	v_mov_b32_e32 v9, v133
	v_mov_b32_e32 v18, v133
	v_mov_b32_e32 v19, v133
	v_mov_b32_e32 v20, v133
	v_mov_b32_e32 v21, v133
	v_mov_b32_e32 v22, v133
	v_mov_b32_e32 v23, v133
	v_mov_b32_e32 v24, v133
	v_mov_b32_e32 v25, v133
	v_mov_b32_e32 v34, v133
	v_mov_b32_e32 v35, v133
	v_mov_b32_e32 v36, v133
	v_mov_b32_e32 v37, v133
	v_mov_b32_e32 v38, v133
	v_mov_b32_e32 v39, v133
	v_mov_b32_e32 v40, v133
	v_mov_b32_e32 v41, v133
	v_mov_b32_e32 v50, v133
	v_mov_b32_e32 v51, v133
	v_mov_b32_e32 v52, v133
	v_mov_b32_e32 v53, v133
	v_mov_b32_e32 v54, v133
	v_mov_b32_e32 v55, v133
	v_mov_b32_e32 v56, v133
	v_mov_b32_e32 v57, v133
	v_mov_b32_e32 v10, v133
	v_mov_b32_e32 v11, v133
	v_mov_b32_e32 v12, v133
	v_mov_b32_e32 v13, v133
	v_mov_b32_e32 v14, v133
	v_mov_b32_e32 v15, v133
	v_mov_b32_e32 v16, v133
	v_mov_b32_e32 v17, v133
	v_mov_b32_e32 v26, v133
	v_mov_b32_e32 v27, v133
	v_mov_b32_e32 v28, v133
	v_mov_b32_e32 v29, v133
	v_mov_b32_e32 v30, v133
	v_mov_b32_e32 v31, v133
	v_mov_b32_e32 v32, v133
	v_mov_b32_e32 v33, v133
	v_mov_b32_e32 v42, v133
	v_mov_b32_e32 v43, v133
	v_mov_b32_e32 v44, v133
	v_mov_b32_e32 v45, v133
	v_mov_b32_e32 v46, v133
	v_mov_b32_e32 v47, v133
	v_mov_b32_e32 v48, v133
	v_mov_b32_e32 v49, v133
	v_mov_b32_e32 v58, v133
	v_mov_b32_e32 v59, v133
	v_mov_b32_e32 v60, v133
	v_mov_b32_e32 v61, v133
	v_mov_b32_e32 v62, v133
	v_mov_b32_e32 v63, v133
	v_mov_b32_e32 v64, v133
	v_mov_b32_e32 v65, v133
	v_mov_b32_e32 v66, v133
	v_mov_b32_e32 v67, v133
	v_mov_b32_e32 v68, v133
	v_mov_b32_e32 v69, v133
	v_mov_b32_e32 v70, v133
	v_mov_b32_e32 v71, v133
	v_mov_b32_e32 v72, v133
	v_mov_b32_e32 v73, v133
	v_mov_b32_e32 v82, v133
	v_mov_b32_e32 v83, v133
	v_mov_b32_e32 v84, v133
	v_mov_b32_e32 v85, v133
	v_mov_b32_e32 v86, v133
	v_mov_b32_e32 v87, v133
	v_mov_b32_e32 v88, v133
	v_mov_b32_e32 v89, v133
	v_mov_b32_e32 v98, v133
	v_mov_b32_e32 v99, v133
	v_mov_b32_e32 v100, v133
	v_mov_b32_e32 v101, v133
	v_mov_b32_e32 v102, v133
	v_mov_b32_e32 v103, v133
	v_mov_b32_e32 v104, v133
	v_mov_b32_e32 v105, v133
	v_mov_b32_e32 v114, v133
	v_mov_b32_e32 v115, v133
	v_mov_b32_e32 v116, v133
	v_mov_b32_e32 v117, v133
	v_mov_b32_e32 v118, v133
	v_mov_b32_e32 v119, v133
	v_mov_b32_e32 v120, v133
	v_mov_b32_e32 v121, v133
	v_mov_b32_e32 v74, v133
	v_mov_b32_e32 v75, v133
	v_mov_b32_e32 v76, v133
	v_mov_b32_e32 v77, v133
	v_mov_b32_e32 v78, v133
	v_mov_b32_e32 v79, v133
	v_mov_b32_e32 v80, v133
	v_mov_b32_e32 v81, v133
	v_mov_b32_e32 v90, v133
	v_mov_b32_e32 v91, v133
	v_mov_b32_e32 v92, v133
	v_mov_b32_e32 v93, v133
	v_mov_b32_e32 v94, v133
	v_mov_b32_e32 v95, v133
	v_mov_b32_e32 v96, v133
	v_mov_b32_e32 v97, v133
	v_mov_b32_e32 v106, v133
	v_mov_b32_e32 v107, v133
	v_mov_b32_e32 v108, v133
	v_mov_b32_e32 v109, v133
	v_mov_b32_e32 v110, v133
	v_mov_b32_e32 v111, v133
	v_mov_b32_e32 v112, v133
	v_mov_b32_e32 v113, v133
	v_mov_b32_e32 v122, v133
	v_mov_b32_e32 v123, v133
	v_mov_b32_e32 v124, v133
	v_mov_b32_e32 v125, v133
	v_mov_b32_e32 v126, v133
	v_mov_b32_e32 v127, v133
	v_mov_b32_e32 v128, v133
	v_mov_b32_e32 v129, v133
	s_barrier
	s_branch .Lal_736
	.p2align 11
; #define PG8_STAGE(bufoff, gbase, voff) do { _Pragma("unroll") for (int _i = 0; _i < 2; ++_i) \
;         __builtin_amdgcn_global_load_lds((const unsigned*)((const char*)(gbase) + (voff)[_i]), (LAS unsigned*)(lds + (bufoff) + ldsw + _i * 8192), 16, 0, 0); } while (0)
; #define PG8_LDA(dst, b, h) do { _Pragma("unroll") for (int m = 0; m < 4; ++m) _Pragma("unroll") for (int k = 0; k < 2; ++k) dst[m][k] = *(const LAS bf16x8*)(lds + PG8_SA(b, h) + aoff + m * 2048 + k * 1024); } while (0)
; #define PG8_LDB(dst, b, h) do { _Pragma("unroll") for (int n = 0; n < 2; ++n) _Pragma("unroll") for (int k = 0; k < 2; ++k) dst[n][k] = *(const LAS bf16x8*)(lds + PG8_SB(b, h) + boff + n * 2048 + k * 1024); } while (0)
; #define PG8_MMA(ai, bj, At, Bt) do { __builtin_amdgcn_s_setprio(1); _Pragma("unroll") for (int m = 0; m < 4; ++m) _Pragma("unroll") for (int n = 0; n < 2; ++n) _Pragma("unroll") for (int k = 0; k < 2; ++k) \
;         acc[ai][bj][m][n] = __builtin_amdgcn_mfma_f32_16x16x32_bf16(Bt[n][k], At[m][k], acc[ai][bj][m][n], 0, 0, 0); __builtin_amdgcn_s_setprio(0); } while (0)
; #define PG8_WAIT_L(n) asm volatile("s_waitcnt lgkmcnt(" #n ")" ::: "memory")
; #define PG8_BAR __builtin_amdgcn_s_barrier()
; #define PG8_SCHED __builtin_amdgcn_sched_barrier(0)
; template <class Sched, class Epi>
; __device__ __forceinline__ void gemm_phase(LAS unsigned char* lds, const Sched& S, const Epi& E, const int K, const int lda, const int ldb) {
;     ...
;         for (int t = 0; t < nt; t += 2) {
;             const bool last = (t == nt - 2);
;             const char* a1 = cA + (size_t)(t + 1) * kstep;
;             const char* a2 = last ? nA : cA + (size_t)(t + 2) * kstep; const char* b2 = last ? nB : cB + (size_t)(t + 2) * kstep;
;             const char* a3 = a2 + kstep; const char* b3 = b2 + kstep;
;             PG8_LDB(B0, 0, 0); PG8_SCHED; PG8_LDA(At, 0, 0); PG8_STAGE(PG8_SA(1, 1), a1 + hstepA, voffA);
;             PG8_WAIT_L(8); PG8_BAR; PG8_WAIT_L(0); PG8_MMA(0, 0, At, B0); PG8_BAR; PG8_SCHED;
;             PG8_LDB(B1, 0, 1); PG8_STAGE(PG8_SB(0, 0), b2, voffB);
;             PG8_BAR; PG8_WAIT_L(0); PG8_MMA(0, 1, At, B1); PG8_BAR;
;             PG8_LDA(At, 0, 1); PG8_STAGE(PG8_SA(0, 0), a2, voffA);
;             PG8_BAR; PG8_WAIT_L(0); if (!chalf) PG8_MMA(1, 0, At, B0); PG8_BAR; PG8_SCHED;
.Lal_736:
.LBB0_736:
	s_add_u32 s22, s18, s20
	ds_read_b128 v[148:151], v143
	ds_read_b128 v[152:155], v143 offset:1024
	ds_read_b128 v[156:159], v143 offset:2048
	ds_read_b128 v[160:163], v143 offset:3072
	s_addc_u32 s23, s19, s21
	s_add_u32 s22, s22, 0x294d8100
	s_addc_u32 s23, s23, 0
	s_add_u32 s41, s26, s20
	s_addc_u32 s42, s27, s21
	s_cmpk_eq_i32 s20, 0xf00
	s_cselect_b32 s25, s13, s23
	s_cselect_b32 s24, s12, s22
	s_cselect_b32 s23, s15, s42
	s_cselect_b32 s22, s14, s41
	s_mov_b32 m0, s29
	v_lshl_add_u64 v[196:197], v[140:141], 0, s[20:21]
	ds_read_b128 v[164:167], v144
	ds_read_b128 v[168:171], v144 offset:1024
	ds_read_b128 v[172:175], v144 offset:2048
	ds_read_b128 v[176:179], v144 offset:3072
	ds_read_b128 v[180:183], v144 offset:4096
	ds_read_b128 v[184:187], v144 offset:5120
	ds_read_b128 v[188:191], v144 offset:6144
	ds_read_b128 v[192:195], v144 offset:7168
	global_load_lds_dwordx4 v[196:197], off
	v_lshl_add_u64 v[196:197], v[138:139], 0, s[20:21]
	s_mov_b32 m0, s30
	s_nop 0
	global_load_lds_dwordx4 v[196:197], off
	s_waitcnt lgkmcnt(8)
	s_barrier
	s_waitcnt lgkmcnt(0)
	s_setprio 1
	s_waitcnt lgkmcnt(0)
	v_mfma_f32_16x16x32_bf16 v[126:129], v[148:151], v[164:167], v[126:129]
	v_mfma_f32_16x16x32_bf16 v[122:125], v[156:159], v[164:167], v[122:125]
	v_mfma_f32_16x16x32_bf16 v[110:113], v[148:151], v[172:175], v[110:113]
	v_mfma_f32_16x16x32_bf16 v[106:109], v[156:159], v[172:175], v[106:109]
	v_mfma_f32_16x16x32_bf16 v[94:97], v[148:151], v[180:183], v[94:97]
	v_mfma_f32_16x16x32_bf16 v[90:93], v[156:159], v[180:183], v[90:93]
	v_mfma_f32_16x16x32_bf16 v[78:81], v[148:151], v[188:191], v[78:81]
	v_mfma_f32_16x16x32_bf16 v[74:77], v[156:159], v[188:191], v[74:77]
	v_mfma_f32_16x16x32_bf16 v[126:129], v[152:155], v[168:171], v[126:129]
	v_mfma_f32_16x16x32_bf16 v[122:125], v[160:163], v[168:171], v[122:125]
	v_mfma_f32_16x16x32_bf16 v[110:113], v[152:155], v[176:179], v[110:113]
	v_mfma_f32_16x16x32_bf16 v[106:109], v[160:163], v[176:179], v[106:109]
	v_mfma_f32_16x16x32_bf16 v[94:97], v[152:155], v[184:187], v[94:97]
	v_mfma_f32_16x16x32_bf16 v[90:93], v[160:163], v[184:187], v[90:93]
	v_mfma_f32_16x16x32_bf16 v[78:81], v[152:155], v[192:195], v[78:81]
	v_mfma_f32_16x16x32_bf16 v[74:77], v[160:163], v[192:195], v[74:77]
	s_setprio 0
	s_barrier
	s_mov_b32 m0, s31
	s_add_u32 s54, s22, s16
	s_addc_u32 s55, s23, s17
	ds_read_b128 v[196:199], v145
	ds_read_b128 v[200:203], v145 offset:1024
	ds_read_b128 v[204:207], v145 offset:2048
	ds_read_b128 v[208:211], v145 offset:3072
	global_load_lds_dwordx4 v132, s[22:23]
	s_add_u32 s56, s22, s16
	s_addc_u32 s57, s23, s17
	s_mov_b32 m0, s34
	s_nop 0
	global_load_lds_dwordx4 v136, s[22:23]
	s_barrier
	s_waitcnt lgkmcnt(0)
	s_setprio 1
	s_waitcnt lgkmcnt(0)
	v_mfma_f32_16x16x32_bf16 v[118:121], v[196:199], v[164:167], v[118:121]
	v_mfma_f32_16x16x32_bf16 v[114:117], v[204:207], v[164:167], v[114:117]
	v_mfma_f32_16x16x32_bf16 v[102:105], v[196:199], v[172:175], v[102:105]
	v_mfma_f32_16x16x32_bf16 v[98:101], v[204:207], v[172:175], v[98:101]
	v_mfma_f32_16x16x32_bf16 v[86:89], v[196:199], v[180:183], v[86:89]
	v_mfma_f32_16x16x32_bf16 v[82:85], v[204:207], v[180:183], v[82:85]
	v_mfma_f32_16x16x32_bf16 v[70:73], v[196:199], v[188:191], v[70:73]
	v_mfma_f32_16x16x32_bf16 v[66:69], v[204:207], v[188:191], v[66:69]
	v_mfma_f32_16x16x32_bf16 v[118:121], v[200:203], v[168:171], v[118:121]
	v_mfma_f32_16x16x32_bf16 v[114:117], v[208:211], v[168:171], v[114:117]
	v_mfma_f32_16x16x32_bf16 v[102:105], v[200:203], v[176:179], v[102:105]
	v_mfma_f32_16x16x32_bf16 v[98:101], v[208:211], v[176:179], v[98:101]
	v_mfma_f32_16x16x32_bf16 v[86:89], v[200:203], v[184:187], v[86:89]
	v_mfma_f32_16x16x32_bf16 v[82:85], v[208:211], v[184:187], v[82:85]
	v_mfma_f32_16x16x32_bf16 v[70:73], v[200:203], v[192:195], v[70:73]
	v_mfma_f32_16x16x32_bf16 v[66:69], v[208:211], v[192:195], v[66:69]
	s_setprio 0
	s_mov_b32 m0, s1
	s_add_u32 s58, s24, s16
	s_addc_u32 s59, s25, s17
	s_barrier
	ds_read_b128 v[164:167], v144 offset:16384
	ds_read_b128 v[168:171], v144 offset:17408
	ds_read_b128 v[172:175], v144 offset:18432
	ds_read_b128 v[176:179], v144 offset:19456
	ds_read_b128 v[180:183], v144 offset:20480
	ds_read_b128 v[184:187], v144 offset:21504
	ds_read_b128 v[188:191], v144 offset:22528
	ds_read_b128 v[192:195], v144 offset:23552
	global_load_lds_dwordx4 v130, s[24:25]
	s_add_u32 s60, s24, s16
	s_addc_u32 s61, s25, s17
	s_mov_b32 m0, s2
	s_nop 0
	global_load_lds_dwordx4 v134, s[24:25]
	s_barrier
	s_waitcnt lgkmcnt(0)
	s_setprio 1
	s_waitcnt lgkmcnt(0)
	v_mfma_f32_16x16x32_bf16 v[62:65], v[148:151], v[164:167], v[62:65]
	v_mfma_f32_16x16x32_bf16 v[58:61], v[156:159], v[164:167], v[58:61]
	v_mfma_f32_16x16x32_bf16 v[46:49], v[148:151], v[172:175], v[46:49]
	v_mfma_f32_16x16x32_bf16 v[42:45], v[156:159], v[172:175], v[42:45]
	v_mfma_f32_16x16x32_bf16 v[30:33], v[148:151], v[180:183], v[30:33]
	v_mfma_f32_16x16x32_bf16 v[26:29], v[156:159], v[180:183], v[26:29]
	v_mfma_f32_16x16x32_bf16 v[14:17], v[148:151], v[188:191], v[14:17]
	v_mfma_f32_16x16x32_bf16 v[10:13], v[156:159], v[188:191], v[10:13]
	v_mfma_f32_16x16x32_bf16 v[62:65], v[152:155], v[168:171], v[62:65]
	v_mfma_f32_16x16x32_bf16 v[58:61], v[160:163], v[168:171], v[58:61]
	v_mfma_f32_16x16x32_bf16 v[46:49], v[152:155], v[176:179], v[46:49]
	v_mfma_f32_16x16x32_bf16 v[42:45], v[160:163], v[176:179], v[42:45]
	v_mfma_f32_16x16x32_bf16 v[30:33], v[152:155], v[184:187], v[30:33]
	v_mfma_f32_16x16x32_bf16 v[26:29], v[160:163], v[184:187], v[26:29]
	v_mfma_f32_16x16x32_bf16 v[14:17], v[152:155], v[192:195], v[14:17]
	v_mfma_f32_16x16x32_bf16 v[10:13], v[160:163], v[192:195], v[10:13]
	s_setprio 0
	s_barrier
; #define PG8_STAGE(bufoff, gbase, voff) do { _Pragma("unroll") for (int _i = 0; _i < 2; ++_i) \
;         __builtin_amdgcn_global_load_lds((const unsigned*)((const char*)(gbase) + (voff)[_i]), (LAS unsigned*)(lds + (bufoff) + ldsw + _i * 8192), 16, 0, 0); } while (0)
; #define PG8_LDA(dst, b, h) do { _Pragma("unroll") for (int m = 0; m < 4; ++m) _Pragma("unroll") for (int k = 0; k < 2; ++k) dst[m][k] = *(const LAS bf16x8*)(lds + PG8_SA(b, h) + aoff + m * 2048 + k * 1024); } while (0)
; #define PG8_LDB(dst, b, h) do { _Pragma("unroll") for (int n = 0; n < 2; ++n) _Pragma("unroll") for (int k = 0; k < 2; ++k) dst[n][k] = *(const LAS bf16x8*)(lds + PG8_SB(b, h) + boff + n * 2048 + k * 1024); } while (0)
; #define PG8_MMA(ai, bj, At, Bt) do { __builtin_amdgcn_s_setprio(1); _Pragma("unroll") for (int m = 0; m < 4; ++m) _Pragma("unroll") for (int n = 0; n < 2; ++n) _Pragma("unroll") for (int k = 0; k < 2; ++k) \
;         acc[ai][bj][m][n] = __builtin_amdgcn_mfma_f32_16x16x32_bf16(Bt[n][k], At[m][k], acc[ai][bj][m][n], 0, 0, 0); __builtin_amdgcn_s_setprio(0); } while (0)
; #define PG8_WAIT_V(n) asm volatile("s_waitcnt vmcnt(" #n ")" ::: "memory")
; #define PG8_WAIT_L(n) asm volatile("s_waitcnt lgkmcnt(" #n ")" ::: "memory")
; #define PG8_BAR __builtin_amdgcn_s_barrier()
; #define PG8_SCHED __builtin_amdgcn_sched_barrier(0)
; template <class Sched, class Epi>
; __device__ __forceinline__ void gemm_phase(LAS unsigned char* lds, const Sched& S, const Epi& E, const int K, const int lda, const int ldb) {
;     ...
;             PG8_STAGE(PG8_SB(0, 1), b2 + hstepB, voffB);
;             PG8_WAIT_V(6); PG8_BAR; if (!chalf) PG8_MMA(1, 1, At, B1); PG8_BAR;
;             PG8_LDB(B0, 1, 0); PG8_SCHED; PG8_LDA(At, 1, 0); PG8_STAGE(PG8_SA(0, 1), a2 + hstepA, voffA);
;             PG8_WAIT_L(8); PG8_BAR; PG8_WAIT_L(0); PG8_MMA(0, 0, At, B0); PG8_BAR; PG8_SCHED;
;             PG8_LDB(B1, 1, 1); PG8_STAGE(PG8_SB(1, 0), b3, voffB);
;             PG8_BAR; PG8_WAIT_L(0); PG8_MMA(0, 1, At, B1); PG8_BAR;
;             PG8_LDA(At, 1, 1); PG8_STAGE(PG8_SA(1, 0), a3, voffA);
	s_add_u32 s42, s22, 0x80000
	s_addc_u32 s43, s23, 0
	s_mov_b32 m0, s35
	s_nop 0
	global_load_lds_dwordx4 v132, s[42:43]
	s_mov_b32 m0, s36
	s_nop 0
	global_load_lds_dwordx4 v136, s[42:43]
	s_waitcnt vmcnt(6)
	s_barrier
	s_setprio 1
	v_mfma_f32_16x16x32_bf16 v[54:57], v[196:199], v[164:167], v[54:57]
	v_mfma_f32_16x16x32_bf16 v[50:53], v[204:207], v[164:167], v[50:53]
	v_mfma_f32_16x16x32_bf16 v[38:41], v[196:199], v[172:175], v[38:41]
	v_mfma_f32_16x16x32_bf16 v[34:37], v[204:207], v[172:175], v[34:37]
	v_mfma_f32_16x16x32_bf16 v[22:25], v[196:199], v[180:183], v[22:25]
	v_mfma_f32_16x16x32_bf16 v[18:21], v[204:207], v[180:183], v[18:21]
	v_mfma_f32_16x16x32_bf16 v[6:9], v[196:199], v[188:191], v[6:9]
	v_mfma_f32_16x16x32_bf16 v[2:5], v[204:207], v[188:191], v[2:5]
	v_mfma_f32_16x16x32_bf16 v[54:57], v[200:203], v[168:171], v[54:57]
	v_mfma_f32_16x16x32_bf16 v[50:53], v[208:211], v[168:171], v[50:53]
	v_mfma_f32_16x16x32_bf16 v[38:41], v[200:203], v[176:179], v[38:41]
	v_mfma_f32_16x16x32_bf16 v[34:37], v[208:211], v[176:179], v[34:37]
	v_mfma_f32_16x16x32_bf16 v[22:25], v[200:203], v[184:187], v[22:25]
	v_mfma_f32_16x16x32_bf16 v[18:21], v[208:211], v[184:187], v[18:21]
	v_mfma_f32_16x16x32_bf16 v[6:9], v[200:203], v[192:195], v[6:9]
	v_mfma_f32_16x16x32_bf16 v[2:5], v[208:211], v[192:195], v[2:5]
	s_setprio 0
	s_barrier
	ds_read_b128 v[148:151], v146
	ds_read_b128 v[152:155], v146 offset:1024
	ds_read_b128 v[156:159], v146 offset:2048
	ds_read_b128 v[160:163], v146 offset:3072
	s_add_u32 s24, s24, 0x80000
	s_addc_u32 s25, s25, 0
	s_mov_b32 m0, s3
	ds_read_b128 v[164:167], v144 offset:32768
	ds_read_b128 v[168:171], v144 offset:33792
	ds_read_b128 v[172:175], v144 offset:34816
	ds_read_b128 v[176:179], v144 offset:35840
	ds_read_b128 v[180:183], v144 offset:36864
	ds_read_b128 v[184:187], v144 offset:37888
	ds_read_b128 v[188:191], v144 offset:38912
	ds_read_b128 v[192:195], v144 offset:39936
	global_load_lds_dwordx4 v130, s[24:25]
	s_mov_b32 m0, s5
	s_nop 0
	global_load_lds_dwordx4 v134, s[24:25]
	s_waitcnt lgkmcnt(8)
	s_barrier
	s_waitcnt lgkmcnt(0)
	s_setprio 1
	s_waitcnt lgkmcnt(0)
	v_mfma_f32_16x16x32_bf16 v[126:129], v[148:151], v[164:167], v[126:129]
	v_mfma_f32_16x16x32_bf16 v[122:125], v[156:159], v[164:167], v[122:125]
	v_mfma_f32_16x16x32_bf16 v[110:113], v[148:151], v[172:175], v[110:113]
	v_mfma_f32_16x16x32_bf16 v[106:109], v[156:159], v[172:175], v[106:109]
	v_mfma_f32_16x16x32_bf16 v[94:97], v[148:151], v[180:183], v[94:97]
	v_mfma_f32_16x16x32_bf16 v[90:93], v[156:159], v[180:183], v[90:93]
	v_mfma_f32_16x16x32_bf16 v[78:81], v[148:151], v[188:191], v[78:81]
	v_mfma_f32_16x16x32_bf16 v[74:77], v[156:159], v[188:191], v[74:77]
	v_mfma_f32_16x16x32_bf16 v[126:129], v[152:155], v[168:171], v[126:129]
	v_mfma_f32_16x16x32_bf16 v[122:125], v[160:163], v[168:171], v[122:125]
	v_mfma_f32_16x16x32_bf16 v[110:113], v[152:155], v[176:179], v[110:113]
	v_mfma_f32_16x16x32_bf16 v[106:109], v[160:163], v[176:179], v[106:109]
	v_mfma_f32_16x16x32_bf16 v[94:97], v[152:155], v[184:187], v[94:97]
	v_mfma_f32_16x16x32_bf16 v[90:93], v[160:163], v[184:187], v[90:93]
	v_mfma_f32_16x16x32_bf16 v[78:81], v[152:155], v[192:195], v[78:81]
	v_mfma_f32_16x16x32_bf16 v[74:77], v[160:163], v[192:195], v[74:77]
	s_setprio 0
	s_barrier
	s_mov_b32 m0, s37
	ds_read_b128 v[196:199], v147
	ds_read_b128 v[200:203], v147 offset:1024
	ds_read_b128 v[204:207], v147 offset:2048
	ds_read_b128 v[208:211], v147 offset:3072
	global_load_lds_dwordx4 v132, s[54:55]
	s_mov_b32 m0, s38
	s_nop 0
	global_load_lds_dwordx4 v136, s[56:57]
	s_barrier
	s_waitcnt lgkmcnt(0)
	s_setprio 1
	s_waitcnt lgkmcnt(0)
	v_mfma_f32_16x16x32_bf16 v[118:121], v[196:199], v[164:167], v[118:121]
	v_mfma_f32_16x16x32_bf16 v[114:117], v[204:207], v[164:167], v[114:117]
	v_mfma_f32_16x16x32_bf16 v[102:105], v[196:199], v[172:175], v[102:105]
	v_mfma_f32_16x16x32_bf16 v[98:101], v[204:207], v[172:175], v[98:101]
	v_mfma_f32_16x16x32_bf16 v[86:89], v[196:199], v[180:183], v[86:89]
	v_mfma_f32_16x16x32_bf16 v[82:85], v[204:207], v[180:183], v[82:85]
	v_mfma_f32_16x16x32_bf16 v[70:73], v[196:199], v[188:191], v[70:73]
	v_mfma_f32_16x16x32_bf16 v[66:69], v[204:207], v[188:191], v[66:69]
	v_mfma_f32_16x16x32_bf16 v[118:121], v[200:203], v[168:171], v[118:121]
	v_mfma_f32_16x16x32_bf16 v[114:117], v[208:211], v[168:171], v[114:117]
	v_mfma_f32_16x16x32_bf16 v[102:105], v[200:203], v[176:179], v[102:105]
	v_mfma_f32_16x16x32_bf16 v[98:101], v[208:211], v[176:179], v[98:101]
	v_mfma_f32_16x16x32_bf16 v[86:89], v[200:203], v[184:187], v[86:89]
	v_mfma_f32_16x16x32_bf16 v[82:85], v[208:211], v[184:187], v[82:85]
	v_mfma_f32_16x16x32_bf16 v[70:73], v[200:203], v[192:195], v[70:73]
	v_mfma_f32_16x16x32_bf16 v[66:69], v[208:211], v[192:195], v[66:69]
	s_setprio 0
	s_mov_b32 m0, s10
	s_barrier
	ds_read_b128 v[164:167], v144 offset:49152
	ds_read_b128 v[168:171], v144 offset:50176
	ds_read_b128 v[172:175], v144 offset:51200
	ds_read_b128 v[176:179], v144 offset:52224
	ds_read_b128 v[180:183], v144 offset:53248
	ds_read_b128 v[184:187], v144 offset:54272
	ds_read_b128 v[188:191], v144 offset:55296
	ds_read_b128 v[192:195], v144 offset:56320
	global_load_lds_dwordx4 v130, s[58:59]
	s_mov_b32 m0, s11
	s_nop 0
	global_load_lds_dwordx4 v134, s[60:61]
	s_barrier
; #define PG8_STAGE(bufoff, gbase, voff) do { _Pragma("unroll") for (int _i = 0; _i < 2; ++_i) \
;         __builtin_amdgcn_global_load_lds((const unsigned*)((const char*)(gbase) + (voff)[_i]), (LAS unsigned*)(lds + (bufoff) + ldsw + _i * 8192), 16, 0, 0); } while (0)
; #define PG8_MMA(ai, bj, At, Bt) do { __builtin_amdgcn_s_setprio(1); _Pragma("unroll") for (int m = 0; m < 4; ++m) _Pragma("unroll") for (int n = 0; n < 2; ++n) _Pragma("unroll") for (int k = 0; k < 2; ++k) \
;         acc[ai][bj][m][n] = __builtin_amdgcn_mfma_f32_16x16x32_bf16(Bt[n][k], At[m][k], acc[ai][bj][m][n], 0, 0, 0); __builtin_amdgcn_s_setprio(0); } while (0)
; #define PG8_WAIT_V(n) asm volatile("s_waitcnt vmcnt(" #n ")" ::: "memory")
; #define PG8_WAIT_L(n) asm volatile("s_waitcnt lgkmcnt(" #n ")" ::: "memory")
; #define PG8_BAR __builtin_amdgcn_s_barrier()
; #define PG8_SCHED __builtin_amdgcn_sched_barrier(0)
; template <class Sched, class Epi>
; __device__ __forceinline__ void gemm_phase(LAS unsigned char* lds, const Sched& S, const Epi& E, const int K, const int lda, const int ldb) {
;     ...
;             PG8_BAR; PG8_WAIT_L(0); if (!chalf) PG8_MMA(1, 0, At, B0); PG8_BAR; PG8_SCHED;
;             PG8_STAGE(PG8_SB(1, 1), b3 + hstepB, voffB);
;             PG8_WAIT_V(6); PG8_BAR; if (!chalf) PG8_MMA(1, 1, At, B1); PG8_BAR;
;     __device__ __forceinline__ void operator()(EPI_ARGS) const {
;     ...
;         for (int ai = 0; ai < 2; ++ai) if (ai == 0 || !u.half) { u32x4 zz[4][2];
; #pragma unroll
;             for (int m = 0; m < 4; ++m)
; #pragma unroll
;                 for (int bj = 0; bj < 2; ++bj) zz[m][bj] = *(const u32x4*)(parts + E_PZC + (size_t)EPI_ROW * 1024 + EPI_COL(bj));
	s_waitcnt lgkmcnt(0)
	s_setprio 1
	s_waitcnt lgkmcnt(0)
	v_mfma_f32_16x16x32_bf16 v[62:65], v[148:151], v[164:167], v[62:65]
	v_mfma_f32_16x16x32_bf16 v[58:61], v[156:159], v[164:167], v[58:61]
	v_mfma_f32_16x16x32_bf16 v[46:49], v[148:151], v[172:175], v[46:49]
	v_mfma_f32_16x16x32_bf16 v[42:45], v[156:159], v[172:175], v[42:45]
	v_mfma_f32_16x16x32_bf16 v[30:33], v[148:151], v[180:183], v[30:33]
	v_mfma_f32_16x16x32_bf16 v[26:29], v[156:159], v[180:183], v[26:29]
	v_mfma_f32_16x16x32_bf16 v[14:17], v[148:151], v[188:191], v[14:17]
	v_mfma_f32_16x16x32_bf16 v[10:13], v[156:159], v[188:191], v[10:13]
	v_mfma_f32_16x16x32_bf16 v[62:65], v[152:155], v[168:171], v[62:65]
	v_mfma_f32_16x16x32_bf16 v[58:61], v[160:163], v[168:171], v[58:61]
	v_mfma_f32_16x16x32_bf16 v[46:49], v[152:155], v[176:179], v[46:49]
	v_mfma_f32_16x16x32_bf16 v[42:45], v[160:163], v[176:179], v[42:45]
	v_mfma_f32_16x16x32_bf16 v[30:33], v[152:155], v[184:187], v[30:33]
	v_mfma_f32_16x16x32_bf16 v[26:29], v[160:163], v[184:187], v[26:29]
	v_mfma_f32_16x16x32_bf16 v[14:17], v[152:155], v[192:195], v[14:17]
	v_mfma_f32_16x16x32_bf16 v[10:13], v[160:163], v[192:195], v[10:13]
	s_setprio 0
	s_barrier
	s_add_u32 s22, s22, 0x80080
	s_addc_u32 s23, s23, 0
	s_mov_b32 m0, s39
	s_nop 0
	global_load_lds_dwordx4 v132, s[22:23]
	s_mov_b32 m0, s40
	s_nop 0
	global_load_lds_dwordx4 v136, s[22:23]
	s_waitcnt vmcnt(6)
	s_barrier
	s_setprio 1
	v_mfma_f32_16x16x32_bf16 v[54:57], v[196:199], v[164:167], v[54:57]
	v_mfma_f32_16x16x32_bf16 v[50:53], v[204:207], v[164:167], v[50:53]
	v_mfma_f32_16x16x32_bf16 v[38:41], v[196:199], v[172:175], v[38:41]
	v_mfma_f32_16x16x32_bf16 v[34:37], v[204:207], v[172:175], v[34:37]
	v_mfma_f32_16x16x32_bf16 v[22:25], v[196:199], v[180:183], v[22:25]
	v_mfma_f32_16x16x32_bf16 v[18:21], v[204:207], v[180:183], v[18:21]
	v_mfma_f32_16x16x32_bf16 v[6:9], v[196:199], v[188:191], v[6:9]
	v_mfma_f32_16x16x32_bf16 v[2:5], v[204:207], v[188:191], v[2:5]
	v_mfma_f32_16x16x32_bf16 v[54:57], v[200:203], v[168:171], v[54:57]
	v_mfma_f32_16x16x32_bf16 v[50:53], v[208:211], v[168:171], v[50:53]
	v_mfma_f32_16x16x32_bf16 v[38:41], v[200:203], v[176:179], v[38:41]
	v_mfma_f32_16x16x32_bf16 v[34:37], v[208:211], v[176:179], v[34:37]
	v_mfma_f32_16x16x32_bf16 v[22:25], v[200:203], v[184:187], v[22:25]
	v_mfma_f32_16x16x32_bf16 v[18:21], v[208:211], v[184:187], v[18:21]
	v_mfma_f32_16x16x32_bf16 v[6:9], v[200:203], v[192:195], v[6:9]
	v_mfma_f32_16x16x32_bf16 v[2:5], v[208:211], v[192:195], v[2:5]
	s_setprio 0
	s_add_i32 s28, s28, 2
	s_add_u32 s20, s20, 0x100
	s_addc_u32 s21, s21, 0
	s_cmp_gt_u32 s28, 29
	s_barrier
	s_cbranch_scc0 .LBB0_736
	s_sext_i32_i8 s1, s4
	v_add_u32_e32 v152, s8, v1
	v_lshl_or_b32 v1, s1, 8, v142
	s_add_u32 s12, s6, 0x1b9d8000
	v_or_b32_e32 v130, s9, v1
	v_ashrrev_i32_e32 v153, 31, v152
	s_addc_u32 s13, s7, 0
	v_ashrrev_i32_e32 v131, 31, v130
	v_lshlrev_b64 v[132:133], 11, v[152:153]
	v_lshl_add_u64 v[134:135], s[12:13], 0, v[132:133]
	v_lshlrev_b64 v[150:151], 1, v[130:131]
	v_lshl_add_u64 v[130:131], v[134:135], 0, v[150:151]
	global_load_dwordx4 v[154:157], v[130:131], off
	global_load_dwordx4 v[158:161], v[130:131], off offset:256
	v_or_b32_e32 v130, 16, v152
	v_or_b32_e32 v134, 32, v152
	v_or_b32_e32 v136, 48, v152
	v_ashrrev_i32_e32 v131, 31, v130
	v_ashrrev_i32_e32 v135, 31, v134
	s_add_u32 s4, s6, 0x252d8000
	v_ashrrev_i32_e32 v137, 31, v136
	v_lshlrev_b64 v[130:131], 11, v[130:131]
	v_lshlrev_b64 v[134:135], 11, v[134:135]
	s_addc_u32 s5, s7, 0
	v_lshlrev_b64 v[136:137], 11, v[136:137]
	v_lshl_add_u64 v[130:131], s[12:13], 0, v[130:131]
	v_lshl_add_u64 v[134:135], s[12:13], 0, v[134:135]
	v_lshl_add_u64 v[136:137], s[12:13], 0, v[136:137]
	v_lshl_add_u64 v[132:133], s[4:5], 0, v[132:133]
	v_lshl_add_u64 v[130:131], v[130:131], 0, v[150:151]
	v_lshl_add_u64 v[134:135], v[134:135], 0, v[150:151]
	v_lshl_add_u64 v[166:167], v[136:137], 0, v[150:151]
	v_lshl_add_u64 v[168:169], v[132:133], 0, v[150:151]
	global_load_dwordx4 v[162:165], v[130:131], off
	global_load_dwordx4 v[146:149], v[130:131], off offset:256
	global_load_dwordx4 v[142:145], v[134:135], off
	global_load_dwordx4 v[138:141], v[134:135], off offset:256
	s_nop 0
	global_load_dwordx4 v[134:137], v[166:167], off
	global_load_dwordx4 v[130:133], v[166:167], off offset:256
	s_cmpk_lt_u32 s0, 0x100
	s_waitcnt vmcnt(0)
; __device__ __forceinline__ float siluf_(float x) { return x * __builtin_amdgcn_rcpf(1.0f + __expf(-x)); }
; __device__ __forceinline__ u32x4 pack8(const float (&f)[8]) { u32x4 r; r[0] = cvt_pk_bf16(f[0], f[1]); r[1] = cvt_pk_bf16(f[2], f[3]); r[2] = cvt_pk_bf16(f[4], f[5]); r[3] = cvt_pk_bf16(f[6], f[7]); return r; }
;     __device__ __forceinline__ void operator()(EPI_ARGS) const {
;     ...
;                 for (int bj = 0; bj < 2; ++bj) { const f32x4 v0 = acc[ai][bj][m][0], v1 = acc[ai][bj][m][1]; float z[8]; unpack8(zz[m][bj], z); float o[8];
; #pragma unroll
;                     for (int j = 0; j < 4; ++j) { o[j] = v0[j] * siluf_(z[j]); o[4 + j] = v1[j] * siluf_(z[4 + j]); }
;                     *(u32x4*)(O + (size_t)EPI_ROW * 1024 + EPI_COL(bj)) = pack8(o); } }
	v_lshlrev_b32_e32 v1, 16, v154
	v_and_b32_e32 v153, 0xffff0000, v154
	v_lshlrev_b32_e32 v154, 16, v155
	v_and_b32_e32 v155, 0xffff0000, v155
	v_lshlrev_b32_e32 v166, 16, v156
	v_and_b32_e32 v156, 0xffff0000, v156
	v_lshlrev_b32_e32 v167, 16, v157
	v_and_b32_e32 v157, 0xffff0000, v157
	v_mul_f32_e32 v171, 0xbfb8aa3b, v1
	v_mul_f32_e32 v172, 0xbfb8aa3b, v166
	v_mul_f32_e32 v173, 0xbfb8aa3b, v153
	v_mul_f32_e32 v174, 0xbfb8aa3b, v156
	v_mul_f32_e32 v175, 0xbfb8aa3b, v154
	v_mul_f32_e32 v176, 0xbfb8aa3b, v167
	v_mul_f32_e32 v177, 0xbfb8aa3b, v155
	v_mul_f32_e32 v178, 0xbfb8aa3b, v157
	v_exp_f32_e32 v171, v171
	v_exp_f32_e32 v172, v172
	v_exp_f32_e32 v173, v173
	v_exp_f32_e32 v174, v174
	v_exp_f32_e32 v175, v175
	v_exp_f32_e32 v176, v176
	v_exp_f32_e32 v177, v177
	v_exp_f32_e32 v178, v178
	v_add_f32_e32 v171, 1.0, v171
	v_add_f32_e32 v172, 1.0, v172
	v_add_f32_e32 v173, 1.0, v173
	v_add_f32_e32 v174, 1.0, v174
	v_add_f32_e32 v175, 1.0, v175
	v_add_f32_e32 v176, 1.0, v176
	v_add_f32_e32 v177, 1.0, v177
	v_add_f32_e32 v178, 1.0, v178
	v_rcp_f32_e32 v171, v171
	v_rcp_f32_e32 v172, v172
	v_rcp_f32_e32 v173, v173
	v_rcp_f32_e32 v174, v174
	v_rcp_f32_e32 v175, v175
	v_rcp_f32_e32 v176, v176
	v_rcp_f32_e32 v177, v177
	v_rcp_f32_e32 v178, v178
	v_mul_f32_e32 v1, v171, v1
	v_mul_f32_e32 v166, v172, v166
	v_mul_f32_e32 v153, v173, v153
	v_mul_f32_e32 v156, v174, v156
	v_mul_f32_e32 v154, v175, v154
	v_mul_f32_e32 v167, v176, v167
	v_mul_f32_e32 v155, v177, v155
	v_lshlrev_b32_e32 v170, 16, v158
	v_mul_f32_e32 v157, v178, v157
	v_mul_f32_e32 v1, v126, v1
	v_mul_f32_e32 v126, v122, v166
	v_mul_f32_e32 v122, v127, v153
	v_mul_f32_e32 v127, v123, v156
	v_mul_f32_e32 v123, v128, v154
	v_mul_f32_e32 v128, v124, v167
	v_mul_f32_e32 v124, v129, v155
	v_mul_f32_e32 v125, v125, v157
	v_cvt_pk_bf16_f32 v122, v1, v122
	v_cvt_pk_bf16_f32 v123, v123, v124
	v_cvt_pk_bf16_f32 v124, v126, v127
	v_mul_f32_e32 v126, 0xbfb8aa3b, v170
	v_cvt_pk_bf16_f32 v125, v128, v125
	global_store_dwordx4 v[168:169], v[122:125], off
	v_exp_f32_e32 v126, v126
	v_and_b32_e32 v1, 0xffff0000, v158
	v_lshlrev_b32_e32 v124, 16, v160
	v_mul_f32_e32 v127, 0xbfb8aa3b, v124
	v_exp_f32_e32 v127, v127
	v_add_f32_e32 v126, 1.0, v126
	v_rcp_f32_e32 v126, v126
	v_and_b32_e32 v125, 0xffff0000, v160
	v_add_f32_e32 v127, 1.0, v127
	v_rcp_f32_e32 v127, v127
	v_mul_f32_e32 v126, v126, v170
	v_mul_f32_e32 v118, v118, v126
	v_mul_f32_e32 v126, 0xbfb8aa3b, v1
	v_mul_f32_e32 v124, v127, v124
	v_exp_f32_e32 v126, v126
	v_mul_f32_e32 v127, 0xbfb8aa3b, v125
	v_exp_f32_e32 v127, v127
	v_lshlrev_b32_e32 v122, 16, v159
	v_mul_f32_e32 v124, v114, v124
	v_add_f32_e32 v114, 1.0, v126
	v_rcp_f32_e32 v114, v114
	v_add_f32_e32 v126, 1.0, v127
	v_mul_f32_e32 v127, 0xbfb8aa3b, v122
	v_exp_f32_e32 v127, v127
	v_mul_f32_e32 v1, v114, v1
	v_rcp_f32_e32 v126, v126
	v_mul_f32_e32 v1, v119, v1
	v_add_f32_e32 v119, 1.0, v127
	v_rcp_f32_e32 v119, v119
	v_lshlrev_b32_e32 v128, 16, v161
	v_and_b32_e32 v123, 0xffff0000, v159
	v_mul_f32_e32 v114, v126, v125
	v_mul_f32_e32 v125, 0xbfb8aa3b, v128
	v_and_b32_e32 v129, 0xffff0000, v161
	v_exp_f32_e32 v125, v125
	v_mul_f32_e32 v126, v115, v114
	v_mul_f32_e32 v114, v119, v122
	v_mul_f32_e32 v119, 0xbfb8aa3b, v123
	v_mul_f32_e32 v115, v120, v114
	v_exp_f32_e32 v119, v119
	v_mul_f32_e32 v120, 0xbfb8aa3b, v129
	v_exp_f32_e32 v120, v120
	v_add_f32_e32 v114, 1.0, v125
	v_rcp_f32_e32 v114, v114
	v_add_f32_e32 v119, 1.0, v119
	v_rcp_f32_e32 v119, v119
	v_add_f32_e32 v120, 1.0, v120
	v_rcp_f32_e32 v120, v120
	v_mul_f32_e32 v114, v114, v128
	v_mul_f32_e32 v122, v116, v114
	v_mul_f32_e32 v114, v119, v123
	v_mul_f32_e32 v116, v121, v114
	v_mul_f32_e32 v114, v120, v129
	v_mul_f32_e32 v117, v117, v114
	v_cvt_pk_bf16_f32 v114, v118, v1
	v_cvt_pk_bf16_f32 v115, v115, v116
	v_cvt_pk_bf16_f32 v116, v124, v126
	v_cvt_pk_bf16_f32 v117, v122, v117
	v_lshlrev_b32_e32 v1, 16, v162
	global_store_dwordx4 v[168:169], v[114:117], off offset:256
	v_mul_f32_e32 v119, 0xbfb8aa3b, v1
	v_exp_f32_e32 v119, v119
	v_lshlrev_b32_e32 v117, 16, v164
	v_mul_f32_e32 v120, 0xbfb8aa3b, v117
	v_exp_f32_e32 v120, v120
	v_add_f32_e32 v119, 1.0, v119
	v_rcp_f32_e32 v119, v119
	v_and_b32_e32 v114, 0xffff0000, v162
	v_add_f32_e32 v120, 1.0, v120
	v_rcp_f32_e32 v120, v120
	v_and_b32_e32 v118, 0xffff0000, v164
	v_mul_f32_e32 v1, v119, v1
	v_mul_f32_e32 v1, v110, v1
	v_mul_f32_e32 v110, v120, v117
	v_mul_f32_e32 v117, 0xbfb8aa3b, v114
	v_mul_f32_e32 v119, 0xbfb8aa3b, v118
	v_exp_f32_e32 v117, v117
	v_exp_f32_e32 v119, v119
	v_lshlrev_b32_e32 v115, 16, v163
	v_mul_f32_e32 v110, v106, v110
	v_add_f32_e32 v106, 1.0, v117
	v_add_f32_e32 v117, 1.0, v119
	v_mul_f32_e32 v119, 0xbfb8aa3b, v115
	v_rcp_f32_e32 v106, v106
	v_exp_f32_e32 v119, v119
	v_rcp_f32_e32 v117, v117
	v_lshlrev_b32_e32 v121, 16, v165
	v_mul_f32_e32 v106, v106, v114
	v_add_f32_e32 v114, 1.0, v119
	v_rcp_f32_e32 v114, v114
	v_and_b32_e32 v116, 0xffff0000, v163
	v_mul_f32_e32 v106, v111, v106
	v_mul_f32_e32 v111, v117, v118
	v_mul_f32_e32 v117, 0xbfb8aa3b, v121
	v_exp_f32_e32 v117, v117
	v_mul_f32_e32 v111, v107, v111
	v_mul_f32_e32 v107, v114, v115
	v_mul_f32_e32 v114, 0xbfb8aa3b, v116
	v_exp_f32_e32 v114, v114
	v_and_b32_e32 v122, 0xffff0000, v165
	v_mul_f32_e32 v107, v112, v107
	v_add_f32_e32 v112, 1.0, v117
	v_mul_f32_e32 v115, 0xbfb8aa3b, v122
	v_rcp_f32_e32 v112, v112
	v_exp_f32_e32 v115, v115
	v_add_f32_e32 v114, 1.0, v114
	v_rcp_f32_e32 v114, v114
	v_mul_f32_e32 v112, v112, v121
	v_add_f32_e32 v115, 1.0, v115
	v_rcp_f32_e32 v115, v115
	v_mul_f32_e32 v112, v108, v112
	v_mul_f32_e32 v108, v114, v116
	v_mul_f32_e32 v108, v113, v108
	v_cvt_pk_bf16_f32 v106, v1, v106
; __device__ __forceinline__ float siluf_(float x) { return x * __builtin_amdgcn_rcpf(1.0f + __expf(-x)); }
; __device__ __forceinline__ u32x4 pack8(const float (&f)[8]) { u32x4 r; r[0] = cvt_pk_bf16(f[0], f[1]); r[1] = cvt_pk_bf16(f[2], f[3]); r[2] = cvt_pk_bf16(f[4], f[5]); r[3] = cvt_pk_bf16(f[6], f[7]); return r; }
;     __device__ __forceinline__ void operator()(EPI_ARGS) const {
;     ...
;                 for (int bj = 0; bj < 2; ++bj) { const f32x4 v0 = acc[ai][bj][m][0], v1 = acc[ai][bj][m][1]; float z[8]; unpack8(zz[m][bj], z); float o[8];
; #pragma unroll
;                     for (int j = 0; j < 4; ++j) { o[j] = v0[j] * siluf_(z[j]); o[4 + j] = v1[j] * siluf_(z[4 + j]); }
;                     *(u32x4*)(O + (size_t)EPI_ROW * 1024 + EPI_COL(bj)) = pack8(o); } }
	v_cvt_pk_bf16_f32 v107, v107, v108
	v_cvt_pk_bf16_f32 v108, v110, v111
	v_add_u32_e32 v110, 16, v152
	v_ashrrev_i32_e32 v111, 31, v110
	v_mul_f32_e32 v113, v115, v122
	v_lshlrev_b64 v[110:111], 11, v[110:111]
	v_mul_f32_e32 v109, v109, v113
	v_lshl_add_u64 v[110:111], s[4:5], 0, v[110:111]
	v_cvt_pk_bf16_f32 v109, v112, v109
	v_lshl_add_u64 v[110:111], v[110:111], 0, v[150:151]
	v_lshlrev_b32_e32 v1, 16, v146
	global_store_dwordx4 v[110:111], v[106:109], off
	v_mul_f32_e32 v113, 0xbfb8aa3b, v1
	v_exp_f32_e32 v113, v113
	v_lshlrev_b32_e32 v109, 16, v148
	v_mul_f32_e32 v114, 0xbfb8aa3b, v109
	v_exp_f32_e32 v114, v114
	v_add_f32_e32 v113, 1.0, v113
	v_rcp_f32_e32 v113, v113
	v_and_b32_e32 v106, 0xffff0000, v146
	v_add_f32_e32 v114, 1.0, v114
	v_rcp_f32_e32 v114, v114
	v_and_b32_e32 v112, 0xffff0000, v148
	v_mul_f32_e32 v1, v113, v1
	v_mul_f32_e32 v1, v102, v1
	v_mul_f32_e32 v102, v114, v109
	v_mul_f32_e32 v109, 0xbfb8aa3b, v106
	v_mul_f32_e32 v113, 0xbfb8aa3b, v112
	v_exp_f32_e32 v109, v109
	v_exp_f32_e32 v113, v113
	v_lshlrev_b32_e32 v107, 16, v147
	v_mul_f32_e32 v102, v98, v102
	v_add_f32_e32 v98, 1.0, v109
	v_add_f32_e32 v109, 1.0, v113
	v_mul_f32_e32 v113, 0xbfb8aa3b, v107
	v_rcp_f32_e32 v98, v98
	v_exp_f32_e32 v113, v113
	v_rcp_f32_e32 v109, v109
	v_lshlrev_b32_e32 v115, 16, v149
	v_mul_f32_e32 v98, v98, v106
	v_add_f32_e32 v106, 1.0, v113
	v_rcp_f32_e32 v106, v106
	v_and_b32_e32 v108, 0xffff0000, v147
	v_mul_f32_e32 v98, v103, v98
	v_mul_f32_e32 v103, v109, v112
	v_mul_f32_e32 v109, 0xbfb8aa3b, v115
	v_and_b32_e32 v116, 0xffff0000, v149
	v_exp_f32_e32 v109, v109
	v_mul_f32_e32 v103, v99, v103
	v_mul_f32_e32 v99, v106, v107
	v_mul_f32_e32 v106, 0xbfb8aa3b, v108
	v_exp_f32_e32 v106, v106
	v_mul_f32_e32 v107, 0xbfb8aa3b, v116
	v_exp_f32_e32 v107, v107
	v_mul_f32_e32 v99, v104, v99
	v_add_f32_e32 v104, 1.0, v109
	v_rcp_f32_e32 v104, v104
	v_add_f32_e32 v106, 1.0, v106
	v_rcp_f32_e32 v106, v106
	v_add_f32_e32 v107, 1.0, v107
	v_rcp_f32_e32 v107, v107
	v_mul_f32_e32 v104, v104, v115
	v_mul_f32_e32 v104, v100, v104
	v_mul_f32_e32 v100, v106, v108
	v_mul_f32_e32 v100, v105, v100
	v_mul_f32_e32 v105, v107, v116
	v_mul_f32_e32 v101, v101, v105
	v_cvt_pk_bf16_f32 v98, v1, v98
	v_cvt_pk_bf16_f32 v99, v99, v100
	v_cvt_pk_bf16_f32 v100, v102, v103
	v_cvt_pk_bf16_f32 v101, v104, v101
	v_lshlrev_b32_e32 v1, 16, v142
	global_store_dwordx4 v[110:111], v[98:101], off offset:256
	v_mul_f32_e32 v103, 0xbfb8aa3b, v1
	v_exp_f32_e32 v103, v103
	v_lshlrev_b32_e32 v101, 16, v144
	v_mul_f32_e32 v104, 0xbfb8aa3b, v101
	v_exp_f32_e32 v104, v104
	v_add_f32_e32 v103, 1.0, v103
	v_rcp_f32_e32 v103, v103
	v_and_b32_e32 v98, 0xffff0000, v142
	v_add_f32_e32 v104, 1.0, v104
	v_rcp_f32_e32 v104, v104
	v_and_b32_e32 v102, 0xffff0000, v144
	v_mul_f32_e32 v1, v103, v1
	v_mul_f32_e32 v1, v94, v1
	v_mul_f32_e32 v94, v104, v101
	v_mul_f32_e32 v101, 0xbfb8aa3b, v98
	v_mul_f32_e32 v103, 0xbfb8aa3b, v102
	v_exp_f32_e32 v101, v101
	v_exp_f32_e32 v103, v103
	v_lshlrev_b32_e32 v99, 16, v143
	v_mul_f32_e32 v94, v90, v94
	v_add_f32_e32 v90, 1.0, v101
	v_add_f32_e32 v101, 1.0, v103
	v_mul_f32_e32 v103, 0xbfb8aa3b, v99
	v_rcp_f32_e32 v90, v90
	v_exp_f32_e32 v103, v103
	v_rcp_f32_e32 v101, v101
	v_lshlrev_b32_e32 v105, 16, v145
	v_mul_f32_e32 v90, v90, v98
	v_add_f32_e32 v98, 1.0, v103
	v_rcp_f32_e32 v98, v98
	v_and_b32_e32 v100, 0xffff0000, v143
	v_mul_f32_e32 v90, v95, v90
	v_mul_f32_e32 v95, v101, v102
	v_mul_f32_e32 v101, 0xbfb8aa3b, v105
	v_exp_f32_e32 v101, v101
	v_mul_f32_e32 v95, v91, v95
	v_mul_f32_e32 v91, v98, v99
	v_mul_f32_e32 v98, 0xbfb8aa3b, v100
	v_exp_f32_e32 v98, v98
	v_and_b32_e32 v106, 0xffff0000, v145
	v_mul_f32_e32 v91, v96, v91
	v_add_f32_e32 v96, 1.0, v101
	v_mul_f32_e32 v99, 0xbfb8aa3b, v106
	v_rcp_f32_e32 v96, v96
	v_exp_f32_e32 v99, v99
	v_add_f32_e32 v98, 1.0, v98
	v_rcp_f32_e32 v98, v98
	v_mul_f32_e32 v96, v96, v105
	v_add_f32_e32 v99, 1.0, v99
	v_rcp_f32_e32 v99, v99
	v_mul_f32_e32 v96, v92, v96
	v_mul_f32_e32 v92, v98, v100
	v_mul_f32_e32 v92, v97, v92
	v_cvt_pk_bf16_f32 v90, v1, v90
	v_cvt_pk_bf16_f32 v91, v91, v92
	v_cvt_pk_bf16_f32 v92, v94, v95
	v_add_u32_e32 v94, 32, v152
	v_ashrrev_i32_e32 v95, 31, v94
	v_mul_f32_e32 v97, v99, v106
	v_lshlrev_b64 v[94:95], 11, v[94:95]
	v_mul_f32_e32 v93, v93, v97
	v_lshl_add_u64 v[94:95], s[4:5], 0, v[94:95]
	v_cvt_pk_bf16_f32 v93, v96, v93
	v_lshl_add_u64 v[94:95], v[94:95], 0, v[150:151]
	v_lshlrev_b32_e32 v1, 16, v138
	global_store_dwordx4 v[94:95], v[90:93], off
	v_mul_f32_e32 v97, 0xbfb8aa3b, v1
	v_exp_f32_e32 v97, v97
	v_lshlrev_b32_e32 v93, 16, v140
	v_mul_f32_e32 v98, 0xbfb8aa3b, v93
	v_exp_f32_e32 v98, v98
	v_add_f32_e32 v97, 1.0, v97
	v_rcp_f32_e32 v97, v97
	v_and_b32_e32 v90, 0xffff0000, v138
	v_add_f32_e32 v98, 1.0, v98
	v_rcp_f32_e32 v98, v98
	v_and_b32_e32 v96, 0xffff0000, v140
	v_mul_f32_e32 v1, v97, v1
	v_mul_f32_e32 v1, v86, v1
	v_mul_f32_e32 v86, v98, v93
	v_mul_f32_e32 v93, 0xbfb8aa3b, v90
	v_mul_f32_e32 v97, 0xbfb8aa3b, v96
	v_exp_f32_e32 v93, v93
	v_exp_f32_e32 v97, v97
	v_lshlrev_b32_e32 v91, 16, v139
	v_mul_f32_e32 v86, v82, v86
	v_add_f32_e32 v82, 1.0, v93
	v_add_f32_e32 v93, 1.0, v97
	v_mul_f32_e32 v97, 0xbfb8aa3b, v91
	v_rcp_f32_e32 v82, v82
	v_exp_f32_e32 v97, v97
	v_rcp_f32_e32 v93, v93
	v_lshlrev_b32_e32 v99, 16, v141
	v_mul_f32_e32 v82, v82, v90
	v_add_f32_e32 v90, 1.0, v97
	v_rcp_f32_e32 v90, v90
	v_and_b32_e32 v92, 0xffff0000, v139
	v_mul_f32_e32 v82, v87, v82
	v_mul_f32_e32 v87, v93, v96
	v_mul_f32_e32 v93, 0xbfb8aa3b, v99
	v_and_b32_e32 v100, 0xffff0000, v141
	v_exp_f32_e32 v93, v93
	v_mul_f32_e32 v87, v83, v87
	v_mul_f32_e32 v83, v90, v91
	v_mul_f32_e32 v90, 0xbfb8aa3b, v92
; __device__ __forceinline__ float siluf_(float x) { return x * __builtin_amdgcn_rcpf(1.0f + __expf(-x)); }
; __device__ __forceinline__ u32x4 pack8(const float (&f)[8]) { u32x4 r; r[0] = cvt_pk_bf16(f[0], f[1]); r[1] = cvt_pk_bf16(f[2], f[3]); r[2] = cvt_pk_bf16(f[4], f[5]); r[3] = cvt_pk_bf16(f[6], f[7]); return r; }
;     __device__ __forceinline__ void operator()(EPI_ARGS) const {
;     ...
;                 for (int bj = 0; bj < 2; ++bj) zz[m][bj] = *(const u32x4*)(parts + E_PZC + (size_t)EPI_ROW * 1024 + EPI_COL(bj));
;     ...
;                 for (int bj = 0; bj < 2; ++bj) { const f32x4 v0 = acc[ai][bj][m][0], v1 = acc[ai][bj][m][1]; float z[8]; unpack8(zz[m][bj], z); float o[8];
; #pragma unroll
;                     for (int j = 0; j < 4; ++j) { o[j] = v0[j] * siluf_(z[j]); o[4 + j] = v1[j] * siluf_(z[4 + j]); }
;                     *(u32x4*)(O + (size_t)EPI_ROW * 1024 + EPI_COL(bj)) = pack8(o); } }
	v_exp_f32_e32 v90, v90
	v_mul_f32_e32 v91, 0xbfb8aa3b, v100
	v_exp_f32_e32 v91, v91
	v_mul_f32_e32 v83, v88, v83
	v_add_f32_e32 v88, 1.0, v93
	v_rcp_f32_e32 v88, v88
	v_add_f32_e32 v90, 1.0, v90
	v_rcp_f32_e32 v90, v90
	v_add_f32_e32 v91, 1.0, v91
	v_rcp_f32_e32 v91, v91
	v_mul_f32_e32 v88, v88, v99
	v_mul_f32_e32 v88, v84, v88
	v_mul_f32_e32 v84, v90, v92
	v_mul_f32_e32 v84, v89, v84
	v_mul_f32_e32 v89, v91, v100
	v_mul_f32_e32 v85, v85, v89
	v_cvt_pk_bf16_f32 v82, v1, v82
	v_cvt_pk_bf16_f32 v83, v83, v84
	v_cvt_pk_bf16_f32 v84, v86, v87
	v_cvt_pk_bf16_f32 v85, v88, v85
	v_lshlrev_b32_e32 v1, 16, v134
	global_store_dwordx4 v[94:95], v[82:85], off offset:256
	v_mul_f32_e32 v87, 0xbfb8aa3b, v1
	v_exp_f32_e32 v87, v87
	v_lshlrev_b32_e32 v85, 16, v136
	v_mul_f32_e32 v88, 0xbfb8aa3b, v85
	v_exp_f32_e32 v88, v88
	v_add_f32_e32 v87, 1.0, v87
	v_rcp_f32_e32 v87, v87
	v_and_b32_e32 v82, 0xffff0000, v134
	v_add_f32_e32 v88, 1.0, v88
	v_rcp_f32_e32 v88, v88
	v_and_b32_e32 v86, 0xffff0000, v136
	v_mul_f32_e32 v1, v87, v1
	v_mul_f32_e32 v1, v78, v1
	v_mul_f32_e32 v78, v88, v85
	v_mul_f32_e32 v85, 0xbfb8aa3b, v82
	v_mul_f32_e32 v87, 0xbfb8aa3b, v86
	v_exp_f32_e32 v85, v85
	v_exp_f32_e32 v87, v87
	v_lshlrev_b32_e32 v83, 16, v135
	v_mul_f32_e32 v78, v74, v78
	v_add_f32_e32 v74, 1.0, v85
	v_add_f32_e32 v85, 1.0, v87
	v_mul_f32_e32 v87, 0xbfb8aa3b, v83
	v_rcp_f32_e32 v74, v74
	v_exp_f32_e32 v87, v87
	v_rcp_f32_e32 v85, v85
	v_lshlrev_b32_e32 v89, 16, v137
	v_mul_f32_e32 v74, v74, v82
	v_add_f32_e32 v82, 1.0, v87
	v_rcp_f32_e32 v82, v82
	v_and_b32_e32 v84, 0xffff0000, v135
	v_mul_f32_e32 v74, v79, v74
	v_mul_f32_e32 v79, v85, v86
	v_mul_f32_e32 v85, 0xbfb8aa3b, v89
	v_exp_f32_e32 v85, v85
	v_mul_f32_e32 v79, v75, v79
	v_mul_f32_e32 v75, v82, v83
	v_mul_f32_e32 v82, 0xbfb8aa3b, v84
	v_exp_f32_e32 v82, v82
	v_and_b32_e32 v90, 0xffff0000, v137
	v_mul_f32_e32 v75, v80, v75
	v_add_f32_e32 v80, 1.0, v85
	v_mul_f32_e32 v83, 0xbfb8aa3b, v90
	v_rcp_f32_e32 v80, v80
	v_exp_f32_e32 v83, v83
	v_add_f32_e32 v82, 1.0, v82
	v_rcp_f32_e32 v82, v82
	v_mul_f32_e32 v80, v80, v89
	v_add_f32_e32 v83, 1.0, v83
	v_rcp_f32_e32 v83, v83
	v_mul_f32_e32 v80, v76, v80
	v_mul_f32_e32 v76, v82, v84
	v_mul_f32_e32 v76, v81, v76
	v_cvt_pk_bf16_f32 v74, v1, v74
	v_cvt_pk_bf16_f32 v75, v75, v76
	v_cvt_pk_bf16_f32 v76, v78, v79
	v_add_u32_e32 v78, 48, v152
	v_ashrrev_i32_e32 v79, 31, v78
	v_mul_f32_e32 v81, v83, v90
	v_lshlrev_b64 v[78:79], 11, v[78:79]
	v_mul_f32_e32 v77, v77, v81
	v_lshl_add_u64 v[78:79], s[4:5], 0, v[78:79]
	v_cvt_pk_bf16_f32 v77, v80, v77
	v_lshl_add_u64 v[78:79], v[78:79], 0, v[150:151]
	v_lshlrev_b32_e32 v1, 16, v130
	global_store_dwordx4 v[78:79], v[74:77], off
	v_mul_f32_e32 v81, 0xbfb8aa3b, v1
	v_exp_f32_e32 v81, v81
	v_lshlrev_b32_e32 v77, 16, v132
	v_mul_f32_e32 v82, 0xbfb8aa3b, v77
	v_exp_f32_e32 v82, v82
	v_add_f32_e32 v81, 1.0, v81
	v_rcp_f32_e32 v81, v81
	v_and_b32_e32 v74, 0xffff0000, v130
	v_add_f32_e32 v82, 1.0, v82
	v_rcp_f32_e32 v82, v82
	v_and_b32_e32 v80, 0xffff0000, v132
	v_mul_f32_e32 v1, v81, v1
	v_mul_f32_e32 v1, v70, v1
	v_mul_f32_e32 v70, v82, v77
	v_mul_f32_e32 v77, 0xbfb8aa3b, v74
	v_mul_f32_e32 v81, 0xbfb8aa3b, v80
	v_exp_f32_e32 v77, v77
	v_exp_f32_e32 v81, v81
	v_lshlrev_b32_e32 v75, 16, v131
	v_mul_f32_e32 v70, v66, v70
	v_add_f32_e32 v66, 1.0, v77
	v_add_f32_e32 v77, 1.0, v81
	v_mul_f32_e32 v81, 0xbfb8aa3b, v75
	v_rcp_f32_e32 v66, v66
	v_exp_f32_e32 v81, v81
	v_rcp_f32_e32 v77, v77
	v_lshlrev_b32_e32 v83, 16, v133
	v_mul_f32_e32 v66, v66, v74
	v_add_f32_e32 v74, 1.0, v81
	v_rcp_f32_e32 v74, v74
	v_and_b32_e32 v76, 0xffff0000, v131
	v_mul_f32_e32 v66, v71, v66
	v_mul_f32_e32 v71, v77, v80
	v_mul_f32_e32 v77, 0xbfb8aa3b, v83
	v_exp_f32_e32 v77, v77
	v_mul_f32_e32 v71, v67, v71
	v_mul_f32_e32 v67, v74, v75
	v_mul_f32_e32 v74, 0xbfb8aa3b, v76
	v_exp_f32_e32 v74, v74
	v_and_b32_e32 v84, 0xffff0000, v133
	v_mul_f32_e32 v67, v72, v67
	v_add_f32_e32 v72, 1.0, v77
	v_rcp_f32_e32 v72, v72
	v_mul_f32_e32 v75, 0xbfb8aa3b, v84
	v_add_f32_e32 v74, 1.0, v74
	v_exp_f32_e32 v75, v75
	v_rcp_f32_e32 v74, v74
	v_mul_f32_e32 v72, v72, v83
	v_mul_f32_e32 v72, v68, v72
	v_add_f32_e32 v75, 1.0, v75
	v_mul_f32_e32 v68, v74, v76
	v_rcp_f32_e32 v75, v75
	v_mul_f32_e32 v68, v73, v68
	v_cvt_pk_bf16_f32 v66, v1, v66
	v_cvt_pk_bf16_f32 v67, v67, v68
	v_cvt_pk_bf16_f32 v68, v70, v71
	v_add_u32_e32 v70, 0x80, v152
	v_ashrrev_i32_e32 v71, 31, v70
	v_lshlrev_b64 v[104:105], 11, v[70:71]
	v_mul_f32_e32 v73, v75, v84
	v_lshl_add_u64 v[70:71], s[12:13], 0, v[104:105]
	v_mul_f32_e32 v69, v69, v73
	v_lshl_add_u64 v[70:71], v[70:71], 0, v[150:151]
	v_cvt_pk_bf16_f32 v69, v72, v69
	global_load_dwordx4 v[92:95], v[70:71], off
	s_nop 0
	global_store_dwordx4 v[78:79], v[66:69], off offset:256
	global_load_dwordx4 v[96:99], v[70:71], off offset:256
	s_waitcnt vmcnt(0)
; __device__ __forceinline__ float siluf_(float x) { return x * __builtin_amdgcn_rcpf(1.0f + __expf(-x)); }
; __device__ __forceinline__ u32x4 pack8(const float (&f)[8]) { u32x4 r; r[0] = cvt_pk_bf16(f[0], f[1]); r[1] = cvt_pk_bf16(f[2], f[3]); r[2] = cvt_pk_bf16(f[4], f[5]); r[3] = cvt_pk_bf16(f[6], f[7]); return r; }
;     __device__ __forceinline__ void operator()(EPI_ARGS) const {
;     ...
;                 for (int bj = 0; bj < 2; ++bj) zz[m][bj] = *(const u32x4*)(parts + E_PZC + (size_t)EPI_ROW * 1024 + EPI_COL(bj));
; #pragma unroll
;             for (int m = 0; m < 4; ++m)
; #pragma unroll
;                 for (int bj = 0; bj < 2; ++bj) { const f32x4 v0 = acc[ai][bj][m][0], v1 = acc[ai][bj][m][1]; float z[8]; unpack8(zz[m][bj], z); float o[8];
; #pragma unroll
;                     for (int j = 0; j < 4; ++j) { o[j] = v0[j] * siluf_(z[j]); o[4 + j] = v1[j] * siluf_(z[4 + j]); }
;                     *(u32x4*)(O + (size_t)EPI_ROW * 1024 + EPI_COL(bj)) = pack8(o); } }
	v_lshlrev_b32_e32 v1, 16, v92
	v_add_u32_e32 v66, 0x90, v152
	v_ashrrev_i32_e32 v67, 31, v66
	v_lshlrev_b64 v[90:91], 11, v[66:67]
	v_lshl_add_u64 v[66:67], s[12:13], 0, v[90:91]
	v_lshl_add_u64 v[66:67], v[66:67], 0, v[150:151]
	global_load_dwordx4 v[100:103], v[66:67], off
	global_load_dwordx4 v[82:85], v[66:67], off offset:256
	v_add_u32_e32 v66, 0xa0, v152
	v_ashrrev_i32_e32 v67, 31, v66
	v_lshlrev_b64 v[88:89], 11, v[66:67]
	v_lshl_add_u64 v[66:67], s[12:13], 0, v[88:89]
	v_lshl_add_u64 v[66:67], v[66:67], 0, v[150:151]
	global_load_dwordx4 v[78:81], v[66:67], off
	global_load_dwordx4 v[74:77], v[66:67], off offset:256
	v_add_u32_e32 v66, 0xb0, v152
	v_ashrrev_i32_e32 v67, 31, v66
	v_lshlrev_b64 v[86:87], 11, v[66:67]
	v_lshl_add_u64 v[66:67], s[12:13], 0, v[86:87]
	v_lshl_add_u64 v[106:107], v[66:67], 0, v[150:151]
	global_load_dwordx4 v[70:73], v[106:107], off
	global_load_dwordx4 v[66:69], v[106:107], off offset:256
	v_lshlrev_b32_e32 v107, 16, v94
	v_mul_f32_e32 v108, 0xbfb8aa3b, v1
	v_exp_f32_e32 v108, v108
	v_mul_f32_e32 v109, 0xbfb8aa3b, v107
	v_exp_f32_e32 v109, v109
	v_and_b32_e32 v92, 0xffff0000, v92
	v_add_f32_e32 v108, 1.0, v108
	v_rcp_f32_e32 v108, v108
	v_add_f32_e32 v109, 1.0, v109
	v_rcp_f32_e32 v109, v109
	v_and_b32_e32 v94, 0xffff0000, v94
	v_mul_f32_e32 v1, v108, v1
	v_mul_f32_e32 v1, v62, v1
	v_mul_f32_e32 v62, v109, v107
	v_mul_f32_e32 v107, 0xbfb8aa3b, v92
	v_mul_f32_e32 v108, 0xbfb8aa3b, v94
	v_exp_f32_e32 v107, v107
	v_exp_f32_e32 v108, v108
	v_lshlrev_b32_e32 v106, 16, v93
	v_mul_f32_e32 v62, v58, v62
	v_add_f32_e32 v58, 1.0, v107
	v_add_f32_e32 v107, 1.0, v108
	v_mul_f32_e32 v108, 0xbfb8aa3b, v106
	v_rcp_f32_e32 v58, v58
	v_exp_f32_e32 v108, v108
	v_rcp_f32_e32 v107, v107
	v_lshlrev_b32_e32 v110, 16, v95
	v_mul_f32_e32 v58, v58, v92
	v_add_f32_e32 v92, 1.0, v108
	v_mul_f32_e32 v58, v63, v58
	v_mul_f32_e32 v63, v107, v94
	v_rcp_f32_e32 v92, v92
	v_mul_f32_e32 v94, 0xbfb8aa3b, v110
	v_exp_f32_e32 v94, v94
	v_and_b32_e32 v93, 0xffff0000, v93
	v_and_b32_e32 v95, 0xffff0000, v95
	v_mul_f32_e32 v63, v59, v63
	v_mul_f32_e32 v59, v92, v106
	v_mul_f32_e32 v92, 0xbfb8aa3b, v93
	v_mul_f32_e32 v59, v64, v59
	v_add_f32_e32 v64, 1.0, v94
	v_exp_f32_e32 v92, v92
	v_mul_f32_e32 v94, 0xbfb8aa3b, v95
	v_exp_f32_e32 v94, v94
	v_rcp_f32_e32 v64, v64
	v_add_f32_e32 v92, 1.0, v92
	v_rcp_f32_e32 v92, v92
	v_add_f32_e32 v94, 1.0, v94
	v_rcp_f32_e32 v94, v94
	v_mul_f32_e32 v64, v64, v110
	v_mul_f32_e32 v64, v60, v64
	v_mul_f32_e32 v60, v92, v93
	v_mul_f32_e32 v60, v65, v60
	v_mul_f32_e32 v65, v94, v95
	v_mul_f32_e32 v61, v61, v65
	v_cvt_pk_bf16_f32 v58, v1, v58
	v_cvt_pk_bf16_f32 v59, v59, v60
	v_cvt_pk_bf16_f32 v60, v62, v63
	v_lshl_add_u64 v[62:63], s[4:5], 0, v[104:105]
	v_cvt_pk_bf16_f32 v61, v64, v61
	v_lshl_add_u64 v[62:63], v[62:63], 0, v[150:151]
	v_lshlrev_b32_e32 v1, 16, v96
	global_store_dwordx4 v[62:63], v[58:61], off
	v_mul_f32_e32 v65, 0xbfb8aa3b, v1
	v_exp_f32_e32 v65, v65
	v_lshlrev_b32_e32 v61, 16, v98
	v_mul_f32_e32 v92, 0xbfb8aa3b, v61
	v_exp_f32_e32 v92, v92
	v_add_f32_e32 v65, 1.0, v65
	v_rcp_f32_e32 v65, v65
	v_and_b32_e32 v58, 0xffff0000, v96
	v_add_f32_e32 v92, 1.0, v92
	v_rcp_f32_e32 v92, v92
	v_and_b32_e32 v64, 0xffff0000, v98
	v_mul_f32_e32 v1, v65, v1
	v_mul_f32_e32 v1, v54, v1
	v_mul_f32_e32 v54, v92, v61
	v_mul_f32_e32 v61, 0xbfb8aa3b, v58
	v_mul_f32_e32 v65, 0xbfb8aa3b, v64
	v_exp_f32_e32 v61, v61
	v_exp_f32_e32 v65, v65
	v_lshlrev_b32_e32 v59, 16, v97
	v_mul_f32_e32 v54, v50, v54
	v_add_f32_e32 v50, 1.0, v61
	v_add_f32_e32 v61, 1.0, v65
	v_mul_f32_e32 v65, 0xbfb8aa3b, v59
	v_rcp_f32_e32 v50, v50
	v_exp_f32_e32 v65, v65
	v_rcp_f32_e32 v61, v61
	v_lshlrev_b32_e32 v93, 16, v99
	v_mul_f32_e32 v50, v50, v58
	v_add_f32_e32 v58, 1.0, v65
	v_rcp_f32_e32 v58, v58
	v_and_b32_e32 v60, 0xffff0000, v97
	v_mul_f32_e32 v50, v55, v50
	v_mul_f32_e32 v55, v61, v64
	v_mul_f32_e32 v61, 0xbfb8aa3b, v93
	v_and_b32_e32 v94, 0xffff0000, v99
	v_exp_f32_e32 v61, v61
	v_mul_f32_e32 v55, v51, v55
	v_mul_f32_e32 v51, v58, v59
	v_mul_f32_e32 v58, 0xbfb8aa3b, v60
	v_exp_f32_e32 v58, v58
	v_mul_f32_e32 v59, 0xbfb8aa3b, v94
	v_exp_f32_e32 v59, v59
	v_mul_f32_e32 v51, v56, v51
	v_add_f32_e32 v56, 1.0, v61
	v_rcp_f32_e32 v56, v56
	v_add_f32_e32 v58, 1.0, v58
	v_rcp_f32_e32 v58, v58
	v_add_f32_e32 v59, 1.0, v59
	v_rcp_f32_e32 v59, v59
	v_mul_f32_e32 v56, v56, v93
	v_mul_f32_e32 v56, v52, v56
	v_mul_f32_e32 v52, v58, v60
	v_mul_f32_e32 v52, v57, v52
	v_mul_f32_e32 v57, v59, v94
	v_mul_f32_e32 v53, v53, v57
	v_cvt_pk_bf16_f32 v50, v1, v50
	v_cvt_pk_bf16_f32 v51, v51, v52
	v_cvt_pk_bf16_f32 v52, v54, v55
	v_cvt_pk_bf16_f32 v53, v56, v53
	s_waitcnt vmcnt(0)
; __device__ __forceinline__ float siluf_(float x) { return x * __builtin_amdgcn_rcpf(1.0f + __expf(-x)); }
; __device__ __forceinline__ u32x4 pack8(const float (&f)[8]) { u32x4 r; r[0] = cvt_pk_bf16(f[0], f[1]); r[1] = cvt_pk_bf16(f[2], f[3]); r[2] = cvt_pk_bf16(f[4], f[5]); r[3] = cvt_pk_bf16(f[6], f[7]); return r; }
;     __device__ __forceinline__ void operator()(EPI_ARGS) const {
;     ...
;                 for (int bj = 0; bj < 2; ++bj) { const f32x4 v0 = acc[ai][bj][m][0], v1 = acc[ai][bj][m][1]; float z[8]; unpack8(zz[m][bj], z); float o[8];
; #pragma unroll
;                     for (int j = 0; j < 4; ++j) { o[j] = v0[j] * siluf_(z[j]); o[4 + j] = v1[j] * siluf_(z[4 + j]); }
;                     *(u32x4*)(O + (size_t)EPI_ROW * 1024 + EPI_COL(bj)) = pack8(o); } }
	v_lshlrev_b32_e32 v1, 16, v100
	global_store_dwordx4 v[62:63], v[50:53], off offset:256
	v_mul_f32_e32 v55, 0xbfb8aa3b, v1
	v_exp_f32_e32 v55, v55
	v_lshlrev_b32_e32 v53, 16, v102
	v_mul_f32_e32 v56, 0xbfb8aa3b, v53
	v_exp_f32_e32 v56, v56
	v_add_f32_e32 v55, 1.0, v55
	v_rcp_f32_e32 v55, v55
	v_and_b32_e32 v50, 0xffff0000, v100
	v_add_f32_e32 v56, 1.0, v56
	v_rcp_f32_e32 v56, v56
	v_and_b32_e32 v54, 0xffff0000, v102
	v_mul_f32_e32 v1, v55, v1
	v_mul_f32_e32 v1, v46, v1
	v_mul_f32_e32 v46, v56, v53
	v_mul_f32_e32 v53, 0xbfb8aa3b, v50
	v_mul_f32_e32 v55, 0xbfb8aa3b, v54
	v_exp_f32_e32 v53, v53
	v_exp_f32_e32 v55, v55
	v_lshlrev_b32_e32 v51, 16, v101
	v_mul_f32_e32 v46, v42, v46
	v_add_f32_e32 v42, 1.0, v53
	v_add_f32_e32 v53, 1.0, v55
	v_mul_f32_e32 v55, 0xbfb8aa3b, v51
	v_rcp_f32_e32 v42, v42
	v_exp_f32_e32 v55, v55
	v_rcp_f32_e32 v53, v53
	v_lshlrev_b32_e32 v57, 16, v103
	v_mul_f32_e32 v42, v42, v50
	v_add_f32_e32 v50, 1.0, v55
	v_rcp_f32_e32 v50, v50
	v_and_b32_e32 v52, 0xffff0000, v101
	v_mul_f32_e32 v42, v47, v42
	v_mul_f32_e32 v47, v53, v54
	v_mul_f32_e32 v53, 0xbfb8aa3b, v57
	v_and_b32_e32 v58, 0xffff0000, v103
	v_exp_f32_e32 v53, v53
	v_mul_f32_e32 v47, v43, v47
	v_mul_f32_e32 v43, v50, v51
	v_mul_f32_e32 v50, 0xbfb8aa3b, v52
	v_exp_f32_e32 v50, v50
	v_mul_f32_e32 v51, 0xbfb8aa3b, v58
	v_exp_f32_e32 v51, v51
	v_mul_f32_e32 v43, v48, v43
	v_add_f32_e32 v48, 1.0, v53
	v_rcp_f32_e32 v48, v48
	v_add_f32_e32 v50, 1.0, v50
	v_rcp_f32_e32 v50, v50
	v_add_f32_e32 v51, 1.0, v51
	v_rcp_f32_e32 v51, v51
	v_mul_f32_e32 v48, v48, v57
	v_mul_f32_e32 v48, v44, v48
	v_mul_f32_e32 v44, v50, v52
	v_mul_f32_e32 v44, v49, v44
	v_mul_f32_e32 v49, v51, v58
	v_mul_f32_e32 v45, v45, v49
	v_cvt_pk_bf16_f32 v42, v1, v42
	v_cvt_pk_bf16_f32 v43, v43, v44
	v_cvt_pk_bf16_f32 v44, v46, v47
	v_lshl_add_u64 v[46:47], s[4:5], 0, v[90:91]
	v_cvt_pk_bf16_f32 v45, v48, v45
	v_lshl_add_u64 v[46:47], v[46:47], 0, v[150:151]
	v_lshlrev_b32_e32 v1, 16, v82
	global_store_dwordx4 v[46:47], v[42:45], off
	v_mul_f32_e32 v49, 0xbfb8aa3b, v1
	v_exp_f32_e32 v49, v49
	v_lshlrev_b32_e32 v45, 16, v84
	v_mul_f32_e32 v50, 0xbfb8aa3b, v45
	v_exp_f32_e32 v50, v50
	v_add_f32_e32 v49, 1.0, v49
	v_rcp_f32_e32 v49, v49
	v_and_b32_e32 v42, 0xffff0000, v82
	v_add_f32_e32 v50, 1.0, v50
	v_rcp_f32_e32 v50, v50
	v_and_b32_e32 v48, 0xffff0000, v84
	v_mul_f32_e32 v1, v49, v1
	v_mul_f32_e32 v1, v38, v1
	v_mul_f32_e32 v38, v50, v45
	v_mul_f32_e32 v45, 0xbfb8aa3b, v42
	v_mul_f32_e32 v49, 0xbfb8aa3b, v48
	v_exp_f32_e32 v45, v45
	v_exp_f32_e32 v49, v49
	v_lshlrev_b32_e32 v43, 16, v83
	v_mul_f32_e32 v38, v34, v38
	v_add_f32_e32 v34, 1.0, v45
	v_add_f32_e32 v45, 1.0, v49
	v_mul_f32_e32 v49, 0xbfb8aa3b, v43
	v_rcp_f32_e32 v34, v34
	v_exp_f32_e32 v49, v49
	v_rcp_f32_e32 v45, v45
	v_lshlrev_b32_e32 v51, 16, v85
	v_mul_f32_e32 v34, v34, v42
	v_add_f32_e32 v42, 1.0, v49
	v_rcp_f32_e32 v42, v42
	v_and_b32_e32 v44, 0xffff0000, v83
	v_mul_f32_e32 v34, v39, v34
	v_mul_f32_e32 v39, v45, v48
	v_mul_f32_e32 v45, 0xbfb8aa3b, v51
	v_and_b32_e32 v52, 0xffff0000, v85
	v_exp_f32_e32 v45, v45
	v_mul_f32_e32 v39, v35, v39
	v_mul_f32_e32 v35, v42, v43
	v_mul_f32_e32 v42, 0xbfb8aa3b, v44
	v_exp_f32_e32 v42, v42
	v_mul_f32_e32 v43, 0xbfb8aa3b, v52
	v_exp_f32_e32 v43, v43
	v_mul_f32_e32 v35, v40, v35
	v_add_f32_e32 v40, 1.0, v45
	v_rcp_f32_e32 v40, v40
	v_add_f32_e32 v42, 1.0, v42
	v_rcp_f32_e32 v42, v42
	v_add_f32_e32 v43, 1.0, v43
	v_rcp_f32_e32 v43, v43
	v_mul_f32_e32 v40, v40, v51
	v_mul_f32_e32 v40, v36, v40
	v_mul_f32_e32 v36, v42, v44
	v_mul_f32_e32 v36, v41, v36
	v_mul_f32_e32 v41, v43, v52
	v_mul_f32_e32 v37, v37, v41
	v_cvt_pk_bf16_f32 v34, v1, v34
	v_cvt_pk_bf16_f32 v35, v35, v36
	v_cvt_pk_bf16_f32 v36, v38, v39
	v_cvt_pk_bf16_f32 v37, v40, v37
	v_lshlrev_b32_e32 v1, 16, v78
	global_store_dwordx4 v[46:47], v[34:37], off offset:256
	v_mul_f32_e32 v39, 0xbfb8aa3b, v1
	v_exp_f32_e32 v39, v39
	v_lshlrev_b32_e32 v37, 16, v80
	v_mul_f32_e32 v40, 0xbfb8aa3b, v37
	v_exp_f32_e32 v40, v40
	v_add_f32_e32 v39, 1.0, v39
	v_rcp_f32_e32 v39, v39
	v_and_b32_e32 v34, 0xffff0000, v78
	v_add_f32_e32 v40, 1.0, v40
	v_rcp_f32_e32 v40, v40
	v_and_b32_e32 v38, 0xffff0000, v80
	v_mul_f32_e32 v1, v39, v1
	v_mul_f32_e32 v1, v30, v1
	v_mul_f32_e32 v30, v40, v37
	v_mul_f32_e32 v37, 0xbfb8aa3b, v34
	v_mul_f32_e32 v39, 0xbfb8aa3b, v38
	v_exp_f32_e32 v37, v37
	v_exp_f32_e32 v39, v39
	v_lshlrev_b32_e32 v35, 16, v79
	v_mul_f32_e32 v30, v26, v30
	v_add_f32_e32 v26, 1.0, v37
	v_add_f32_e32 v37, 1.0, v39
	v_mul_f32_e32 v39, 0xbfb8aa3b, v35
	v_rcp_f32_e32 v26, v26
	v_exp_f32_e32 v39, v39
	v_rcp_f32_e32 v37, v37
	v_lshlrev_b32_e32 v41, 16, v81
	v_mul_f32_e32 v26, v26, v34
	v_add_f32_e32 v34, 1.0, v39
	v_rcp_f32_e32 v34, v34
	v_and_b32_e32 v36, 0xffff0000, v79
	v_mul_f32_e32 v26, v31, v26
	v_mul_f32_e32 v31, v37, v38
	v_mul_f32_e32 v37, 0xbfb8aa3b, v41
	v_and_b32_e32 v42, 0xffff0000, v81
	v_exp_f32_e32 v37, v37
	v_mul_f32_e32 v31, v27, v31
	v_mul_f32_e32 v27, v34, v35
	v_mul_f32_e32 v34, 0xbfb8aa3b, v36
	v_exp_f32_e32 v34, v34
	v_mul_f32_e32 v35, 0xbfb8aa3b, v42
	v_exp_f32_e32 v35, v35
	v_mul_f32_e32 v27, v32, v27
	v_add_f32_e32 v32, 1.0, v37
	v_rcp_f32_e32 v32, v32
	v_add_f32_e32 v34, 1.0, v34
	v_rcp_f32_e32 v34, v34
	v_add_f32_e32 v35, 1.0, v35
	v_rcp_f32_e32 v35, v35
	v_mul_f32_e32 v32, v32, v41
	v_mul_f32_e32 v32, v28, v32
	v_mul_f32_e32 v28, v34, v36
	v_mul_f32_e32 v28, v33, v28
	v_mul_f32_e32 v33, v35, v42
	v_mul_f32_e32 v29, v29, v33
	v_cvt_pk_bf16_f32 v26, v1, v26
	v_cvt_pk_bf16_f32 v27, v27, v28
	v_cvt_pk_bf16_f32 v28, v30, v31
	v_lshl_add_u64 v[30:31], s[4:5], 0, v[88:89]
	v_cvt_pk_bf16_f32 v29, v32, v29
; __device__ __forceinline__ float siluf_(float x) { return x * __builtin_amdgcn_rcpf(1.0f + __expf(-x)); }
; __device__ __forceinline__ u32x4 pack8(const float (&f)[8]) { u32x4 r; r[0] = cvt_pk_bf16(f[0], f[1]); r[1] = cvt_pk_bf16(f[2], f[3]); r[2] = cvt_pk_bf16(f[4], f[5]); r[3] = cvt_pk_bf16(f[6], f[7]); return r; }
; #define PG8_WAIT_V(n) asm volatile("s_waitcnt vmcnt(" #n ")" ::: "memory")
; #define PG8_BAR __builtin_amdgcn_s_barrier()
; template <class Sched, class Epi>
; __device__ __forceinline__ void gemm_phase(LAS unsigned char* lds, const Sched& S, const Epi& E, const int K, const int lda, const int ldb) {
;     ...
;     PG8_WAIT_V(0);
;     if (wr == 0) PG8_BAR;
;     PG8_BAR;
;     __device__ __forceinline__ void operator()(EPI_ARGS) const {
;     ...
;                 for (int bj = 0; bj < 2; ++bj) { const f32x4 v0 = acc[ai][bj][m][0], v1 = acc[ai][bj][m][1]; float z[8]; unpack8(zz[m][bj], z); float o[8];
; #pragma unroll
;                     for (int j = 0; j < 4; ++j) { o[j] = v0[j] * siluf_(z[j]); o[4 + j] = v1[j] * siluf_(z[4 + j]); }
;                     *(u32x4*)(O + (size_t)EPI_ROW * 1024 + EPI_COL(bj)) = pack8(o); } }
	v_lshl_add_u64 v[30:31], v[30:31], 0, v[150:151]
	v_lshlrev_b32_e32 v1, 16, v74
	global_store_dwordx4 v[30:31], v[26:29], off
	v_mul_f32_e32 v33, 0xbfb8aa3b, v1
	v_exp_f32_e32 v33, v33
	v_lshlrev_b32_e32 v29, 16, v76
	v_mul_f32_e32 v34, 0xbfb8aa3b, v29
	v_exp_f32_e32 v34, v34
	v_add_f32_e32 v33, 1.0, v33
	v_rcp_f32_e32 v33, v33
	v_and_b32_e32 v26, 0xffff0000, v74
	v_add_f32_e32 v34, 1.0, v34
	v_rcp_f32_e32 v34, v34
	v_and_b32_e32 v32, 0xffff0000, v76
	v_mul_f32_e32 v1, v33, v1
	v_mul_f32_e32 v1, v22, v1
	v_mul_f32_e32 v22, v34, v29
	v_mul_f32_e32 v29, 0xbfb8aa3b, v26
	v_mul_f32_e32 v33, 0xbfb8aa3b, v32
	v_exp_f32_e32 v29, v29
	v_exp_f32_e32 v33, v33
	v_lshlrev_b32_e32 v27, 16, v75
	v_mul_f32_e32 v22, v18, v22
	v_add_f32_e32 v18, 1.0, v29
	v_add_f32_e32 v29, 1.0, v33
	v_mul_f32_e32 v33, 0xbfb8aa3b, v27
	v_rcp_f32_e32 v18, v18
	v_exp_f32_e32 v33, v33
	v_rcp_f32_e32 v29, v29
	v_lshlrev_b32_e32 v35, 16, v77
	v_mul_f32_e32 v18, v18, v26
	v_add_f32_e32 v26, 1.0, v33
	v_rcp_f32_e32 v26, v26
	v_and_b32_e32 v28, 0xffff0000, v75
	v_mul_f32_e32 v18, v23, v18
	v_mul_f32_e32 v23, v29, v32
	v_mul_f32_e32 v29, 0xbfb8aa3b, v35
	v_and_b32_e32 v36, 0xffff0000, v77
	v_exp_f32_e32 v29, v29
	v_mul_f32_e32 v23, v19, v23
	v_mul_f32_e32 v19, v26, v27
	v_mul_f32_e32 v26, 0xbfb8aa3b, v28
	v_exp_f32_e32 v26, v26
	v_mul_f32_e32 v27, 0xbfb8aa3b, v36
	v_exp_f32_e32 v27, v27
	v_mul_f32_e32 v19, v24, v19
	v_add_f32_e32 v24, 1.0, v29
	v_rcp_f32_e32 v24, v24
	v_add_f32_e32 v26, 1.0, v26
	v_rcp_f32_e32 v26, v26
	v_add_f32_e32 v27, 1.0, v27
	v_rcp_f32_e32 v27, v27
	v_mul_f32_e32 v24, v24, v35
	v_mul_f32_e32 v24, v20, v24
	v_mul_f32_e32 v20, v26, v28
	v_mul_f32_e32 v20, v25, v20
	v_mul_f32_e32 v25, v27, v36
	v_mul_f32_e32 v21, v21, v25
	v_cvt_pk_bf16_f32 v18, v1, v18
	v_cvt_pk_bf16_f32 v19, v19, v20
	v_cvt_pk_bf16_f32 v20, v22, v23
	v_cvt_pk_bf16_f32 v21, v24, v21
	v_lshlrev_b32_e32 v1, 16, v70
	global_store_dwordx4 v[30:31], v[18:21], off offset:256
	v_mul_f32_e32 v23, 0xbfb8aa3b, v1
	v_exp_f32_e32 v23, v23
	v_lshlrev_b32_e32 v21, 16, v72
	v_mul_f32_e32 v24, 0xbfb8aa3b, v21
	v_exp_f32_e32 v24, v24
	v_add_f32_e32 v23, 1.0, v23
	v_rcp_f32_e32 v23, v23
	v_and_b32_e32 v18, 0xffff0000, v70
	v_add_f32_e32 v24, 1.0, v24
	v_rcp_f32_e32 v24, v24
	v_and_b32_e32 v22, 0xffff0000, v72
	v_mul_f32_e32 v1, v23, v1
	v_mul_f32_e32 v1, v14, v1
	v_mul_f32_e32 v14, v24, v21
	v_mul_f32_e32 v21, 0xbfb8aa3b, v18
	v_mul_f32_e32 v23, 0xbfb8aa3b, v22
	v_exp_f32_e32 v21, v21
	v_exp_f32_e32 v23, v23
	v_lshlrev_b32_e32 v19, 16, v71
	v_mul_f32_e32 v14, v10, v14
	v_add_f32_e32 v10, 1.0, v21
	v_add_f32_e32 v21, 1.0, v23
	v_mul_f32_e32 v23, 0xbfb8aa3b, v19
	v_rcp_f32_e32 v10, v10
	v_exp_f32_e32 v23, v23
	v_rcp_f32_e32 v21, v21
	v_lshlrev_b32_e32 v25, 16, v73
	v_mul_f32_e32 v10, v10, v18
	v_add_f32_e32 v18, 1.0, v23
	v_rcp_f32_e32 v18, v18
	v_and_b32_e32 v20, 0xffff0000, v71
	v_mul_f32_e32 v10, v15, v10
	v_mul_f32_e32 v15, v21, v22
	v_mul_f32_e32 v21, 0xbfb8aa3b, v25
	v_and_b32_e32 v26, 0xffff0000, v73
	v_exp_f32_e32 v21, v21
	v_mul_f32_e32 v15, v11, v15
	v_mul_f32_e32 v11, v18, v19
	v_mul_f32_e32 v18, 0xbfb8aa3b, v20
	v_exp_f32_e32 v18, v18
	v_mul_f32_e32 v19, 0xbfb8aa3b, v26
	v_exp_f32_e32 v19, v19
	v_mul_f32_e32 v11, v16, v11
	v_add_f32_e32 v16, 1.0, v21
	v_rcp_f32_e32 v16, v16
	v_add_f32_e32 v18, 1.0, v18
	v_rcp_f32_e32 v18, v18
	v_add_f32_e32 v19, 1.0, v19
	v_rcp_f32_e32 v19, v19
	v_mul_f32_e32 v16, v16, v25
	v_mul_f32_e32 v16, v12, v16
	v_mul_f32_e32 v12, v18, v20
	v_mul_f32_e32 v12, v17, v12
	v_mul_f32_e32 v17, v19, v26
	v_mul_f32_e32 v13, v13, v17
	v_cvt_pk_bf16_f32 v10, v1, v10
	v_cvt_pk_bf16_f32 v11, v11, v12
	v_cvt_pk_bf16_f32 v12, v14, v15
	v_lshl_add_u64 v[14:15], s[4:5], 0, v[86:87]
	v_cvt_pk_bf16_f32 v13, v16, v13
	v_lshl_add_u64 v[14:15], v[14:15], 0, v[150:151]
	v_lshlrev_b32_e32 v1, 16, v66
	global_store_dwordx4 v[14:15], v[10:13], off
	v_mul_f32_e32 v17, 0xbfb8aa3b, v1
	v_exp_f32_e32 v17, v17
	v_lshlrev_b32_e32 v13, 16, v68
	v_mul_f32_e32 v18, 0xbfb8aa3b, v13
	v_exp_f32_e32 v18, v18
	v_add_f32_e32 v17, 1.0, v17
	v_rcp_f32_e32 v17, v17
	v_and_b32_e32 v10, 0xffff0000, v66
	v_add_f32_e32 v18, 1.0, v18
	v_rcp_f32_e32 v18, v18
	v_and_b32_e32 v16, 0xffff0000, v68
	v_mul_f32_e32 v1, v17, v1
	v_mul_f32_e32 v1, v6, v1
	v_mul_f32_e32 v6, v18, v13
	v_mul_f32_e32 v13, 0xbfb8aa3b, v10
	v_mul_f32_e32 v17, 0xbfb8aa3b, v16
	v_exp_f32_e32 v13, v13
	v_exp_f32_e32 v17, v17
	v_lshlrev_b32_e32 v11, 16, v67
	v_mul_f32_e32 v6, v2, v6
	v_add_f32_e32 v2, 1.0, v13
	v_add_f32_e32 v13, 1.0, v17
	v_mul_f32_e32 v17, 0xbfb8aa3b, v11
	v_rcp_f32_e32 v2, v2
	v_exp_f32_e32 v17, v17
	v_rcp_f32_e32 v13, v13
	v_lshlrev_b32_e32 v19, 16, v69
	v_mul_f32_e32 v2, v2, v10
	v_add_f32_e32 v10, 1.0, v17
	v_rcp_f32_e32 v10, v10
	v_and_b32_e32 v12, 0xffff0000, v67
	v_mul_f32_e32 v2, v7, v2
	v_mul_f32_e32 v7, v13, v16
	v_mul_f32_e32 v13, 0xbfb8aa3b, v19
	v_and_b32_e32 v20, 0xffff0000, v69
	v_exp_f32_e32 v13, v13
	v_mul_f32_e32 v7, v3, v7
	v_mul_f32_e32 v3, v10, v11
	v_mul_f32_e32 v10, 0xbfb8aa3b, v12
	v_exp_f32_e32 v10, v10
	v_mul_f32_e32 v11, 0xbfb8aa3b, v20
	v_exp_f32_e32 v11, v11
	v_mul_f32_e32 v3, v8, v3
	v_add_f32_e32 v8, 1.0, v13
	v_rcp_f32_e32 v8, v8
	v_add_f32_e32 v10, 1.0, v10
	v_rcp_f32_e32 v10, v10
	v_add_f32_e32 v11, 1.0, v11
	v_rcp_f32_e32 v11, v11
	v_mul_f32_e32 v8, v8, v19
	v_mul_f32_e32 v8, v4, v8
	v_mul_f32_e32 v4, v10, v12
	v_mul_f32_e32 v4, v9, v4
	v_mul_f32_e32 v9, v11, v20
	v_mul_f32_e32 v5, v5, v9
	v_cvt_pk_bf16_f32 v2, v1, v2
	v_cvt_pk_bf16_f32 v3, v3, v4
	v_cvt_pk_bf16_f32 v4, v6, v7
	v_cvt_pk_bf16_f32 v5, v8, v5
	global_store_dwordx4 v[14:15], v[2:5], off offset:256
	s_waitcnt vmcnt(0)
	s_cbranch_scc0 .LBB0_739
	s_barrier

; #define PG8_STAGE(bufoff, gbase, voff) do { _Pragma("unroll") for (int _i = 0; _i < 2; ++_i) \
;         __builtin_amdgcn_global_load_lds((const unsigned*)((const char*)(gbase) + (voff)[_i]), (LAS unsigned*)(lds + (bufoff) + ldsw + _i * 8192), 16, 0, 0); } while (0)
; #define PG8_LDA(dst, b, h) do { _Pragma("unroll") for (int m = 0; m < 4; ++m) _Pragma("unroll") for (int k = 0; k < 2; ++k) dst[m][k] = *(const LAS bf16x8*)(lds + PG8_SA(b, h) + aoff + m * 2048 + k * 1024); } while (0)
; #define PG8_LDB(dst, b, h) do { _Pragma("unroll") for (int n = 0; n < 2; ++n) _Pragma("unroll") for (int k = 0; k < 2; ++k) dst[n][k] = *(const LAS bf16x8*)(lds + PG8_SB(b, h) + boff + n * 2048 + k * 1024); } while (0)
; #define PG8_MMA(ai, bj, At, Bt) do { __builtin_amdgcn_s_setprio(1); _Pragma("unroll") for (int m = 0; m < 4; ++m) _Pragma("unroll") for (int n = 0; n < 2; ++n) _Pragma("unroll") for (int k = 0; k < 2; ++k) \
;         acc[ai][bj][m][n] = __builtin_amdgcn_mfma_f32_16x16x32_bf16(Bt[n][k], At[m][k], acc[ai][bj][m][n], 0, 0, 0); __builtin_amdgcn_s_setprio(0); } while (0)
; #define PG8_WAIT_L(n) asm volatile("s_waitcnt lgkmcnt(" #n ")" ::: "memory")
; #define PG8_BAR __builtin_amdgcn_s_barrier()
; #define PG8_SCHED __builtin_amdgcn_sched_barrier(0)
; template <class Sched, class Epi>
; __device__ __forceinline__ void gemm_phase(LAS unsigned char* lds, const Sched& S, const Epi& E, const int K, const int lda, const int ldb) {
;     ...
;         for (int t = 0; t < nt; t += 2) {
;             const bool last = (t == nt - 2);
;             const char* a1 = cA + (size_t)(t + 1) * kstep;
;             const char* a2 = last ? nA : cA + (size_t)(t + 2) * kstep; const char* b2 = last ? nB : cB + (size_t)(t + 2) * kstep;
;             const char* a3 = a2 + kstep; const char* b3 = b2 + kstep;
;             PG8_LDB(B0, 0, 0); PG8_SCHED; PG8_LDA(At, 0, 0); PG8_STAGE(PG8_SA(1, 1), a1 + hstepA, voffA);
;             PG8_WAIT_L(8); PG8_BAR; PG8_WAIT_L(0); PG8_MMA(0, 0, At, B0); PG8_BAR; PG8_SCHED;
;     ...
;         for (int a = 0; a < 2; ++a)
; #pragma unroll
;             for (int b = 0; b < 2; ++b)
; #pragma unroll
;                 for (int m = 0; m < 4; ++m)
; #pragma unroll
;                     for (int n = 0; n < 2; ++n) acc[a][b][m][n] = (f32x4){0.f, 0.f, 0.f, 0.f};
;         cur = nxt; cA = nA; cB = nB; ++ui;
.LBB0_760:
	s_add_u32 s15, s34, 0x100
	s_addc_u32 s17, s35, 0
	s_add_u32 s28, s28, 0x40080
	v_mov_b32_e32 v2, 0
	s_addc_u32 s29, s29, 0
	s_mov_b32 s49, -2
	v_mov_b32_e32 v3, v2
	v_mov_b32_e32 v4, v2
	v_mov_b32_e32 v5, v2
	v_mov_b32_e32 v6, v2
	v_mov_b32_e32 v7, v2
	v_mov_b32_e32 v8, v2
	v_mov_b32_e32 v9, v2
	v_mov_b32_e32 v18, v2
	v_mov_b32_e32 v19, v2
	v_mov_b32_e32 v20, v2
	v_mov_b32_e32 v21, v2
	v_mov_b32_e32 v22, v2
	v_mov_b32_e32 v23, v2
	v_mov_b32_e32 v24, v2
	v_mov_b32_e32 v25, v2
	v_mov_b32_e32 v34, v2
	v_mov_b32_e32 v35, v2
	v_mov_b32_e32 v36, v2
	v_mov_b32_e32 v37, v2
	v_mov_b32_e32 v38, v2
	v_mov_b32_e32 v39, v2
	v_mov_b32_e32 v40, v2
	v_mov_b32_e32 v41, v2
	v_mov_b32_e32 v50, v2
	v_mov_b32_e32 v51, v2
	v_mov_b32_e32 v52, v2
	v_mov_b32_e32 v53, v2
	v_mov_b32_e32 v54, v2
	v_mov_b32_e32 v55, v2
	v_mov_b32_e32 v56, v2
	v_mov_b32_e32 v57, v2
	v_mov_b32_e32 v10, v2
	v_mov_b32_e32 v11, v2
	v_mov_b32_e32 v12, v2
	v_mov_b32_e32 v13, v2
	v_mov_b32_e32 v14, v2
	v_mov_b32_e32 v15, v2
	v_mov_b32_e32 v16, v2
	v_mov_b32_e32 v17, v2
	v_mov_b32_e32 v26, v2
	v_mov_b32_e32 v27, v2
	v_mov_b32_e32 v28, v2
	v_mov_b32_e32 v29, v2
	v_mov_b32_e32 v30, v2
	v_mov_b32_e32 v31, v2
	v_mov_b32_e32 v32, v2
	v_mov_b32_e32 v33, v2
	v_mov_b32_e32 v42, v2
	v_mov_b32_e32 v43, v2
	v_mov_b32_e32 v44, v2
	v_mov_b32_e32 v45, v2
	v_mov_b32_e32 v46, v2
	v_mov_b32_e32 v47, v2
	v_mov_b32_e32 v48, v2
	v_mov_b32_e32 v49, v2
	v_mov_b32_e32 v58, v2
	v_mov_b32_e32 v59, v2
	v_mov_b32_e32 v60, v2
	v_mov_b32_e32 v61, v2
	v_mov_b32_e32 v62, v2
	v_mov_b32_e32 v63, v2
	v_mov_b32_e32 v64, v2
	v_mov_b32_e32 v65, v2
	v_mov_b32_e32 v66, v2
	v_mov_b32_e32 v67, v2
	v_mov_b32_e32 v68, v2
	v_mov_b32_e32 v69, v2
	v_mov_b32_e32 v70, v2
	v_mov_b32_e32 v71, v2
	v_mov_b32_e32 v72, v2
	v_mov_b32_e32 v73, v2
	v_mov_b32_e32 v82, v2
	v_mov_b32_e32 v83, v2
	v_mov_b32_e32 v84, v2
	v_mov_b32_e32 v85, v2
	v_mov_b32_e32 v86, v2
	v_mov_b32_e32 v87, v2
	v_mov_b32_e32 v88, v2
	v_mov_b32_e32 v89, v2
	v_mov_b32_e32 v98, v2
	v_mov_b32_e32 v99, v2
	v_mov_b32_e32 v100, v2
	v_mov_b32_e32 v101, v2
	v_mov_b32_e32 v102, v2
	v_mov_b32_e32 v103, v2
	v_mov_b32_e32 v104, v2
	v_mov_b32_e32 v105, v2
	v_mov_b32_e32 v122, v2
	v_mov_b32_e32 v123, v2
	v_mov_b32_e32 v124, v2
	v_mov_b32_e32 v125, v2
	v_mov_b32_e32 v126, v2
	v_mov_b32_e32 v127, v2
	v_mov_b32_e32 v128, v2
	v_mov_b32_e32 v129, v2
	v_mov_b32_e32 v74, v2
	v_mov_b32_e32 v75, v2
	v_mov_b32_e32 v76, v2
	v_mov_b32_e32 v77, v2
	v_mov_b32_e32 v78, v2
	v_mov_b32_e32 v79, v2
	v_mov_b32_e32 v80, v2
	v_mov_b32_e32 v81, v2
	v_mov_b32_e32 v90, v2
	v_mov_b32_e32 v91, v2
	v_mov_b32_e32 v92, v2
	v_mov_b32_e32 v93, v2
	v_mov_b32_e32 v94, v2
	v_mov_b32_e32 v95, v2
	v_mov_b32_e32 v96, v2
	v_mov_b32_e32 v97, v2
	v_mov_b32_e32 v106, v2
	v_mov_b32_e32 v107, v2
	v_mov_b32_e32 v108, v2
	v_mov_b32_e32 v109, v2
	v_mov_b32_e32 v110, v2
	v_mov_b32_e32 v111, v2
	v_mov_b32_e32 v112, v2
	v_mov_b32_e32 v113, v2
	v_mov_b32_e32 v114, v2
	v_mov_b32_e32 v115, v2
	v_mov_b32_e32 v116, v2
	v_mov_b32_e32 v117, v2
	v_mov_b32_e32 v118, v2
	v_mov_b32_e32 v119, v2
	v_mov_b32_e32 v120, v2
	v_mov_b32_e32 v121, v2
	s_branch .Lal_761
	.p2align 11
.Lal_761:
.LBB0_761:
	ds_read_b128 v[144:147], v155
	ds_read_b128 v[158:161], v155 offset:1024
	ds_read_b128 v[162:165], v155 offset:2048
	ds_read_b128 v[166:169], v155 offset:3072
	s_add_u32 s34, s28, 0xfffc0080
	s_addc_u32 s35, s29, -1
	s_cmp_eq_u32 s49, 12
	s_cselect_b32 s37, s25, s35
	s_cselect_b32 s36, s24, s34
	s_cselect_b32 s35, s27, s17
	s_cselect_b32 s34, s26, s15
	s_add_i32 m0, s23, 0xc000
	ds_read_b128 v[170:173], v156
	ds_read_b128 v[174:177], v156 offset:1024
	ds_read_b128 v[178:181], v156 offset:2048
	ds_read_b128 v[182:185], v156 offset:3072
	ds_read_b128 v[186:189], v156 offset:4096
	ds_read_b128 v[190:193], v156 offset:5120
	ds_read_b128 v[194:197], v156 offset:6144
	ds_read_b128 v[198:201], v156 offset:7168
	global_load_lds_dwordx4 v140, s[28:29]
	s_add_i32 m0, s23, 0xe000
	s_nop 0
	global_load_lds_dwordx4 v138, s[28:29]
	s_waitcnt lgkmcnt(8)
	s_barrier
	s_waitcnt lgkmcnt(0)
	s_setprio 1
	s_waitcnt lgkmcnt(0)
	v_mfma_f32_16x16x32_bf16 v[118:121], v[144:147], v[170:173], v[118:121]
	v_mfma_f32_16x16x32_bf16 v[114:117], v[162:165], v[170:173], v[114:117]
	v_mfma_f32_16x16x32_bf16 v[110:113], v[144:147], v[178:181], v[110:113]
	v_mfma_f32_16x16x32_bf16 v[106:109], v[162:165], v[178:181], v[106:109]
	v_mfma_f32_16x16x32_bf16 v[94:97], v[144:147], v[186:189], v[94:97]
	v_mfma_f32_16x16x32_bf16 v[90:93], v[162:165], v[186:189], v[90:93]
	v_mfma_f32_16x16x32_bf16 v[78:81], v[144:147], v[194:197], v[78:81]
	v_mfma_f32_16x16x32_bf16 v[74:77], v[162:165], v[194:197], v[74:77]
	v_mfma_f32_16x16x32_bf16 v[118:121], v[158:161], v[174:177], v[118:121]
	v_mfma_f32_16x16x32_bf16 v[114:117], v[166:169], v[174:177], v[114:117]
	v_mfma_f32_16x16x32_bf16 v[110:113], v[158:161], v[182:185], v[110:113]
	v_mfma_f32_16x16x32_bf16 v[106:109], v[166:169], v[182:185], v[106:109]
	v_mfma_f32_16x16x32_bf16 v[94:97], v[158:161], v[190:193], v[94:97]
	v_mfma_f32_16x16x32_bf16 v[90:93], v[166:169], v[190:193], v[90:93]
	v_mfma_f32_16x16x32_bf16 v[78:81], v[158:161], v[198:201], v[78:81]
	v_mfma_f32_16x16x32_bf16 v[74:77], v[166:169], v[198:201], v[74:77]
	s_setprio 0
	s_barrier
	s_add_i32 s50, s46, s38
	s_add_u32 s62, s34, s8
	s_addc_u32 s63, s35, s9
	s_mov_b32 m0, s50
	ds_read_b128 v[202:205], v157
	ds_read_b128 v[206:209], v157 offset:1024
	ds_read_b128 v[210:213], v157 offset:2048
	ds_read_b128 v[214:217], v157 offset:3072
	global_load_lds_dwordx4 v132, s[34:35]
	s_add_u32 s64, s34, s8
	s_addc_u32 s65, s35, s9
	s_add_i32 m0, s50, 0x2000
	s_nop 0
	global_load_lds_dwordx4 v136, s[34:35]
	s_barrier
; #define PG8_STAGE(bufoff, gbase, voff) do { _Pragma("unroll") for (int _i = 0; _i < 2; ++_i) \
;         __builtin_amdgcn_global_load_lds((const unsigned*)((const char*)(gbase) + (voff)[_i]), (LAS unsigned*)(lds + (bufoff) + ldsw + _i * 8192), 16, 0, 0); } while (0)
; #define PG8_LDA(dst, b, h) do { _Pragma("unroll") for (int m = 0; m < 4; ++m) _Pragma("unroll") for (int k = 0; k < 2; ++k) dst[m][k] = *(const LAS bf16x8*)(lds + PG8_SA(b, h) + aoff + m * 2048 + k * 1024); } while (0)
; #define PG8_LDB(dst, b, h) do { _Pragma("unroll") for (int n = 0; n < 2; ++n) _Pragma("unroll") for (int k = 0; k < 2; ++k) dst[n][k] = *(const LAS bf16x8*)(lds + PG8_SB(b, h) + boff + n * 2048 + k * 1024); } while (0)
; #define PG8_MMA(ai, bj, At, Bt) do { __builtin_amdgcn_s_setprio(1); _Pragma("unroll") for (int m = 0; m < 4; ++m) _Pragma("unroll") for (int n = 0; n < 2; ++n) _Pragma("unroll") for (int k = 0; k < 2; ++k) \
;         acc[ai][bj][m][n] = __builtin_amdgcn_mfma_f32_16x16x32_bf16(Bt[n][k], At[m][k], acc[ai][bj][m][n], 0, 0, 0); __builtin_amdgcn_s_setprio(0); } while (0)
; #define PG8_WAIT_V(n) asm volatile("s_waitcnt vmcnt(" #n ")" ::: "memory")
; #define PG8_WAIT_L(n) asm volatile("s_waitcnt lgkmcnt(" #n ")" ::: "memory")
; #define PG8_BAR __builtin_amdgcn_s_barrier()
; #define PG8_SCHED __builtin_amdgcn_sched_barrier(0)
; template <class Sched, class Epi>
; __device__ __forceinline__ void gemm_phase(LAS unsigned char* lds, const Sched& S, const Epi& E, const int K, const int lda, const int ldb) {
;     ...
;             PG8_LDB(B1, 0, 1); PG8_STAGE(PG8_SB(0, 0), b2, voffB);
;             PG8_BAR; PG8_WAIT_L(0); PG8_MMA(0, 1, At, B1); PG8_BAR;
;             PG8_LDA(At, 0, 1); PG8_STAGE(PG8_SA(0, 0), a2, voffA);
;             PG8_BAR; PG8_WAIT_L(0); if (!chalf) PG8_MMA(1, 0, At, B0); PG8_BAR; PG8_SCHED;
;             PG8_STAGE(PG8_SB(0, 1), b2 + hstepB, voffB);
;             PG8_WAIT_V(6); PG8_BAR; if (!chalf) PG8_MMA(1, 1, At, B1); PG8_BAR;
;             PG8_LDB(B0, 1, 0); PG8_SCHED; PG8_LDA(At, 1, 0); PG8_STAGE(PG8_SA(0, 1), a2 + hstepA, voffA);
	s_waitcnt lgkmcnt(0)
	s_setprio 1
	s_waitcnt lgkmcnt(0)
	v_mfma_f32_16x16x32_bf16 v[126:129], v[202:205], v[170:173], v[126:129]
	v_mfma_f32_16x16x32_bf16 v[122:125], v[210:213], v[170:173], v[122:125]
	v_mfma_f32_16x16x32_bf16 v[102:105], v[202:205], v[178:181], v[102:105]
	v_mfma_f32_16x16x32_bf16 v[98:101], v[210:213], v[178:181], v[98:101]
	v_mfma_f32_16x16x32_bf16 v[86:89], v[202:205], v[186:189], v[86:89]
	v_mfma_f32_16x16x32_bf16 v[82:85], v[210:213], v[186:189], v[82:85]
	v_mfma_f32_16x16x32_bf16 v[70:73], v[202:205], v[194:197], v[70:73]
	v_mfma_f32_16x16x32_bf16 v[66:69], v[210:213], v[194:197], v[66:69]
	v_mfma_f32_16x16x32_bf16 v[126:129], v[206:209], v[174:177], v[126:129]
	v_mfma_f32_16x16x32_bf16 v[122:125], v[214:217], v[174:177], v[122:125]
	v_mfma_f32_16x16x32_bf16 v[102:105], v[206:209], v[182:185], v[102:105]
	v_mfma_f32_16x16x32_bf16 v[98:101], v[214:217], v[182:185], v[98:101]
	v_mfma_f32_16x16x32_bf16 v[86:89], v[206:209], v[190:193], v[86:89]
	v_mfma_f32_16x16x32_bf16 v[82:85], v[214:217], v[190:193], v[82:85]
	v_mfma_f32_16x16x32_bf16 v[70:73], v[206:209], v[198:201], v[70:73]
	v_mfma_f32_16x16x32_bf16 v[66:69], v[214:217], v[198:201], v[66:69]
	s_setprio 0
	s_mov_b32 m0, s23
	s_add_u32 s66, s36, s8
	s_addc_u32 s67, s37, s9
	s_barrier
	ds_read_b128 v[170:173], v156 offset:16384
	ds_read_b128 v[174:177], v156 offset:17408
	ds_read_b128 v[178:181], v156 offset:18432
	ds_read_b128 v[182:185], v156 offset:19456
	ds_read_b128 v[186:189], v156 offset:20480
	ds_read_b128 v[190:193], v156 offset:21504
	ds_read_b128 v[194:197], v156 offset:22528
	ds_read_b128 v[198:201], v156 offset:23552
	global_load_lds_dwordx4 v130, s[36:37]
	s_add_u32 s68, s36, s8
	s_addc_u32 s69, s37, s9
	s_mov_b32 m0, s39
	s_nop 0
	global_load_lds_dwordx4 v134, s[36:37]
	s_barrier
	s_waitcnt lgkmcnt(0)
	s_setprio 1
	s_waitcnt lgkmcnt(0)
	v_mfma_f32_16x16x32_bf16 v[62:65], v[144:147], v[170:173], v[62:65]
	v_mfma_f32_16x16x32_bf16 v[58:61], v[162:165], v[170:173], v[58:61]
	v_mfma_f32_16x16x32_bf16 v[46:49], v[144:147], v[178:181], v[46:49]
	v_mfma_f32_16x16x32_bf16 v[42:45], v[162:165], v[178:181], v[42:45]
	v_mfma_f32_16x16x32_bf16 v[30:33], v[144:147], v[186:189], v[30:33]
	v_mfma_f32_16x16x32_bf16 v[26:29], v[162:165], v[186:189], v[26:29]
	v_mfma_f32_16x16x32_bf16 v[14:17], v[144:147], v[194:197], v[14:17]
	v_mfma_f32_16x16x32_bf16 v[10:13], v[162:165], v[194:197], v[10:13]
	v_mfma_f32_16x16x32_bf16 v[62:65], v[158:161], v[174:177], v[62:65]
	v_mfma_f32_16x16x32_bf16 v[58:61], v[166:169], v[174:177], v[58:61]
	v_mfma_f32_16x16x32_bf16 v[46:49], v[158:161], v[182:185], v[46:49]
	v_mfma_f32_16x16x32_bf16 v[42:45], v[166:169], v[182:185], v[42:45]
	v_mfma_f32_16x16x32_bf16 v[30:33], v[158:161], v[190:193], v[30:33]
	v_mfma_f32_16x16x32_bf16 v[26:29], v[166:169], v[190:193], v[26:29]
	v_mfma_f32_16x16x32_bf16 v[14:17], v[158:161], v[198:201], v[14:17]
	v_mfma_f32_16x16x32_bf16 v[10:13], v[166:169], v[198:201], v[10:13]
	s_setprio 0
	s_barrier
	s_add_u32 s50, s34, 0x40000
	s_addc_u32 s51, s35, 0
	s_add_i32 s52, s47, s38
	s_mov_b32 m0, s52
	s_nop 0
	global_load_lds_dwordx4 v132, s[50:51]
	s_add_i32 m0, s52, 0x2000
	s_nop 0
	global_load_lds_dwordx4 v136, s[50:51]
	s_waitcnt vmcnt(6)
	s_barrier
	s_setprio 1
	v_mfma_f32_16x16x32_bf16 v[54:57], v[202:205], v[170:173], v[54:57]
	v_mfma_f32_16x16x32_bf16 v[50:53], v[210:213], v[170:173], v[50:53]
	v_mfma_f32_16x16x32_bf16 v[38:41], v[202:205], v[178:181], v[38:41]
	v_mfma_f32_16x16x32_bf16 v[34:37], v[210:213], v[178:181], v[34:37]
	v_mfma_f32_16x16x32_bf16 v[22:25], v[202:205], v[186:189], v[22:25]
	v_mfma_f32_16x16x32_bf16 v[18:21], v[210:213], v[186:189], v[18:21]
	v_mfma_f32_16x16x32_bf16 v[6:9], v[202:205], v[194:197], v[6:9]
	v_mfma_f32_16x16x32_bf16 v[2:5], v[210:213], v[194:197], v[2:5]
	v_mfma_f32_16x16x32_bf16 v[54:57], v[206:209], v[174:177], v[54:57]
	v_mfma_f32_16x16x32_bf16 v[50:53], v[214:217], v[174:177], v[50:53]
	v_mfma_f32_16x16x32_bf16 v[38:41], v[206:209], v[182:185], v[38:41]
	v_mfma_f32_16x16x32_bf16 v[34:37], v[214:217], v[182:185], v[34:37]
	v_mfma_f32_16x16x32_bf16 v[22:25], v[206:209], v[190:193], v[22:25]
	v_mfma_f32_16x16x32_bf16 v[18:21], v[214:217], v[190:193], v[18:21]
	v_mfma_f32_16x16x32_bf16 v[6:9], v[206:209], v[198:201], v[6:9]
	v_mfma_f32_16x16x32_bf16 v[2:5], v[214:217], v[198:201], v[2:5]
	s_setprio 0
	s_add_i32 s50, 16, 0x18000
	v_add_u32_e32 v166, s50, v150
	s_barrier
	ds_read_b128 v[144:147], v166
	ds_read_b128 v[158:161], v166 offset:1024
	ds_read_b128 v[162:165], v166 offset:2048
	ds_read_b128 v[166:169], v166 offset:3072
	s_add_u32 s36, s36, 0x40000
	s_addc_u32 s37, s37, 0
	s_mov_b32 m0, s40
	ds_read_b128 v[170:173], v156 offset:32768
	ds_read_b128 v[174:177], v156 offset:33792
	ds_read_b128 v[178:181], v156 offset:34816
	ds_read_b128 v[182:185], v156 offset:35840
	ds_read_b128 v[186:189], v156 offset:36864
	ds_read_b128 v[190:193], v156 offset:37888
	ds_read_b128 v[194:197], v156 offset:38912
	ds_read_b128 v[198:201], v156 offset:39936
	global_load_lds_dwordx4 v130, s[36:37]
	s_mov_b32 m0, s41
	s_nop 0
	global_load_lds_dwordx4 v134, s[36:37]
	s_waitcnt lgkmcnt(8)
	s_barrier
; #define PG8_STAGE(bufoff, gbase, voff) do { _Pragma("unroll") for (int _i = 0; _i < 2; ++_i) \
;         __builtin_amdgcn_global_load_lds((const unsigned*)((const char*)(gbase) + (voff)[_i]), (LAS unsigned*)(lds + (bufoff) + ldsw + _i * 8192), 16, 0, 0); } while (0)
; #define PG8_LDA(dst, b, h) do { _Pragma("unroll") for (int m = 0; m < 4; ++m) _Pragma("unroll") for (int k = 0; k < 2; ++k) dst[m][k] = *(const LAS bf16x8*)(lds + PG8_SA(b, h) + aoff + m * 2048 + k * 1024); } while (0)
; #define PG8_LDB(dst, b, h) do { _Pragma("unroll") for (int n = 0; n < 2; ++n) _Pragma("unroll") for (int k = 0; k < 2; ++k) dst[n][k] = *(const LAS bf16x8*)(lds + PG8_SB(b, h) + boff + n * 2048 + k * 1024); } while (0)
; #define PG8_MMA(ai, bj, At, Bt) do { __builtin_amdgcn_s_setprio(1); _Pragma("unroll") for (int m = 0; m < 4; ++m) _Pragma("unroll") for (int n = 0; n < 2; ++n) _Pragma("unroll") for (int k = 0; k < 2; ++k) \
;         acc[ai][bj][m][n] = __builtin_amdgcn_mfma_f32_16x16x32_bf16(Bt[n][k], At[m][k], acc[ai][bj][m][n], 0, 0, 0); __builtin_amdgcn_s_setprio(0); } while (0)
; #define PG8_WAIT_V(n) asm volatile("s_waitcnt vmcnt(" #n ")" ::: "memory")
; #define PG8_WAIT_L(n) asm volatile("s_waitcnt lgkmcnt(" #n ")" ::: "memory")
; #define PG8_BAR __builtin_amdgcn_s_barrier()
; #define PG8_SCHED __builtin_amdgcn_sched_barrier(0)
; template <class Sched, class Epi>
; __device__ __forceinline__ void gemm_phase(LAS unsigned char* lds, const Sched& S, const Epi& E, const int K, const int lda, const int ldb) {
;     ...
;             PG8_WAIT_L(8); PG8_BAR; PG8_WAIT_L(0); PG8_MMA(0, 0, At, B0); PG8_BAR; PG8_SCHED;
;             PG8_LDB(B1, 1, 1); PG8_STAGE(PG8_SB(1, 0), b3, voffB);
;             PG8_BAR; PG8_WAIT_L(0); PG8_MMA(0, 1, At, B1); PG8_BAR;
;             PG8_LDA(At, 1, 1); PG8_STAGE(PG8_SA(1, 0), a3, voffA);
;             PG8_BAR; PG8_WAIT_L(0); if (!chalf) PG8_MMA(1, 0, At, B0); PG8_BAR; PG8_SCHED;
;             PG8_STAGE(PG8_SB(1, 1), b3 + hstepB, voffB);
;             PG8_WAIT_V(6); PG8_BAR; if (!chalf) PG8_MMA(1, 1, At, B1); PG8_BAR;
	s_waitcnt lgkmcnt(0)
	s_setprio 1
	s_waitcnt lgkmcnt(0)
	v_mfma_f32_16x16x32_bf16 v[118:121], v[144:147], v[170:173], v[118:121]
	v_mfma_f32_16x16x32_bf16 v[114:117], v[162:165], v[170:173], v[114:117]
	v_mfma_f32_16x16x32_bf16 v[110:113], v[144:147], v[178:181], v[110:113]
	v_mfma_f32_16x16x32_bf16 v[106:109], v[162:165], v[178:181], v[106:109]
	v_mfma_f32_16x16x32_bf16 v[94:97], v[144:147], v[186:189], v[94:97]
	v_mfma_f32_16x16x32_bf16 v[90:93], v[162:165], v[186:189], v[90:93]
	v_mfma_f32_16x16x32_bf16 v[78:81], v[144:147], v[194:197], v[78:81]
	v_mfma_f32_16x16x32_bf16 v[74:77], v[162:165], v[194:197], v[74:77]
	v_mfma_f32_16x16x32_bf16 v[118:121], v[158:161], v[174:177], v[118:121]
	v_mfma_f32_16x16x32_bf16 v[114:117], v[166:169], v[174:177], v[114:117]
	v_mfma_f32_16x16x32_bf16 v[110:113], v[158:161], v[182:185], v[110:113]
	v_mfma_f32_16x16x32_bf16 v[106:109], v[166:169], v[182:185], v[106:109]
	v_mfma_f32_16x16x32_bf16 v[94:97], v[158:161], v[190:193], v[94:97]
	v_mfma_f32_16x16x32_bf16 v[90:93], v[166:169], v[190:193], v[90:93]
	v_mfma_f32_16x16x32_bf16 v[78:81], v[158:161], v[198:201], v[78:81]
	v_mfma_f32_16x16x32_bf16 v[74:77], v[166:169], v[198:201], v[74:77]
	s_setprio 0
	s_barrier
	s_add_i32 s36, 16, 0x1c000
	s_add_i32 s37, s50, s38
	v_add_u32_e32 v214, s36, v150
	s_mov_b32 m0, s37
	ds_read_b128 v[202:205], v214
	ds_read_b128 v[206:209], v214 offset:1024
	ds_read_b128 v[210:213], v214 offset:2048
	ds_read_b128 v[214:217], v214 offset:3072
	global_load_lds_dwordx4 v132, s[62:63]
	s_add_i32 m0, s37, 0x2000
	s_nop 0
	global_load_lds_dwordx4 v136, s[64:65]
	s_barrier
	s_waitcnt lgkmcnt(0)
	s_setprio 1
	s_waitcnt lgkmcnt(0)
	v_mfma_f32_16x16x32_bf16 v[126:129], v[202:205], v[170:173], v[126:129]
	v_mfma_f32_16x16x32_bf16 v[122:125], v[210:213], v[170:173], v[122:125]
	v_mfma_f32_16x16x32_bf16 v[102:105], v[202:205], v[178:181], v[102:105]
	v_mfma_f32_16x16x32_bf16 v[98:101], v[210:213], v[178:181], v[98:101]
	v_mfma_f32_16x16x32_bf16 v[86:89], v[202:205], v[186:189], v[86:89]
	v_mfma_f32_16x16x32_bf16 v[82:85], v[210:213], v[186:189], v[82:85]
	v_mfma_f32_16x16x32_bf16 v[70:73], v[202:205], v[194:197], v[70:73]
	v_mfma_f32_16x16x32_bf16 v[66:69], v[210:213], v[194:197], v[66:69]
	v_mfma_f32_16x16x32_bf16 v[126:129], v[206:209], v[174:177], v[126:129]
	v_mfma_f32_16x16x32_bf16 v[122:125], v[214:217], v[174:177], v[122:125]
	v_mfma_f32_16x16x32_bf16 v[102:105], v[206:209], v[182:185], v[102:105]
	v_mfma_f32_16x16x32_bf16 v[98:101], v[214:217], v[182:185], v[98:101]
	v_mfma_f32_16x16x32_bf16 v[86:89], v[206:209], v[190:193], v[86:89]
	v_mfma_f32_16x16x32_bf16 v[82:85], v[214:217], v[190:193], v[82:85]
	v_mfma_f32_16x16x32_bf16 v[70:73], v[206:209], v[198:201], v[70:73]
	v_mfma_f32_16x16x32_bf16 v[66:69], v[214:217], v[198:201], v[66:69]
	s_setprio 0
	s_mov_b32 m0, s42
	s_barrier
	ds_read_b128 v[170:173], v156 offset:49152
	ds_read_b128 v[174:177], v156 offset:50176
	ds_read_b128 v[178:181], v156 offset:51200
	ds_read_b128 v[182:185], v156 offset:52224
	ds_read_b128 v[186:189], v156 offset:53248
	ds_read_b128 v[190:193], v156 offset:54272
	ds_read_b128 v[194:197], v156 offset:55296
	ds_read_b128 v[198:201], v156 offset:56320
	global_load_lds_dwordx4 v130, s[66:67]
	s_mov_b32 m0, s43
	s_nop 0
	global_load_lds_dwordx4 v134, s[68:69]
	s_barrier
	s_waitcnt lgkmcnt(0)
	s_setprio 1
	s_waitcnt lgkmcnt(0)
	v_mfma_f32_16x16x32_bf16 v[62:65], v[144:147], v[170:173], v[62:65]
	v_mfma_f32_16x16x32_bf16 v[58:61], v[162:165], v[170:173], v[58:61]
	v_mfma_f32_16x16x32_bf16 v[46:49], v[144:147], v[178:181], v[46:49]
	v_mfma_f32_16x16x32_bf16 v[42:45], v[162:165], v[178:181], v[42:45]
	v_mfma_f32_16x16x32_bf16 v[30:33], v[144:147], v[186:189], v[30:33]
	v_mfma_f32_16x16x32_bf16 v[26:29], v[162:165], v[186:189], v[26:29]
	v_mfma_f32_16x16x32_bf16 v[14:17], v[144:147], v[194:197], v[14:17]
	v_mfma_f32_16x16x32_bf16 v[10:13], v[162:165], v[194:197], v[10:13]
	v_mfma_f32_16x16x32_bf16 v[62:65], v[158:161], v[174:177], v[62:65]
	v_mfma_f32_16x16x32_bf16 v[58:61], v[166:169], v[174:177], v[58:61]
	v_mfma_f32_16x16x32_bf16 v[46:49], v[158:161], v[182:185], v[46:49]
	v_mfma_f32_16x16x32_bf16 v[42:45], v[166:169], v[182:185], v[42:45]
	v_mfma_f32_16x16x32_bf16 v[30:33], v[158:161], v[190:193], v[30:33]
	v_mfma_f32_16x16x32_bf16 v[26:29], v[166:169], v[190:193], v[26:29]
	v_mfma_f32_16x16x32_bf16 v[14:17], v[158:161], v[198:201], v[14:17]
	v_mfma_f32_16x16x32_bf16 v[10:13], v[166:169], v[198:201], v[10:13]
	s_setprio 0
	s_barrier
	s_add_u32 s34, s34, 0x40080
	s_addc_u32 s35, s35, 0
	s_add_i32 s36, s36, s38
	s_mov_b32 m0, s36
	s_nop 0
	global_load_lds_dwordx4 v132, s[34:35]
	s_add_i32 m0, s36, 0x2000
	s_nop 0
	global_load_lds_dwordx4 v136, s[34:35]
	s_waitcnt vmcnt(6)
	s_barrier
	s_setprio 1
	v_mfma_f32_16x16x32_bf16 v[54:57], v[202:205], v[170:173], v[54:57]
	v_mfma_f32_16x16x32_bf16 v[50:53], v[210:213], v[170:173], v[50:53]
	v_mfma_f32_16x16x32_bf16 v[38:41], v[202:205], v[178:181], v[38:41]
	v_mfma_f32_16x16x32_bf16 v[34:37], v[210:213], v[178:181], v[34:37]
	v_mfma_f32_16x16x32_bf16 v[22:25], v[202:205], v[186:189], v[22:25]
	v_mfma_f32_16x16x32_bf16 v[18:21], v[210:213], v[186:189], v[18:21]
	v_mfma_f32_16x16x32_bf16 v[6:9], v[202:205], v[194:197], v[6:9]
	v_mfma_f32_16x16x32_bf16 v[2:5], v[210:213], v[194:197], v[2:5]
	v_mfma_f32_16x16x32_bf16 v[54:57], v[206:209], v[174:177], v[54:57]
	v_mfma_f32_16x16x32_bf16 v[50:53], v[214:217], v[174:177], v[50:53]
	v_mfma_f32_16x16x32_bf16 v[38:41], v[206:209], v[182:185], v[38:41]
	v_mfma_f32_16x16x32_bf16 v[34:37], v[214:217], v[182:185], v[34:37]
	v_mfma_f32_16x16x32_bf16 v[22:25], v[206:209], v[190:193], v[22:25]
	v_mfma_f32_16x16x32_bf16 v[18:21], v[214:217], v[190:193], v[18:21]
	v_mfma_f32_16x16x32_bf16 v[6:9], v[206:209], v[198:201], v[6:9]
	v_mfma_f32_16x16x32_bf16 v[2:5], v[214:217], v[198:201], v[2:5]
	s_setprio 0
	s_add_i32 s49, s49, 2
	s_add_u32 s15, s15, 0x100
	s_addc_u32 s17, s17, 0
	s_add_u32 s28, s28, 0x100
	s_addc_u32 s29, s29, 0
	s_cmp_gt_u32 s49, 13
	s_barrier
; __device__ __forceinline__ u32x4 pack8(const float (&f)[8]) { u32x4 r; r[0] = cvt_pk_bf16(f[0], f[1]); r[1] = cvt_pk_bf16(f[2], f[3]); r[2] = cvt_pk_bf16(f[4], f[5]); r[3] = cvt_pk_bf16(f[6], f[7]); return r; }
;     __device__ __forceinline__ void operator()(EPI_ARGS) const {
;         const int col = u.pn * 128 + wc * 32 + 8 * fq;
; #pragma unroll
;         for (int ai = 0; ai < 2; ++ai) if (ai == 0 || !u.half) { u32x4 zz[4];
; #pragma unroll
;             for (int m = 0; m < 4; ++m) zz[m] = *(const u32x4*)(parts + E_PZB + (size_t)EPI_ROW * 1024 + col);
; #pragma unroll
;             for (int m = 0; m < 4; ++m) { float z[8]; unpack8(zz[m], z);
;                 const f32x4 a0 = acc[ai][0][m][0], a1 = acc[ai][0][m][1], b0 = acc[ai][1][m][0], b1 = acc[ai][1][m][1]; float o[8];
; #pragma unroll
;                 for (int j = 0; j < 4; ++j) { o[j] = a0[j] * z[j] * __builtin_amdgcn_rcpf((1.0f + __expf(-b0[j])) * (1.0f + __expf(-z[j]))); o[4 + j] = a1[j] * z[4 + j] * __builtin_amdgcn_rcpf((1.0f + __expf(-b1[j])) * (1.0f + __expf(-z[4 + j]))); }
;                 *(u32x4*)(O + (size_t)EPI_ROW * 1024 + col) = pack8(o); } }
	s_cbranch_scc0 .LBB0_761
	v_lshl_or_b32 v144, s48, 7, v154
	v_ashrrev_i32_e32 v145, 31, v144
	v_add_u32_e32 v148, s22, v1
	v_lshlrev_b64 v[144:145], 1, v[144:145]
	v_ashrrev_i32_e32 v149, 31, v148
	v_lshl_add_u64 v[146:147], s[6:7], 0, v[144:145]
	v_lshlrev_b64 v[166:167], 11, v[148:149]
	v_lshl_add_u64 v[158:159], v[146:147], 0, v[166:167]
	global_load_dwordx4 v[158:161], v[158:159], off
	v_mul_f32_e32 v149, 0xbfb8aa3b, v122
	v_mul_f32_e32 v123, 0xbfb8aa3b, v123
	v_add_u32_e32 v122, 16, v148
	v_exp_f32_e32 v174, v123
	v_ashrrev_i32_e32 v123, 31, v122
	v_lshlrev_b64 v[122:123], 11, v[122:123]
	v_mul_f32_e32 v126, 0xbfb8aa3b, v126
	v_mul_f32_e32 v127, 0xbfb8aa3b, v127
	v_mul_f32_e32 v128, 0xbfb8aa3b, v128
	v_mul_f32_e32 v129, 0xbfb8aa3b, v129
	v_lshl_add_u64 v[122:123], v[146:147], 0, v[122:123]
	v_exp_f32_e32 v168, v126
	v_exp_f32_e32 v172, v127
	v_exp_f32_e32 v176, v128
	v_exp_f32_e32 v180, v129
	global_load_dwordx4 v[126:129], v[122:123], off
	v_mul_f32_e32 v163, 0xbfb8aa3b, v124
	v_mul_f32_e32 v125, 0xbfb8aa3b, v125
	v_add_u32_e32 v124, 32, v148
	v_add_u32_e32 v162, 48, v148
	v_exp_f32_e32 v178, v163
	v_exp_f32_e32 v182, v125
	v_ashrrev_i32_e32 v125, 31, v124
	v_ashrrev_i32_e32 v163, 31, v162
	v_lshlrev_b64 v[122:123], 11, v[124:125]
	v_lshlrev_b64 v[124:125], 11, v[162:163]
	v_lshl_add_u64 v[122:123], v[146:147], 0, v[122:123]
	v_lshl_add_u64 v[124:125], v[146:147], 0, v[124:125]
	global_load_dwordx4 v[162:165], v[122:123], off
	s_nop 0
	global_load_dwordx4 v[122:125], v[124:125], off
	v_exp_f32_e32 v170, v149
	v_mul_f32_e32 v102, 0xbfb8aa3b, v102
	v_mul_f32_e32 v98, 0xbfb8aa3b, v98
	v_mul_f32_e32 v100, 0xbfb8aa3b, v100
	v_mul_f32_e32 v86, 0xbfb8aa3b, v86
	v_mul_f32_e32 v82, 0xbfb8aa3b, v82
	v_mul_f32_e32 v84, 0xbfb8aa3b, v84
	v_mul_f32_e32 v70, 0xbfb8aa3b, v70
	v_mul_f32_e32 v66, 0xbfb8aa3b, v66
	v_mul_f32_e32 v68, 0xbfb8aa3b, v68
	v_mul_f32_e32 v54, 0xbfb8aa3b, v54
	v_mul_f32_e32 v50, 0xbfb8aa3b, v50
	v_mul_f32_e32 v52, 0xbfb8aa3b, v52
	v_mul_f32_e32 v38, 0xbfb8aa3b, v38
	v_mul_f32_e32 v34, 0xbfb8aa3b, v34
	v_mul_f32_e32 v36, 0xbfb8aa3b, v36
	v_mul_f32_e32 v22, 0xbfb8aa3b, v22
	v_mul_f32_e32 v18, 0xbfb8aa3b, v18
	v_mul_f32_e32 v20, 0xbfb8aa3b, v20
	v_mul_f32_e32 v6, 0xbfb8aa3b, v6
	v_mul_f32_e32 v2, 0xbfb8aa3b, v2
	v_mul_f32_e32 v4, 0xbfb8aa3b, v4
	s_and_b64 vcc, exec, s[12:13]
	s_mov_b32 s48, s14
	s_mov_b64 s[34:35], s[20:21]
	s_mov_b64 s[28:29], s[18:19]
	s_waitcnt vmcnt(0)
	v_lshlrev_b32_e32 v149, 16, v158
	v_and_b32_e32 v158, 0xffff0000, v158
	v_lshlrev_b32_e32 v169, 16, v159
	v_and_b32_e32 v184, 0xffff0000, v159
	v_lshlrev_b32_e32 v159, 16, v160
	v_and_b32_e32 v160, 0xffff0000, v160
	v_lshlrev_b32_e32 v171, 16, v161
	v_mul_f32_e32 v186, v118, v149
	v_mul_f32_e32 v118, 0xbfb8aa3b, v149
	v_mul_f32_e32 v149, v114, v159
	v_mul_f32_e32 v114, 0xbfb8aa3b, v159
	v_mul_f32_e32 v187, v119, v158
	v_mul_f32_e32 v119, 0xbfb8aa3b, v158
	v_mul_f32_e32 v188, v115, v160
	v_mul_f32_e32 v115, 0xbfb8aa3b, v160
	v_mul_f32_e32 v158, 0xbfb8aa3b, v169
	v_mul_f32_e32 v159, 0xbfb8aa3b, v171
	v_mul_f32_e32 v120, v120, v169
	v_mul_f32_e32 v116, v116, v171
	v_exp_f32_e32 v169, v118
	v_exp_f32_e32 v171, v114
	v_exp_f32_e32 v173, v119
	v_exp_f32_e32 v175, v115
	v_exp_f32_e32 v177, v158
	v_exp_f32_e32 v179, v159
	v_and_b32_e32 v185, 0xffff0000, v161
	v_mul_f32_e32 v160, 0xbfb8aa3b, v184
	v_mul_f32_e32 v161, 0xbfb8aa3b, v185
	v_exp_f32_e32 v181, v160
	v_exp_f32_e32 v183, v161
	v_pk_add_f32 v[114:115], v[168:169], 1.0 op_sel_hi:[1,0]
	v_pk_add_f32 v[118:119], v[170:171], 1.0 op_sel_hi:[1,0]
	v_pk_add_f32 v[158:159], v[172:173], 1.0 op_sel_hi:[1,0]
	v_pk_add_f32 v[160:161], v[174:175], 1.0 op_sel_hi:[1,0]
	v_pk_add_f32 v[168:169], v[176:177], 1.0 op_sel_hi:[1,0]
	v_pk_add_f32 v[170:171], v[178:179], 1.0 op_sel_hi:[1,0]
	v_mul_f32_e32 v114, v114, v115
	v_mul_f32_e32 v115, v118, v119
	v_mul_f32_e32 v118, v158, v159
	v_mul_f32_e32 v119, v160, v161
	v_mul_f32_e32 v158, v168, v169
	v_mul_f32_e32 v159, v170, v171
	v_rcp_f32_e32 v115, v115
	v_rcp_f32_e32 v118, v118
	v_rcp_f32_e32 v119, v119
	v_rcp_f32_e32 v158, v158
	v_rcp_f32_e32 v159, v159
	v_pk_add_f32 v[172:173], v[180:181], 1.0 op_sel_hi:[1,0]
	v_pk_add_f32 v[174:175], v[182:183], 1.0 op_sel_hi:[1,0]
	v_mul_f32_e32 v160, v172, v173
	v_rcp_f32_e32 v114, v114
	v_mul_f32_e32 v149, v149, v115
	v_mul_f32_e32 v115, v187, v118
	v_mul_f32_e32 v118, v188, v119
	v_mul_f32_e32 v119, v120, v158
	v_mul_f32_e32 v120, v116, v159
	v_mul_f32_e32 v116, v174, v175
	v_rcp_f32_e32 v160, v160
	v_rcp_f32_e32 v116, v116
	v_mul_f32_e32 v114, v186, v114
	v_mul_f32_e32 v121, v121, v184
	v_mul_f32_e32 v117, v117, v185
	v_mul_f32_e32 v121, v121, v160
	v_mul_f32_e32 v117, v117, v116
	v_cvt_pk_bf16_f32 v114, v114, v115
	v_cvt_pk_bf16_f32 v115, v119, v121
	v_cvt_pk_bf16_f32 v116, v149, v118
	v_lshl_add_u64 v[118:119], s[4:5], 0, v[166:167]
	v_lshl_add_u64 v[118:119], v[118:119], 0, v[144:145]
	v_cvt_pk_bf16_f32 v117, v120, v117
	global_store_dwordx4 v[118:119], v[114:117], off
	v_lshlrev_b32_e32 v118, 16, v126
	v_and_b32_e32 v119, 0xffff0000, v126
	v_lshlrev_b32_e32 v126, 16, v128
	v_exp_f32_e32 v114, v102
	v_mul_f32_e32 v102, 0xbfb8aa3b, v118
	v_exp_f32_e32 v115, v102
	v_exp_f32_e32 v116, v98
	v_mul_f32_e32 v98, 0xbfb8aa3b, v126
	v_exp_f32_e32 v117, v98
	v_pk_add_f32 v[114:115], v[114:115], 1.0 op_sel_hi:[1,0]
	v_mul_f32_e32 v110, v110, v118
	v_mul_f32_e32 v98, v114, v115
	v_pk_add_f32 v[114:115], v[116:117], 1.0 op_sel_hi:[1,0]
	v_rcp_f32_e32 v98, v98
	v_mul_f32_e32 v102, v114, v115
	v_rcp_f32_e32 v102, v102
	v_lshlrev_b32_e32 v120, 16, v127
	v_mul_f32_e32 v110, v110, v98
	v_mul_f32_e32 v98, v106, v126
	v_mul_f32_e32 v106, v98, v102
; __device__ __forceinline__ u32x4 pack8(const float (&f)[8]) { u32x4 r; r[0] = cvt_pk_bf16(f[0], f[1]); r[1] = cvt_pk_bf16(f[2], f[3]); r[2] = cvt_pk_bf16(f[4], f[5]); r[3] = cvt_pk_bf16(f[6], f[7]); return r; }
;     __device__ __forceinline__ void operator()(EPI_ARGS) const {
;     ...
;         for (int ai = 0; ai < 2; ++ai) if (ai == 0 || !u.half) { u32x4 zz[4];
; #pragma unroll
;             for (int m = 0; m < 4; ++m) zz[m] = *(const u32x4*)(parts + E_PZB + (size_t)EPI_ROW * 1024 + col);
; #pragma unroll
;             for (int m = 0; m < 4; ++m) { float z[8]; unpack8(zz[m], z);
;                 const f32x4 a0 = acc[ai][0][m][0], a1 = acc[ai][0][m][1], b0 = acc[ai][1][m][0], b1 = acc[ai][1][m][1]; float o[8];
; #pragma unroll
;                 for (int j = 0; j < 4; ++j) { o[j] = a0[j] * z[j] * __builtin_amdgcn_rcpf((1.0f + __expf(-b0[j])) * (1.0f + __expf(-z[j]))); o[4 + j] = a1[j] * z[4 + j] * __builtin_amdgcn_rcpf((1.0f + __expf(-b1[j])) * (1.0f + __expf(-z[4 + j]))); }
;                 *(u32x4*)(O + (size_t)EPI_ROW * 1024 + col) = pack8(o); } }
	v_mul_f32_e32 v98, 0xbfb8aa3b, v103
	v_and_b32_e32 v121, 0xffff0000, v127
	v_and_b32_e32 v127, 0xffff0000, v128
	v_exp_f32_e32 v102, v98
	v_mul_f32_e32 v98, 0xbfb8aa3b, v119
	v_exp_f32_e32 v103, v98
	v_mul_f32_e32 v98, 0xbfb8aa3b, v99
	v_mul_f32_e32 v99, 0xbfb8aa3b, v127
	v_exp_f32_e32 v98, v98
	v_exp_f32_e32 v99, v99
	v_pk_add_f32 v[102:103], v[102:103], 1.0 op_sel_hi:[1,0]
	v_lshlrev_b32_e32 v128, 16, v129
	v_mul_f32_e32 v102, v102, v103
	v_pk_add_f32 v[98:99], v[98:99], 1.0 op_sel_hi:[1,0]
	v_rcp_f32_e32 v102, v102
	v_mul_f32_e32 v98, v98, v99
	v_rcp_f32_e32 v98, v98
	v_mul_f32_e32 v99, v111, v119
	v_mul_f32_e32 v111, v99, v102
	v_mul_f32_e32 v99, v107, v127
	v_mul_f32_e32 v107, v99, v98
	v_mul_f32_e32 v98, 0xbfb8aa3b, v104
	v_mul_f32_e32 v99, 0xbfb8aa3b, v120
	v_exp_f32_e32 v98, v98
	v_exp_f32_e32 v99, v99
	v_exp_f32_e32 v102, v100
	v_mul_f32_e32 v100, 0xbfb8aa3b, v128
	v_exp_f32_e32 v103, v100
	v_pk_add_f32 v[98:99], v[98:99], 1.0 op_sel_hi:[1,0]
	v_and_b32_e32 v129, 0xffff0000, v129
	v_mul_f32_e32 v98, v98, v99
	v_rcp_f32_e32 v100, v98
	v_pk_add_f32 v[98:99], v[102:103], 1.0 op_sel_hi:[1,0]
	s_nop 0
	v_mul_f32_e32 v98, v98, v99
	v_rcp_f32_e32 v98, v98
	v_mul_f32_e32 v99, v112, v120
	v_mul_f32_e32 v102, v99, v100
	v_mul_f32_e32 v99, v108, v128
	v_mul_f32_e32 v103, v99, v98
	v_mul_f32_e32 v98, 0xbfb8aa3b, v105
	v_mul_f32_e32 v99, 0xbfb8aa3b, v121
	v_exp_f32_e32 v98, v98
	v_exp_f32_e32 v99, v99
	v_mul_f32_e32 v100, 0xbfb8aa3b, v101
	v_mul_f32_e32 v101, 0xbfb8aa3b, v129
	v_exp_f32_e32 v100, v100
	v_exp_f32_e32 v101, v101
	v_pk_add_f32 v[98:99], v[98:99], 1.0 op_sel_hi:[1,0]
	v_lshlrev_b32_e32 v108, 16, v165
	v_mul_f32_e32 v98, v98, v99
	v_rcp_f32_e32 v104, v98
	v_pk_add_f32 v[98:99], v[100:101], 1.0 op_sel_hi:[1,0]
	v_mul_f32_e32 v100, v109, v129
	v_mul_f32_e32 v98, v98, v99
	v_rcp_f32_e32 v98, v98
	v_mul_f32_e32 v99, v113, v121
	v_mul_f32_e32 v99, v99, v104
	v_lshlrev_b32_e32 v104, 16, v163
	v_mul_f32_e32 v101, v100, v98
	v_cvt_pk_bf16_f32 v98, v110, v111
	v_cvt_pk_bf16_f32 v99, v102, v99
	v_add_u32_e32 v102, s22, v151
	v_cvt_pk_bf16_f32 v100, v106, v107
	v_cvt_pk_bf16_f32 v101, v103, v101
	v_ashrrev_i32_e32 v103, 31, v102
	v_lshlrev_b64 v[102:103], 11, v[102:103]
	v_lshl_add_u64 v[102:103], s[4:5], 0, v[102:103]
	v_lshl_add_u64 v[102:103], v[102:103], 0, v[144:145]
	global_store_dwordx4 v[102:103], v[98:101], off
	v_lshlrev_b32_e32 v102, 16, v162
	v_lshlrev_b32_e32 v106, 16, v164
	v_exp_f32_e32 v98, v86
	v_mul_f32_e32 v86, 0xbfb8aa3b, v102
	v_exp_f32_e32 v99, v86
	v_exp_f32_e32 v100, v82
	v_mul_f32_e32 v82, 0xbfb8aa3b, v106
	v_exp_f32_e32 v101, v82
	v_pk_add_f32 v[98:99], v[98:99], 1.0 op_sel_hi:[1,0]
	v_mul_f32_e32 v94, v94, v102
	v_mul_f32_e32 v82, v98, v99
	v_pk_add_f32 v[98:99], v[100:101], 1.0 op_sel_hi:[1,0]
	v_rcp_f32_e32 v82, v82
	v_mul_f32_e32 v86, v98, v99
	v_rcp_f32_e32 v86, v86
	v_and_b32_e32 v103, 0xffff0000, v162
	v_mul_f32_e32 v94, v94, v82
	v_mul_f32_e32 v82, v90, v106
	v_mul_f32_e32 v90, v82, v86
	v_mul_f32_e32 v82, 0xbfb8aa3b, v87
	v_and_b32_e32 v107, 0xffff0000, v164
	v_exp_f32_e32 v86, v82
	v_mul_f32_e32 v82, 0xbfb8aa3b, v103
	v_exp_f32_e32 v87, v82
	v_mul_f32_e32 v82, 0xbfb8aa3b, v83
	v_mul_f32_e32 v83, 0xbfb8aa3b, v107
	v_exp_f32_e32 v82, v82
	v_exp_f32_e32 v83, v83
	v_pk_add_f32 v[86:87], v[86:87], 1.0 op_sel_hi:[1,0]
	v_and_b32_e32 v105, 0xffff0000, v163
	v_mul_f32_e32 v86, v86, v87
	v_pk_add_f32 v[82:83], v[82:83], 1.0 op_sel_hi:[1,0]
	v_rcp_f32_e32 v86, v86
	v_mul_f32_e32 v82, v82, v83
	v_rcp_f32_e32 v82, v82
	v_mul_f32_e32 v83, v95, v103
	v_mul_f32_e32 v95, v83, v86
	v_mul_f32_e32 v83, v91, v107
	v_mul_f32_e32 v91, v83, v82
	v_mul_f32_e32 v82, 0xbfb8aa3b, v88
	v_mul_f32_e32 v83, 0xbfb8aa3b, v104
	v_exp_f32_e32 v82, v82
	v_exp_f32_e32 v83, v83
	v_exp_f32_e32 v86, v84
	v_mul_f32_e32 v84, 0xbfb8aa3b, v108
	v_exp_f32_e32 v87, v84
	v_pk_add_f32 v[82:83], v[82:83], 1.0 op_sel_hi:[1,0]
	v_and_b32_e32 v109, 0xffff0000, v165
	v_mul_f32_e32 v82, v82, v83
	v_rcp_f32_e32 v84, v82
	v_pk_add_f32 v[82:83], v[86:87], 1.0 op_sel_hi:[1,0]
	s_nop 0
	v_mul_f32_e32 v82, v82, v83
	v_rcp_f32_e32 v82, v82
	v_mul_f32_e32 v83, v96, v104
	v_mul_f32_e32 v86, v83, v84
	v_mul_f32_e32 v83, v92, v108
	v_mul_f32_e32 v87, v83, v82
	v_mul_f32_e32 v82, 0xbfb8aa3b, v89
	v_mul_f32_e32 v83, 0xbfb8aa3b, v105
	v_exp_f32_e32 v82, v82
	v_exp_f32_e32 v83, v83
	v_mul_f32_e32 v84, 0xbfb8aa3b, v85
	v_mul_f32_e32 v85, 0xbfb8aa3b, v109
	v_exp_f32_e32 v84, v84
	v_exp_f32_e32 v85, v85
	v_pk_add_f32 v[82:83], v[82:83], 1.0 op_sel_hi:[1,0]
	v_lshlrev_b32_e32 v92, 16, v125
	v_mul_f32_e32 v82, v82, v83
	v_rcp_f32_e32 v88, v82
	v_pk_add_f32 v[82:83], v[84:85], 1.0 op_sel_hi:[1,0]
	v_mul_f32_e32 v84, v93, v109
	v_mul_f32_e32 v82, v82, v83
	v_rcp_f32_e32 v82, v82
	v_mul_f32_e32 v83, v97, v105
	v_mul_f32_e32 v83, v83, v88
	v_lshlrev_b32_e32 v88, 16, v123
	v_mul_f32_e32 v85, v84, v82
	v_cvt_pk_bf16_f32 v82, v94, v95
	v_cvt_pk_bf16_f32 v83, v86, v83
	v_add_u32_e32 v86, s22, v152
	v_cvt_pk_bf16_f32 v84, v90, v91
	v_cvt_pk_bf16_f32 v85, v87, v85
	v_ashrrev_i32_e32 v87, 31, v86
	v_lshlrev_b64 v[86:87], 11, v[86:87]
	v_lshl_add_u64 v[86:87], s[4:5], 0, v[86:87]
	v_lshl_add_u64 v[86:87], v[86:87], 0, v[144:145]
	global_store_dwordx4 v[86:87], v[82:85], off
	v_lshlrev_b32_e32 v86, 16, v122
	v_lshlrev_b32_e32 v90, 16, v124
	v_exp_f32_e32 v82, v70
	v_mul_f32_e32 v70, 0xbfb8aa3b, v86
	v_exp_f32_e32 v83, v70
	v_exp_f32_e32 v84, v66
	v_mul_f32_e32 v66, 0xbfb8aa3b, v90
	v_exp_f32_e32 v85, v66
	v_pk_add_f32 v[82:83], v[82:83], 1.0 op_sel_hi:[1,0]
	v_mul_f32_e32 v78, v78, v86
	v_mul_f32_e32 v66, v82, v83
	v_pk_add_f32 v[82:83], v[84:85], 1.0 op_sel_hi:[1,0]
	v_rcp_f32_e32 v66, v66
; __device__ __forceinline__ u32x4 pack8(const float (&f)[8]) { u32x4 r; r[0] = cvt_pk_bf16(f[0], f[1]); r[1] = cvt_pk_bf16(f[2], f[3]); r[2] = cvt_pk_bf16(f[4], f[5]); r[3] = cvt_pk_bf16(f[6], f[7]); return r; }
;     __device__ __forceinline__ void operator()(EPI_ARGS) const {
;     ...
;         for (int ai = 0; ai < 2; ++ai) if (ai == 0 || !u.half) { u32x4 zz[4];
; #pragma unroll
;             for (int m = 0; m < 4; ++m) zz[m] = *(const u32x4*)(parts + E_PZB + (size_t)EPI_ROW * 1024 + col);
; #pragma unroll
;             for (int m = 0; m < 4; ++m) { float z[8]; unpack8(zz[m], z);
;                 const f32x4 a0 = acc[ai][0][m][0], a1 = acc[ai][0][m][1], b0 = acc[ai][1][m][0], b1 = acc[ai][1][m][1]; float o[8];
; #pragma unroll
;                 for (int j = 0; j < 4; ++j) { o[j] = a0[j] * z[j] * __builtin_amdgcn_rcpf((1.0f + __expf(-b0[j])) * (1.0f + __expf(-z[j]))); o[4 + j] = a1[j] * z[4 + j] * __builtin_amdgcn_rcpf((1.0f + __expf(-b1[j])) * (1.0f + __expf(-z[4 + j]))); }
;                 *(u32x4*)(O + (size_t)EPI_ROW * 1024 + col) = pack8(o); } }
	v_mul_f32_e32 v70, v82, v83
	v_rcp_f32_e32 v70, v70
	v_and_b32_e32 v87, 0xffff0000, v122
	v_mul_f32_e32 v78, v78, v66
	v_mul_f32_e32 v66, v74, v90
	v_mul_f32_e32 v74, v66, v70
	v_mul_f32_e32 v66, 0xbfb8aa3b, v71
	v_and_b32_e32 v91, 0xffff0000, v124
	v_exp_f32_e32 v70, v66
	v_mul_f32_e32 v66, 0xbfb8aa3b, v87
	v_exp_f32_e32 v71, v66
	v_mul_f32_e32 v66, 0xbfb8aa3b, v67
	v_mul_f32_e32 v67, 0xbfb8aa3b, v91
	v_exp_f32_e32 v66, v66
	v_exp_f32_e32 v67, v67
	v_pk_add_f32 v[70:71], v[70:71], 1.0 op_sel_hi:[1,0]
	v_and_b32_e32 v89, 0xffff0000, v123
	v_mul_f32_e32 v70, v70, v71
	v_pk_add_f32 v[66:67], v[66:67], 1.0 op_sel_hi:[1,0]
	v_rcp_f32_e32 v70, v70
	v_mul_f32_e32 v66, v66, v67
	v_rcp_f32_e32 v66, v66
	v_mul_f32_e32 v67, v79, v87
	v_mul_f32_e32 v79, v67, v70
	v_mul_f32_e32 v67, v75, v91
	v_mul_f32_e32 v75, v67, v66
	v_mul_f32_e32 v66, 0xbfb8aa3b, v72
	v_mul_f32_e32 v67, 0xbfb8aa3b, v88
	v_exp_f32_e32 v66, v66
	v_exp_f32_e32 v67, v67
	v_exp_f32_e32 v70, v68
	v_mul_f32_e32 v68, 0xbfb8aa3b, v92
	v_exp_f32_e32 v71, v68
	v_pk_add_f32 v[66:67], v[66:67], 1.0 op_sel_hi:[1,0]
	v_and_b32_e32 v93, 0xffff0000, v125
	v_mul_f32_e32 v66, v66, v67
	v_rcp_f32_e32 v68, v66
	v_pk_add_f32 v[66:67], v[70:71], 1.0 op_sel_hi:[1,0]
	s_nop 0
	v_mul_f32_e32 v66, v66, v67
	v_rcp_f32_e32 v66, v66
	v_mul_f32_e32 v67, v80, v88
	v_mul_f32_e32 v70, v67, v68
	v_mul_f32_e32 v67, v76, v92
	v_mul_f32_e32 v71, v67, v66
	v_mul_f32_e32 v66, 0xbfb8aa3b, v73
	v_mul_f32_e32 v67, 0xbfb8aa3b, v89
	v_exp_f32_e32 v66, v66
	v_exp_f32_e32 v67, v67
	v_mul_f32_e32 v68, 0xbfb8aa3b, v69
	v_mul_f32_e32 v69, 0xbfb8aa3b, v93
	v_exp_f32_e32 v68, v68
	v_exp_f32_e32 v69, v69
	v_pk_add_f32 v[66:67], v[66:67], 1.0 op_sel_hi:[1,0]
	s_nop 0
	v_mul_f32_e32 v66, v66, v67
	v_rcp_f32_e32 v72, v66
	v_pk_add_f32 v[66:67], v[68:69], 1.0 op_sel_hi:[1,0]
	v_mul_f32_e32 v68, v77, v93
	v_mul_f32_e32 v66, v66, v67
	v_rcp_f32_e32 v66, v66
	v_mul_f32_e32 v67, v81, v89
	v_mul_f32_e32 v67, v67, v72
	v_mul_f32_e32 v69, v68, v66
	v_cvt_pk_bf16_f32 v66, v78, v79
	v_cvt_pk_bf16_f32 v67, v70, v67
	v_add_u32_e32 v70, s22, v153
	v_cvt_pk_bf16_f32 v68, v74, v75
	v_cvt_pk_bf16_f32 v69, v71, v69
	v_ashrrev_i32_e32 v71, 31, v70
	v_lshlrev_b64 v[70:71], 11, v[70:71]
	v_lshl_add_u64 v[70:71], s[4:5], 0, v[70:71]
	v_lshl_add_u64 v[70:71], v[70:71], 0, v[144:145]
	global_store_dwordx4 v[70:71], v[66:69], off
	s_mov_b32 s22, s16
	s_nop 0
	v_add_u32_e32 v66, 0x80, v148
	v_ashrrev_i32_e32 v67, 31, v66
	v_lshlrev_b64 v[88:89], 11, v[66:67]
	v_lshl_add_u64 v[66:67], v[146:147], 0, v[88:89]
	global_load_dwordx4 v[80:83], v[66:67], off
	v_add_u32_e32 v66, 0x90, v148
	v_ashrrev_i32_e32 v67, 31, v66
	v_lshlrev_b64 v[78:79], 11, v[66:67]
	v_lshl_add_u64 v[66:67], v[146:147], 0, v[78:79]
	global_load_dwordx4 v[84:87], v[66:67], off
	v_add_u32_e32 v66, 0xa0, v148
	v_ashrrev_i32_e32 v67, 31, v66
	v_lshlrev_b64 v[76:77], 11, v[66:67]
	v_add_u32_e32 v66, 0xb0, v148
	v_ashrrev_i32_e32 v67, 31, v66
	v_lshl_add_u64 v[90:91], v[146:147], 0, v[76:77]
	v_lshlrev_b64 v[74:75], 11, v[66:67]
	v_lshl_add_u64 v[92:93], v[146:147], 0, v[74:75]
	global_load_dwordx4 v[70:73], v[90:91], off
	global_load_dwordx4 v[66:69], v[92:93], off
	s_waitcnt vmcnt(0)
	v_lshlrev_b32_e32 v90, 16, v80
	v_and_b32_e32 v91, 0xffff0000, v80
	v_lshlrev_b32_e32 v94, 16, v82
	v_exp_f32_e32 v80, v54
	v_mul_f32_e32 v54, 0xbfb8aa3b, v90
	v_lshlrev_b32_e32 v92, 16, v81
	v_and_b32_e32 v93, 0xffff0000, v81
	v_and_b32_e32 v95, 0xffff0000, v82
	v_exp_f32_e32 v81, v54
	v_exp_f32_e32 v82, v50
	v_mul_f32_e32 v50, 0xbfb8aa3b, v94
	v_lshlrev_b32_e32 v96, 16, v83
	v_and_b32_e32 v97, 0xffff0000, v83
	v_exp_f32_e32 v83, v50
	v_pk_add_f32 v[80:81], v[80:81], 1.0 op_sel_hi:[1,0]
	v_mul_f32_e32 v62, v62, v90
	v_mul_f32_e32 v50, v80, v81
	v_pk_add_f32 v[80:81], v[82:83], 1.0 op_sel_hi:[1,0]
	v_rcp_f32_e32 v50, v50
	v_mul_f32_e32 v54, v80, v81
	v_rcp_f32_e32 v54, v54
	v_mul_f32_e32 v62, v62, v50
	v_mul_f32_e32 v50, v58, v94
	v_mul_f32_e32 v58, v50, v54
	v_mul_f32_e32 v50, 0xbfb8aa3b, v55
	v_exp_f32_e32 v54, v50
	v_mul_f32_e32 v50, 0xbfb8aa3b, v91
	v_exp_f32_e32 v55, v50
	v_mul_f32_e32 v50, 0xbfb8aa3b, v51
	v_mul_f32_e32 v51, 0xbfb8aa3b, v95
	v_exp_f32_e32 v50, v50
	v_exp_f32_e32 v51, v51
	v_pk_add_f32 v[54:55], v[54:55], 1.0 op_sel_hi:[1,0]
	v_pk_add_f32 v[50:51], v[50:51], 1.0 op_sel_hi:[1,0]
	v_mul_f32_e32 v54, v54, v55
	v_rcp_f32_e32 v54, v54
	v_mul_f32_e32 v50, v50, v51
	v_rcp_f32_e32 v50, v50
	v_mul_f32_e32 v51, v63, v91
	v_mul_f32_e32 v63, v51, v54
	v_mul_f32_e32 v51, v59, v95
	v_mul_f32_e32 v59, v51, v50
	v_mul_f32_e32 v50, 0xbfb8aa3b, v56
	v_mul_f32_e32 v51, 0xbfb8aa3b, v92
	v_exp_f32_e32 v50, v50
	v_exp_f32_e32 v51, v51
	v_exp_f32_e32 v54, v52
	v_mul_f32_e32 v52, 0xbfb8aa3b, v96
	v_exp_f32_e32 v55, v52
	v_pk_add_f32 v[50:51], v[50:51], 1.0 op_sel_hi:[1,0]
	s_nop 0
	v_mul_f32_e32 v50, v50, v51
	v_rcp_f32_e32 v52, v50
	v_pk_add_f32 v[50:51], v[54:55], 1.0 op_sel_hi:[1,0]
	s_nop 0
	v_mul_f32_e32 v50, v50, v51
	v_rcp_f32_e32 v50, v50
	v_mul_f32_e32 v51, v64, v92
	v_mul_f32_e32 v54, v51, v52
	v_mul_f32_e32 v51, v60, v96
	v_mul_f32_e32 v55, v51, v50
	v_mul_f32_e32 v50, 0xbfb8aa3b, v57
	v_mul_f32_e32 v51, 0xbfb8aa3b, v93
	v_exp_f32_e32 v50, v50
	v_exp_f32_e32 v51, v51
	v_mul_f32_e32 v52, 0xbfb8aa3b, v53
	v_mul_f32_e32 v53, 0xbfb8aa3b, v97
	v_exp_f32_e32 v52, v52
	v_exp_f32_e32 v53, v53
	v_pk_add_f32 v[50:51], v[50:51], 1.0 op_sel_hi:[1,0]
	v_lshlrev_b32_e32 v60, 16, v87
	v_mul_f32_e32 v50, v50, v51
	v_rcp_f32_e32 v56, v50
	v_pk_add_f32 v[50:51], v[52:53], 1.0 op_sel_hi:[1,0]
	v_mul_f32_e32 v52, v61, v97
	v_mul_f32_e32 v50, v50, v51
	v_rcp_f32_e32 v50, v50
	v_mul_f32_e32 v51, v65, v93
	v_mul_f32_e32 v51, v51, v56
; __device__ __forceinline__ u32x4 pack8(const float (&f)[8]) { u32x4 r; r[0] = cvt_pk_bf16(f[0], f[1]); r[1] = cvt_pk_bf16(f[2], f[3]); r[2] = cvt_pk_bf16(f[4], f[5]); r[3] = cvt_pk_bf16(f[6], f[7]); return r; }
;     __device__ __forceinline__ void operator()(EPI_ARGS) const {
;     ...
;         for (int ai = 0; ai < 2; ++ai) if (ai == 0 || !u.half) { u32x4 zz[4];
; #pragma unroll
;             for (int m = 0; m < 4; ++m) zz[m] = *(const u32x4*)(parts + E_PZB + (size_t)EPI_ROW * 1024 + col);
; #pragma unroll
;             for (int m = 0; m < 4; ++m) { float z[8]; unpack8(zz[m], z);
;                 const f32x4 a0 = acc[ai][0][m][0], a1 = acc[ai][0][m][1], b0 = acc[ai][1][m][0], b1 = acc[ai][1][m][1]; float o[8];
; #pragma unroll
;                 for (int j = 0; j < 4; ++j) { o[j] = a0[j] * z[j] * __builtin_amdgcn_rcpf((1.0f + __expf(-b0[j])) * (1.0f + __expf(-z[j]))); o[4 + j] = a1[j] * z[4 + j] * __builtin_amdgcn_rcpf((1.0f + __expf(-b1[j])) * (1.0f + __expf(-z[4 + j]))); }
;                 *(u32x4*)(O + (size_t)EPI_ROW * 1024 + col) = pack8(o); } }
	v_lshlrev_b32_e32 v56, 16, v85
	v_mul_f32_e32 v53, v52, v50
	v_cvt_pk_bf16_f32 v50, v62, v63
	v_cvt_pk_bf16_f32 v51, v54, v51
	v_cvt_pk_bf16_f32 v52, v58, v59
	v_cvt_pk_bf16_f32 v53, v55, v53
	v_lshl_add_u64 v[54:55], s[4:5], 0, v[88:89]
	v_lshl_add_u64 v[54:55], v[54:55], 0, v[144:145]
	global_store_dwordx4 v[54:55], v[50:53], off
	v_lshlrev_b32_e32 v54, 16, v84
	v_lshlrev_b32_e32 v58, 16, v86
	v_exp_f32_e32 v50, v38
	v_mul_f32_e32 v38, 0xbfb8aa3b, v54
	v_exp_f32_e32 v51, v38
	v_exp_f32_e32 v52, v34
	v_mul_f32_e32 v34, 0xbfb8aa3b, v58
	v_exp_f32_e32 v53, v34
	v_pk_add_f32 v[50:51], v[50:51], 1.0 op_sel_hi:[1,0]
	v_mul_f32_e32 v46, v46, v54
	v_mul_f32_e32 v34, v50, v51
	v_pk_add_f32 v[50:51], v[52:53], 1.0 op_sel_hi:[1,0]
	v_rcp_f32_e32 v34, v34
	v_mul_f32_e32 v38, v50, v51
	v_rcp_f32_e32 v38, v38
	v_and_b32_e32 v55, 0xffff0000, v84
	v_mul_f32_e32 v46, v46, v34
	v_mul_f32_e32 v34, v42, v58
	v_mul_f32_e32 v42, v34, v38
	v_mul_f32_e32 v34, 0xbfb8aa3b, v39
	v_and_b32_e32 v59, 0xffff0000, v86
	v_exp_f32_e32 v38, v34
	v_mul_f32_e32 v34, 0xbfb8aa3b, v55
	v_exp_f32_e32 v39, v34
	v_mul_f32_e32 v34, 0xbfb8aa3b, v35
	v_mul_f32_e32 v35, 0xbfb8aa3b, v59
	v_exp_f32_e32 v34, v34
	v_exp_f32_e32 v35, v35
	v_pk_add_f32 v[38:39], v[38:39], 1.0 op_sel_hi:[1,0]
	v_and_b32_e32 v57, 0xffff0000, v85
	v_mul_f32_e32 v38, v38, v39
	v_pk_add_f32 v[34:35], v[34:35], 1.0 op_sel_hi:[1,0]
	v_rcp_f32_e32 v38, v38
	v_mul_f32_e32 v34, v34, v35
	v_rcp_f32_e32 v34, v34
	v_mul_f32_e32 v35, v47, v55
	v_mul_f32_e32 v47, v35, v38
	v_mul_f32_e32 v35, v43, v59
	v_mul_f32_e32 v43, v35, v34
	v_mul_f32_e32 v34, 0xbfb8aa3b, v40
	v_mul_f32_e32 v35, 0xbfb8aa3b, v56
	v_exp_f32_e32 v34, v34
	v_exp_f32_e32 v35, v35
	v_exp_f32_e32 v38, v36
	v_mul_f32_e32 v36, 0xbfb8aa3b, v60
	v_exp_f32_e32 v39, v36
	v_pk_add_f32 v[34:35], v[34:35], 1.0 op_sel_hi:[1,0]
	v_and_b32_e32 v61, 0xffff0000, v87
	v_mul_f32_e32 v34, v34, v35
	v_rcp_f32_e32 v36, v34
	v_pk_add_f32 v[34:35], v[38:39], 1.0 op_sel_hi:[1,0]
	s_nop 0
	v_mul_f32_e32 v34, v34, v35
	v_rcp_f32_e32 v34, v34
	v_mul_f32_e32 v35, v48, v56
	v_mul_f32_e32 v38, v35, v36
	v_mul_f32_e32 v35, v44, v60
	v_mul_f32_e32 v39, v35, v34
	v_mul_f32_e32 v34, 0xbfb8aa3b, v41
	v_mul_f32_e32 v35, 0xbfb8aa3b, v57
	v_exp_f32_e32 v34, v34
	v_exp_f32_e32 v35, v35
	v_mul_f32_e32 v36, 0xbfb8aa3b, v37
	v_mul_f32_e32 v37, 0xbfb8aa3b, v61
	v_exp_f32_e32 v36, v36
	v_exp_f32_e32 v37, v37
	v_pk_add_f32 v[34:35], v[34:35], 1.0 op_sel_hi:[1,0]
	v_lshlrev_b32_e32 v44, 16, v73
	v_mul_f32_e32 v34, v34, v35
	v_rcp_f32_e32 v40, v34
	v_pk_add_f32 v[34:35], v[36:37], 1.0 op_sel_hi:[1,0]
	v_mul_f32_e32 v36, v45, v61
	v_mul_f32_e32 v34, v34, v35
	v_rcp_f32_e32 v34, v34
	v_mul_f32_e32 v35, v49, v57
	v_mul_f32_e32 v35, v35, v40
	v_lshlrev_b32_e32 v40, 16, v71
	v_mul_f32_e32 v37, v36, v34
	v_cvt_pk_bf16_f32 v34, v46, v47
	v_cvt_pk_bf16_f32 v35, v38, v35
	v_cvt_pk_bf16_f32 v36, v42, v43
	v_cvt_pk_bf16_f32 v37, v39, v37
	v_lshl_add_u64 v[38:39], s[4:5], 0, v[78:79]
	v_lshl_add_u64 v[38:39], v[38:39], 0, v[144:145]
	global_store_dwordx4 v[38:39], v[34:37], off
	v_lshlrev_b32_e32 v38, 16, v70
	v_lshlrev_b32_e32 v42, 16, v72
	v_exp_f32_e32 v34, v22
	v_mul_f32_e32 v22, 0xbfb8aa3b, v38
	v_exp_f32_e32 v35, v22
	v_exp_f32_e32 v36, v18
	v_mul_f32_e32 v18, 0xbfb8aa3b, v42
	v_exp_f32_e32 v37, v18
	v_pk_add_f32 v[34:35], v[34:35], 1.0 op_sel_hi:[1,0]
	v_mul_f32_e32 v30, v30, v38
	v_mul_f32_e32 v18, v34, v35
	v_pk_add_f32 v[34:35], v[36:37], 1.0 op_sel_hi:[1,0]
	v_rcp_f32_e32 v18, v18
	v_mul_f32_e32 v22, v34, v35
	v_rcp_f32_e32 v22, v22
	v_and_b32_e32 v39, 0xffff0000, v70
	v_mul_f32_e32 v30, v30, v18
	v_mul_f32_e32 v18, v26, v42
	v_mul_f32_e32 v26, v18, v22
	v_mul_f32_e32 v18, 0xbfb8aa3b, v23
	v_and_b32_e32 v43, 0xffff0000, v72
	v_exp_f32_e32 v22, v18
	v_mul_f32_e32 v18, 0xbfb8aa3b, v39
	v_exp_f32_e32 v23, v18
	v_mul_f32_e32 v18, 0xbfb8aa3b, v19
	v_mul_f32_e32 v19, 0xbfb8aa3b, v43
	v_exp_f32_e32 v18, v18
	v_exp_f32_e32 v19, v19
	v_pk_add_f32 v[22:23], v[22:23], 1.0 op_sel_hi:[1,0]
	v_and_b32_e32 v41, 0xffff0000, v71
	v_mul_f32_e32 v22, v22, v23
	v_pk_add_f32 v[18:19], v[18:19], 1.0 op_sel_hi:[1,0]
	v_rcp_f32_e32 v22, v22
	v_mul_f32_e32 v18, v18, v19
	v_rcp_f32_e32 v18, v18
	v_mul_f32_e32 v19, v31, v39
; __device__ __forceinline__ u32x4 pack8(const float (&f)[8]) { u32x4 r; r[0] = cvt_pk_bf16(f[0], f[1]); r[1] = cvt_pk_bf16(f[2], f[3]); r[2] = cvt_pk_bf16(f[4], f[5]); r[3] = cvt_pk_bf16(f[6], f[7]); return r; }
; #define PG8_WAIT_V(n) asm volatile("s_waitcnt vmcnt(" #n ")" ::: "memory")
; #define PG8_BAR __builtin_amdgcn_s_barrier()
; template <class Sched, class Epi>
; __device__ __forceinline__ void gemm_phase(LAS unsigned char* lds, const Sched& S, const Epi& E, const int K, const int lda, const int ldb) {
;     ...
;         if (!has_next) break;
; #pragma unroll
;         for (int a = 0; a < 2; ++a)
; #pragma unroll
;             for (int b = 0; b < 2; ++b)
; #pragma unroll
;                 for (int m = 0; m < 4; ++m)
; #pragma unroll
;                     for (int n = 0; n < 2; ++n) acc[a][b][m][n] = (f32x4){0.f, 0.f, 0.f, 0.f};
;         cur = nxt; cA = nA; cB = nB; ++ui;
;     }
;     PG8_WAIT_V(0);
;     if (wr == 0) PG8_BAR;
;     PG8_BAR;
;     __device__ __forceinline__ void operator()(EPI_ARGS) const {
;     ...
;         for (int ai = 0; ai < 2; ++ai) if (ai == 0 || !u.half) { u32x4 zz[4];
; #pragma unroll
;             for (int m = 0; m < 4; ++m) zz[m] = *(const u32x4*)(parts + E_PZB + (size_t)EPI_ROW * 1024 + col);
; #pragma unroll
;             for (int m = 0; m < 4; ++m) { float z[8]; unpack8(zz[m], z);
;                 const f32x4 a0 = acc[ai][0][m][0], a1 = acc[ai][0][m][1], b0 = acc[ai][1][m][0], b1 = acc[ai][1][m][1]; float o[8];
; #pragma unroll
;                 for (int j = 0; j < 4; ++j) { o[j] = a0[j] * z[j] * __builtin_amdgcn_rcpf((1.0f + __expf(-b0[j])) * (1.0f + __expf(-z[j]))); o[4 + j] = a1[j] * z[4 + j] * __builtin_amdgcn_rcpf((1.0f + __expf(-b1[j])) * (1.0f + __expf(-z[4 + j]))); }
;                 *(u32x4*)(O + (size_t)EPI_ROW * 1024 + col) = pack8(o); } }
	v_mul_f32_e32 v31, v19, v22
	v_mul_f32_e32 v19, v27, v43
	v_mul_f32_e32 v27, v19, v18
	v_mul_f32_e32 v18, 0xbfb8aa3b, v24
	v_mul_f32_e32 v19, 0xbfb8aa3b, v40
	v_exp_f32_e32 v18, v18
	v_exp_f32_e32 v19, v19
	v_exp_f32_e32 v22, v20
	v_mul_f32_e32 v20, 0xbfb8aa3b, v44
	v_exp_f32_e32 v23, v20
	v_pk_add_f32 v[18:19], v[18:19], 1.0 op_sel_hi:[1,0]
	v_and_b32_e32 v45, 0xffff0000, v73
	v_mul_f32_e32 v18, v18, v19
	v_rcp_f32_e32 v20, v18
	v_pk_add_f32 v[18:19], v[22:23], 1.0 op_sel_hi:[1,0]
	s_nop 0
	v_mul_f32_e32 v18, v18, v19
	v_rcp_f32_e32 v18, v18
	v_mul_f32_e32 v19, v32, v40
	v_mul_f32_e32 v22, v19, v20
	v_mul_f32_e32 v19, v28, v44
	v_mul_f32_e32 v23, v19, v18
	v_mul_f32_e32 v18, 0xbfb8aa3b, v25
	v_mul_f32_e32 v19, 0xbfb8aa3b, v41
	v_exp_f32_e32 v18, v18
	v_exp_f32_e32 v19, v19
	v_mul_f32_e32 v20, 0xbfb8aa3b, v21
	v_mul_f32_e32 v21, 0xbfb8aa3b, v45
	v_exp_f32_e32 v20, v20
	v_exp_f32_e32 v21, v21
	v_pk_add_f32 v[18:19], v[18:19], 1.0 op_sel_hi:[1,0]
	v_lshlrev_b32_e32 v28, 16, v69
	v_mul_f32_e32 v18, v18, v19
	v_rcp_f32_e32 v24, v18
	v_pk_add_f32 v[18:19], v[20:21], 1.0 op_sel_hi:[1,0]
	v_mul_f32_e32 v20, v29, v45
	v_mul_f32_e32 v18, v18, v19
	v_rcp_f32_e32 v18, v18
	v_mul_f32_e32 v19, v33, v41
	v_mul_f32_e32 v19, v19, v24
	v_lshlrev_b32_e32 v24, 16, v67
	v_mul_f32_e32 v21, v20, v18
	v_cvt_pk_bf16_f32 v18, v30, v31
	v_cvt_pk_bf16_f32 v19, v22, v19
	v_cvt_pk_bf16_f32 v20, v26, v27
	v_cvt_pk_bf16_f32 v21, v23, v21
	v_lshl_add_u64 v[22:23], s[4:5], 0, v[76:77]
	v_lshl_add_u64 v[22:23], v[22:23], 0, v[144:145]
	global_store_dwordx4 v[22:23], v[18:21], off
	v_lshlrev_b32_e32 v22, 16, v66
	v_lshlrev_b32_e32 v26, 16, v68
	v_exp_f32_e32 v18, v6
	v_mul_f32_e32 v6, 0xbfb8aa3b, v22
	v_exp_f32_e32 v19, v6
	v_exp_f32_e32 v20, v2
	v_mul_f32_e32 v2, 0xbfb8aa3b, v26
	v_exp_f32_e32 v21, v2
	v_pk_add_f32 v[18:19], v[18:19], 1.0 op_sel_hi:[1,0]
	v_mul_f32_e32 v14, v14, v22
	v_mul_f32_e32 v2, v18, v19
	v_pk_add_f32 v[18:19], v[20:21], 1.0 op_sel_hi:[1,0]
	v_rcp_f32_e32 v2, v2
	v_mul_f32_e32 v6, v18, v19
	v_rcp_f32_e32 v6, v6
	v_and_b32_e32 v23, 0xffff0000, v66
	v_mul_f32_e32 v14, v14, v2
	v_mul_f32_e32 v2, v10, v26
	v_mul_f32_e32 v10, v2, v6
	v_mul_f32_e32 v2, 0xbfb8aa3b, v7
	v_and_b32_e32 v27, 0xffff0000, v68
	v_exp_f32_e32 v6, v2
	v_mul_f32_e32 v2, 0xbfb8aa3b, v23
	v_exp_f32_e32 v7, v2
	v_mul_f32_e32 v2, 0xbfb8aa3b, v3
	v_mul_f32_e32 v3, 0xbfb8aa3b, v27
	v_exp_f32_e32 v2, v2
	v_exp_f32_e32 v3, v3
	v_pk_add_f32 v[6:7], v[6:7], 1.0 op_sel_hi:[1,0]
	v_and_b32_e32 v25, 0xffff0000, v67
	v_mul_f32_e32 v6, v6, v7
	v_pk_add_f32 v[2:3], v[2:3], 1.0 op_sel_hi:[1,0]
	v_rcp_f32_e32 v6, v6
	v_mul_f32_e32 v2, v2, v3
	v_rcp_f32_e32 v2, v2
	v_mul_f32_e32 v3, v15, v23
	v_mul_f32_e32 v15, v3, v6
	v_mul_f32_e32 v3, v11, v27
	v_mul_f32_e32 v11, v3, v2
	v_mul_f32_e32 v2, 0xbfb8aa3b, v8
	v_mul_f32_e32 v3, 0xbfb8aa3b, v24
	v_exp_f32_e32 v2, v2
	v_exp_f32_e32 v3, v3
	v_exp_f32_e32 v6, v4
	v_mul_f32_e32 v4, 0xbfb8aa3b, v28
	v_exp_f32_e32 v7, v4
	v_pk_add_f32 v[2:3], v[2:3], 1.0 op_sel_hi:[1,0]
	v_and_b32_e32 v29, 0xffff0000, v69
	v_mul_f32_e32 v2, v2, v3
	v_rcp_f32_e32 v4, v2
	v_pk_add_f32 v[2:3], v[6:7], 1.0 op_sel_hi:[1,0]
	s_nop 0
	v_mul_f32_e32 v2, v2, v3
	v_rcp_f32_e32 v2, v2
	v_mul_f32_e32 v3, v16, v24
	v_mul_f32_e32 v6, v3, v4
	v_mul_f32_e32 v3, v12, v28
	v_mul_f32_e32 v7, v3, v2
	v_mul_f32_e32 v2, 0xbfb8aa3b, v9
	v_mul_f32_e32 v3, 0xbfb8aa3b, v25
	v_exp_f32_e32 v2, v2
	v_exp_f32_e32 v3, v3
	v_mul_f32_e32 v4, 0xbfb8aa3b, v5
	v_mul_f32_e32 v5, 0xbfb8aa3b, v29
	v_exp_f32_e32 v4, v4
	v_exp_f32_e32 v5, v5
	v_pk_add_f32 v[2:3], v[2:3], 1.0 op_sel_hi:[1,0]
	s_nop 0
	v_mul_f32_e32 v2, v2, v3
	v_rcp_f32_e32 v8, v2
	v_pk_add_f32 v[2:3], v[4:5], 1.0 op_sel_hi:[1,0]
	v_mul_f32_e32 v4, v13, v29
	v_mul_f32_e32 v2, v2, v3
	v_rcp_f32_e32 v2, v2
	v_mul_f32_e32 v3, v17, v25
	v_mul_f32_e32 v3, v3, v8
	v_mul_f32_e32 v5, v4, v2
	v_cvt_pk_bf16_f32 v2, v14, v15
	v_cvt_pk_bf16_f32 v3, v6, v3
	v_cvt_pk_bf16_f32 v4, v10, v11
	v_cvt_pk_bf16_f32 v5, v7, v5
	v_lshl_add_u64 v[6:7], s[4:5], 0, v[74:75]
	v_lshl_add_u64 v[6:7], v[6:7], 0, v[144:145]
	global_store_dwordx4 v[6:7], v[2:5], off
	s_cbranch_vccz .LBB0_754
	s_waitcnt vmcnt(0)
	s_cmpk_gt_u32 s2, 0xff
	s_cbranch_scc1 .LBB0_765
	s_barrier

; #define PG8_STAGE(bufoff, gbase, voff) do { _Pragma("unroll") for (int _i = 0; _i < 2; ++_i) \
;         __builtin_amdgcn_global_load_lds((const unsigned*)((const char*)(gbase) + (voff)[_i]), (LAS unsigned*)(lds + (bufoff) + ldsw + _i * 8192), 16, 0, 0); } while (0)
; #define PG8_LDA(dst, b, h) do { _Pragma("unroll") for (int m = 0; m < 4; ++m) _Pragma("unroll") for (int k = 0; k < 2; ++k) dst[m][k] = *(const LAS bf16x8*)(lds + PG8_SA(b, h) + aoff + m * 2048 + k * 1024); } while (0)
; #define PG8_LDB(dst, b, h) do { _Pragma("unroll") for (int n = 0; n < 2; ++n) _Pragma("unroll") for (int k = 0; k < 2; ++k) dst[n][k] = *(const LAS bf16x8*)(lds + PG8_SB(b, h) + boff + n * 2048 + k * 1024); } while (0)
; #define PG8_MMA(ai, bj, At, Bt) do { __builtin_amdgcn_s_setprio(1); _Pragma("unroll") for (int m = 0; m < 4; ++m) _Pragma("unroll") for (int n = 0; n < 2; ++n) _Pragma("unroll") for (int k = 0; k < 2; ++k) \
;         acc[ai][bj][m][n] = __builtin_amdgcn_mfma_f32_16x16x32_bf16(Bt[n][k], At[m][k], acc[ai][bj][m][n], 0, 0, 0); __builtin_amdgcn_s_setprio(0); } while (0)
; #define PG8_WAIT_L(n) asm volatile("s_waitcnt lgkmcnt(" #n ")" ::: "memory")
; #define PG8_BAR __builtin_amdgcn_s_barrier()
; #define PG8_SCHED __builtin_amdgcn_sched_barrier(0)
; template <class Sched, class Epi>
; __device__ __forceinline__ void gemm_phase(LAS unsigned char* lds, const Sched& S, const Epi& E, const int K, const int lda, const int ldb) {
;     ...
;         for (int t = 0; t < nt; t += 2) {
;             const bool last = (t == nt - 2);
;             const char* a1 = cA + (size_t)(t + 1) * kstep;
;             const char* a2 = last ? nA : cA + (size_t)(t + 2) * kstep; const char* b2 = last ? nB : cB + (size_t)(t + 2) * kstep;
;             const char* a3 = a2 + kstep; const char* b3 = b2 + kstep;
;             PG8_LDB(B0, 0, 0); PG8_SCHED; PG8_LDA(At, 0, 0); PG8_STAGE(PG8_SA(1, 1), a1 + hstepA, voffA);
;             PG8_WAIT_L(8); PG8_BAR; PG8_WAIT_L(0); PG8_MMA(0, 0, At, B0); PG8_BAR; PG8_SCHED;
;     ...
;         for (int a = 0; a < 2; ++a)
; #pragma unroll
;             for (int b = 0; b < 2; ++b)
; #pragma unroll
;                 for (int m = 0; m < 4; ++m)
; #pragma unroll
;                     for (int n = 0; n < 2; ++n) acc[a][b][m][n] = (f32x4){0.f, 0.f, 0.f, 0.f};
;         cur = nxt; cA = nA; cB = nB; ++ui;
.LBB0_841:
	s_add_u32 s17, s34, 0x100
	s_addc_u32 s19, s35, 0
	s_add_u32 s6, s28, 0x40080
	v_mov_b32_e32 v2, 0
	s_addc_u32 s7, s29, 0
	s_mov_b32 s21, -2
	v_mov_b32_e32 v3, v2
	v_mov_b32_e32 v4, v2
	v_mov_b32_e32 v5, v2
	v_mov_b32_e32 v6, v2
	v_mov_b32_e32 v7, v2
	v_mov_b32_e32 v8, v2
	v_mov_b32_e32 v9, v2
	v_mov_b32_e32 v10, v2
	v_mov_b32_e32 v11, v2
	v_mov_b32_e32 v12, v2
	v_mov_b32_e32 v13, v2
	v_mov_b32_e32 v14, v2
	v_mov_b32_e32 v15, v2
	v_mov_b32_e32 v16, v2
	v_mov_b32_e32 v17, v2
	v_mov_b32_e32 v18, v2
	v_mov_b32_e32 v19, v2
	v_mov_b32_e32 v20, v2
	v_mov_b32_e32 v21, v2
	v_mov_b32_e32 v22, v2
	v_mov_b32_e32 v23, v2
	v_mov_b32_e32 v24, v2
	v_mov_b32_e32 v25, v2
	v_mov_b32_e32 v26, v2
	v_mov_b32_e32 v27, v2
	v_mov_b32_e32 v28, v2
	v_mov_b32_e32 v29, v2
	v_mov_b32_e32 v30, v2
	v_mov_b32_e32 v31, v2
	v_mov_b32_e32 v32, v2
	v_mov_b32_e32 v33, v2
	v_mov_b32_e32 v34, v2
	v_mov_b32_e32 v35, v2
	v_mov_b32_e32 v36, v2
	v_mov_b32_e32 v37, v2
	v_mov_b32_e32 v38, v2
	v_mov_b32_e32 v39, v2
	v_mov_b32_e32 v40, v2
	v_mov_b32_e32 v41, v2
	v_mov_b32_e32 v42, v2
	v_mov_b32_e32 v43, v2
	v_mov_b32_e32 v44, v2
	v_mov_b32_e32 v45, v2
	v_mov_b32_e32 v46, v2
	v_mov_b32_e32 v47, v2
	v_mov_b32_e32 v48, v2
	v_mov_b32_e32 v49, v2
	v_mov_b32_e32 v50, v2
	v_mov_b32_e32 v51, v2
	v_mov_b32_e32 v52, v2
	v_mov_b32_e32 v53, v2
	v_mov_b32_e32 v54, v2
	v_mov_b32_e32 v55, v2
	v_mov_b32_e32 v56, v2
	v_mov_b32_e32 v57, v2
	v_mov_b32_e32 v58, v2
	v_mov_b32_e32 v59, v2
	v_mov_b32_e32 v60, v2
	v_mov_b32_e32 v61, v2
	v_mov_b32_e32 v62, v2
	v_mov_b32_e32 v63, v2
	v_mov_b32_e32 v64, v2
	v_mov_b32_e32 v65, v2
	v_mov_b32_e32 v66, v2
	v_mov_b32_e32 v67, v2
	v_mov_b32_e32 v68, v2
	v_mov_b32_e32 v69, v2
	v_mov_b32_e32 v70, v2
	v_mov_b32_e32 v71, v2
	v_mov_b32_e32 v72, v2
	v_mov_b32_e32 v73, v2
	v_mov_b32_e32 v74, v2
	v_mov_b32_e32 v75, v2
	v_mov_b32_e32 v76, v2
	v_mov_b32_e32 v77, v2
	v_mov_b32_e32 v78, v2
	v_mov_b32_e32 v79, v2
	v_mov_b32_e32 v80, v2
	v_mov_b32_e32 v81, v2
	v_mov_b32_e32 v82, v2
	v_mov_b32_e32 v83, v2
	v_mov_b32_e32 v84, v2
	v_mov_b32_e32 v85, v2
	v_mov_b32_e32 v86, v2
	v_mov_b32_e32 v87, v2
	v_mov_b32_e32 v88, v2
	v_mov_b32_e32 v89, v2
	v_mov_b32_e32 v90, v2
	v_mov_b32_e32 v91, v2
	v_mov_b32_e32 v92, v2
	v_mov_b32_e32 v93, v2
	v_mov_b32_e32 v94, v2
	v_mov_b32_e32 v95, v2
	v_mov_b32_e32 v96, v2
	v_mov_b32_e32 v97, v2
	v_mov_b32_e32 v98, v2
	v_mov_b32_e32 v99, v2
	v_mov_b32_e32 v100, v2
	v_mov_b32_e32 v101, v2
	v_mov_b32_e32 v102, v2
	v_mov_b32_e32 v103, v2
	v_mov_b32_e32 v104, v2
	v_mov_b32_e32 v105, v2
	v_mov_b32_e32 v106, v2
	v_mov_b32_e32 v107, v2
	v_mov_b32_e32 v108, v2
	v_mov_b32_e32 v109, v2
	v_mov_b32_e32 v110, v2
	v_mov_b32_e32 v111, v2
	v_mov_b32_e32 v112, v2
	v_mov_b32_e32 v113, v2
	v_mov_b32_e32 v114, v2
	v_mov_b32_e32 v115, v2
	v_mov_b32_e32 v116, v2
	v_mov_b32_e32 v117, v2
	v_mov_b32_e32 v118, v2
	v_mov_b32_e32 v119, v2
	v_mov_b32_e32 v120, v2
	v_mov_b32_e32 v121, v2
	v_mov_b32_e32 v122, v2
	v_mov_b32_e32 v123, v2
	v_mov_b32_e32 v124, v2
	v_mov_b32_e32 v125, v2
	v_mov_b32_e32 v126, v2
	v_mov_b32_e32 v127, v2
	v_mov_b32_e32 v128, v2
	v_mov_b32_e32 v129, v2
	s_branch .Lal_842
	.p2align 11
.Lal_842:
.LBB0_842:
	ds_read_b128 v[130:133], v233
	ds_read_b128 v[134:137], v233 offset:1024
	ds_read_b128 v[138:141], v233 offset:2048
	ds_read_b128 v[142:145], v233 offset:3072
	s_add_u32 s28, s6, 0xfffc0080
	s_addc_u32 s29, s7, -1
	s_cmp_eq_u32 s21, 12
	s_cselect_b32 s35, s23, s29
	s_cselect_b32 s34, s22, s28
	s_cselect_b32 s29, s25, s19
	s_cselect_b32 s28, s24, s17
	s_add_i32 m0, s31, 0xc000
	ds_read_b128 v[146:149], v234
	ds_read_b128 v[150:153], v234 offset:1024
	ds_read_b128 v[154:157], v234 offset:2048
	ds_read_b128 v[158:161], v234 offset:3072
	ds_read_b128 v[162:165], v234 offset:4096
	ds_read_b128 v[166:169], v234 offset:5120
	ds_read_b128 v[170:173], v234 offset:6144
	ds_read_b128 v[174:177], v234 offset:7168
	global_load_lds_dwordx4 v208, s[6:7]
	s_add_i32 m0, s31, 0xe000
	s_nop 0
	global_load_lds_dwordx4 v206, s[6:7]
	s_waitcnt lgkmcnt(8)
	s_barrier
	s_waitcnt lgkmcnt(0)
	s_setprio 1
	s_waitcnt lgkmcnt(0)
	v_mfma_f32_16x16x32_bf16 v[126:129], v[130:133], v[146:149], v[126:129]
	v_mfma_f32_16x16x32_bf16 v[122:125], v[138:141], v[146:149], v[122:125]
	v_mfma_f32_16x16x32_bf16 v[118:121], v[130:133], v[154:157], v[118:121]
	v_mfma_f32_16x16x32_bf16 v[114:117], v[138:141], v[154:157], v[114:117]
	v_mfma_f32_16x16x32_bf16 v[110:113], v[130:133], v[162:165], v[110:113]
	v_mfma_f32_16x16x32_bf16 v[106:109], v[138:141], v[162:165], v[106:109]
	v_mfma_f32_16x16x32_bf16 v[102:105], v[130:133], v[170:173], v[102:105]
	v_mfma_f32_16x16x32_bf16 v[98:101], v[138:141], v[170:173], v[98:101]
	v_mfma_f32_16x16x32_bf16 v[126:129], v[134:137], v[150:153], v[126:129]
	v_mfma_f32_16x16x32_bf16 v[122:125], v[142:145], v[150:153], v[122:125]
	v_mfma_f32_16x16x32_bf16 v[118:121], v[134:137], v[158:161], v[118:121]
	v_mfma_f32_16x16x32_bf16 v[114:117], v[142:145], v[158:161], v[114:117]
	v_mfma_f32_16x16x32_bf16 v[110:113], v[134:137], v[166:169], v[110:113]
	v_mfma_f32_16x16x32_bf16 v[106:109], v[142:145], v[166:169], v[106:109]
	v_mfma_f32_16x16x32_bf16 v[102:105], v[134:137], v[174:177], v[102:105]
	v_mfma_f32_16x16x32_bf16 v[98:101], v[142:145], v[174:177], v[98:101]
	s_setprio 0
	s_barrier
	s_add_i32 s49, s43, s27
	s_add_u32 s52, s28, s14
	s_addc_u32 s53, s29, s15
	s_mov_b32 m0, s49
	ds_read_b128 v[178:181], v235
	ds_read_b128 v[182:185], v235 offset:1024
	ds_read_b128 v[186:189], v235 offset:2048
	ds_read_b128 v[190:193], v235 offset:3072
	global_load_lds_dwordx4 v200, s[28:29]
	s_add_u32 s54, s28, s14
	s_addc_u32 s55, s29, s15
	s_add_i32 m0, s49, 0x2000
	s_nop 0
	global_load_lds_dwordx4 v204, s[28:29]
	s_barrier
; #define PG8_STAGE(bufoff, gbase, voff) do { _Pragma("unroll") for (int _i = 0; _i < 2; ++_i) \
;         __builtin_amdgcn_global_load_lds((const unsigned*)((const char*)(gbase) + (voff)[_i]), (LAS unsigned*)(lds + (bufoff) + ldsw + _i * 8192), 16, 0, 0); } while (0)
; #define PG8_LDA(dst, b, h) do { _Pragma("unroll") for (int m = 0; m < 4; ++m) _Pragma("unroll") for (int k = 0; k < 2; ++k) dst[m][k] = *(const LAS bf16x8*)(lds + PG8_SA(b, h) + aoff + m * 2048 + k * 1024); } while (0)
; #define PG8_LDB(dst, b, h) do { _Pragma("unroll") for (int n = 0; n < 2; ++n) _Pragma("unroll") for (int k = 0; k < 2; ++k) dst[n][k] = *(const LAS bf16x8*)(lds + PG8_SB(b, h) + boff + n * 2048 + k * 1024); } while (0)
; #define PG8_MMA(ai, bj, At, Bt) do { __builtin_amdgcn_s_setprio(1); _Pragma("unroll") for (int m = 0; m < 4; ++m) _Pragma("unroll") for (int n = 0; n < 2; ++n) _Pragma("unroll") for (int k = 0; k < 2; ++k) \
;         acc[ai][bj][m][n] = __builtin_amdgcn_mfma_f32_16x16x32_bf16(Bt[n][k], At[m][k], acc[ai][bj][m][n], 0, 0, 0); __builtin_amdgcn_s_setprio(0); } while (0)
; #define PG8_WAIT_V(n) asm volatile("s_waitcnt vmcnt(" #n ")" ::: "memory")
; #define PG8_WAIT_L(n) asm volatile("s_waitcnt lgkmcnt(" #n ")" ::: "memory")
; #define PG8_BAR __builtin_amdgcn_s_barrier()
; #define PG8_SCHED __builtin_amdgcn_sched_barrier(0)
; template <class Sched, class Epi>
; __device__ __forceinline__ void gemm_phase(LAS unsigned char* lds, const Sched& S, const Epi& E, const int K, const int lda, const int ldb) {
;     ...
;             PG8_WAIT_L(8); PG8_BAR; PG8_WAIT_L(0); PG8_MMA(0, 0, At, B0); PG8_BAR; PG8_SCHED;
;             PG8_LDB(B1, 0, 1); PG8_STAGE(PG8_SB(0, 0), b2, voffB);
;             PG8_BAR; PG8_WAIT_L(0); PG8_MMA(0, 1, At, B1); PG8_BAR;
;             PG8_LDA(At, 0, 1); PG8_STAGE(PG8_SA(0, 0), a2, voffA);
;             PG8_BAR; PG8_WAIT_L(0); if (!chalf) PG8_MMA(1, 0, At, B0); PG8_BAR; PG8_SCHED;
;             PG8_STAGE(PG8_SB(0, 1), b2 + hstepB, voffB);
;             PG8_WAIT_V(6); PG8_BAR; if (!chalf) PG8_MMA(1, 1, At, B1); PG8_BAR;
;             PG8_LDB(B0, 1, 0); PG8_SCHED; PG8_LDA(At, 1, 0); PG8_STAGE(PG8_SA(0, 1), a2 + hstepA, voffA);
;             PG8_WAIT_L(8); PG8_BAR; PG8_WAIT_L(0); PG8_MMA(0, 0, At, B0); PG8_BAR; PG8_SCHED;
	s_waitcnt lgkmcnt(0)
	s_setprio 1
	s_waitcnt lgkmcnt(0)
	v_mfma_f32_16x16x32_bf16 v[94:97], v[178:181], v[146:149], v[94:97]
	v_mfma_f32_16x16x32_bf16 v[90:93], v[186:189], v[146:149], v[90:93]
	v_mfma_f32_16x16x32_bf16 v[86:89], v[178:181], v[154:157], v[86:89]
	v_mfma_f32_16x16x32_bf16 v[82:85], v[186:189], v[154:157], v[82:85]
	v_mfma_f32_16x16x32_bf16 v[78:81], v[178:181], v[162:165], v[78:81]
	v_mfma_f32_16x16x32_bf16 v[74:77], v[186:189], v[162:165], v[74:77]
	v_mfma_f32_16x16x32_bf16 v[70:73], v[178:181], v[170:173], v[70:73]
	v_mfma_f32_16x16x32_bf16 v[66:69], v[186:189], v[170:173], v[66:69]
	v_mfma_f32_16x16x32_bf16 v[94:97], v[182:185], v[150:153], v[94:97]
	v_mfma_f32_16x16x32_bf16 v[90:93], v[190:193], v[150:153], v[90:93]
	v_mfma_f32_16x16x32_bf16 v[86:89], v[182:185], v[158:161], v[86:89]
	v_mfma_f32_16x16x32_bf16 v[82:85], v[190:193], v[158:161], v[82:85]
	v_mfma_f32_16x16x32_bf16 v[78:81], v[182:185], v[166:169], v[78:81]
	v_mfma_f32_16x16x32_bf16 v[74:77], v[190:193], v[166:169], v[74:77]
	v_mfma_f32_16x16x32_bf16 v[70:73], v[182:185], v[174:177], v[70:73]
	v_mfma_f32_16x16x32_bf16 v[66:69], v[190:193], v[174:177], v[66:69]
	s_setprio 0
	s_mov_b32 m0, s31
	s_add_u32 s56, s34, s14
	s_addc_u32 s57, s35, s15
	s_barrier
	ds_read_b128 v[146:149], v234 offset:16384
	ds_read_b128 v[150:153], v234 offset:17408
	ds_read_b128 v[154:157], v234 offset:18432
	ds_read_b128 v[158:161], v234 offset:19456
	ds_read_b128 v[162:165], v234 offset:20480
	ds_read_b128 v[166:169], v234 offset:21504
	ds_read_b128 v[170:173], v234 offset:22528
	ds_read_b128 v[174:177], v234 offset:23552
	global_load_lds_dwordx4 v198, s[34:35]
	s_add_u32 s58, s34, s14
	s_addc_u32 s59, s35, s15
	s_mov_b32 m0, s33
	s_nop 0
	global_load_lds_dwordx4 v202, s[34:35]
	s_barrier
	s_waitcnt lgkmcnt(0)
	s_setprio 1
	s_waitcnt lgkmcnt(0)
	v_mfma_f32_16x16x32_bf16 v[62:65], v[130:133], v[146:149], v[62:65]
	v_mfma_f32_16x16x32_bf16 v[58:61], v[138:141], v[146:149], v[58:61]
	v_mfma_f32_16x16x32_bf16 v[54:57], v[130:133], v[154:157], v[54:57]
	v_mfma_f32_16x16x32_bf16 v[50:53], v[138:141], v[154:157], v[50:53]
	v_mfma_f32_16x16x32_bf16 v[46:49], v[130:133], v[162:165], v[46:49]
	v_mfma_f32_16x16x32_bf16 v[42:45], v[138:141], v[162:165], v[42:45]
	v_mfma_f32_16x16x32_bf16 v[38:41], v[130:133], v[170:173], v[38:41]
	v_mfma_f32_16x16x32_bf16 v[34:37], v[138:141], v[170:173], v[34:37]
	v_mfma_f32_16x16x32_bf16 v[62:65], v[134:137], v[150:153], v[62:65]
	v_mfma_f32_16x16x32_bf16 v[58:61], v[142:145], v[150:153], v[58:61]
	v_mfma_f32_16x16x32_bf16 v[54:57], v[134:137], v[158:161], v[54:57]
	v_mfma_f32_16x16x32_bf16 v[50:53], v[142:145], v[158:161], v[50:53]
	v_mfma_f32_16x16x32_bf16 v[46:49], v[134:137], v[166:169], v[46:49]
	v_mfma_f32_16x16x32_bf16 v[42:45], v[142:145], v[166:169], v[42:45]
	v_mfma_f32_16x16x32_bf16 v[38:41], v[134:137], v[174:177], v[38:41]
	v_mfma_f32_16x16x32_bf16 v[34:37], v[142:145], v[174:177], v[34:37]
	s_setprio 0
	s_barrier
	s_add_u32 s50, s28, 0x40000
	s_addc_u32 s51, s29, 0
	s_add_i32 s49, s44, s27
	s_mov_b32 m0, s49
	s_nop 0
	global_load_lds_dwordx4 v200, s[50:51]
	s_add_i32 m0, s49, 0x2000
	s_nop 0
	global_load_lds_dwordx4 v204, s[50:51]
	s_waitcnt vmcnt(6)
	s_barrier
	s_setprio 1
	v_mfma_f32_16x16x32_bf16 v[30:33], v[178:181], v[146:149], v[30:33]
	v_mfma_f32_16x16x32_bf16 v[26:29], v[186:189], v[146:149], v[26:29]
	v_mfma_f32_16x16x32_bf16 v[22:25], v[178:181], v[154:157], v[22:25]
	v_mfma_f32_16x16x32_bf16 v[18:21], v[186:189], v[154:157], v[18:21]
	v_mfma_f32_16x16x32_bf16 v[14:17], v[178:181], v[162:165], v[14:17]
	v_mfma_f32_16x16x32_bf16 v[10:13], v[186:189], v[162:165], v[10:13]
	v_mfma_f32_16x16x32_bf16 v[6:9], v[178:181], v[170:173], v[6:9]
	v_mfma_f32_16x16x32_bf16 v[2:5], v[186:189], v[170:173], v[2:5]
	v_mfma_f32_16x16x32_bf16 v[30:33], v[182:185], v[150:153], v[30:33]
	v_mfma_f32_16x16x32_bf16 v[26:29], v[190:193], v[150:153], v[26:29]
	v_mfma_f32_16x16x32_bf16 v[22:25], v[182:185], v[158:161], v[22:25]
	v_mfma_f32_16x16x32_bf16 v[18:21], v[190:193], v[158:161], v[18:21]
	v_mfma_f32_16x16x32_bf16 v[14:17], v[182:185], v[166:169], v[14:17]
	v_mfma_f32_16x16x32_bf16 v[10:13], v[190:193], v[166:169], v[10:13]
	v_mfma_f32_16x16x32_bf16 v[6:9], v[182:185], v[174:177], v[6:9]
	v_mfma_f32_16x16x32_bf16 v[2:5], v[190:193], v[174:177], v[2:5]
	s_setprio 0
	s_add_i32 s49, 16, 0x18000
	v_add_u32_e32 v142, s49, v224
	s_barrier
	ds_read_b128 v[130:133], v142
	ds_read_b128 v[134:137], v142 offset:1024
	ds_read_b128 v[138:141], v142 offset:2048
	ds_read_b128 v[142:145], v142 offset:3072
	s_add_u32 s34, s34, 0x40000
	s_addc_u32 s35, s35, 0
	s_mov_b32 m0, s36
	ds_read_b128 v[146:149], v234 offset:32768
	ds_read_b128 v[150:153], v234 offset:33792
	ds_read_b128 v[154:157], v234 offset:34816
	ds_read_b128 v[158:161], v234 offset:35840
	ds_read_b128 v[162:165], v234 offset:36864
	ds_read_b128 v[166:169], v234 offset:37888
	ds_read_b128 v[170:173], v234 offset:38912
	ds_read_b128 v[174:177], v234 offset:39936
	global_load_lds_dwordx4 v198, s[34:35]
	s_mov_b32 m0, s37
	s_nop 0
	global_load_lds_dwordx4 v202, s[34:35]
	s_waitcnt lgkmcnt(8)
	s_barrier
; #define PG8_STAGE(bufoff, gbase, voff) do { _Pragma("unroll") for (int _i = 0; _i < 2; ++_i) \
;         __builtin_amdgcn_global_load_lds((const unsigned*)((const char*)(gbase) + (voff)[_i]), (LAS unsigned*)(lds + (bufoff) + ldsw + _i * 8192), 16, 0, 0); } while (0)
; #define PG8_LDA(dst, b, h) do { _Pragma("unroll") for (int m = 0; m < 4; ++m) _Pragma("unroll") for (int k = 0; k < 2; ++k) dst[m][k] = *(const LAS bf16x8*)(lds + PG8_SA(b, h) + aoff + m * 2048 + k * 1024); } while (0)
; #define PG8_LDB(dst, b, h) do { _Pragma("unroll") for (int n = 0; n < 2; ++n) _Pragma("unroll") for (int k = 0; k < 2; ++k) dst[n][k] = *(const LAS bf16x8*)(lds + PG8_SB(b, h) + boff + n * 2048 + k * 1024); } while (0)
; #define PG8_MMA(ai, bj, At, Bt) do { __builtin_amdgcn_s_setprio(1); _Pragma("unroll") for (int m = 0; m < 4; ++m) _Pragma("unroll") for (int n = 0; n < 2; ++n) _Pragma("unroll") for (int k = 0; k < 2; ++k) \
;         acc[ai][bj][m][n] = __builtin_amdgcn_mfma_f32_16x16x32_bf16(Bt[n][k], At[m][k], acc[ai][bj][m][n], 0, 0, 0); __builtin_amdgcn_s_setprio(0); } while (0)
; #define PG8_WAIT_V(n) asm volatile("s_waitcnt vmcnt(" #n ")" ::: "memory")
; #define PG8_WAIT_L(n) asm volatile("s_waitcnt lgkmcnt(" #n ")" ::: "memory")
; #define PG8_BAR __builtin_amdgcn_s_barrier()
; #define PG8_SCHED __builtin_amdgcn_sched_barrier(0)
; template <class Sched, class Epi>
; __device__ __forceinline__ void gemm_phase(LAS unsigned char* lds, const Sched& S, const Epi& E, const int K, const int lda, const int ldb) {
;     ...
;             PG8_WAIT_L(8); PG8_BAR; PG8_WAIT_L(0); PG8_MMA(0, 0, At, B0); PG8_BAR; PG8_SCHED;
;             PG8_LDB(B1, 1, 1); PG8_STAGE(PG8_SB(1, 0), b3, voffB);
;             PG8_BAR; PG8_WAIT_L(0); PG8_MMA(0, 1, At, B1); PG8_BAR;
;             PG8_LDA(At, 1, 1); PG8_STAGE(PG8_SA(1, 0), a3, voffA);
;             PG8_BAR; PG8_WAIT_L(0); if (!chalf) PG8_MMA(1, 0, At, B0); PG8_BAR; PG8_SCHED;
;             PG8_STAGE(PG8_SB(1, 1), b3 + hstepB, voffB);
;             PG8_WAIT_V(6); PG8_BAR; if (!chalf) PG8_MMA(1, 1, At, B1); PG8_BAR;
;         }
;     __device__ __forceinline__ void operator()(EPI_ARGS) const {
;     ...
;         u32x4 gg[2][4], pp[2][4];
	s_waitcnt lgkmcnt(0)
	s_setprio 1
	s_waitcnt lgkmcnt(0)
	v_mfma_f32_16x16x32_bf16 v[126:129], v[130:133], v[146:149], v[126:129]
	v_mfma_f32_16x16x32_bf16 v[122:125], v[138:141], v[146:149], v[122:125]
	v_mfma_f32_16x16x32_bf16 v[118:121], v[130:133], v[154:157], v[118:121]
	v_mfma_f32_16x16x32_bf16 v[114:117], v[138:141], v[154:157], v[114:117]
	v_mfma_f32_16x16x32_bf16 v[110:113], v[130:133], v[162:165], v[110:113]
	v_mfma_f32_16x16x32_bf16 v[106:109], v[138:141], v[162:165], v[106:109]
	v_mfma_f32_16x16x32_bf16 v[102:105], v[130:133], v[170:173], v[102:105]
	v_mfma_f32_16x16x32_bf16 v[98:101], v[138:141], v[170:173], v[98:101]
	v_mfma_f32_16x16x32_bf16 v[126:129], v[134:137], v[150:153], v[126:129]
	v_mfma_f32_16x16x32_bf16 v[122:125], v[142:145], v[150:153], v[122:125]
	v_mfma_f32_16x16x32_bf16 v[118:121], v[134:137], v[158:161], v[118:121]
	v_mfma_f32_16x16x32_bf16 v[114:117], v[142:145], v[158:161], v[114:117]
	v_mfma_f32_16x16x32_bf16 v[110:113], v[134:137], v[166:169], v[110:113]
	v_mfma_f32_16x16x32_bf16 v[106:109], v[142:145], v[166:169], v[106:109]
	v_mfma_f32_16x16x32_bf16 v[102:105], v[134:137], v[174:177], v[102:105]
	v_mfma_f32_16x16x32_bf16 v[98:101], v[142:145], v[174:177], v[98:101]
	s_setprio 0
	s_barrier
	s_add_i32 s34, 16, 0x1c000
	s_add_i32 s35, s49, s27
	v_add_u32_e32 v190, s34, v224
	s_mov_b32 m0, s35
	ds_read_b128 v[178:181], v190
	ds_read_b128 v[182:185], v190 offset:1024
	ds_read_b128 v[186:189], v190 offset:2048
	ds_read_b128 v[190:193], v190 offset:3072
	global_load_lds_dwordx4 v200, s[52:53]
	s_add_i32 m0, s35, 0x2000
	s_nop 0
	global_load_lds_dwordx4 v204, s[54:55]
	s_barrier
	s_waitcnt lgkmcnt(0)
	s_setprio 1
	s_waitcnt lgkmcnt(0)
	v_mfma_f32_16x16x32_bf16 v[94:97], v[178:181], v[146:149], v[94:97]
	v_mfma_f32_16x16x32_bf16 v[90:93], v[186:189], v[146:149], v[90:93]
	v_mfma_f32_16x16x32_bf16 v[86:89], v[178:181], v[154:157], v[86:89]
	v_mfma_f32_16x16x32_bf16 v[82:85], v[186:189], v[154:157], v[82:85]
	v_mfma_f32_16x16x32_bf16 v[78:81], v[178:181], v[162:165], v[78:81]
	v_mfma_f32_16x16x32_bf16 v[74:77], v[186:189], v[162:165], v[74:77]
	v_mfma_f32_16x16x32_bf16 v[70:73], v[178:181], v[170:173], v[70:73]
	v_mfma_f32_16x16x32_bf16 v[66:69], v[186:189], v[170:173], v[66:69]
	v_mfma_f32_16x16x32_bf16 v[94:97], v[182:185], v[150:153], v[94:97]
	v_mfma_f32_16x16x32_bf16 v[90:93], v[190:193], v[150:153], v[90:93]
	v_mfma_f32_16x16x32_bf16 v[86:89], v[182:185], v[158:161], v[86:89]
	v_mfma_f32_16x16x32_bf16 v[82:85], v[190:193], v[158:161], v[82:85]
	v_mfma_f32_16x16x32_bf16 v[78:81], v[182:185], v[166:169], v[78:81]
	v_mfma_f32_16x16x32_bf16 v[74:77], v[190:193], v[166:169], v[74:77]
	v_mfma_f32_16x16x32_bf16 v[70:73], v[182:185], v[174:177], v[70:73]
	v_mfma_f32_16x16x32_bf16 v[66:69], v[190:193], v[174:177], v[66:69]
	s_setprio 0
	s_mov_b32 m0, s39
	s_barrier
	ds_read_b128 v[146:149], v234 offset:49152
	ds_read_b128 v[150:153], v234 offset:50176
	ds_read_b128 v[154:157], v234 offset:51200
	ds_read_b128 v[158:161], v234 offset:52224
	ds_read_b128 v[162:165], v234 offset:53248
	ds_read_b128 v[166:169], v234 offset:54272
	ds_read_b128 v[170:173], v234 offset:55296
	ds_read_b128 v[174:177], v234 offset:56320
	global_load_lds_dwordx4 v198, s[56:57]
	s_mov_b32 m0, s40
	s_nop 0
	global_load_lds_dwordx4 v202, s[58:59]
	s_barrier
	s_waitcnt lgkmcnt(0)
	s_setprio 1
	s_waitcnt lgkmcnt(0)
	v_mfma_f32_16x16x32_bf16 v[62:65], v[130:133], v[146:149], v[62:65]
	v_mfma_f32_16x16x32_bf16 v[58:61], v[138:141], v[146:149], v[58:61]
	v_mfma_f32_16x16x32_bf16 v[54:57], v[130:133], v[154:157], v[54:57]
	v_mfma_f32_16x16x32_bf16 v[50:53], v[138:141], v[154:157], v[50:53]
	v_mfma_f32_16x16x32_bf16 v[46:49], v[130:133], v[162:165], v[46:49]
	v_mfma_f32_16x16x32_bf16 v[42:45], v[138:141], v[162:165], v[42:45]
	v_mfma_f32_16x16x32_bf16 v[38:41], v[130:133], v[170:173], v[38:41]
	v_mfma_f32_16x16x32_bf16 v[34:37], v[138:141], v[170:173], v[34:37]
	v_mfma_f32_16x16x32_bf16 v[62:65], v[134:137], v[150:153], v[62:65]
	v_mfma_f32_16x16x32_bf16 v[58:61], v[142:145], v[150:153], v[58:61]
	v_mfma_f32_16x16x32_bf16 v[54:57], v[134:137], v[158:161], v[54:57]
	v_mfma_f32_16x16x32_bf16 v[50:53], v[142:145], v[158:161], v[50:53]
	v_mfma_f32_16x16x32_bf16 v[46:49], v[134:137], v[166:169], v[46:49]
	v_mfma_f32_16x16x32_bf16 v[42:45], v[142:145], v[166:169], v[42:45]
	v_mfma_f32_16x16x32_bf16 v[38:41], v[134:137], v[174:177], v[38:41]
	v_mfma_f32_16x16x32_bf16 v[34:37], v[142:145], v[174:177], v[34:37]
	s_setprio 0
	s_barrier
	s_add_u32 s28, s28, 0x40080
	s_addc_u32 s29, s29, 0
	s_add_i32 s34, s34, s27
	s_mov_b32 m0, s34
	s_nop 0
	global_load_lds_dwordx4 v200, s[28:29]
	s_add_i32 m0, s34, 0x2000
	s_nop 0
	global_load_lds_dwordx4 v204, s[28:29]
	s_waitcnt vmcnt(6)
	s_barrier
	s_setprio 1
	v_mfma_f32_16x16x32_bf16 v[30:33], v[178:181], v[146:149], v[30:33]
	v_mfma_f32_16x16x32_bf16 v[26:29], v[186:189], v[146:149], v[26:29]
	v_mfma_f32_16x16x32_bf16 v[22:25], v[178:181], v[154:157], v[22:25]
	v_mfma_f32_16x16x32_bf16 v[18:21], v[186:189], v[154:157], v[18:21]
	v_mfma_f32_16x16x32_bf16 v[14:17], v[178:181], v[162:165], v[14:17]
	v_mfma_f32_16x16x32_bf16 v[10:13], v[186:189], v[162:165], v[10:13]
	v_mfma_f32_16x16x32_bf16 v[6:9], v[178:181], v[170:173], v[6:9]
	v_mfma_f32_16x16x32_bf16 v[2:5], v[186:189], v[170:173], v[2:5]
	v_mfma_f32_16x16x32_bf16 v[30:33], v[182:185], v[150:153], v[30:33]
	v_mfma_f32_16x16x32_bf16 v[26:29], v[190:193], v[150:153], v[26:29]
	v_mfma_f32_16x16x32_bf16 v[22:25], v[182:185], v[158:161], v[22:25]
	v_mfma_f32_16x16x32_bf16 v[18:21], v[190:193], v[158:161], v[18:21]
	v_mfma_f32_16x16x32_bf16 v[14:17], v[182:185], v[166:169], v[14:17]
	v_mfma_f32_16x16x32_bf16 v[10:13], v[190:193], v[166:169], v[10:13]
	v_mfma_f32_16x16x32_bf16 v[6:9], v[182:185], v[174:177], v[6:9]
	v_mfma_f32_16x16x32_bf16 v[2:5], v[190:193], v[174:177], v[2:5]
	s_setprio 0
	s_add_i32 s21, s21, 2
	s_add_u32 s17, s17, 0x100
	s_addc_u32 s19, s19, 0
	s_add_u32 s6, s6, 0x100
	s_addc_u32 s7, s7, 0
	s_cmp_gt_u32 s21, 13
	s_barrier
	s_cbranch_scc0 .LBB0_842
	s_lshl_b32 s6, s48, 11
	s_ashr_i32 s7, s6, 31
	s_lshl_b64 s[28:29], s[6:7], 1
	v_lshl_or_b32 v134, s47, 8, v232
	s_add_u32 s6, s41, s28
	v_ashrrev_i32_e32 v135, 31, v134
	s_addc_u32 s7, s42, s29
	v_lshlrev_b64 v[212:213], 1, v[134:135]
	v_add_u32_e32 v130, s26, v1
	v_lshl_add_u64 v[216:217], s[6:7], 0, v[212:213]
	v_mad_i64_i32 v[132:133], s[6:7], v130, s45, v[216:217]
	global_load_dwordx4 v[194:197], v[132:133], off
	v_ashrrev_i32_e32 v131, 31, v130
	s_cmp_gt_i32 s48, 0
	v_lshl_add_u64 v[218:219], s[12:13], 0, v[212:213]
	v_lshlrev_b64 v[132:133], 12, v[130:131]
	s_cselect_b64 s[34:35], -1, 0
	s_cmp_lt_i32 s48, 1
	v_lshl_add_u64 v[136:137], v[218:219], 0, v[132:133]
	s_cbranch_scc1 .LBB0_845
	global_load_dwordx4 v[190:193], v[136:137], off
	s_branch .LBB0_846

; #define PG8_STAGE(bufoff, gbase, voff) do { _Pragma("unroll") for (int _i = 0; _i < 2; ++_i) \
;         __builtin_amdgcn_global_load_lds((const unsigned*)((const char*)(gbase) + (voff)[_i]), (LAS unsigned*)(lds + (bufoff) + ldsw + _i * 8192), 16, 0, 0); } while (0)
; #define PG8_LDA(dst, b, h) do { _Pragma("unroll") for (int m = 0; m < 4; ++m) _Pragma("unroll") for (int k = 0; k < 2; ++k) dst[m][k] = *(const LAS bf16x8*)(lds + PG8_SA(b, h) + aoff + m * 2048 + k * 1024); } while (0)
; #define PG8_LDB(dst, b, h) do { _Pragma("unroll") for (int n = 0; n < 2; ++n) _Pragma("unroll") for (int k = 0; k < 2; ++k) dst[n][k] = *(const LAS bf16x8*)(lds + PG8_SB(b, h) + boff + n * 2048 + k * 1024); } while (0)
; #define PG8_MMA(ai, bj, At, Bt) do { __builtin_amdgcn_s_setprio(1); _Pragma("unroll") for (int m = 0; m < 4; ++m) _Pragma("unroll") for (int n = 0; n < 2; ++n) _Pragma("unroll") for (int k = 0; k < 2; ++k) \
;         acc[ai][bj][m][n] = __builtin_amdgcn_mfma_f32_16x16x32_bf16(Bt[n][k], At[m][k], acc[ai][bj][m][n], 0, 0, 0); __builtin_amdgcn_s_setprio(0); } while (0)
; #define PG8_WAIT_L(n) asm volatile("s_waitcnt lgkmcnt(" #n ")" ::: "memory")
; #define PG8_BAR __builtin_amdgcn_s_barrier()
; #define PG8_SCHED __builtin_amdgcn_sched_barrier(0)
; template <class Sched, class Epi>
; __device__ __forceinline__ void gemm_phase(LAS unsigned char* lds, const Sched& S, const Epi& E, const int K, const int lda, const int ldb) {
;     ...
;         for (int t = 0; t < nt; t += 2) {
;             const bool last = (t == nt - 2);
;             const char* a1 = cA + (size_t)(t + 1) * kstep;
;             const char* a2 = last ? nA : cA + (size_t)(t + 2) * kstep; const char* b2 = last ? nB : cB + (size_t)(t + 2) * kstep;
;             const char* a3 = a2 + kstep; const char* b3 = b2 + kstep;
;             PG8_LDB(B0, 0, 0); PG8_SCHED; PG8_LDA(At, 0, 0); PG8_STAGE(PG8_SA(1, 1), a1 + hstepA, voffA);
;             PG8_WAIT_L(8); PG8_BAR; PG8_WAIT_L(0); PG8_MMA(0, 0, At, B0); PG8_BAR; PG8_SCHED;
;     ...
;         for (int a = 0; a < 2; ++a)
; #pragma unroll
;             for (int b = 0; b < 2; ++b)
; #pragma unroll
;                 for (int m = 0; m < 4; ++m)
; #pragma unroll
;                     for (int n = 0; n < 2; ++n) acc[a][b][m][n] = (f32x4){0.f, 0.f, 0.f, 0.f};
;         cur = nxt; cA = nA; cB = nB; ++ui;
.LBB0_956:
	s_add_u32 s15, s28, 0x100
	s_addc_u32 s17, s29, 0
	s_add_u32 s26, s26, 0x80080
	v_mov_b32_e32 v2, 0
	s_addc_u32 s27, s27, 0
	s_mov_b32 s46, -2
	v_mov_b32_e32 v3, v2
	v_mov_b32_e32 v4, v2
	v_mov_b32_e32 v5, v2
	v_mov_b32_e32 v6, v2
	v_mov_b32_e32 v7, v2
	v_mov_b32_e32 v8, v2
	v_mov_b32_e32 v9, v2
	v_mov_b32_e32 v10, v2
	v_mov_b32_e32 v11, v2
	v_mov_b32_e32 v12, v2
	v_mov_b32_e32 v13, v2
	v_mov_b32_e32 v18, v2
	v_mov_b32_e32 v19, v2
	v_mov_b32_e32 v20, v2
	v_mov_b32_e32 v21, v2
	v_mov_b32_e32 v26, v2
	v_mov_b32_e32 v27, v2
	v_mov_b32_e32 v28, v2
	v_mov_b32_e32 v29, v2
	v_mov_b32_e32 v34, v2
	v_mov_b32_e32 v35, v2
	v_mov_b32_e32 v36, v2
	v_mov_b32_e32 v37, v2
	v_mov_b32_e32 v42, v2
	v_mov_b32_e32 v43, v2
	v_mov_b32_e32 v44, v2
	v_mov_b32_e32 v45, v2
	v_mov_b32_e32 v50, v2
	v_mov_b32_e32 v51, v2
	v_mov_b32_e32 v52, v2
	v_mov_b32_e32 v53, v2
	v_mov_b32_e32 v14, v2
	v_mov_b32_e32 v15, v2
	v_mov_b32_e32 v16, v2
	v_mov_b32_e32 v17, v2
	v_mov_b32_e32 v22, v2
	v_mov_b32_e32 v23, v2
	v_mov_b32_e32 v24, v2
	v_mov_b32_e32 v25, v2
	v_mov_b32_e32 v30, v2
	v_mov_b32_e32 v31, v2
	v_mov_b32_e32 v32, v2
	v_mov_b32_e32 v33, v2
	v_mov_b32_e32 v38, v2
	v_mov_b32_e32 v39, v2
	v_mov_b32_e32 v40, v2
	v_mov_b32_e32 v41, v2
	v_mov_b32_e32 v46, v2
	v_mov_b32_e32 v47, v2
	v_mov_b32_e32 v48, v2
	v_mov_b32_e32 v49, v2
	v_mov_b32_e32 v54, v2
	v_mov_b32_e32 v55, v2
	v_mov_b32_e32 v56, v2
	v_mov_b32_e32 v57, v2
	v_mov_b32_e32 v58, v2
	v_mov_b32_e32 v59, v2
	v_mov_b32_e32 v60, v2
	v_mov_b32_e32 v61, v2
	v_mov_b32_e32 v62, v2
	v_mov_b32_e32 v63, v2
	v_mov_b32_e32 v64, v2
	v_mov_b32_e32 v65, v2
	v_mov_b32_e32 v66, v2
	v_mov_b32_e32 v67, v2
	v_mov_b32_e32 v68, v2
	v_mov_b32_e32 v69, v2
	v_mov_b32_e32 v70, v2
	v_mov_b32_e32 v71, v2
	v_mov_b32_e32 v72, v2
	v_mov_b32_e32 v73, v2
	v_mov_b32_e32 v78, v2
	v_mov_b32_e32 v79, v2
	v_mov_b32_e32 v80, v2
	v_mov_b32_e32 v81, v2
	v_mov_b32_e32 v86, v2
	v_mov_b32_e32 v87, v2
	v_mov_b32_e32 v88, v2
	v_mov_b32_e32 v89, v2
	v_mov_b32_e32 v94, v2
	v_mov_b32_e32 v95, v2
	v_mov_b32_e32 v96, v2
	v_mov_b32_e32 v97, v2
	v_mov_b32_e32 v102, v2
	v_mov_b32_e32 v103, v2
	v_mov_b32_e32 v104, v2
	v_mov_b32_e32 v105, v2
	v_mov_b32_e32 v110, v2
	v_mov_b32_e32 v111, v2
	v_mov_b32_e32 v112, v2
	v_mov_b32_e32 v113, v2
	v_mov_b32_e32 v118, v2
	v_mov_b32_e32 v119, v2
	v_mov_b32_e32 v120, v2
	v_mov_b32_e32 v121, v2
	v_mov_b32_e32 v74, v2
	v_mov_b32_e32 v75, v2
	v_mov_b32_e32 v76, v2
	v_mov_b32_e32 v77, v2
	v_mov_b32_e32 v82, v2
	v_mov_b32_e32 v83, v2
	v_mov_b32_e32 v84, v2
	v_mov_b32_e32 v85, v2
	v_mov_b32_e32 v90, v2
	v_mov_b32_e32 v91, v2
	v_mov_b32_e32 v92, v2
	v_mov_b32_e32 v93, v2
	v_mov_b32_e32 v98, v2
	v_mov_b32_e32 v99, v2
	v_mov_b32_e32 v100, v2
	v_mov_b32_e32 v101, v2
	v_mov_b32_e32 v106, v2
	v_mov_b32_e32 v107, v2
	v_mov_b32_e32 v108, v2
	v_mov_b32_e32 v109, v2
	v_mov_b32_e32 v114, v2
	v_mov_b32_e32 v115, v2
	v_mov_b32_e32 v116, v2
	v_mov_b32_e32 v117, v2
	v_mov_b32_e32 v122, v2
	v_mov_b32_e32 v123, v2
	v_mov_b32_e32 v124, v2
	v_mov_b32_e32 v125, v2
	v_mov_b32_e32 v126, v2
	v_mov_b32_e32 v127, v2
	v_mov_b32_e32 v128, v2
	v_mov_b32_e32 v129, v2
	s_branch .Lal_957
	.p2align 11
.Lal_957:
.LBB0_957:
	ds_read_b128 v[156:159], v153
	ds_read_b128 v[160:163], v153 offset:1024
	ds_read_b128 v[164:167], v153 offset:2048
	ds_read_b128 v[168:171], v153 offset:3072
	s_add_u32 s28, s26, 0xfff80080
	s_addc_u32 s29, s27, -1
	s_cmp_eq_u32 s46, 28
	s_cselect_b32 s35, s23, s29
	s_cselect_b32 s34, s22, s28
	s_cselect_b32 s29, s25, s17
	s_cselect_b32 s28, s24, s15
	s_add_i32 m0, s5, 0xc000
	ds_read_b128 v[172:175], v154
	ds_read_b128 v[176:179], v154 offset:1024
	ds_read_b128 v[180:183], v154 offset:2048
	ds_read_b128 v[184:187], v154 offset:3072
	ds_read_b128 v[188:191], v154 offset:4096
	ds_read_b128 v[192:195], v154 offset:5120
	ds_read_b128 v[196:199], v154 offset:6144
	ds_read_b128 v[200:203], v154 offset:7168
	global_load_lds_dwordx4 v140, s[26:27]
	s_add_i32 m0, s5, 0xe000
	s_nop 0
	global_load_lds_dwordx4 v138, s[26:27]
	s_waitcnt lgkmcnt(8)
	s_barrier
	s_waitcnt lgkmcnt(0)
	s_setprio 1
	s_waitcnt lgkmcnt(0)
	v_mfma_f32_16x16x32_bf16 v[126:129], v[156:159], v[172:175], v[126:129]
	v_mfma_f32_16x16x32_bf16 v[122:125], v[164:167], v[172:175], v[122:125]
	v_mfma_f32_16x16x32_bf16 v[114:117], v[156:159], v[180:183], v[114:117]
	v_mfma_f32_16x16x32_bf16 v[106:109], v[164:167], v[180:183], v[106:109]
	v_mfma_f32_16x16x32_bf16 v[98:101], v[156:159], v[188:191], v[98:101]
	v_mfma_f32_16x16x32_bf16 v[90:93], v[164:167], v[188:191], v[90:93]
	v_mfma_f32_16x16x32_bf16 v[82:85], v[156:159], v[196:199], v[82:85]
	v_mfma_f32_16x16x32_bf16 v[74:77], v[164:167], v[196:199], v[74:77]
	v_mfma_f32_16x16x32_bf16 v[126:129], v[160:163], v[176:179], v[126:129]
	v_mfma_f32_16x16x32_bf16 v[122:125], v[168:171], v[176:179], v[122:125]
	v_mfma_f32_16x16x32_bf16 v[114:117], v[160:163], v[184:187], v[114:117]
	v_mfma_f32_16x16x32_bf16 v[106:109], v[168:171], v[184:187], v[106:109]
	v_mfma_f32_16x16x32_bf16 v[98:101], v[160:163], v[192:195], v[98:101]
	v_mfma_f32_16x16x32_bf16 v[90:93], v[168:171], v[192:195], v[90:93]
	v_mfma_f32_16x16x32_bf16 v[82:85], v[160:163], v[200:203], v[82:85]
	v_mfma_f32_16x16x32_bf16 v[74:77], v[168:171], v[200:203], v[74:77]
	s_setprio 0
	s_barrier
	s_add_i32 s47, s43, s33
	s_add_u32 s52, s28, s8
	s_addc_u32 s53, s29, s9
	s_mov_b32 m0, s47
	ds_read_b128 v[204:207], v155
	ds_read_b128 v[208:211], v155 offset:1024
	ds_read_b128 v[212:215], v155 offset:2048
	ds_read_b128 v[216:219], v155 offset:3072
	global_load_lds_dwordx4 v132, s[28:29]
	s_add_u32 s54, s28, s8
	s_addc_u32 s55, s29, s9
	s_add_i32 m0, s47, 0x2000
	s_nop 0
	global_load_lds_dwordx4 v136, s[28:29]
	s_barrier
; #define PG8_STAGE(bufoff, gbase, voff) do { _Pragma("unroll") for (int _i = 0; _i < 2; ++_i) \
;         __builtin_amdgcn_global_load_lds((const unsigned*)((const char*)(gbase) + (voff)[_i]), (LAS unsigned*)(lds + (bufoff) + ldsw + _i * 8192), 16, 0, 0); } while (0)
; #define PG8_LDA(dst, b, h) do { _Pragma("unroll") for (int m = 0; m < 4; ++m) _Pragma("unroll") for (int k = 0; k < 2; ++k) dst[m][k] = *(const LAS bf16x8*)(lds + PG8_SA(b, h) + aoff + m * 2048 + k * 1024); } while (0)
; #define PG8_LDB(dst, b, h) do { _Pragma("unroll") for (int n = 0; n < 2; ++n) _Pragma("unroll") for (int k = 0; k < 2; ++k) dst[n][k] = *(const LAS bf16x8*)(lds + PG8_SB(b, h) + boff + n * 2048 + k * 1024); } while (0)
; #define PG8_MMA(ai, bj, At, Bt) do { __builtin_amdgcn_s_setprio(1); _Pragma("unroll") for (int m = 0; m < 4; ++m) _Pragma("unroll") for (int n = 0; n < 2; ++n) _Pragma("unroll") for (int k = 0; k < 2; ++k) \
;         acc[ai][bj][m][n] = __builtin_amdgcn_mfma_f32_16x16x32_bf16(Bt[n][k], At[m][k], acc[ai][bj][m][n], 0, 0, 0); __builtin_amdgcn_s_setprio(0); } while (0)
; #define PG8_WAIT_V(n) asm volatile("s_waitcnt vmcnt(" #n ")" ::: "memory")
; #define PG8_WAIT_L(n) asm volatile("s_waitcnt lgkmcnt(" #n ")" ::: "memory")
; #define PG8_BAR __builtin_amdgcn_s_barrier()
; #define PG8_SCHED __builtin_amdgcn_sched_barrier(0)
; template <class Sched, class Epi>
; __device__ __forceinline__ void gemm_phase(LAS unsigned char* lds, const Sched& S, const Epi& E, const int K, const int lda, const int ldb) {
;     ...
;             PG8_WAIT_L(8); PG8_BAR; PG8_WAIT_L(0); PG8_MMA(0, 0, At, B0); PG8_BAR; PG8_SCHED;
;             PG8_LDB(B1, 0, 1); PG8_STAGE(PG8_SB(0, 0), b2, voffB);
;             PG8_BAR; PG8_WAIT_L(0); PG8_MMA(0, 1, At, B1); PG8_BAR;
;             PG8_LDA(At, 0, 1); PG8_STAGE(PG8_SA(0, 0), a2, voffA);
;             PG8_BAR; PG8_WAIT_L(0); if (!chalf) PG8_MMA(1, 0, At, B0); PG8_BAR; PG8_SCHED;
;             PG8_STAGE(PG8_SB(0, 1), b2 + hstepB, voffB);
;             PG8_WAIT_V(6); PG8_BAR; if (!chalf) PG8_MMA(1, 1, At, B1); PG8_BAR;
;             PG8_LDB(B0, 1, 0); PG8_SCHED; PG8_LDA(At, 1, 0); PG8_STAGE(PG8_SA(0, 1), a2 + hstepA, voffA);
;             PG8_WAIT_L(8); PG8_BAR; PG8_WAIT_L(0); PG8_MMA(0, 0, At, B0); PG8_BAR; PG8_SCHED;
	s_waitcnt lgkmcnt(0)
	s_setprio 1
	s_waitcnt lgkmcnt(0)
	v_mfma_f32_16x16x32_bf16 v[118:121], v[204:207], v[172:175], v[118:121]
	v_mfma_f32_16x16x32_bf16 v[110:113], v[212:215], v[172:175], v[110:113]
	v_mfma_f32_16x16x32_bf16 v[102:105], v[204:207], v[180:183], v[102:105]
	v_mfma_f32_16x16x32_bf16 v[94:97], v[212:215], v[180:183], v[94:97]
	v_mfma_f32_16x16x32_bf16 v[86:89], v[204:207], v[188:191], v[86:89]
	v_mfma_f32_16x16x32_bf16 v[78:81], v[212:215], v[188:191], v[78:81]
	v_mfma_f32_16x16x32_bf16 v[70:73], v[204:207], v[196:199], v[70:73]
	v_mfma_f32_16x16x32_bf16 v[66:69], v[212:215], v[196:199], v[66:69]
	v_mfma_f32_16x16x32_bf16 v[118:121], v[208:211], v[176:179], v[118:121]
	v_mfma_f32_16x16x32_bf16 v[110:113], v[216:219], v[176:179], v[110:113]
	v_mfma_f32_16x16x32_bf16 v[102:105], v[208:211], v[184:187], v[102:105]
	v_mfma_f32_16x16x32_bf16 v[94:97], v[216:219], v[184:187], v[94:97]
	v_mfma_f32_16x16x32_bf16 v[86:89], v[208:211], v[192:195], v[86:89]
	v_mfma_f32_16x16x32_bf16 v[78:81], v[216:219], v[192:195], v[78:81]
	v_mfma_f32_16x16x32_bf16 v[70:73], v[208:211], v[200:203], v[70:73]
	v_mfma_f32_16x16x32_bf16 v[66:69], v[216:219], v[200:203], v[66:69]
	s_setprio 0
	s_mov_b32 m0, s5
	s_add_u32 s56, s34, s8
	s_addc_u32 s57, s35, s9
	s_barrier
	ds_read_b128 v[172:175], v154 offset:16384
	ds_read_b128 v[176:179], v154 offset:17408
	ds_read_b128 v[180:183], v154 offset:18432
	ds_read_b128 v[184:187], v154 offset:19456
	ds_read_b128 v[188:191], v154 offset:20480
	ds_read_b128 v[192:195], v154 offset:21504
	ds_read_b128 v[196:199], v154 offset:22528
	ds_read_b128 v[200:203], v154 offset:23552
	global_load_lds_dwordx4 v130, s[34:35]
	s_add_u32 s58, s34, s8
	s_addc_u32 s59, s35, s9
	s_mov_b32 m0, s36
	s_nop 0
	global_load_lds_dwordx4 v134, s[34:35]
	s_barrier
	s_waitcnt lgkmcnt(0)
	s_setprio 1
	s_waitcnt lgkmcnt(0)
	v_mfma_f32_16x16x32_bf16 v[62:65], v[156:159], v[172:175], v[62:65]
	v_mfma_f32_16x16x32_bf16 v[58:61], v[164:167], v[172:175], v[58:61]
	v_mfma_f32_16x16x32_bf16 v[54:57], v[156:159], v[180:183], v[54:57]
	v_mfma_f32_16x16x32_bf16 v[46:49], v[164:167], v[180:183], v[46:49]
	v_mfma_f32_16x16x32_bf16 v[38:41], v[156:159], v[188:191], v[38:41]
	v_mfma_f32_16x16x32_bf16 v[30:33], v[164:167], v[188:191], v[30:33]
	v_mfma_f32_16x16x32_bf16 v[22:25], v[156:159], v[196:199], v[22:25]
	v_mfma_f32_16x16x32_bf16 v[14:17], v[164:167], v[196:199], v[14:17]
	v_mfma_f32_16x16x32_bf16 v[62:65], v[160:163], v[176:179], v[62:65]
	v_mfma_f32_16x16x32_bf16 v[58:61], v[168:171], v[176:179], v[58:61]
	v_mfma_f32_16x16x32_bf16 v[54:57], v[160:163], v[184:187], v[54:57]
	v_mfma_f32_16x16x32_bf16 v[46:49], v[168:171], v[184:187], v[46:49]
	v_mfma_f32_16x16x32_bf16 v[38:41], v[160:163], v[192:195], v[38:41]
	v_mfma_f32_16x16x32_bf16 v[30:33], v[168:171], v[192:195], v[30:33]
	v_mfma_f32_16x16x32_bf16 v[22:25], v[160:163], v[200:203], v[22:25]
	v_mfma_f32_16x16x32_bf16 v[14:17], v[168:171], v[200:203], v[14:17]
	s_setprio 0
	s_barrier
	s_add_u32 s48, s28, 0x80000
	s_addc_u32 s49, s29, 0
	s_add_i32 s47, s44, s33
	s_mov_b32 m0, s47
	s_nop 0
	global_load_lds_dwordx4 v132, s[48:49]
	s_add_i32 m0, s47, 0x2000
	s_nop 0
	global_load_lds_dwordx4 v136, s[48:49]
	s_waitcnt vmcnt(6)
	s_barrier
	s_setprio 1
	v_mfma_f32_16x16x32_bf16 v[50:53], v[204:207], v[172:175], v[50:53]
	v_mfma_f32_16x16x32_bf16 v[42:45], v[212:215], v[172:175], v[42:45]
	v_mfma_f32_16x16x32_bf16 v[34:37], v[204:207], v[180:183], v[34:37]
	v_mfma_f32_16x16x32_bf16 v[26:29], v[212:215], v[180:183], v[26:29]
	v_mfma_f32_16x16x32_bf16 v[18:21], v[204:207], v[188:191], v[18:21]
	v_mfma_f32_16x16x32_bf16 v[10:13], v[212:215], v[188:191], v[10:13]
	v_mfma_f32_16x16x32_bf16 v[6:9], v[204:207], v[196:199], v[6:9]
	v_mfma_f32_16x16x32_bf16 v[2:5], v[212:215], v[196:199], v[2:5]
	v_mfma_f32_16x16x32_bf16 v[50:53], v[208:211], v[176:179], v[50:53]
	v_mfma_f32_16x16x32_bf16 v[42:45], v[216:219], v[176:179], v[42:45]
	v_mfma_f32_16x16x32_bf16 v[34:37], v[208:211], v[184:187], v[34:37]
	v_mfma_f32_16x16x32_bf16 v[26:29], v[216:219], v[184:187], v[26:29]
	v_mfma_f32_16x16x32_bf16 v[18:21], v[208:211], v[192:195], v[18:21]
	v_mfma_f32_16x16x32_bf16 v[10:13], v[216:219], v[192:195], v[10:13]
	v_mfma_f32_16x16x32_bf16 v[6:9], v[208:211], v[200:203], v[6:9]
	v_mfma_f32_16x16x32_bf16 v[2:5], v[216:219], v[200:203], v[2:5]
	s_setprio 0
	s_add_i32 s47, 16, 0x18000
	v_add_u32_e32 v168, s47, v144
	s_barrier
	ds_read_b128 v[156:159], v168
	ds_read_b128 v[160:163], v168 offset:1024
	ds_read_b128 v[164:167], v168 offset:2048
	ds_read_b128 v[168:171], v168 offset:3072
	s_add_u32 s34, s34, 0x80000
	s_addc_u32 s35, s35, 0
	s_mov_b32 m0, s37
	ds_read_b128 v[172:175], v154 offset:32768
	ds_read_b128 v[176:179], v154 offset:33792
	ds_read_b128 v[180:183], v154 offset:34816
	ds_read_b128 v[184:187], v154 offset:35840
	ds_read_b128 v[188:191], v154 offset:36864
	ds_read_b128 v[192:195], v154 offset:37888
	ds_read_b128 v[196:199], v154 offset:38912
	ds_read_b128 v[200:203], v154 offset:39936
	global_load_lds_dwordx4 v130, s[34:35]
	s_mov_b32 m0, s38
	s_nop 0
	global_load_lds_dwordx4 v134, s[34:35]
	s_waitcnt lgkmcnt(8)
	s_barrier
; #define PG8_STAGE(bufoff, gbase, voff) do { _Pragma("unroll") for (int _i = 0; _i < 2; ++_i) \
;         __builtin_amdgcn_global_load_lds((const unsigned*)((const char*)(gbase) + (voff)[_i]), (LAS unsigned*)(lds + (bufoff) + ldsw + _i * 8192), 16, 0, 0); } while (0)
; #define PG8_LDA(dst, b, h) do { _Pragma("unroll") for (int m = 0; m < 4; ++m) _Pragma("unroll") for (int k = 0; k < 2; ++k) dst[m][k] = *(const LAS bf16x8*)(lds + PG8_SA(b, h) + aoff + m * 2048 + k * 1024); } while (0)
; #define PG8_LDB(dst, b, h) do { _Pragma("unroll") for (int n = 0; n < 2; ++n) _Pragma("unroll") for (int k = 0; k < 2; ++k) dst[n][k] = *(const LAS bf16x8*)(lds + PG8_SB(b, h) + boff + n * 2048 + k * 1024); } while (0)
; #define PG8_MMA(ai, bj, At, Bt) do { __builtin_amdgcn_s_setprio(1); _Pragma("unroll") for (int m = 0; m < 4; ++m) _Pragma("unroll") for (int n = 0; n < 2; ++n) _Pragma("unroll") for (int k = 0; k < 2; ++k) \
;         acc[ai][bj][m][n] = __builtin_amdgcn_mfma_f32_16x16x32_bf16(Bt[n][k], At[m][k], acc[ai][bj][m][n], 0, 0, 0); __builtin_amdgcn_s_setprio(0); } while (0)
; #define PG8_WAIT_V(n) asm volatile("s_waitcnt vmcnt(" #n ")" ::: "memory")
; #define PG8_WAIT_L(n) asm volatile("s_waitcnt lgkmcnt(" #n ")" ::: "memory")
; #define PG8_BAR __builtin_amdgcn_s_barrier()
; #define PG8_SCHED __builtin_amdgcn_sched_barrier(0)
; template <class Sched, class Epi>
; __device__ __forceinline__ void gemm_phase(LAS unsigned char* lds, const Sched& S, const Epi& E, const int K, const int lda, const int ldb) {
;     ...
;             PG8_WAIT_L(8); PG8_BAR; PG8_WAIT_L(0); PG8_MMA(0, 0, At, B0); PG8_BAR; PG8_SCHED;
;             PG8_LDB(B1, 1, 1); PG8_STAGE(PG8_SB(1, 0), b3, voffB);
;             PG8_BAR; PG8_WAIT_L(0); PG8_MMA(0, 1, At, B1); PG8_BAR;
;             PG8_LDA(At, 1, 1); PG8_STAGE(PG8_SA(1, 0), a3, voffA);
;             PG8_BAR; PG8_WAIT_L(0); if (!chalf) PG8_MMA(1, 0, At, B0); PG8_BAR; PG8_SCHED;
;             PG8_STAGE(PG8_SB(1, 1), b3 + hstepB, voffB);
;             PG8_WAIT_V(6); PG8_BAR; if (!chalf) PG8_MMA(1, 1, At, B1); PG8_BAR;
	s_waitcnt lgkmcnt(0)
	s_setprio 1
	s_waitcnt lgkmcnt(0)
	v_mfma_f32_16x16x32_bf16 v[126:129], v[156:159], v[172:175], v[126:129]
	v_mfma_f32_16x16x32_bf16 v[122:125], v[164:167], v[172:175], v[122:125]
	v_mfma_f32_16x16x32_bf16 v[114:117], v[156:159], v[180:183], v[114:117]
	v_mfma_f32_16x16x32_bf16 v[106:109], v[164:167], v[180:183], v[106:109]
	v_mfma_f32_16x16x32_bf16 v[98:101], v[156:159], v[188:191], v[98:101]
	v_mfma_f32_16x16x32_bf16 v[90:93], v[164:167], v[188:191], v[90:93]
	v_mfma_f32_16x16x32_bf16 v[82:85], v[156:159], v[196:199], v[82:85]
	v_mfma_f32_16x16x32_bf16 v[74:77], v[164:167], v[196:199], v[74:77]
	v_mfma_f32_16x16x32_bf16 v[126:129], v[160:163], v[176:179], v[126:129]
	v_mfma_f32_16x16x32_bf16 v[122:125], v[168:171], v[176:179], v[122:125]
	v_mfma_f32_16x16x32_bf16 v[114:117], v[160:163], v[184:187], v[114:117]
	v_mfma_f32_16x16x32_bf16 v[106:109], v[168:171], v[184:187], v[106:109]
	v_mfma_f32_16x16x32_bf16 v[98:101], v[160:163], v[192:195], v[98:101]
	v_mfma_f32_16x16x32_bf16 v[90:93], v[168:171], v[192:195], v[90:93]
	v_mfma_f32_16x16x32_bf16 v[82:85], v[160:163], v[200:203], v[82:85]
	v_mfma_f32_16x16x32_bf16 v[74:77], v[168:171], v[200:203], v[74:77]
	s_setprio 0
	s_barrier
	s_add_i32 s34, 16, 0x1c000
	s_add_i32 s35, s47, s33
	v_add_u32_e32 v216, s34, v144
	s_mov_b32 m0, s35
	ds_read_b128 v[204:207], v216
	ds_read_b128 v[208:211], v216 offset:1024
	ds_read_b128 v[212:215], v216 offset:2048
	ds_read_b128 v[216:219], v216 offset:3072
	global_load_lds_dwordx4 v132, s[52:53]
	s_add_i32 m0, s35, 0x2000
	s_nop 0
	global_load_lds_dwordx4 v136, s[54:55]
	s_barrier
	s_waitcnt lgkmcnt(0)
	s_setprio 1
	s_waitcnt lgkmcnt(0)
	v_mfma_f32_16x16x32_bf16 v[118:121], v[204:207], v[172:175], v[118:121]
	v_mfma_f32_16x16x32_bf16 v[110:113], v[212:215], v[172:175], v[110:113]
	v_mfma_f32_16x16x32_bf16 v[102:105], v[204:207], v[180:183], v[102:105]
	v_mfma_f32_16x16x32_bf16 v[94:97], v[212:215], v[180:183], v[94:97]
	v_mfma_f32_16x16x32_bf16 v[86:89], v[204:207], v[188:191], v[86:89]
	v_mfma_f32_16x16x32_bf16 v[78:81], v[212:215], v[188:191], v[78:81]
	v_mfma_f32_16x16x32_bf16 v[70:73], v[204:207], v[196:199], v[70:73]
	v_mfma_f32_16x16x32_bf16 v[66:69], v[212:215], v[196:199], v[66:69]
	v_mfma_f32_16x16x32_bf16 v[118:121], v[208:211], v[176:179], v[118:121]
	v_mfma_f32_16x16x32_bf16 v[110:113], v[216:219], v[176:179], v[110:113]
	v_mfma_f32_16x16x32_bf16 v[102:105], v[208:211], v[184:187], v[102:105]
	v_mfma_f32_16x16x32_bf16 v[94:97], v[216:219], v[184:187], v[94:97]
	v_mfma_f32_16x16x32_bf16 v[86:89], v[208:211], v[192:195], v[86:89]
	v_mfma_f32_16x16x32_bf16 v[78:81], v[216:219], v[192:195], v[78:81]
	v_mfma_f32_16x16x32_bf16 v[70:73], v[208:211], v[200:203], v[70:73]
	v_mfma_f32_16x16x32_bf16 v[66:69], v[216:219], v[200:203], v[66:69]
	s_setprio 0
	s_mov_b32 m0, s39
	s_barrier
	ds_read_b128 v[172:175], v154 offset:49152
	ds_read_b128 v[176:179], v154 offset:50176
	ds_read_b128 v[180:183], v154 offset:51200
	ds_read_b128 v[184:187], v154 offset:52224
	ds_read_b128 v[188:191], v154 offset:53248
	ds_read_b128 v[192:195], v154 offset:54272
	ds_read_b128 v[196:199], v154 offset:55296
	ds_read_b128 v[200:203], v154 offset:56320
	global_load_lds_dwordx4 v130, s[56:57]
	s_mov_b32 m0, s40
	s_nop 0
	global_load_lds_dwordx4 v134, s[58:59]
	s_barrier
	s_waitcnt lgkmcnt(0)
	s_setprio 1
	s_waitcnt lgkmcnt(0)
	v_mfma_f32_16x16x32_bf16 v[62:65], v[156:159], v[172:175], v[62:65]
	v_mfma_f32_16x16x32_bf16 v[58:61], v[164:167], v[172:175], v[58:61]
	v_mfma_f32_16x16x32_bf16 v[54:57], v[156:159], v[180:183], v[54:57]
	v_mfma_f32_16x16x32_bf16 v[46:49], v[164:167], v[180:183], v[46:49]
	v_mfma_f32_16x16x32_bf16 v[38:41], v[156:159], v[188:191], v[38:41]
	v_mfma_f32_16x16x32_bf16 v[30:33], v[164:167], v[188:191], v[30:33]
	v_mfma_f32_16x16x32_bf16 v[22:25], v[156:159], v[196:199], v[22:25]
	v_mfma_f32_16x16x32_bf16 v[14:17], v[164:167], v[196:199], v[14:17]
	v_mfma_f32_16x16x32_bf16 v[62:65], v[160:163], v[176:179], v[62:65]
	v_mfma_f32_16x16x32_bf16 v[58:61], v[168:171], v[176:179], v[58:61]
	v_mfma_f32_16x16x32_bf16 v[54:57], v[160:163], v[184:187], v[54:57]
	v_mfma_f32_16x16x32_bf16 v[46:49], v[168:171], v[184:187], v[46:49]
	v_mfma_f32_16x16x32_bf16 v[38:41], v[160:163], v[192:195], v[38:41]
	v_mfma_f32_16x16x32_bf16 v[30:33], v[168:171], v[192:195], v[30:33]
	v_mfma_f32_16x16x32_bf16 v[22:25], v[160:163], v[200:203], v[22:25]
	v_mfma_f32_16x16x32_bf16 v[14:17], v[168:171], v[200:203], v[14:17]
	s_setprio 0
	s_barrier
	s_add_u32 s28, s28, 0x80080
	s_addc_u32 s29, s29, 0
	s_add_i32 s34, s34, s33
	s_mov_b32 m0, s34
	s_nop 0
	global_load_lds_dwordx4 v132, s[28:29]
	s_add_i32 m0, s34, 0x2000
	s_nop 0
	global_load_lds_dwordx4 v136, s[28:29]
	s_waitcnt vmcnt(6)
	s_barrier
	s_setprio 1
	v_mfma_f32_16x16x32_bf16 v[50:53], v[204:207], v[172:175], v[50:53]
	v_mfma_f32_16x16x32_bf16 v[42:45], v[212:215], v[172:175], v[42:45]
	v_mfma_f32_16x16x32_bf16 v[34:37], v[204:207], v[180:183], v[34:37]
	v_mfma_f32_16x16x32_bf16 v[26:29], v[212:215], v[180:183], v[26:29]
	v_mfma_f32_16x16x32_bf16 v[18:21], v[204:207], v[188:191], v[18:21]
	v_mfma_f32_16x16x32_bf16 v[10:13], v[212:215], v[188:191], v[10:13]
	v_mfma_f32_16x16x32_bf16 v[6:9], v[204:207], v[196:199], v[6:9]
	v_mfma_f32_16x16x32_bf16 v[2:5], v[212:215], v[196:199], v[2:5]
	v_mfma_f32_16x16x32_bf16 v[50:53], v[208:211], v[176:179], v[50:53]
	v_mfma_f32_16x16x32_bf16 v[42:45], v[216:219], v[176:179], v[42:45]
	v_mfma_f32_16x16x32_bf16 v[34:37], v[208:211], v[184:187], v[34:37]
	v_mfma_f32_16x16x32_bf16 v[26:29], v[216:219], v[184:187], v[26:29]
	v_mfma_f32_16x16x32_bf16 v[18:21], v[208:211], v[192:195], v[18:21]
	v_mfma_f32_16x16x32_bf16 v[10:13], v[216:219], v[192:195], v[10:13]
	v_mfma_f32_16x16x32_bf16 v[6:9], v[208:211], v[200:203], v[6:9]
	v_mfma_f32_16x16x32_bf16 v[2:5], v[216:219], v[200:203], v[2:5]
	s_setprio 0
	s_add_i32 s46, s46, 2
	s_add_u32 s15, s15, 0x100
	s_addc_u32 s17, s17, 0
	s_add_u32 s26, s26, 0x100
	s_addc_u32 s27, s27, 0
	s_cmp_gt_u32 s46, 29
	s_barrier
; __device__ __forceinline__ unsigned cvt_pk_bf16(float lo, float hi) { unsigned r; asm volatile("v_cvt_pk_bf16_f32 %0, %1, %2" : "=v"(r) : "v"(lo), "v"(hi)); return r; }
; #define PG8_WAIT_V(n) asm volatile("s_waitcnt vmcnt(" #n ")" ::: "memory")
; #define PG8_BAR __builtin_amdgcn_s_barrier()
; #define EPI_FOR_ROWS _Pragma("unroll") for (int ai = 0; ai < 2; ++ai) if (ai == 0 || !u.half) _Pragma("unroll") for (int m = 0; m < 4; ++m)
; template <class Sched, class Epi>
; __device__ __forceinline__ void gemm_phase(LAS unsigned char* lds, const Sched& S, const Epi& E, const int K, const int lda, const int ldb) {
;     ...
;         if (!has_next) break;
; #pragma unroll
;         for (int a = 0; a < 2; ++a)
; #pragma unroll
;             for (int b = 0; b < 2; ++b)
; #pragma unroll
;                 for (int m = 0; m < 4; ++m)
; #pragma unroll
;                     for (int n = 0; n < 2; ++n) acc[a][b][m][n] = (f32x4){0.f, 0.f, 0.f, 0.f};
;         cur = nxt; cA = nA; cB = nB; ++ui;
;     }
;     PG8_WAIT_V(0);
;     if (wr == 0) PG8_BAR;
;     PG8_BAR;
;     __device__ __forceinline__ void operator()(EPI_ARGS) const {
;         EPI_FOR_ROWS { bf16_t* rp = O + (size_t)EPI_ROW * ldc;
; #pragma unroll
;             for (int bj = 0; bj < 2; ++bj) { const f32x4 v0 = acc[ai][bj][m][0], v1 = acc[ai][bj][m][1]; u32x4 o;
;                 o[0] = cvt_pk_bf16(v0[0], v0[1]); o[1] = cvt_pk_bf16(v0[2], v0[3]); o[2] = cvt_pk_bf16(v1[0], v1[1]); o[3] = cvt_pk_bf16(v1[2], v1[3]);
;                 *(u32x4*)(rp + EPI_COL(bj)) = o; } }
;     }
	s_cbranch_scc0 .LBB0_957
	v_add_u32_e32 v156, s4, v1
	v_ashrrev_i32_e32 v157, 31, v156
	v_cvt_pk_bf16_f32 v126, v126, v127
	v_cvt_pk_bf16_f32 v127, v128, v129
	v_cvt_pk_bf16_f32 v128, v122, v123
	v_lshl_or_b32 v122, s45, 8, v152
	v_lshlrev_b64 v[156:157], 12, v[156:157]
	v_ashrrev_i32_e32 v123, 31, v122
	v_lshl_add_u64 v[156:157], s[6:7], 0, v[156:157]
	v_lshlrev_b64 v[122:123], 1, v[122:123]
	v_cvt_pk_bf16_f32 v129, v124, v125
	v_lshl_add_u64 v[124:125], v[156:157], 0, v[122:123]
	global_store_dwordx4 v[124:125], v[126:129], off
	v_cvt_pk_bf16_f32 v118, v118, v119
	v_cvt_pk_bf16_f32 v119, v120, v121
	v_cvt_pk_bf16_f32 v120, v110, v111
	v_add_u32_e32 v110, s4, v145
	v_ashrrev_i32_e32 v111, 31, v110
	v_lshlrev_b64 v[110:111], 12, v[110:111]
	v_cvt_pk_bf16_f32 v121, v112, v113
	global_store_dwordx4 v[124:125], v[118:121], off offset:256
	s_and_b64 vcc, exec, s[12:13]
	s_mov_b32 s45, s14
	v_lshl_add_u64 v[118:119], s[6:7], 0, v[110:111]
	v_cvt_pk_bf16_f32 v110, v114, v115
	v_cvt_pk_bf16_f32 v111, v116, v117
	v_cvt_pk_bf16_f32 v112, v106, v107
	v_lshl_add_u64 v[106:107], v[118:119], 0, v[122:123]
	v_cvt_pk_bf16_f32 v113, v108, v109
	global_store_dwordx4 v[106:107], v[110:113], off
	v_cvt_pk_bf16_f32 v102, v102, v103
	v_cvt_pk_bf16_f32 v103, v104, v105
	v_cvt_pk_bf16_f32 v104, v94, v95
	v_add_u32_e32 v94, s4, v146
	v_ashrrev_i32_e32 v95, 31, v94
	v_lshlrev_b64 v[94:95], 12, v[94:95]
	v_cvt_pk_bf16_f32 v105, v96, v97
	global_store_dwordx4 v[106:107], v[102:105], off offset:256
	s_mov_b64 s[28:29], s[20:21]
	s_mov_b64 s[26:27], s[18:19]
	v_lshl_add_u64 v[102:103], s[6:7], 0, v[94:95]
	v_cvt_pk_bf16_f32 v94, v98, v99
	v_cvt_pk_bf16_f32 v95, v100, v101
	v_cvt_pk_bf16_f32 v96, v90, v91
	v_lshl_add_u64 v[90:91], v[102:103], 0, v[122:123]
	v_cvt_pk_bf16_f32 v97, v92, v93
	global_store_dwordx4 v[90:91], v[94:97], off
	v_cvt_pk_bf16_f32 v86, v86, v87
	v_cvt_pk_bf16_f32 v87, v88, v89
	v_cvt_pk_bf16_f32 v88, v78, v79
	v_add_u32_e32 v78, s4, v147
	v_ashrrev_i32_e32 v79, 31, v78
	v_lshlrev_b64 v[78:79], 12, v[78:79]
	v_cvt_pk_bf16_f32 v89, v80, v81
	global_store_dwordx4 v[90:91], v[86:89], off offset:256
	s_nop 1
	v_lshl_add_u64 v[86:87], s[6:7], 0, v[78:79]
	v_cvt_pk_bf16_f32 v78, v82, v83
	v_cvt_pk_bf16_f32 v79, v84, v85
	v_cvt_pk_bf16_f32 v80, v74, v75
	v_lshl_add_u64 v[74:75], v[86:87], 0, v[122:123]
	v_cvt_pk_bf16_f32 v81, v76, v77
	global_store_dwordx4 v[74:75], v[78:81], off
	v_cvt_pk_bf16_f32 v70, v70, v71
	v_cvt_pk_bf16_f32 v71, v72, v73
	v_cvt_pk_bf16_f32 v72, v66, v67
	v_add_u32_e32 v66, s4, v148
	v_ashrrev_i32_e32 v67, 31, v66
	v_lshlrev_b64 v[66:67], 12, v[66:67]
	v_lshl_add_u64 v[66:67], s[6:7], 0, v[66:67]
	v_cvt_pk_bf16_f32 v73, v68, v69
	global_store_dwordx4 v[74:75], v[70:73], off offset:256
	v_cvt_pk_bf16_f32 v62, v62, v63
	v_cvt_pk_bf16_f32 v63, v64, v65
	v_cvt_pk_bf16_f32 v64, v58, v59
	v_lshl_add_u64 v[58:59], v[66:67], 0, v[122:123]
	v_cvt_pk_bf16_f32 v65, v60, v61
	global_store_dwordx4 v[58:59], v[62:65], off
	v_cvt_pk_bf16_f32 v50, v50, v51
	v_cvt_pk_bf16_f32 v51, v52, v53
	v_cvt_pk_bf16_f32 v52, v42, v43
	v_add_u32_e32 v42, s4, v149
	v_ashrrev_i32_e32 v43, 31, v42
	v_lshlrev_b64 v[42:43], 12, v[42:43]
	v_cvt_pk_bf16_f32 v53, v44, v45
	global_store_dwordx4 v[58:59], v[50:53], off offset:256
	s_nop 1
	v_lshl_add_u64 v[50:51], s[6:7], 0, v[42:43]
	v_cvt_pk_bf16_f32 v42, v54, v55
	v_cvt_pk_bf16_f32 v43, v56, v57
	v_cvt_pk_bf16_f32 v44, v46, v47
	v_lshl_add_u64 v[46:47], v[50:51], 0, v[122:123]
	v_cvt_pk_bf16_f32 v45, v48, v49
	global_store_dwordx4 v[46:47], v[42:45], off
	v_cvt_pk_bf16_f32 v34, v34, v35
	v_cvt_pk_bf16_f32 v35, v36, v37
	v_cvt_pk_bf16_f32 v36, v26, v27
	v_add_u32_e32 v26, s4, v150
	v_ashrrev_i32_e32 v27, 31, v26
	v_lshlrev_b64 v[26:27], 12, v[26:27]
	v_cvt_pk_bf16_f32 v37, v28, v29
	global_store_dwordx4 v[46:47], v[34:37], off offset:256
	s_nop 1
	v_lshl_add_u64 v[34:35], s[6:7], 0, v[26:27]
	v_cvt_pk_bf16_f32 v26, v38, v39
	v_cvt_pk_bf16_f32 v27, v40, v41
	v_cvt_pk_bf16_f32 v28, v30, v31
	v_lshl_add_u64 v[30:31], v[34:35], 0, v[122:123]
	v_cvt_pk_bf16_f32 v29, v32, v33
	global_store_dwordx4 v[30:31], v[26:29], off
	v_cvt_pk_bf16_f32 v18, v18, v19
	v_cvt_pk_bf16_f32 v19, v20, v21
	v_cvt_pk_bf16_f32 v20, v10, v11
	v_add_u32_e32 v10, s4, v151
	v_ashrrev_i32_e32 v11, 31, v10
	v_lshlrev_b64 v[10:11], 12, v[10:11]
	v_cvt_pk_bf16_f32 v21, v12, v13
	global_store_dwordx4 v[30:31], v[18:21], off offset:256
	s_mov_b32 s4, s16
	s_nop 0
	v_lshl_add_u64 v[18:19], s[6:7], 0, v[10:11]
	v_cvt_pk_bf16_f32 v10, v22, v23
	v_cvt_pk_bf16_f32 v11, v24, v25
	v_cvt_pk_bf16_f32 v12, v14, v15
	v_lshl_add_u64 v[14:15], v[18:19], 0, v[122:123]
	v_cvt_pk_bf16_f32 v13, v16, v17
	global_store_dwordx4 v[14:15], v[10:13], off
	v_cvt_pk_bf16_f32 v6, v6, v7
	v_cvt_pk_bf16_f32 v7, v8, v9
	v_cvt_pk_bf16_f32 v8, v2, v3
	v_cvt_pk_bf16_f32 v9, v4, v5
	global_store_dwordx4 v[14:15], v[6:9], off offset:256
	s_cbranch_vccz .LBB0_950
	s_waitcnt vmcnt(0)
	s_cmpk_gt_u32 s2, 0xff
	s_cbranch_scc1 .LBB0_961
	s_barrier

; #define PG8_STAGE(bufoff, gbase, voff) do { _Pragma("unroll") for (int _i = 0; _i < 2; ++_i) \
;         __builtin_amdgcn_global_load_lds((const unsigned*)((const char*)(gbase) + (voff)[_i]), (LAS unsigned*)(lds + (bufoff) + ldsw + _i * 8192), 16, 0, 0); } while (0)
; #define PG8_LDA(dst, b, h) do { _Pragma("unroll") for (int m = 0; m < 4; ++m) _Pragma("unroll") for (int k = 0; k < 2; ++k) dst[m][k] = *(const LAS bf16x8*)(lds + PG8_SA(b, h) + aoff + m * 2048 + k * 1024); } while (0)
; #define PG8_LDB(dst, b, h) do { _Pragma("unroll") for (int n = 0; n < 2; ++n) _Pragma("unroll") for (int k = 0; k < 2; ++k) dst[n][k] = *(const LAS bf16x8*)(lds + PG8_SB(b, h) + boff + n * 2048 + k * 1024); } while (0)
; #define PG8_MMA(ai, bj, At, Bt) do { __builtin_amdgcn_s_setprio(1); _Pragma("unroll") for (int m = 0; m < 4; ++m) _Pragma("unroll") for (int n = 0; n < 2; ++n) _Pragma("unroll") for (int k = 0; k < 2; ++k) \
;         acc[ai][bj][m][n] = __builtin_amdgcn_mfma_f32_16x16x32_bf16(Bt[n][k], At[m][k], acc[ai][bj][m][n], 0, 0, 0); __builtin_amdgcn_s_setprio(0); } while (0)
; #define PG8_WAIT_L(n) asm volatile("s_waitcnt lgkmcnt(" #n ")" ::: "memory")
; #define PG8_BAR __builtin_amdgcn_s_barrier()
; #define PG8_SCHED __builtin_amdgcn_sched_barrier(0)
; template <class Sched, class Epi>
; __device__ __forceinline__ void gemm_phase(LAS unsigned char* lds, const Sched& S, const Epi& E, const int K, const int lda, const int ldb) {
;     ...
;         for (int t = 0; t < nt; t += 2) {
;             const bool last = (t == nt - 2);
;             const char* a1 = cA + (size_t)(t + 1) * kstep;
;             const char* a2 = last ? nA : cA + (size_t)(t + 2) * kstep; const char* b2 = last ? nB : cB + (size_t)(t + 2) * kstep;
;             const char* a3 = a2 + kstep; const char* b3 = b2 + kstep;
;             PG8_LDB(B0, 0, 0); PG8_SCHED; PG8_LDA(At, 0, 0); PG8_STAGE(PG8_SA(1, 1), a1 + hstepA, voffA);
;             PG8_WAIT_L(8); PG8_BAR; PG8_WAIT_L(0); PG8_MMA(0, 0, At, B0); PG8_BAR; PG8_SCHED;
;     ...
;         for (int a = 0; a < 2; ++a)
; #pragma unroll
;             for (int b = 0; b < 2; ++b)
; #pragma unroll
;                 for (int m = 0; m < 4; ++m)
; #pragma unroll
;                     for (int n = 0; n < 2; ++n) acc[a][b][m][n] = (f32x4){0.f, 0.f, 0.f, 0.f};
;         cur = nxt; cA = nA; cB = nB; ++ui;
.LBB0_1091:
	s_add_u32 s13, s26, 0x100
	s_addc_u32 s15, s27, 0
	s_add_u32 s24, s24, 0x80080
	v_mov_b32_e32 v2, 0
	s_addc_u32 s25, s25, 0
	s_mov_b32 s48, -2
	v_mov_b32_e32 v3, v2
	v_mov_b32_e32 v4, v2
	v_mov_b32_e32 v5, v2
	v_mov_b32_e32 v6, v2
	v_mov_b32_e32 v7, v2
	v_mov_b32_e32 v8, v2
	v_mov_b32_e32 v9, v2
	v_mov_b32_e32 v14, v2
	v_mov_b32_e32 v15, v2
	v_mov_b32_e32 v16, v2
	v_mov_b32_e32 v17, v2
	v_mov_b32_e32 v22, v2
	v_mov_b32_e32 v23, v2
	v_mov_b32_e32 v24, v2
	v_mov_b32_e32 v25, v2
	v_mov_b32_e32 v30, v2
	v_mov_b32_e32 v31, v2
	v_mov_b32_e32 v32, v2
	v_mov_b32_e32 v33, v2
	v_mov_b32_e32 v38, v2
	v_mov_b32_e32 v39, v2
	v_mov_b32_e32 v40, v2
	v_mov_b32_e32 v41, v2
	v_mov_b32_e32 v46, v2
	v_mov_b32_e32 v47, v2
	v_mov_b32_e32 v48, v2
	v_mov_b32_e32 v49, v2
	v_mov_b32_e32 v54, v2
	v_mov_b32_e32 v55, v2
	v_mov_b32_e32 v56, v2
	v_mov_b32_e32 v57, v2
	v_mov_b32_e32 v10, v2
	v_mov_b32_e32 v11, v2
	v_mov_b32_e32 v12, v2
	v_mov_b32_e32 v13, v2
	v_mov_b32_e32 v18, v2
	v_mov_b32_e32 v19, v2
	v_mov_b32_e32 v20, v2
	v_mov_b32_e32 v21, v2
	v_mov_b32_e32 v26, v2
	v_mov_b32_e32 v27, v2
	v_mov_b32_e32 v28, v2
	v_mov_b32_e32 v29, v2
	v_mov_b32_e32 v34, v2
	v_mov_b32_e32 v35, v2
	v_mov_b32_e32 v36, v2
	v_mov_b32_e32 v37, v2
	v_mov_b32_e32 v42, v2
	v_mov_b32_e32 v43, v2
	v_mov_b32_e32 v44, v2
	v_mov_b32_e32 v45, v2
	v_mov_b32_e32 v50, v2
	v_mov_b32_e32 v51, v2
	v_mov_b32_e32 v52, v2
	v_mov_b32_e32 v53, v2
	v_mov_b32_e32 v58, v2
	v_mov_b32_e32 v59, v2
	v_mov_b32_e32 v60, v2
	v_mov_b32_e32 v61, v2
	v_mov_b32_e32 v62, v2
	v_mov_b32_e32 v63, v2
	v_mov_b32_e32 v64, v2
	v_mov_b32_e32 v65, v2
	v_mov_b32_e32 v66, v2
	v_mov_b32_e32 v67, v2
	v_mov_b32_e32 v68, v2
	v_mov_b32_e32 v69, v2
	v_mov_b32_e32 v70, v2
	v_mov_b32_e32 v71, v2
	v_mov_b32_e32 v72, v2
	v_mov_b32_e32 v73, v2
	v_mov_b32_e32 v78, v2
	v_mov_b32_e32 v79, v2
	v_mov_b32_e32 v80, v2
	v_mov_b32_e32 v81, v2
	v_mov_b32_e32 v86, v2
	v_mov_b32_e32 v87, v2
	v_mov_b32_e32 v88, v2
	v_mov_b32_e32 v89, v2
	v_mov_b32_e32 v94, v2
	v_mov_b32_e32 v95, v2
	v_mov_b32_e32 v96, v2
	v_mov_b32_e32 v97, v2
	v_mov_b32_e32 v102, v2
	v_mov_b32_e32 v103, v2
	v_mov_b32_e32 v104, v2
	v_mov_b32_e32 v105, v2
	v_mov_b32_e32 v110, v2
	v_mov_b32_e32 v111, v2
	v_mov_b32_e32 v112, v2
	v_mov_b32_e32 v113, v2
	v_mov_b32_e32 v118, v2
	v_mov_b32_e32 v119, v2
	v_mov_b32_e32 v120, v2
	v_mov_b32_e32 v121, v2
	v_mov_b32_e32 v74, v2
	v_mov_b32_e32 v75, v2
	v_mov_b32_e32 v76, v2
	v_mov_b32_e32 v77, v2
	v_mov_b32_e32 v82, v2
	v_mov_b32_e32 v83, v2
	v_mov_b32_e32 v84, v2
	v_mov_b32_e32 v85, v2
	v_mov_b32_e32 v90, v2
	v_mov_b32_e32 v91, v2
	v_mov_b32_e32 v92, v2
	v_mov_b32_e32 v93, v2
	v_mov_b32_e32 v98, v2
	v_mov_b32_e32 v99, v2
	v_mov_b32_e32 v100, v2
	v_mov_b32_e32 v101, v2
	v_mov_b32_e32 v106, v2
	v_mov_b32_e32 v107, v2
	v_mov_b32_e32 v108, v2
	v_mov_b32_e32 v109, v2
	v_mov_b32_e32 v114, v2
	v_mov_b32_e32 v115, v2
	v_mov_b32_e32 v116, v2
	v_mov_b32_e32 v117, v2
	v_mov_b32_e32 v122, v2
	v_mov_b32_e32 v123, v2
	v_mov_b32_e32 v124, v2
	v_mov_b32_e32 v125, v2
	v_mov_b32_e32 v126, v2
	v_mov_b32_e32 v127, v2
	v_mov_b32_e32 v128, v2
	v_mov_b32_e32 v129, v2
	s_branch .Lal_1092
	.p2align 11
.Lal_1092:
.LBB0_1092:
	ds_read_b128 v[160:163], v156
	ds_read_b128 v[164:167], v156 offset:1024
	ds_read_b128 v[168:171], v156 offset:2048
	ds_read_b128 v[172:175], v156 offset:3072
	s_add_u32 s26, s24, 0xfff80080
	s_addc_u32 s27, s25, -1
	s_cmp_eq_u32 s48, 28
	s_cselect_b32 s29, s21, s27
	s_cselect_b32 s28, s20, s26
	s_cselect_b32 s27, s23, s15
	s_cselect_b32 s26, s22, s13
	s_add_i32 m0, s5, 0xc000
	ds_read_b128 v[176:179], v157
	ds_read_b128 v[180:183], v157 offset:1024
	ds_read_b128 v[184:187], v157 offset:2048
	ds_read_b128 v[188:191], v157 offset:3072
	ds_read_b128 v[192:195], v157 offset:4096
	ds_read_b128 v[196:199], v157 offset:5120
	ds_read_b128 v[200:203], v157 offset:6144
	ds_read_b128 v[204:207], v157 offset:7168
	global_load_lds_dwordx4 v142, s[24:25]
	s_add_i32 m0, s5, 0xe000
	s_nop 0
	global_load_lds_dwordx4 v140, s[24:25]
	s_waitcnt lgkmcnt(8)
	s_barrier
	s_waitcnt lgkmcnt(0)
	s_setprio 1
	s_waitcnt lgkmcnt(0)
	v_mfma_f32_16x16x32_bf16 v[126:129], v[160:163], v[176:179], v[126:129]
	v_mfma_f32_16x16x32_bf16 v[122:125], v[168:171], v[176:179], v[122:125]
	v_mfma_f32_16x16x32_bf16 v[114:117], v[160:163], v[184:187], v[114:117]
	v_mfma_f32_16x16x32_bf16 v[106:109], v[168:171], v[184:187], v[106:109]
	v_mfma_f32_16x16x32_bf16 v[98:101], v[160:163], v[192:195], v[98:101]
	v_mfma_f32_16x16x32_bf16 v[90:93], v[168:171], v[192:195], v[90:93]
	v_mfma_f32_16x16x32_bf16 v[82:85], v[160:163], v[200:203], v[82:85]
	v_mfma_f32_16x16x32_bf16 v[74:77], v[168:171], v[200:203], v[74:77]
	v_mfma_f32_16x16x32_bf16 v[126:129], v[164:167], v[180:183], v[126:129]
	v_mfma_f32_16x16x32_bf16 v[122:125], v[172:175], v[180:183], v[122:125]
	v_mfma_f32_16x16x32_bf16 v[114:117], v[164:167], v[188:191], v[114:117]
	v_mfma_f32_16x16x32_bf16 v[106:109], v[172:175], v[188:191], v[106:109]
	v_mfma_f32_16x16x32_bf16 v[98:101], v[164:167], v[196:199], v[98:101]
	v_mfma_f32_16x16x32_bf16 v[90:93], v[172:175], v[196:199], v[90:93]
	v_mfma_f32_16x16x32_bf16 v[82:85], v[164:167], v[204:207], v[82:85]
	v_mfma_f32_16x16x32_bf16 v[74:77], v[172:175], v[204:207], v[74:77]
	s_setprio 0
	s_barrier
	s_add_i32 s49, s44, s11
	s_add_u32 s52, s26, s6
	s_addc_u32 s53, s27, s7
	s_mov_b32 m0, s49
	ds_read_b128 v[208:211], v158
	ds_read_b128 v[212:215], v158 offset:1024
	ds_read_b128 v[216:219], v158 offset:2048
	ds_read_b128 v[220:223], v158 offset:3072
	global_load_lds_dwordx4 v134, s[26:27]
	s_add_u32 s54, s26, s6
	s_addc_u32 s55, s27, s7
	s_add_i32 m0, s49, 0x2000
	s_nop 0
	global_load_lds_dwordx4 v130, s[26:27]
	s_barrier
; #define PG8_STAGE(bufoff, gbase, voff) do { _Pragma("unroll") for (int _i = 0; _i < 2; ++_i) \
;         __builtin_amdgcn_global_load_lds((const unsigned*)((const char*)(gbase) + (voff)[_i]), (LAS unsigned*)(lds + (bufoff) + ldsw + _i * 8192), 16, 0, 0); } while (0)
; #define PG8_LDA(dst, b, h) do { _Pragma("unroll") for (int m = 0; m < 4; ++m) _Pragma("unroll") for (int k = 0; k < 2; ++k) dst[m][k] = *(const LAS bf16x8*)(lds + PG8_SA(b, h) + aoff + m * 2048 + k * 1024); } while (0)
; #define PG8_LDB(dst, b, h) do { _Pragma("unroll") for (int n = 0; n < 2; ++n) _Pragma("unroll") for (int k = 0; k < 2; ++k) dst[n][k] = *(const LAS bf16x8*)(lds + PG8_SB(b, h) + boff + n * 2048 + k * 1024); } while (0)
; #define PG8_MMA(ai, bj, At, Bt) do { __builtin_amdgcn_s_setprio(1); _Pragma("unroll") for (int m = 0; m < 4; ++m) _Pragma("unroll") for (int n = 0; n < 2; ++n) _Pragma("unroll") for (int k = 0; k < 2; ++k) \
;         acc[ai][bj][m][n] = __builtin_amdgcn_mfma_f32_16x16x32_bf16(Bt[n][k], At[m][k], acc[ai][bj][m][n], 0, 0, 0); __builtin_amdgcn_s_setprio(0); } while (0)
; #define PG8_WAIT_V(n) asm volatile("s_waitcnt vmcnt(" #n ")" ::: "memory")
; #define PG8_WAIT_L(n) asm volatile("s_waitcnt lgkmcnt(" #n ")" ::: "memory")
; #define PG8_BAR __builtin_amdgcn_s_barrier()
; #define PG8_SCHED __builtin_amdgcn_sched_barrier(0)
; template <class Sched, class Epi>
; __device__ __forceinline__ void gemm_phase(LAS unsigned char* lds, const Sched& S, const Epi& E, const int K, const int lda, const int ldb) {
;     ...
;             PG8_WAIT_L(8); PG8_BAR; PG8_WAIT_L(0); PG8_MMA(0, 0, At, B0); PG8_BAR; PG8_SCHED;
;             PG8_LDB(B1, 0, 1); PG8_STAGE(PG8_SB(0, 0), b2, voffB);
;             PG8_BAR; PG8_WAIT_L(0); PG8_MMA(0, 1, At, B1); PG8_BAR;
;             PG8_LDA(At, 0, 1); PG8_STAGE(PG8_SA(0, 0), a2, voffA);
;             PG8_BAR; PG8_WAIT_L(0); if (!chalf) PG8_MMA(1, 0, At, B0); PG8_BAR; PG8_SCHED;
;             PG8_STAGE(PG8_SB(0, 1), b2 + hstepB, voffB);
;             PG8_WAIT_V(6); PG8_BAR; if (!chalf) PG8_MMA(1, 1, At, B1); PG8_BAR;
;             PG8_LDB(B0, 1, 0); PG8_SCHED; PG8_LDA(At, 1, 0); PG8_STAGE(PG8_SA(0, 1), a2 + hstepA, voffA);
;             PG8_WAIT_L(8); PG8_BAR; PG8_WAIT_L(0); PG8_MMA(0, 0, At, B0); PG8_BAR; PG8_SCHED;
	s_waitcnt lgkmcnt(0)
	s_setprio 1
	s_waitcnt lgkmcnt(0)
	v_mfma_f32_16x16x32_bf16 v[118:121], v[208:211], v[176:179], v[118:121]
	v_mfma_f32_16x16x32_bf16 v[110:113], v[216:219], v[176:179], v[110:113]
	v_mfma_f32_16x16x32_bf16 v[102:105], v[208:211], v[184:187], v[102:105]
	v_mfma_f32_16x16x32_bf16 v[94:97], v[216:219], v[184:187], v[94:97]
	v_mfma_f32_16x16x32_bf16 v[86:89], v[208:211], v[192:195], v[86:89]
	v_mfma_f32_16x16x32_bf16 v[78:81], v[216:219], v[192:195], v[78:81]
	v_mfma_f32_16x16x32_bf16 v[70:73], v[208:211], v[200:203], v[70:73]
	v_mfma_f32_16x16x32_bf16 v[66:69], v[216:219], v[200:203], v[66:69]
	v_mfma_f32_16x16x32_bf16 v[118:121], v[212:215], v[180:183], v[118:121]
	v_mfma_f32_16x16x32_bf16 v[110:113], v[220:223], v[180:183], v[110:113]
	v_mfma_f32_16x16x32_bf16 v[102:105], v[212:215], v[188:191], v[102:105]
	v_mfma_f32_16x16x32_bf16 v[94:97], v[220:223], v[188:191], v[94:97]
	v_mfma_f32_16x16x32_bf16 v[86:89], v[212:215], v[196:199], v[86:89]
	v_mfma_f32_16x16x32_bf16 v[78:81], v[220:223], v[196:199], v[78:81]
	v_mfma_f32_16x16x32_bf16 v[70:73], v[212:215], v[204:207], v[70:73]
	v_mfma_f32_16x16x32_bf16 v[66:69], v[220:223], v[204:207], v[66:69]
	s_setprio 0
	s_mov_b32 m0, s5
	s_add_u32 s56, s28, s6
	s_addc_u32 s57, s29, s7
	s_barrier
	ds_read_b128 v[176:179], v157 offset:16384
	ds_read_b128 v[180:183], v157 offset:17408
	ds_read_b128 v[184:187], v157 offset:18432
	ds_read_b128 v[188:191], v157 offset:19456
	ds_read_b128 v[192:195], v157 offset:20480
	ds_read_b128 v[196:199], v157 offset:21504
	ds_read_b128 v[200:203], v157 offset:22528
	ds_read_b128 v[204:207], v157 offset:23552
	global_load_lds_dwordx4 v136, s[28:29]
	s_add_u32 s58, s28, s6
	s_addc_u32 s59, s29, s7
	s_mov_b32 m0, s35
	s_nop 0
	global_load_lds_dwordx4 v132, s[28:29]
	s_barrier
	s_waitcnt lgkmcnt(0)
	s_setprio 1
	s_waitcnt lgkmcnt(0)
	v_mfma_f32_16x16x32_bf16 v[62:65], v[160:163], v[176:179], v[62:65]
	v_mfma_f32_16x16x32_bf16 v[58:61], v[168:171], v[176:179], v[58:61]
	v_mfma_f32_16x16x32_bf16 v[50:53], v[160:163], v[184:187], v[50:53]
	v_mfma_f32_16x16x32_bf16 v[42:45], v[168:171], v[184:187], v[42:45]
	v_mfma_f32_16x16x32_bf16 v[34:37], v[160:163], v[192:195], v[34:37]
	v_mfma_f32_16x16x32_bf16 v[26:29], v[168:171], v[192:195], v[26:29]
	v_mfma_f32_16x16x32_bf16 v[18:21], v[160:163], v[200:203], v[18:21]
	v_mfma_f32_16x16x32_bf16 v[10:13], v[168:171], v[200:203], v[10:13]
	v_mfma_f32_16x16x32_bf16 v[62:65], v[164:167], v[180:183], v[62:65]
	v_mfma_f32_16x16x32_bf16 v[58:61], v[172:175], v[180:183], v[58:61]
	v_mfma_f32_16x16x32_bf16 v[50:53], v[164:167], v[188:191], v[50:53]
	v_mfma_f32_16x16x32_bf16 v[42:45], v[172:175], v[188:191], v[42:45]
	v_mfma_f32_16x16x32_bf16 v[34:37], v[164:167], v[196:199], v[34:37]
	v_mfma_f32_16x16x32_bf16 v[26:29], v[172:175], v[196:199], v[26:29]
	v_mfma_f32_16x16x32_bf16 v[18:21], v[164:167], v[204:207], v[18:21]
	v_mfma_f32_16x16x32_bf16 v[10:13], v[172:175], v[204:207], v[10:13]
	s_setprio 0
	s_barrier
	s_add_u32 s50, s26, 0x80000
	s_addc_u32 s51, s27, 0
	s_add_i32 s49, s45, s11
	s_mov_b32 m0, s49
	s_nop 0
	global_load_lds_dwordx4 v134, s[50:51]
	s_add_i32 m0, s49, 0x2000
	s_nop 0
	global_load_lds_dwordx4 v130, s[50:51]
	s_waitcnt vmcnt(6)
	s_barrier
	s_setprio 1
	v_mfma_f32_16x16x32_bf16 v[54:57], v[208:211], v[176:179], v[54:57]
	v_mfma_f32_16x16x32_bf16 v[46:49], v[216:219], v[176:179], v[46:49]
	v_mfma_f32_16x16x32_bf16 v[38:41], v[208:211], v[184:187], v[38:41]
	v_mfma_f32_16x16x32_bf16 v[30:33], v[216:219], v[184:187], v[30:33]
	v_mfma_f32_16x16x32_bf16 v[22:25], v[208:211], v[192:195], v[22:25]
	v_mfma_f32_16x16x32_bf16 v[14:17], v[216:219], v[192:195], v[14:17]
	v_mfma_f32_16x16x32_bf16 v[6:9], v[208:211], v[200:203], v[6:9]
	v_mfma_f32_16x16x32_bf16 v[2:5], v[216:219], v[200:203], v[2:5]
	v_mfma_f32_16x16x32_bf16 v[54:57], v[212:215], v[180:183], v[54:57]
	v_mfma_f32_16x16x32_bf16 v[46:49], v[220:223], v[180:183], v[46:49]
	v_mfma_f32_16x16x32_bf16 v[38:41], v[212:215], v[188:191], v[38:41]
	v_mfma_f32_16x16x32_bf16 v[30:33], v[220:223], v[188:191], v[30:33]
	v_mfma_f32_16x16x32_bf16 v[22:25], v[212:215], v[196:199], v[22:25]
	v_mfma_f32_16x16x32_bf16 v[14:17], v[220:223], v[196:199], v[14:17]
	v_mfma_f32_16x16x32_bf16 v[6:9], v[212:215], v[204:207], v[6:9]
	v_mfma_f32_16x16x32_bf16 v[2:5], v[220:223], v[204:207], v[2:5]
	s_setprio 0
	s_add_i32 s49, 16, 0x18000
	v_add_u32_e32 v159, s49, v148
	s_barrier
	ds_read_b128 v[160:163], v159
	ds_read_b128 v[164:167], v159 offset:1024
	ds_read_b128 v[168:171], v159 offset:2048
	ds_read_b128 v[172:175], v159 offset:3072
	s_add_u32 s28, s28, 0x80000
	s_addc_u32 s29, s29, 0
	s_mov_b32 m0, s36
	ds_read_b128 v[176:179], v157 offset:32768
	ds_read_b128 v[180:183], v157 offset:33792
	ds_read_b128 v[184:187], v157 offset:34816
	ds_read_b128 v[188:191], v157 offset:35840
	ds_read_b128 v[192:195], v157 offset:36864
	ds_read_b128 v[196:199], v157 offset:37888
	ds_read_b128 v[200:203], v157 offset:38912
	ds_read_b128 v[204:207], v157 offset:39936
	global_load_lds_dwordx4 v136, s[28:29]
	s_mov_b32 m0, s37
	s_nop 0
	global_load_lds_dwordx4 v132, s[28:29]
	s_waitcnt lgkmcnt(8)
	s_barrier
; #define PG8_STAGE(bufoff, gbase, voff) do { _Pragma("unroll") for (int _i = 0; _i < 2; ++_i) \
;         __builtin_amdgcn_global_load_lds((const unsigned*)((const char*)(gbase) + (voff)[_i]), (LAS unsigned*)(lds + (bufoff) + ldsw + _i * 8192), 16, 0, 0); } while (0)
; #define PG8_LDA(dst, b, h) do { _Pragma("unroll") for (int m = 0; m < 4; ++m) _Pragma("unroll") for (int k = 0; k < 2; ++k) dst[m][k] = *(const LAS bf16x8*)(lds + PG8_SA(b, h) + aoff + m * 2048 + k * 1024); } while (0)
; #define PG8_LDB(dst, b, h) do { _Pragma("unroll") for (int n = 0; n < 2; ++n) _Pragma("unroll") for (int k = 0; k < 2; ++k) dst[n][k] = *(const LAS bf16x8*)(lds + PG8_SB(b, h) + boff + n * 2048 + k * 1024); } while (0)
; #define PG8_MMA(ai, bj, At, Bt) do { __builtin_amdgcn_s_setprio(1); _Pragma("unroll") for (int m = 0; m < 4; ++m) _Pragma("unroll") for (int n = 0; n < 2; ++n) _Pragma("unroll") for (int k = 0; k < 2; ++k) \
;         acc[ai][bj][m][n] = __builtin_amdgcn_mfma_f32_16x16x32_bf16(Bt[n][k], At[m][k], acc[ai][bj][m][n], 0, 0, 0); __builtin_amdgcn_s_setprio(0); } while (0)
; #define PG8_WAIT_V(n) asm volatile("s_waitcnt vmcnt(" #n ")" ::: "memory")
; template <class Sched, class Epi>
; __device__ __forceinline__ void gemm_phase(LAS unsigned char* lds, const Sched& S, const Epi& E, const int K, const int lda, const int ldb) {
;     ...
;             PG8_WAIT_L(8); PG8_BAR; PG8_WAIT_L(0); PG8_MMA(0, 0, At, B0); PG8_BAR; PG8_SCHED;
;             PG8_LDB(B1, 1, 1); PG8_STAGE(PG8_SB(1, 0), b3, voffB);
;             PG8_BAR; PG8_WAIT_L(0); PG8_MMA(0, 1, At, B1); PG8_BAR;
;             PG8_LDA(At, 1, 1); PG8_STAGE(PG8_SA(1, 0), a3, voffA);
;             PG8_BAR; PG8_WAIT_L(0); if (!chalf) PG8_MMA(1, 0, At, B0); PG8_BAR; PG8_SCHED;
;             PG8_STAGE(PG8_SB(1, 1), b3 + hstepB, voffB);
;             PG8_WAIT_V(6); PG8_BAR; if (!chalf) PG8_MMA(1, 1, At, B1); PG8_BAR;
;     __device__ __forceinline__ void operator()(EPI_ARGS) const {
;         const int c0 = u.pn * 256; size_t eb; int pitch, cl;
;         if (c0 < C_U) { eb = E_PC; pitch = 4096; cl = c0; } else if (c0 < C_ZB) { eb = E_PU; pitch = 1024; cl = c0 - C_U; } else if (c0 < C_F) { eb = E_PZB; pitch = 1024; cl = c0 - C_ZB; }
;         else if (c0 < C_ZC) { eb = E_PF; pitch = 1024; cl = c0 - C_F; } else if (c0 < C_GL) { eb = E_PZC; pitch = 1024; cl = c0 - C_ZC; } else { eb = E_PGL; pitch = 6144; cl = c0 - C_GL; }
	s_waitcnt lgkmcnt(0)
	s_setprio 1
	s_waitcnt lgkmcnt(0)
	v_mfma_f32_16x16x32_bf16 v[126:129], v[160:163], v[176:179], v[126:129]
	v_mfma_f32_16x16x32_bf16 v[122:125], v[168:171], v[176:179], v[122:125]
	v_mfma_f32_16x16x32_bf16 v[114:117], v[160:163], v[184:187], v[114:117]
	v_mfma_f32_16x16x32_bf16 v[106:109], v[168:171], v[184:187], v[106:109]
	v_mfma_f32_16x16x32_bf16 v[98:101], v[160:163], v[192:195], v[98:101]
	v_mfma_f32_16x16x32_bf16 v[90:93], v[168:171], v[192:195], v[90:93]
	v_mfma_f32_16x16x32_bf16 v[82:85], v[160:163], v[200:203], v[82:85]
	v_mfma_f32_16x16x32_bf16 v[74:77], v[168:171], v[200:203], v[74:77]
	v_mfma_f32_16x16x32_bf16 v[126:129], v[164:167], v[180:183], v[126:129]
	v_mfma_f32_16x16x32_bf16 v[122:125], v[172:175], v[180:183], v[122:125]
	v_mfma_f32_16x16x32_bf16 v[114:117], v[164:167], v[188:191], v[114:117]
	v_mfma_f32_16x16x32_bf16 v[106:109], v[172:175], v[188:191], v[106:109]
	v_mfma_f32_16x16x32_bf16 v[98:101], v[164:167], v[196:199], v[98:101]
	v_mfma_f32_16x16x32_bf16 v[90:93], v[172:175], v[196:199], v[90:93]
	v_mfma_f32_16x16x32_bf16 v[82:85], v[164:167], v[204:207], v[82:85]
	v_mfma_f32_16x16x32_bf16 v[74:77], v[172:175], v[204:207], v[74:77]
	s_setprio 0
	s_barrier
	s_add_i32 s28, 16, 0x1c000
	s_add_i32 s29, s49, s11
	v_add_u32_e32 v159, s28, v148
	s_mov_b32 m0, s29
	ds_read_b128 v[208:211], v159
	ds_read_b128 v[212:215], v159 offset:1024
	ds_read_b128 v[216:219], v159 offset:2048
	ds_read_b128 v[220:223], v159 offset:3072
	global_load_lds_dwordx4 v134, s[52:53]
	s_add_i32 m0, s29, 0x2000
	s_nop 0
	global_load_lds_dwordx4 v130, s[54:55]
	s_barrier
	s_waitcnt lgkmcnt(0)
	s_setprio 1
	s_waitcnt lgkmcnt(0)
	v_mfma_f32_16x16x32_bf16 v[118:121], v[208:211], v[176:179], v[118:121]
	v_mfma_f32_16x16x32_bf16 v[110:113], v[216:219], v[176:179], v[110:113]
	v_mfma_f32_16x16x32_bf16 v[102:105], v[208:211], v[184:187], v[102:105]
	v_mfma_f32_16x16x32_bf16 v[94:97], v[216:219], v[184:187], v[94:97]
	v_mfma_f32_16x16x32_bf16 v[86:89], v[208:211], v[192:195], v[86:89]
	v_mfma_f32_16x16x32_bf16 v[78:81], v[216:219], v[192:195], v[78:81]
	v_mfma_f32_16x16x32_bf16 v[70:73], v[208:211], v[200:203], v[70:73]
	v_mfma_f32_16x16x32_bf16 v[66:69], v[216:219], v[200:203], v[66:69]
	v_mfma_f32_16x16x32_bf16 v[118:121], v[212:215], v[180:183], v[118:121]
	v_mfma_f32_16x16x32_bf16 v[110:113], v[220:223], v[180:183], v[110:113]
	v_mfma_f32_16x16x32_bf16 v[102:105], v[212:215], v[188:191], v[102:105]
	v_mfma_f32_16x16x32_bf16 v[94:97], v[220:223], v[188:191], v[94:97]
	v_mfma_f32_16x16x32_bf16 v[86:89], v[212:215], v[196:199], v[86:89]
	v_mfma_f32_16x16x32_bf16 v[78:81], v[220:223], v[196:199], v[78:81]
	v_mfma_f32_16x16x32_bf16 v[70:73], v[212:215], v[204:207], v[70:73]
	v_mfma_f32_16x16x32_bf16 v[66:69], v[220:223], v[204:207], v[66:69]
	s_setprio 0
	s_mov_b32 m0, s41
	s_barrier
	ds_read_b128 v[176:179], v157 offset:49152
	ds_read_b128 v[180:183], v157 offset:50176
	ds_read_b128 v[184:187], v157 offset:51200
	ds_read_b128 v[188:191], v157 offset:52224
	ds_read_b128 v[192:195], v157 offset:53248
	ds_read_b128 v[196:199], v157 offset:54272
	ds_read_b128 v[200:203], v157 offset:55296
	ds_read_b128 v[204:207], v157 offset:56320
	global_load_lds_dwordx4 v136, s[56:57]
	s_mov_b32 m0, s42
	s_nop 0
	global_load_lds_dwordx4 v132, s[58:59]
	s_barrier
	s_waitcnt lgkmcnt(0)
	s_setprio 1
	s_waitcnt lgkmcnt(0)
	v_mfma_f32_16x16x32_bf16 v[62:65], v[160:163], v[176:179], v[62:65]
	v_mfma_f32_16x16x32_bf16 v[58:61], v[168:171], v[176:179], v[58:61]
	v_mfma_f32_16x16x32_bf16 v[50:53], v[160:163], v[184:187], v[50:53]
	v_mfma_f32_16x16x32_bf16 v[42:45], v[168:171], v[184:187], v[42:45]
	v_mfma_f32_16x16x32_bf16 v[34:37], v[160:163], v[192:195], v[34:37]
	v_mfma_f32_16x16x32_bf16 v[26:29], v[168:171], v[192:195], v[26:29]
	v_mfma_f32_16x16x32_bf16 v[18:21], v[160:163], v[200:203], v[18:21]
	v_mfma_f32_16x16x32_bf16 v[10:13], v[168:171], v[200:203], v[10:13]
	v_mfma_f32_16x16x32_bf16 v[62:65], v[164:167], v[180:183], v[62:65]
	v_mfma_f32_16x16x32_bf16 v[58:61], v[172:175], v[180:183], v[58:61]
	v_mfma_f32_16x16x32_bf16 v[50:53], v[164:167], v[188:191], v[50:53]
	v_mfma_f32_16x16x32_bf16 v[42:45], v[172:175], v[188:191], v[42:45]
	v_mfma_f32_16x16x32_bf16 v[34:37], v[164:167], v[196:199], v[34:37]
	v_mfma_f32_16x16x32_bf16 v[26:29], v[172:175], v[196:199], v[26:29]
	v_mfma_f32_16x16x32_bf16 v[18:21], v[164:167], v[204:207], v[18:21]
	v_mfma_f32_16x16x32_bf16 v[10:13], v[172:175], v[204:207], v[10:13]
	s_setprio 0
	s_barrier
	s_add_u32 s26, s26, 0x80080
	s_addc_u32 s27, s27, 0
	s_add_i32 s28, s28, s11
	s_mov_b32 m0, s28
	s_nop 0
	global_load_lds_dwordx4 v134, s[26:27]
	s_add_i32 m0, s28, 0x2000
	s_nop 0
	global_load_lds_dwordx4 v130, s[26:27]
	s_waitcnt vmcnt(6)
	s_barrier
	s_setprio 1
	v_mfma_f32_16x16x32_bf16 v[54:57], v[208:211], v[176:179], v[54:57]
	v_mfma_f32_16x16x32_bf16 v[46:49], v[216:219], v[176:179], v[46:49]
	v_mfma_f32_16x16x32_bf16 v[38:41], v[208:211], v[184:187], v[38:41]
	v_mfma_f32_16x16x32_bf16 v[30:33], v[216:219], v[184:187], v[30:33]
	v_mfma_f32_16x16x32_bf16 v[22:25], v[208:211], v[192:195], v[22:25]
	v_mfma_f32_16x16x32_bf16 v[14:17], v[216:219], v[192:195], v[14:17]
	v_mfma_f32_16x16x32_bf16 v[6:9], v[208:211], v[200:203], v[6:9]
	v_mfma_f32_16x16x32_bf16 v[2:5], v[216:219], v[200:203], v[2:5]
	v_mfma_f32_16x16x32_bf16 v[54:57], v[212:215], v[180:183], v[54:57]
	v_mfma_f32_16x16x32_bf16 v[46:49], v[220:223], v[180:183], v[46:49]
	v_mfma_f32_16x16x32_bf16 v[38:41], v[212:215], v[188:191], v[38:41]
	v_mfma_f32_16x16x32_bf16 v[30:33], v[220:223], v[188:191], v[30:33]
	v_mfma_f32_16x16x32_bf16 v[22:25], v[212:215], v[196:199], v[22:25]
	v_mfma_f32_16x16x32_bf16 v[14:17], v[220:223], v[196:199], v[14:17]
	v_mfma_f32_16x16x32_bf16 v[6:9], v[212:215], v[204:207], v[6:9]
	v_mfma_f32_16x16x32_bf16 v[2:5], v[220:223], v[204:207], v[2:5]
	s_setprio 0
	s_add_i32 s48, s48, 2
	s_add_u32 s13, s13, 0x100
	s_addc_u32 s15, s15, 0
	s_add_u32 s24, s24, 0x100
	s_addc_u32 s25, s25, 0
	s_cmp_gt_u32 s48, 29
	s_barrier
	s_cbranch_scc0 .LBB0_1092
	s_lshl_b32 s22, s47, 8
	s_cmp_lt_i32 s47, 16
	s_cbranch_scc1 .LBB0_1109
	s_cmp_gt_u32 s47, 19
	s_mov_b64 s[26:27], -1
	s_cbranch_scc0 .LBB0_1107
	s_cmp_gt_u32 s47, 23
	s_cbranch_scc0 .LBB0_1104
	s_cmp_gt_u32 s47, 27
	s_cbranch_scc0 .LBB0_1101
	s_cmp_gt_u32 s47, 31
	s_mov_b64 s[20:21], -1
	s_cbranch_scc0 .LBB0_1099
	s_add_i32 s13, s22, 0xffffe000
	s_mov_b64 s[20:21], 0

; #define PG8_STAGE(bufoff, gbase, voff) do { _Pragma("unroll") for (int _i = 0; _i < 2; ++_i) \
;         __builtin_amdgcn_global_load_lds((const unsigned*)((const char*)(gbase) + (voff)[_i]), (LAS unsigned*)(lds + (bufoff) + ldsw + _i * 8192), 16, 0, 0); } while (0)
; #define PG8_WAIT_V(n) asm volatile("s_waitcnt vmcnt(" #n ")" ::: "memory")
; #define PG8_BAR __builtin_amdgcn_s_barrier()
; template <class Sched, class Epi>
; __device__ __forceinline__ void gemm_phase(LAS unsigned char* lds, const Sched& S, const Epi& E, const int K, const int lda, const int ldb) {
;     ...
;     f32x4 acc[2][2][4][2];
; #pragma unroll
;     for (int a = 0; a < 2; ++a)
; #pragma unroll
;         for (int b = 0; b < 2; ++b)
; #pragma unroll
;             for (int m = 0; m < 4; ++m)
; #pragma unroll
;                 for (int n = 0; n < 2; ++n) acc[a][b][m][n] = (f32x4){0.f, 0.f, 0.f, 0.f};
;     bf16x8 At[4][2], B0[2][2], B1[2][2];
;     const char* cA = cur.A; const char* cB = cur.B;
;     PG8_STAGE(PG8_SB(0, 0), cB, voffB); PG8_STAGE(PG8_SA(0, 0), cA, voffA); PG8_STAGE(PG8_SB(0, 1), cB + hstepB, voffB); PG8_STAGE(PG8_SA(0, 1), cA + hstepA, voffA);
;     if (wr == 1) PG8_BAR;
;     PG8_WAIT_V(4); PG8_BAR;
;     PG8_STAGE(PG8_SB(1, 0), cB + kstep, voffB); PG8_STAGE(PG8_SA(1, 0), cA + kstep, voffA); PG8_STAGE(PG8_SB(1, 1), cB + hstepB + kstep, voffB);
;     PG8_WAIT_V(6); PG8_BAR;
.LBB0_1389:
	v_lshrrev_b32_e32 v18, 1, v13
	v_and_b32_e32 v142, 24, v18
	v_and_b32_e32 v17, 15, v13
	v_lshlrev_b32_e32 v18, 1, v142
	v_lshlrev_b32_e32 v13, 2, v13
	v_lshl_or_b32 v1, s10, 6, v17
	v_lshl_or_b32 v17, v17, 6, v18
	s_lshl_b32 s9, s10, 13
	v_and_b32_e32 v13, 32, v13
	v_bitop3_b32 v18, v17, s9, v13 bitop3:0xde
	s_lshl_b32 s9, s11, 5
	s_and_b32 s9, s9, 0x60
	s_mov_b64 s[16:17], 0x80
	s_lshl_b32 s10, s9, 7
	s_add_i32 m0, s1, 0x18000
	v_lshl_add_u64 v[8:9], v[8:9], 0, s[16:17]
	v_bitop3_b32 v13, v17, s10, v13 bitop3:0xde
	s_waitcnt vmcnt(4)
	s_barrier
	global_load_lds_dwordx4 v[8:9], off
	v_lshl_add_u64 v[6:7], v[6:7], 0, s[16:17]
	s_add_i32 m0, s1, 0x1a000
	s_add_i32 s10, s1, 0x8000
	s_add_i32 s11, s1, 0xa000
	global_load_lds_dwordx4 v[6:7], off
	v_lshl_add_u64 v[4:5], v[4:5], 0, s[16:17]
	s_mov_b32 m0, s10
	s_add_u32 s24, s14, 0x80080
	global_load_lds_dwordx4 v[4:5], off
	v_lshl_add_u64 v[2:3], v[2:3], 0, s[16:17]
	s_mov_b32 m0, s11
	s_addc_u32 s25, s15, 0
	global_load_lds_dwordx4 v[2:3], off
	s_add_i32 m0, s1, 0x1c000
	v_lshl_add_u64 v[2:3], s[24:25], 0, v[132:133]
	global_load_lds_dwordx4 v[2:3], off
	v_lshl_add_u64 v[2:3], s[24:25], 0, v[136:137]
	s_add_i32 m0, s1, 0x1e000
	s_add_u32 s20, s4, s20
	global_load_lds_dwordx4 v[2:3], off
	s_addc_u32 s21, s5, s21
	v_lshlrev_b32_e32 v2, 15, v14
	s_add_u32 s26, s20, 0xb822100
	v_and_b32_e32 v2, 0xffff0000, v2
	s_addc_u32 s27, s21, 0
	v_lshl_add_u32 v2, v15, 12, v2
	v_and_b32_e32 v3, 1, v14
	v_lshl_or_b32 v2, v3, 6, v2
	s_add_u32 s18, s4, s18
	v_lshl_add_u32 v2, v16, 1, v2
	v_mov_b32_e32 v3, v133
	s_addc_u32 s19, s5, s19
	v_lshl_add_u64 v[2:3], s[18:19], 0, v[2:3]
	s_mov_b64 s[20:21], 0x29558080
	v_lshl_add_u64 v[138:139], v[2:3], 0, s[20:21]
	v_lshlrev_b32_e32 v2, 15, v10
	v_and_b32_e32 v2, 0xffff0000, v2
	v_lshl_add_u32 v2, v11, 12, v2
	v_and_b32_e32 v3, 1, v10
	v_lshl_or_b32 v2, v3, 6, v2
	s_waitcnt vmcnt(6)
	v_lshl_add_u32 v2, v12, 1, v2
	v_mov_b32_e32 v3, v133
	s_add_i32 s31, 16, 0x10000
	s_add_i32 s35, 16, 0x14000
	s_add_i32 s37, 16, 0x18000
	s_add_i32 s39, 16, 0x1c000
	v_lshl_add_u64 v[2:3], s[18:19], 0, v[2:3]
	v_add_u32_e32 v143, s31, v13
	v_add_u32_e32 v145, s35, v13
	s_add_i32 s31, s31, s22
	s_add_i32 s35, s35, s22
	v_add_u32_e32 v146, s37, v13
	v_add_u32_e32 v147, s39, v13
	s_add_i32 s37, s37, s22
	s_add_i32 s39, s39, s22
	v_lshl_add_u64 v[140:141], v[2:3], 0, s[20:21]
	s_mov_b32 s28, -2
	s_mov_b64 s[20:21], 0
	v_add_u32_e32 v144, 16, v18
	s_add_i32 s29, s1, 0xc000
	s_add_i32 s30, s1, 0xe000
	s_add_i32 s34, s31, 0x2000
	s_add_i32 s36, s35, 0x2000
	s_add_i32 s38, s37, 0x2000
	s_add_i32 s40, s39, 0x2000
	v_mov_b32_e32 v2, v133
	v_mov_b32_e32 v3, v133
	v_mov_b32_e32 v4, v133
	v_mov_b32_e32 v5, v133
	v_mov_b32_e32 v6, v133
	v_mov_b32_e32 v7, v133
	v_mov_b32_e32 v8, v133
	v_mov_b32_e32 v9, v133
	v_mov_b32_e32 v18, v133
	v_mov_b32_e32 v19, v133
	v_mov_b32_e32 v20, v133
	v_mov_b32_e32 v21, v133
	v_mov_b32_e32 v22, v133
	v_mov_b32_e32 v23, v133
	v_mov_b32_e32 v24, v133
	v_mov_b32_e32 v25, v133
	v_mov_b32_e32 v34, v133
	v_mov_b32_e32 v35, v133
	v_mov_b32_e32 v36, v133
	v_mov_b32_e32 v37, v133
	v_mov_b32_e32 v38, v133
	v_mov_b32_e32 v39, v133
	v_mov_b32_e32 v40, v133
	v_mov_b32_e32 v41, v133
	v_mov_b32_e32 v50, v133
	v_mov_b32_e32 v51, v133
	v_mov_b32_e32 v52, v133
	v_mov_b32_e32 v53, v133
	v_mov_b32_e32 v54, v133
	v_mov_b32_e32 v55, v133
	v_mov_b32_e32 v56, v133
	v_mov_b32_e32 v57, v133
	v_mov_b32_e32 v10, v133
	v_mov_b32_e32 v11, v133
	v_mov_b32_e32 v12, v133
	v_mov_b32_e32 v13, v133
	v_mov_b32_e32 v14, v133
	v_mov_b32_e32 v15, v133
	v_mov_b32_e32 v16, v133
	v_mov_b32_e32 v17, v133
	v_mov_b32_e32 v26, v133
	v_mov_b32_e32 v27, v133
	v_mov_b32_e32 v28, v133
	v_mov_b32_e32 v29, v133
	v_mov_b32_e32 v30, v133
	v_mov_b32_e32 v31, v133
	v_mov_b32_e32 v32, v133
	v_mov_b32_e32 v33, v133
	v_mov_b32_e32 v42, v133
	v_mov_b32_e32 v43, v133
	v_mov_b32_e32 v44, v133
	v_mov_b32_e32 v45, v133
	v_mov_b32_e32 v46, v133
	v_mov_b32_e32 v47, v133
	v_mov_b32_e32 v48, v133
	v_mov_b32_e32 v49, v133
	v_mov_b32_e32 v58, v133
	v_mov_b32_e32 v59, v133
	v_mov_b32_e32 v60, v133
	v_mov_b32_e32 v61, v133
	v_mov_b32_e32 v62, v133
	v_mov_b32_e32 v63, v133
	v_mov_b32_e32 v64, v133
	v_mov_b32_e32 v65, v133
	v_mov_b32_e32 v66, v133
	v_mov_b32_e32 v67, v133
	v_mov_b32_e32 v68, v133
	v_mov_b32_e32 v69, v133
	v_mov_b32_e32 v70, v133
	v_mov_b32_e32 v71, v133
	v_mov_b32_e32 v72, v133
	v_mov_b32_e32 v73, v133
	v_mov_b32_e32 v82, v133
	v_mov_b32_e32 v83, v133
	v_mov_b32_e32 v84, v133
	v_mov_b32_e32 v85, v133
	v_mov_b32_e32 v86, v133
	v_mov_b32_e32 v87, v133
	v_mov_b32_e32 v88, v133
	v_mov_b32_e32 v89, v133
	v_mov_b32_e32 v98, v133
	v_mov_b32_e32 v99, v133
	v_mov_b32_e32 v100, v133
	v_mov_b32_e32 v101, v133
	v_mov_b32_e32 v102, v133
	v_mov_b32_e32 v103, v133
	v_mov_b32_e32 v104, v133
	v_mov_b32_e32 v105, v133
	v_mov_b32_e32 v114, v133
	v_mov_b32_e32 v115, v133
	v_mov_b32_e32 v116, v133
	v_mov_b32_e32 v117, v133
	v_mov_b32_e32 v118, v133
	v_mov_b32_e32 v119, v133
	v_mov_b32_e32 v120, v133
	v_mov_b32_e32 v121, v133
	v_mov_b32_e32 v74, v133
	v_mov_b32_e32 v75, v133
	v_mov_b32_e32 v76, v133
	v_mov_b32_e32 v77, v133
	v_mov_b32_e32 v78, v133
	v_mov_b32_e32 v79, v133
	v_mov_b32_e32 v80, v133
	v_mov_b32_e32 v81, v133
	v_mov_b32_e32 v90, v133
	v_mov_b32_e32 v91, v133
	v_mov_b32_e32 v92, v133
	v_mov_b32_e32 v93, v133
	v_mov_b32_e32 v94, v133
	v_mov_b32_e32 v95, v133
	v_mov_b32_e32 v96, v133
	v_mov_b32_e32 v97, v133
	v_mov_b32_e32 v106, v133
	v_mov_b32_e32 v107, v133
	v_mov_b32_e32 v108, v133
	v_mov_b32_e32 v109, v133
	v_mov_b32_e32 v110, v133
	v_mov_b32_e32 v111, v133
	v_mov_b32_e32 v112, v133
	v_mov_b32_e32 v113, v133
	v_mov_b32_e32 v122, v133
	v_mov_b32_e32 v123, v133
	v_mov_b32_e32 v124, v133
	v_mov_b32_e32 v125, v133
	v_mov_b32_e32 v126, v133
	v_mov_b32_e32 v127, v133
	v_mov_b32_e32 v128, v133
	v_mov_b32_e32 v129, v133
	s_barrier
	s_branch .Lal_1390
	.p2align 11
; #define PG8_STAGE(bufoff, gbase, voff) do { _Pragma("unroll") for (int _i = 0; _i < 2; ++_i) \
;         __builtin_amdgcn_global_load_lds((const unsigned*)((const char*)(gbase) + (voff)[_i]), (LAS unsigned*)(lds + (bufoff) + ldsw + _i * 8192), 16, 0, 0); } while (0)
; #define PG8_LDA(dst, b, h) do { _Pragma("unroll") for (int m = 0; m < 4; ++m) _Pragma("unroll") for (int k = 0; k < 2; ++k) dst[m][k] = *(const LAS bf16x8*)(lds + PG8_SA(b, h) + aoff + m * 2048 + k * 1024); } while (0)
; #define PG8_LDB(dst, b, h) do { _Pragma("unroll") for (int n = 0; n < 2; ++n) _Pragma("unroll") for (int k = 0; k < 2; ++k) dst[n][k] = *(const LAS bf16x8*)(lds + PG8_SB(b, h) + boff + n * 2048 + k * 1024); } while (0)
; #define PG8_MMA(ai, bj, At, Bt) do { __builtin_amdgcn_s_setprio(1); _Pragma("unroll") for (int m = 0; m < 4; ++m) _Pragma("unroll") for (int n = 0; n < 2; ++n) _Pragma("unroll") for (int k = 0; k < 2; ++k) \
;         acc[ai][bj][m][n] = __builtin_amdgcn_mfma_f32_16x16x32_bf16(Bt[n][k], At[m][k], acc[ai][bj][m][n], 0, 0, 0); __builtin_amdgcn_s_setprio(0); } while (0)
; #define PG8_WAIT_L(n) asm volatile("s_waitcnt lgkmcnt(" #n ")" ::: "memory")
; #define PG8_BAR __builtin_amdgcn_s_barrier()
; #define PG8_SCHED __builtin_amdgcn_sched_barrier(0)
; template <class Sched, class Epi>
; __device__ __forceinline__ void gemm_phase(LAS unsigned char* lds, const Sched& S, const Epi& E, const int K, const int lda, const int ldb) {
;     ...
;         for (int t = 0; t < nt; t += 2) {
;             const bool last = (t == nt - 2);
;             const char* a1 = cA + (size_t)(t + 1) * kstep;
;             const char* a2 = last ? nA : cA + (size_t)(t + 2) * kstep; const char* b2 = last ? nB : cB + (size_t)(t + 2) * kstep;
;             const char* a3 = a2 + kstep; const char* b3 = b2 + kstep;
;             PG8_LDB(B0, 0, 0); PG8_SCHED; PG8_LDA(At, 0, 0); PG8_STAGE(PG8_SA(1, 1), a1 + hstepA, voffA);
;             PG8_WAIT_L(8); PG8_BAR; PG8_WAIT_L(0); PG8_MMA(0, 0, At, B0); PG8_BAR; PG8_SCHED;
;             PG8_LDB(B1, 0, 1); PG8_STAGE(PG8_SB(0, 0), b2, voffB);
;             PG8_BAR; PG8_WAIT_L(0); PG8_MMA(0, 1, At, B1); PG8_BAR;
.Lal_1390:
.LBB0_1390:
	s_add_u32 s22, s18, s20
	ds_read_b128 v[148:151], v143
	ds_read_b128 v[152:155], v143 offset:1024
	ds_read_b128 v[156:159], v143 offset:2048
	ds_read_b128 v[160:163], v143 offset:3072
	s_addc_u32 s23, s19, s21
	s_add_u32 s22, s22, 0x294d8100
	s_addc_u32 s23, s23, 0
	s_add_u32 s41, s26, s20
	s_addc_u32 s42, s27, s21
	s_cmpk_eq_i32 s20, 0xf00
	s_cselect_b32 s25, s13, s23
	s_cselect_b32 s24, s12, s22
	s_cselect_b32 s23, s15, s42
	s_cselect_b32 s22, s14, s41
	s_mov_b32 m0, s29
	v_lshl_add_u64 v[196:197], v[140:141], 0, s[20:21]
	ds_read_b128 v[164:167], v144
	ds_read_b128 v[168:171], v144 offset:1024
	ds_read_b128 v[172:175], v144 offset:2048
	ds_read_b128 v[176:179], v144 offset:3072
	ds_read_b128 v[180:183], v144 offset:4096
	ds_read_b128 v[184:187], v144 offset:5120
	ds_read_b128 v[188:191], v144 offset:6144
	ds_read_b128 v[192:195], v144 offset:7168
	global_load_lds_dwordx4 v[196:197], off
	v_lshl_add_u64 v[196:197], v[138:139], 0, s[20:21]
	s_mov_b32 m0, s30
	s_nop 0
	global_load_lds_dwordx4 v[196:197], off
	s_waitcnt lgkmcnt(8)
	s_barrier
	s_waitcnt lgkmcnt(0)
	s_setprio 1
	s_waitcnt lgkmcnt(0)
	v_mfma_f32_16x16x32_bf16 v[126:129], v[148:151], v[164:167], v[126:129]
	v_mfma_f32_16x16x32_bf16 v[122:125], v[156:159], v[164:167], v[122:125]
	v_mfma_f32_16x16x32_bf16 v[110:113], v[148:151], v[172:175], v[110:113]
	v_mfma_f32_16x16x32_bf16 v[106:109], v[156:159], v[172:175], v[106:109]
	v_mfma_f32_16x16x32_bf16 v[94:97], v[148:151], v[180:183], v[94:97]
	v_mfma_f32_16x16x32_bf16 v[90:93], v[156:159], v[180:183], v[90:93]
	v_mfma_f32_16x16x32_bf16 v[78:81], v[148:151], v[188:191], v[78:81]
	v_mfma_f32_16x16x32_bf16 v[74:77], v[156:159], v[188:191], v[74:77]
	v_mfma_f32_16x16x32_bf16 v[126:129], v[152:155], v[168:171], v[126:129]
	v_mfma_f32_16x16x32_bf16 v[122:125], v[160:163], v[168:171], v[122:125]
	v_mfma_f32_16x16x32_bf16 v[110:113], v[152:155], v[176:179], v[110:113]
	v_mfma_f32_16x16x32_bf16 v[106:109], v[160:163], v[176:179], v[106:109]
	v_mfma_f32_16x16x32_bf16 v[94:97], v[152:155], v[184:187], v[94:97]
	v_mfma_f32_16x16x32_bf16 v[90:93], v[160:163], v[184:187], v[90:93]
	v_mfma_f32_16x16x32_bf16 v[78:81], v[152:155], v[192:195], v[78:81]
	v_mfma_f32_16x16x32_bf16 v[74:77], v[160:163], v[192:195], v[74:77]
	s_setprio 0
	s_barrier
	s_mov_b32 m0, s31
	s_add_u32 s54, s22, s16
	s_addc_u32 s55, s23, s17
	ds_read_b128 v[196:199], v145
	ds_read_b128 v[200:203], v145 offset:1024
	ds_read_b128 v[204:207], v145 offset:2048
	ds_read_b128 v[208:211], v145 offset:3072
	global_load_lds_dwordx4 v132, s[22:23]
	s_add_u32 s56, s22, s16
	s_addc_u32 s57, s23, s17
	s_mov_b32 m0, s34
	s_nop 0
	global_load_lds_dwordx4 v136, s[22:23]
	s_barrier
	s_waitcnt lgkmcnt(0)
	s_setprio 1
	s_waitcnt lgkmcnt(0)
	v_mfma_f32_16x16x32_bf16 v[118:121], v[196:199], v[164:167], v[118:121]
	v_mfma_f32_16x16x32_bf16 v[114:117], v[204:207], v[164:167], v[114:117]
	v_mfma_f32_16x16x32_bf16 v[102:105], v[196:199], v[172:175], v[102:105]
	v_mfma_f32_16x16x32_bf16 v[98:101], v[204:207], v[172:175], v[98:101]
	v_mfma_f32_16x16x32_bf16 v[86:89], v[196:199], v[180:183], v[86:89]
	v_mfma_f32_16x16x32_bf16 v[82:85], v[204:207], v[180:183], v[82:85]
	v_mfma_f32_16x16x32_bf16 v[70:73], v[196:199], v[188:191], v[70:73]
	v_mfma_f32_16x16x32_bf16 v[66:69], v[204:207], v[188:191], v[66:69]
	v_mfma_f32_16x16x32_bf16 v[118:121], v[200:203], v[168:171], v[118:121]
	v_mfma_f32_16x16x32_bf16 v[114:117], v[208:211], v[168:171], v[114:117]
	v_mfma_f32_16x16x32_bf16 v[102:105], v[200:203], v[176:179], v[102:105]
	v_mfma_f32_16x16x32_bf16 v[98:101], v[208:211], v[176:179], v[98:101]
	v_mfma_f32_16x16x32_bf16 v[86:89], v[200:203], v[184:187], v[86:89]
	v_mfma_f32_16x16x32_bf16 v[82:85], v[208:211], v[184:187], v[82:85]
	v_mfma_f32_16x16x32_bf16 v[70:73], v[200:203], v[192:195], v[70:73]
	v_mfma_f32_16x16x32_bf16 v[66:69], v[208:211], v[192:195], v[66:69]
	s_setprio 0
	s_mov_b32 m0, s1
	s_add_u32 s58, s24, s16
	s_addc_u32 s59, s25, s17
	s_barrier
	ds_read_b128 v[164:167], v144 offset:16384
	ds_read_b128 v[168:171], v144 offset:17408
	ds_read_b128 v[172:175], v144 offset:18432
	ds_read_b128 v[176:179], v144 offset:19456
	ds_read_b128 v[180:183], v144 offset:20480
	ds_read_b128 v[184:187], v144 offset:21504
	ds_read_b128 v[188:191], v144 offset:22528
	ds_read_b128 v[192:195], v144 offset:23552
	global_load_lds_dwordx4 v130, s[24:25]
	s_add_u32 s60, s24, s16
	s_addc_u32 s61, s25, s17
	s_mov_b32 m0, s2
	s_nop 0
	global_load_lds_dwordx4 v134, s[24:25]
	s_barrier
	s_waitcnt lgkmcnt(0)
	s_setprio 1
	s_waitcnt lgkmcnt(0)
	v_mfma_f32_16x16x32_bf16 v[62:65], v[148:151], v[164:167], v[62:65]
	v_mfma_f32_16x16x32_bf16 v[58:61], v[156:159], v[164:167], v[58:61]
	v_mfma_f32_16x16x32_bf16 v[46:49], v[148:151], v[172:175], v[46:49]
	v_mfma_f32_16x16x32_bf16 v[42:45], v[156:159], v[172:175], v[42:45]
	v_mfma_f32_16x16x32_bf16 v[30:33], v[148:151], v[180:183], v[30:33]
	v_mfma_f32_16x16x32_bf16 v[26:29], v[156:159], v[180:183], v[26:29]
	v_mfma_f32_16x16x32_bf16 v[14:17], v[148:151], v[188:191], v[14:17]
	v_mfma_f32_16x16x32_bf16 v[10:13], v[156:159], v[188:191], v[10:13]
	v_mfma_f32_16x16x32_bf16 v[62:65], v[152:155], v[168:171], v[62:65]
	v_mfma_f32_16x16x32_bf16 v[58:61], v[160:163], v[168:171], v[58:61]
	v_mfma_f32_16x16x32_bf16 v[46:49], v[152:155], v[176:179], v[46:49]
	v_mfma_f32_16x16x32_bf16 v[42:45], v[160:163], v[176:179], v[42:45]
	v_mfma_f32_16x16x32_bf16 v[30:33], v[152:155], v[184:187], v[30:33]
	v_mfma_f32_16x16x32_bf16 v[26:29], v[160:163], v[184:187], v[26:29]
	v_mfma_f32_16x16x32_bf16 v[14:17], v[152:155], v[192:195], v[14:17]
	v_mfma_f32_16x16x32_bf16 v[10:13], v[160:163], v[192:195], v[10:13]
	s_setprio 0
	s_barrier
; #define PG8_STAGE(bufoff, gbase, voff) do { _Pragma("unroll") for (int _i = 0; _i < 2; ++_i) \
;         __builtin_amdgcn_global_load_lds((const unsigned*)((const char*)(gbase) + (voff)[_i]), (LAS unsigned*)(lds + (bufoff) + ldsw + _i * 8192), 16, 0, 0); } while (0)
; #define PG8_LDA(dst, b, h) do { _Pragma("unroll") for (int m = 0; m < 4; ++m) _Pragma("unroll") for (int k = 0; k < 2; ++k) dst[m][k] = *(const LAS bf16x8*)(lds + PG8_SA(b, h) + aoff + m * 2048 + k * 1024); } while (0)
; #define PG8_LDB(dst, b, h) do { _Pragma("unroll") for (int n = 0; n < 2; ++n) _Pragma("unroll") for (int k = 0; k < 2; ++k) dst[n][k] = *(const LAS bf16x8*)(lds + PG8_SB(b, h) + boff + n * 2048 + k * 1024); } while (0)
; #define PG8_MMA(ai, bj, At, Bt) do { __builtin_amdgcn_s_setprio(1); _Pragma("unroll") for (int m = 0; m < 4; ++m) _Pragma("unroll") for (int n = 0; n < 2; ++n) _Pragma("unroll") for (int k = 0; k < 2; ++k) \
;         acc[ai][bj][m][n] = __builtin_amdgcn_mfma_f32_16x16x32_bf16(Bt[n][k], At[m][k], acc[ai][bj][m][n], 0, 0, 0); __builtin_amdgcn_s_setprio(0); } while (0)
; #define PG8_WAIT_V(n) asm volatile("s_waitcnt vmcnt(" #n ")" ::: "memory")
; #define PG8_WAIT_L(n) asm volatile("s_waitcnt lgkmcnt(" #n ")" ::: "memory")
; #define PG8_BAR __builtin_amdgcn_s_barrier()
; #define PG8_SCHED __builtin_amdgcn_sched_barrier(0)
; template <class Sched, class Epi>
; __device__ __forceinline__ void gemm_phase(LAS unsigned char* lds, const Sched& S, const Epi& E, const int K, const int lda, const int ldb) {
;     ...
;             PG8_BAR; PG8_WAIT_L(0); PG8_MMA(0, 1, At, B1); PG8_BAR;
;             PG8_LDA(At, 0, 1); PG8_STAGE(PG8_SA(0, 0), a2, voffA);
;             PG8_BAR; PG8_WAIT_L(0); if (!chalf) PG8_MMA(1, 0, At, B0); PG8_BAR; PG8_SCHED;
;             PG8_STAGE(PG8_SB(0, 1), b2 + hstepB, voffB);
;             PG8_WAIT_V(6); PG8_BAR; if (!chalf) PG8_MMA(1, 1, At, B1); PG8_BAR;
;             PG8_LDB(B0, 1, 0); PG8_SCHED; PG8_LDA(At, 1, 0); PG8_STAGE(PG8_SA(0, 1), a2 + hstepA, voffA);
;             PG8_WAIT_L(8); PG8_BAR; PG8_WAIT_L(0); PG8_MMA(0, 0, At, B0); PG8_BAR; PG8_SCHED;
;             PG8_LDB(B1, 1, 1); PG8_STAGE(PG8_SB(1, 0), b3, voffB);
;             PG8_BAR; PG8_WAIT_L(0); PG8_MMA(0, 1, At, B1); PG8_BAR;
;             PG8_LDA(At, 1, 1); PG8_STAGE(PG8_SA(1, 0), a3, voffA);
;             PG8_BAR; PG8_WAIT_L(0); if (!chalf) PG8_MMA(1, 0, At, B0); PG8_BAR; PG8_SCHED;
	s_add_u32 s42, s22, 0x80000
	s_addc_u32 s43, s23, 0
	s_mov_b32 m0, s35
	s_nop 0
	global_load_lds_dwordx4 v132, s[42:43]
	s_mov_b32 m0, s36
	s_nop 0
	global_load_lds_dwordx4 v136, s[42:43]
	s_waitcnt vmcnt(6)
	s_barrier
	s_setprio 1
	v_mfma_f32_16x16x32_bf16 v[54:57], v[196:199], v[164:167], v[54:57]
	v_mfma_f32_16x16x32_bf16 v[50:53], v[204:207], v[164:167], v[50:53]
	v_mfma_f32_16x16x32_bf16 v[38:41], v[196:199], v[172:175], v[38:41]
	v_mfma_f32_16x16x32_bf16 v[34:37], v[204:207], v[172:175], v[34:37]
	v_mfma_f32_16x16x32_bf16 v[22:25], v[196:199], v[180:183], v[22:25]
	v_mfma_f32_16x16x32_bf16 v[18:21], v[204:207], v[180:183], v[18:21]
	v_mfma_f32_16x16x32_bf16 v[6:9], v[196:199], v[188:191], v[6:9]
	v_mfma_f32_16x16x32_bf16 v[2:5], v[204:207], v[188:191], v[2:5]
	v_mfma_f32_16x16x32_bf16 v[54:57], v[200:203], v[168:171], v[54:57]
	v_mfma_f32_16x16x32_bf16 v[50:53], v[208:211], v[168:171], v[50:53]
	v_mfma_f32_16x16x32_bf16 v[38:41], v[200:203], v[176:179], v[38:41]
	v_mfma_f32_16x16x32_bf16 v[34:37], v[208:211], v[176:179], v[34:37]
	v_mfma_f32_16x16x32_bf16 v[22:25], v[200:203], v[184:187], v[22:25]
	v_mfma_f32_16x16x32_bf16 v[18:21], v[208:211], v[184:187], v[18:21]
	v_mfma_f32_16x16x32_bf16 v[6:9], v[200:203], v[192:195], v[6:9]
	v_mfma_f32_16x16x32_bf16 v[2:5], v[208:211], v[192:195], v[2:5]
	s_setprio 0
	s_barrier
	ds_read_b128 v[148:151], v146
	ds_read_b128 v[152:155], v146 offset:1024
	ds_read_b128 v[156:159], v146 offset:2048
	ds_read_b128 v[160:163], v146 offset:3072
	s_add_u32 s24, s24, 0x80000
	s_addc_u32 s25, s25, 0
	s_mov_b32 m0, s3
	ds_read_b128 v[164:167], v144 offset:32768
	ds_read_b128 v[168:171], v144 offset:33792
	ds_read_b128 v[172:175], v144 offset:34816
	ds_read_b128 v[176:179], v144 offset:35840
	ds_read_b128 v[180:183], v144 offset:36864
	ds_read_b128 v[184:187], v144 offset:37888
	ds_read_b128 v[188:191], v144 offset:38912
	ds_read_b128 v[192:195], v144 offset:39936
	global_load_lds_dwordx4 v130, s[24:25]
	s_mov_b32 m0, s7
	s_nop 0
	global_load_lds_dwordx4 v134, s[24:25]
	s_waitcnt lgkmcnt(8)
	s_barrier
	s_waitcnt lgkmcnt(0)
	s_setprio 1
	s_waitcnt lgkmcnt(0)
	v_mfma_f32_16x16x32_bf16 v[126:129], v[148:151], v[164:167], v[126:129]
	v_mfma_f32_16x16x32_bf16 v[122:125], v[156:159], v[164:167], v[122:125]
	v_mfma_f32_16x16x32_bf16 v[110:113], v[148:151], v[172:175], v[110:113]
	v_mfma_f32_16x16x32_bf16 v[106:109], v[156:159], v[172:175], v[106:109]
	v_mfma_f32_16x16x32_bf16 v[94:97], v[148:151], v[180:183], v[94:97]
	v_mfma_f32_16x16x32_bf16 v[90:93], v[156:159], v[180:183], v[90:93]
	v_mfma_f32_16x16x32_bf16 v[78:81], v[148:151], v[188:191], v[78:81]
	v_mfma_f32_16x16x32_bf16 v[74:77], v[156:159], v[188:191], v[74:77]
	v_mfma_f32_16x16x32_bf16 v[126:129], v[152:155], v[168:171], v[126:129]
	v_mfma_f32_16x16x32_bf16 v[122:125], v[160:163], v[168:171], v[122:125]
	v_mfma_f32_16x16x32_bf16 v[110:113], v[152:155], v[176:179], v[110:113]
	v_mfma_f32_16x16x32_bf16 v[106:109], v[160:163], v[176:179], v[106:109]
	v_mfma_f32_16x16x32_bf16 v[94:97], v[152:155], v[184:187], v[94:97]
	v_mfma_f32_16x16x32_bf16 v[90:93], v[160:163], v[184:187], v[90:93]
	v_mfma_f32_16x16x32_bf16 v[78:81], v[152:155], v[192:195], v[78:81]
	v_mfma_f32_16x16x32_bf16 v[74:77], v[160:163], v[192:195], v[74:77]
	s_setprio 0
	s_barrier
	s_mov_b32 m0, s37
	ds_read_b128 v[196:199], v147
	ds_read_b128 v[200:203], v147 offset:1024
	ds_read_b128 v[204:207], v147 offset:2048
	ds_read_b128 v[208:211], v147 offset:3072
	global_load_lds_dwordx4 v132, s[54:55]
	s_mov_b32 m0, s38
	s_nop 0
	global_load_lds_dwordx4 v136, s[56:57]
	s_barrier
	s_waitcnt lgkmcnt(0)
	s_setprio 1
	s_waitcnt lgkmcnt(0)
	v_mfma_f32_16x16x32_bf16 v[118:121], v[196:199], v[164:167], v[118:121]
	v_mfma_f32_16x16x32_bf16 v[114:117], v[204:207], v[164:167], v[114:117]
	v_mfma_f32_16x16x32_bf16 v[102:105], v[196:199], v[172:175], v[102:105]
	v_mfma_f32_16x16x32_bf16 v[98:101], v[204:207], v[172:175], v[98:101]
	v_mfma_f32_16x16x32_bf16 v[86:89], v[196:199], v[180:183], v[86:89]
	v_mfma_f32_16x16x32_bf16 v[82:85], v[204:207], v[180:183], v[82:85]
	v_mfma_f32_16x16x32_bf16 v[70:73], v[196:199], v[188:191], v[70:73]
	v_mfma_f32_16x16x32_bf16 v[66:69], v[204:207], v[188:191], v[66:69]
	v_mfma_f32_16x16x32_bf16 v[118:121], v[200:203], v[168:171], v[118:121]
	v_mfma_f32_16x16x32_bf16 v[114:117], v[208:211], v[168:171], v[114:117]
	v_mfma_f32_16x16x32_bf16 v[102:105], v[200:203], v[176:179], v[102:105]
	v_mfma_f32_16x16x32_bf16 v[98:101], v[208:211], v[176:179], v[98:101]
	v_mfma_f32_16x16x32_bf16 v[86:89], v[200:203], v[184:187], v[86:89]
	v_mfma_f32_16x16x32_bf16 v[82:85], v[208:211], v[184:187], v[82:85]
	v_mfma_f32_16x16x32_bf16 v[70:73], v[200:203], v[192:195], v[70:73]
	v_mfma_f32_16x16x32_bf16 v[66:69], v[208:211], v[192:195], v[66:69]
	s_setprio 0
	s_mov_b32 m0, s10
	s_barrier
	ds_read_b128 v[164:167], v144 offset:49152
	ds_read_b128 v[168:171], v144 offset:50176
	ds_read_b128 v[172:175], v144 offset:51200
	ds_read_b128 v[176:179], v144 offset:52224
	ds_read_b128 v[180:183], v144 offset:53248
	ds_read_b128 v[184:187], v144 offset:54272
	ds_read_b128 v[188:191], v144 offset:55296
	ds_read_b128 v[192:195], v144 offset:56320
	global_load_lds_dwordx4 v130, s[58:59]
	s_mov_b32 m0, s11
	s_nop 0
	global_load_lds_dwordx4 v134, s[60:61]
	s_barrier
; #define PG8_STAGE(bufoff, gbase, voff) do { _Pragma("unroll") for (int _i = 0; _i < 2; ++_i) \
;         __builtin_amdgcn_global_load_lds((const unsigned*)((const char*)(gbase) + (voff)[_i]), (LAS unsigned*)(lds + (bufoff) + ldsw + _i * 8192), 16, 0, 0); } while (0)
; #define PG8_MMA(ai, bj, At, Bt) do { __builtin_amdgcn_s_setprio(1); _Pragma("unroll") for (int m = 0; m < 4; ++m) _Pragma("unroll") for (int n = 0; n < 2; ++n) _Pragma("unroll") for (int k = 0; k < 2; ++k) \
;         acc[ai][bj][m][n] = __builtin_amdgcn_mfma_f32_16x16x32_bf16(Bt[n][k], At[m][k], acc[ai][bj][m][n], 0, 0, 0); __builtin_amdgcn_s_setprio(0); } while (0)
; #define PG8_WAIT_V(n) asm volatile("s_waitcnt vmcnt(" #n ")" ::: "memory")
; #define PG8_WAIT_L(n) asm volatile("s_waitcnt lgkmcnt(" #n ")" ::: "memory")
; #define PG8_BAR __builtin_amdgcn_s_barrier()
; #define PG8_SCHED __builtin_amdgcn_sched_barrier(0)
; template <class Sched, class Epi>
; __device__ __forceinline__ void gemm_phase(LAS unsigned char* lds, const Sched& S, const Epi& E, const int K, const int lda, const int ldb) {
;     ...
;             PG8_BAR; PG8_WAIT_L(0); if (!chalf) PG8_MMA(1, 0, At, B0); PG8_BAR; PG8_SCHED;
;             PG8_STAGE(PG8_SB(1, 1), b3 + hstepB, voffB);
;             PG8_WAIT_V(6); PG8_BAR; if (!chalf) PG8_MMA(1, 1, At, B1); PG8_BAR;
;     __device__ __forceinline__ void operator()(EPI_ARGS) const {
; #pragma unroll
;         for (int ai = 0; ai < 2; ++ai) if (ai == 0 || !u.half) { u32x4 zz[4][2];
; #pragma unroll
;             for (int m = 0; m < 4; ++m)
; #pragma unroll
;                 for (int bj = 0; bj < 2; ++bj) zz[m][bj] = *(const u32x4*)(parts + E_PZC + (size_t)EPI_ROW * 1024 + EPI_COL(bj));
	s_waitcnt lgkmcnt(0)
	s_setprio 1
	s_waitcnt lgkmcnt(0)
	v_mfma_f32_16x16x32_bf16 v[62:65], v[148:151], v[164:167], v[62:65]
	v_mfma_f32_16x16x32_bf16 v[58:61], v[156:159], v[164:167], v[58:61]
	v_mfma_f32_16x16x32_bf16 v[46:49], v[148:151], v[172:175], v[46:49]
	v_mfma_f32_16x16x32_bf16 v[42:45], v[156:159], v[172:175], v[42:45]
	v_mfma_f32_16x16x32_bf16 v[30:33], v[148:151], v[180:183], v[30:33]
	v_mfma_f32_16x16x32_bf16 v[26:29], v[156:159], v[180:183], v[26:29]
	v_mfma_f32_16x16x32_bf16 v[14:17], v[148:151], v[188:191], v[14:17]
	v_mfma_f32_16x16x32_bf16 v[10:13], v[156:159], v[188:191], v[10:13]
	v_mfma_f32_16x16x32_bf16 v[62:65], v[152:155], v[168:171], v[62:65]
	v_mfma_f32_16x16x32_bf16 v[58:61], v[160:163], v[168:171], v[58:61]
	v_mfma_f32_16x16x32_bf16 v[46:49], v[152:155], v[176:179], v[46:49]
	v_mfma_f32_16x16x32_bf16 v[42:45], v[160:163], v[176:179], v[42:45]
	v_mfma_f32_16x16x32_bf16 v[30:33], v[152:155], v[184:187], v[30:33]
	v_mfma_f32_16x16x32_bf16 v[26:29], v[160:163], v[184:187], v[26:29]
	v_mfma_f32_16x16x32_bf16 v[14:17], v[152:155], v[192:195], v[14:17]
	v_mfma_f32_16x16x32_bf16 v[10:13], v[160:163], v[192:195], v[10:13]
	s_setprio 0
	s_barrier
	s_add_u32 s22, s22, 0x80080
	s_addc_u32 s23, s23, 0
	s_mov_b32 m0, s39
	s_nop 0
	global_load_lds_dwordx4 v132, s[22:23]
	s_mov_b32 m0, s40
	s_nop 0
	global_load_lds_dwordx4 v136, s[22:23]
	s_waitcnt vmcnt(6)
	s_barrier
	s_setprio 1
	v_mfma_f32_16x16x32_bf16 v[54:57], v[196:199], v[164:167], v[54:57]
	v_mfma_f32_16x16x32_bf16 v[50:53], v[204:207], v[164:167], v[50:53]
	v_mfma_f32_16x16x32_bf16 v[38:41], v[196:199], v[172:175], v[38:41]
	v_mfma_f32_16x16x32_bf16 v[34:37], v[204:207], v[172:175], v[34:37]
	v_mfma_f32_16x16x32_bf16 v[22:25], v[196:199], v[180:183], v[22:25]
	v_mfma_f32_16x16x32_bf16 v[18:21], v[204:207], v[180:183], v[18:21]
	v_mfma_f32_16x16x32_bf16 v[6:9], v[196:199], v[188:191], v[6:9]
	v_mfma_f32_16x16x32_bf16 v[2:5], v[204:207], v[188:191], v[2:5]
	v_mfma_f32_16x16x32_bf16 v[54:57], v[200:203], v[168:171], v[54:57]
	v_mfma_f32_16x16x32_bf16 v[50:53], v[208:211], v[168:171], v[50:53]
	v_mfma_f32_16x16x32_bf16 v[38:41], v[200:203], v[176:179], v[38:41]
	v_mfma_f32_16x16x32_bf16 v[34:37], v[208:211], v[176:179], v[34:37]
	v_mfma_f32_16x16x32_bf16 v[22:25], v[200:203], v[184:187], v[22:25]
	v_mfma_f32_16x16x32_bf16 v[18:21], v[208:211], v[184:187], v[18:21]
	v_mfma_f32_16x16x32_bf16 v[6:9], v[200:203], v[192:195], v[6:9]
	v_mfma_f32_16x16x32_bf16 v[2:5], v[208:211], v[192:195], v[2:5]
	s_setprio 0
	s_add_i32 s28, s28, 2
	s_add_u32 s20, s20, 0x100
	s_addc_u32 s21, s21, 0
	s_cmp_gt_u32 s28, 29
	s_barrier
	s_cbranch_scc0 .LBB0_1390
	s_sext_i32_i8 s1, s6
	v_add_u32_e32 v152, s8, v1
	v_lshl_or_b32 v1, s1, 8, v142
	s_add_u32 s12, s4, 0x1b9d8000
	v_or_b32_e32 v130, s9, v1
	v_ashrrev_i32_e32 v153, 31, v152
	s_addc_u32 s13, s5, 0
	v_ashrrev_i32_e32 v131, 31, v130
	v_lshlrev_b64 v[132:133], 11, v[152:153]
	v_lshl_add_u64 v[134:135], s[12:13], 0, v[132:133]
	v_lshlrev_b64 v[150:151], 1, v[130:131]
	v_lshl_add_u64 v[130:131], v[134:135], 0, v[150:151]
	global_load_dwordx4 v[154:157], v[130:131], off
	global_load_dwordx4 v[158:161], v[130:131], off offset:256
	v_or_b32_e32 v130, 16, v152
	v_or_b32_e32 v134, 32, v152
	v_or_b32_e32 v136, 48, v152
	v_ashrrev_i32_e32 v131, 31, v130
	v_ashrrev_i32_e32 v135, 31, v134
	s_add_u32 s6, s4, 0x252d8000
	v_ashrrev_i32_e32 v137, 31, v136
	v_lshlrev_b64 v[130:131], 11, v[130:131]
	v_lshlrev_b64 v[134:135], 11, v[134:135]
	s_addc_u32 s7, s5, 0
	v_lshlrev_b64 v[136:137], 11, v[136:137]
	v_lshl_add_u64 v[130:131], s[12:13], 0, v[130:131]
	v_lshl_add_u64 v[134:135], s[12:13], 0, v[134:135]
	v_lshl_add_u64 v[136:137], s[12:13], 0, v[136:137]
	v_lshl_add_u64 v[132:133], s[6:7], 0, v[132:133]
	v_lshl_add_u64 v[130:131], v[130:131], 0, v[150:151]
	v_lshl_add_u64 v[134:135], v[134:135], 0, v[150:151]
	v_lshl_add_u64 v[166:167], v[136:137], 0, v[150:151]
	v_lshl_add_u64 v[168:169], v[132:133], 0, v[150:151]
	global_load_dwordx4 v[162:165], v[130:131], off
	global_load_dwordx4 v[146:149], v[130:131], off offset:256
	global_load_dwordx4 v[142:145], v[134:135], off
	global_load_dwordx4 v[138:141], v[134:135], off offset:256
	s_nop 0
	global_load_dwordx4 v[134:137], v[166:167], off
	global_load_dwordx4 v[130:133], v[166:167], off offset:256
	s_cmpk_lt_u32 s0, 0x100
	s_waitcnt vmcnt(0)
; __device__ __forceinline__ float siluf_(float x) { return x * __builtin_amdgcn_rcpf(1.0f + __expf(-x)); }
; __device__ __forceinline__ u32x4 pack8(const float (&f)[8]) { u32x4 r; r[0] = cvt_pk_bf16(f[0], f[1]); r[1] = cvt_pk_bf16(f[2], f[3]); r[2] = cvt_pk_bf16(f[4], f[5]); r[3] = cvt_pk_bf16(f[6], f[7]); return r; }
;     __device__ __forceinline__ void operator()(EPI_ARGS) const {
;     ...
;         for (int ai = 0; ai < 2; ++ai) if (ai == 0 || !u.half) { u32x4 zz[4][2];
; #pragma unroll
;             for (int m = 0; m < 4; ++m)
; #pragma unroll
;                 for (int bj = 0; bj < 2; ++bj) zz[m][bj] = *(const u32x4*)(parts + E_PZC + (size_t)EPI_ROW * 1024 + EPI_COL(bj));
; #pragma unroll
;             for (int m = 0; m < 4; ++m)
; #pragma unroll
;                 for (int bj = 0; bj < 2; ++bj) { const f32x4 v0 = acc[ai][bj][m][0], v1 = acc[ai][bj][m][1]; float z[8]; unpack8(zz[m][bj], z); float o[8];
; #pragma unroll
;                     for (int j = 0; j < 4; ++j) { o[j] = v0[j] * siluf_(z[j]); o[4 + j] = v1[j] * siluf_(z[4 + j]); }
;                     *(u32x4*)(O + (size_t)EPI_ROW * 1024 + EPI_COL(bj)) = pack8(o); } }
	v_lshlrev_b32_e32 v1, 16, v154
	v_and_b32_e32 v153, 0xffff0000, v154
	v_lshlrev_b32_e32 v154, 16, v155
	v_and_b32_e32 v155, 0xffff0000, v155
	v_lshlrev_b32_e32 v166, 16, v156
	v_and_b32_e32 v156, 0xffff0000, v156
	v_lshlrev_b32_e32 v167, 16, v157
	v_and_b32_e32 v157, 0xffff0000, v157
	v_mul_f32_e32 v171, 0xbfb8aa3b, v1
	v_mul_f32_e32 v172, 0xbfb8aa3b, v166
	v_mul_f32_e32 v173, 0xbfb8aa3b, v153
	v_mul_f32_e32 v174, 0xbfb8aa3b, v156
	v_mul_f32_e32 v175, 0xbfb8aa3b, v154
	v_mul_f32_e32 v176, 0xbfb8aa3b, v167
	v_mul_f32_e32 v177, 0xbfb8aa3b, v155
	v_mul_f32_e32 v178, 0xbfb8aa3b, v157
	v_exp_f32_e32 v171, v171
	v_exp_f32_e32 v172, v172
	v_exp_f32_e32 v173, v173
	v_exp_f32_e32 v174, v174
	v_exp_f32_e32 v175, v175
	v_exp_f32_e32 v176, v176
	v_exp_f32_e32 v177, v177
	v_exp_f32_e32 v178, v178
	v_add_f32_e32 v171, 1.0, v171
	v_add_f32_e32 v172, 1.0, v172
	v_add_f32_e32 v173, 1.0, v173
	v_add_f32_e32 v174, 1.0, v174
	v_add_f32_e32 v175, 1.0, v175
	v_add_f32_e32 v176, 1.0, v176
	v_add_f32_e32 v177, 1.0, v177
	v_add_f32_e32 v178, 1.0, v178
	v_rcp_f32_e32 v171, v171
	v_rcp_f32_e32 v172, v172
	v_rcp_f32_e32 v173, v173
	v_rcp_f32_e32 v174, v174
	v_rcp_f32_e32 v175, v175
	v_rcp_f32_e32 v176, v176
	v_rcp_f32_e32 v177, v177
	v_rcp_f32_e32 v178, v178
	v_mul_f32_e32 v1, v171, v1
	v_mul_f32_e32 v166, v172, v166
	v_mul_f32_e32 v153, v173, v153
	v_mul_f32_e32 v156, v174, v156
	v_mul_f32_e32 v154, v175, v154
	v_mul_f32_e32 v167, v176, v167
	v_mul_f32_e32 v155, v177, v155
	v_lshlrev_b32_e32 v170, 16, v158
	v_mul_f32_e32 v157, v178, v157
	v_mul_f32_e32 v1, v126, v1
	v_mul_f32_e32 v126, v122, v166
	v_mul_f32_e32 v122, v127, v153
	v_mul_f32_e32 v127, v123, v156
	v_mul_f32_e32 v123, v128, v154
	v_mul_f32_e32 v128, v124, v167
	v_mul_f32_e32 v124, v129, v155
	v_mul_f32_e32 v125, v125, v157
	v_cvt_pk_bf16_f32 v122, v1, v122
	v_cvt_pk_bf16_f32 v123, v123, v124
	v_cvt_pk_bf16_f32 v124, v126, v127
	v_mul_f32_e32 v126, 0xbfb8aa3b, v170
	v_cvt_pk_bf16_f32 v125, v128, v125
	global_store_dwordx4 v[168:169], v[122:125], off
	v_exp_f32_e32 v126, v126
	v_and_b32_e32 v1, 0xffff0000, v158
	v_lshlrev_b32_e32 v124, 16, v160
	v_mul_f32_e32 v127, 0xbfb8aa3b, v124
	v_exp_f32_e32 v127, v127
	v_add_f32_e32 v126, 1.0, v126
	v_rcp_f32_e32 v126, v126
	v_and_b32_e32 v125, 0xffff0000, v160
	v_add_f32_e32 v127, 1.0, v127
	v_rcp_f32_e32 v127, v127
	v_mul_f32_e32 v126, v126, v170
	v_mul_f32_e32 v118, v118, v126
	v_mul_f32_e32 v126, 0xbfb8aa3b, v1
	v_mul_f32_e32 v124, v127, v124
	v_exp_f32_e32 v126, v126
	v_mul_f32_e32 v127, 0xbfb8aa3b, v125
	v_exp_f32_e32 v127, v127
	v_lshlrev_b32_e32 v122, 16, v159
	v_mul_f32_e32 v124, v114, v124
	v_add_f32_e32 v114, 1.0, v126
	v_rcp_f32_e32 v114, v114
	v_add_f32_e32 v126, 1.0, v127
	v_mul_f32_e32 v127, 0xbfb8aa3b, v122
	v_exp_f32_e32 v127, v127
	v_mul_f32_e32 v1, v114, v1
	v_rcp_f32_e32 v126, v126
	v_mul_f32_e32 v1, v119, v1
	v_add_f32_e32 v119, 1.0, v127
	v_rcp_f32_e32 v119, v119
	v_lshlrev_b32_e32 v128, 16, v161
	v_and_b32_e32 v123, 0xffff0000, v159
	v_mul_f32_e32 v114, v126, v125
	v_mul_f32_e32 v125, 0xbfb8aa3b, v128
	v_and_b32_e32 v129, 0xffff0000, v161
	v_exp_f32_e32 v125, v125
	v_mul_f32_e32 v126, v115, v114
	v_mul_f32_e32 v114, v119, v122
	v_mul_f32_e32 v119, 0xbfb8aa3b, v123
	v_mul_f32_e32 v115, v120, v114
	v_exp_f32_e32 v119, v119
	v_mul_f32_e32 v120, 0xbfb8aa3b, v129
	v_exp_f32_e32 v120, v120
	v_add_f32_e32 v114, 1.0, v125
	v_rcp_f32_e32 v114, v114
	v_add_f32_e32 v119, 1.0, v119
	v_rcp_f32_e32 v119, v119
	v_add_f32_e32 v120, 1.0, v120
	v_rcp_f32_e32 v120, v120
	v_mul_f32_e32 v114, v114, v128
	v_mul_f32_e32 v122, v116, v114
	v_mul_f32_e32 v114, v119, v123
	v_mul_f32_e32 v116, v121, v114
	v_mul_f32_e32 v114, v120, v129
	v_mul_f32_e32 v117, v117, v114
	v_cvt_pk_bf16_f32 v114, v118, v1
	v_cvt_pk_bf16_f32 v115, v115, v116
	v_cvt_pk_bf16_f32 v116, v124, v126
	v_cvt_pk_bf16_f32 v117, v122, v117
	v_lshlrev_b32_e32 v1, 16, v162
	global_store_dwordx4 v[168:169], v[114:117], off offset:256
	v_mul_f32_e32 v119, 0xbfb8aa3b, v1
	v_exp_f32_e32 v119, v119
	v_lshlrev_b32_e32 v117, 16, v164
	v_mul_f32_e32 v120, 0xbfb8aa3b, v117
	v_exp_f32_e32 v120, v120
	v_add_f32_e32 v119, 1.0, v119
	v_rcp_f32_e32 v119, v119
	v_and_b32_e32 v114, 0xffff0000, v162
	v_add_f32_e32 v120, 1.0, v120
	v_rcp_f32_e32 v120, v120
	v_and_b32_e32 v118, 0xffff0000, v164
	v_mul_f32_e32 v1, v119, v1
	v_mul_f32_e32 v1, v110, v1
	v_mul_f32_e32 v110, v120, v117
	v_mul_f32_e32 v117, 0xbfb8aa3b, v114
	v_mul_f32_e32 v119, 0xbfb8aa3b, v118
	v_exp_f32_e32 v117, v117
	v_exp_f32_e32 v119, v119
	v_lshlrev_b32_e32 v115, 16, v163
	v_mul_f32_e32 v110, v106, v110
	v_add_f32_e32 v106, 1.0, v117
	v_add_f32_e32 v117, 1.0, v119
	v_mul_f32_e32 v119, 0xbfb8aa3b, v115
	v_rcp_f32_e32 v106, v106
	v_exp_f32_e32 v119, v119
	v_rcp_f32_e32 v117, v117
	v_lshlrev_b32_e32 v121, 16, v165
	v_mul_f32_e32 v106, v106, v114
	v_add_f32_e32 v114, 1.0, v119
	v_rcp_f32_e32 v114, v114
	v_and_b32_e32 v116, 0xffff0000, v163
	v_mul_f32_e32 v106, v111, v106
	v_mul_f32_e32 v111, v117, v118
	v_mul_f32_e32 v117, 0xbfb8aa3b, v121
	v_exp_f32_e32 v117, v117
	v_mul_f32_e32 v111, v107, v111
	v_mul_f32_e32 v107, v114, v115
	v_mul_f32_e32 v114, 0xbfb8aa3b, v116
	v_exp_f32_e32 v114, v114
	v_and_b32_e32 v122, 0xffff0000, v165
	v_mul_f32_e32 v107, v112, v107
	v_add_f32_e32 v112, 1.0, v117
	v_mul_f32_e32 v115, 0xbfb8aa3b, v122
	v_rcp_f32_e32 v112, v112
	v_exp_f32_e32 v115, v115
	v_add_f32_e32 v114, 1.0, v114
	v_rcp_f32_e32 v114, v114
	v_mul_f32_e32 v112, v112, v121
	v_add_f32_e32 v115, 1.0, v115
	v_rcp_f32_e32 v115, v115
	v_mul_f32_e32 v112, v108, v112
	v_mul_f32_e32 v108, v114, v116
	v_mul_f32_e32 v108, v113, v108
	v_cvt_pk_bf16_f32 v106, v1, v106
; __device__ __forceinline__ float siluf_(float x) { return x * __builtin_amdgcn_rcpf(1.0f + __expf(-x)); }
; __device__ __forceinline__ u32x4 pack8(const float (&f)[8]) { u32x4 r; r[0] = cvt_pk_bf16(f[0], f[1]); r[1] = cvt_pk_bf16(f[2], f[3]); r[2] = cvt_pk_bf16(f[4], f[5]); r[3] = cvt_pk_bf16(f[6], f[7]); return r; }
;     __device__ __forceinline__ void operator()(EPI_ARGS) const {
;     ...
;         for (int ai = 0; ai < 2; ++ai) if (ai == 0 || !u.half) { u32x4 zz[4][2];
; #pragma unroll
;             for (int m = 0; m < 4; ++m)
; #pragma unroll
;                 for (int bj = 0; bj < 2; ++bj) zz[m][bj] = *(const u32x4*)(parts + E_PZC + (size_t)EPI_ROW * 1024 + EPI_COL(bj));
; #pragma unroll
;             for (int m = 0; m < 4; ++m)
; #pragma unroll
;                 for (int bj = 0; bj < 2; ++bj) { const f32x4 v0 = acc[ai][bj][m][0], v1 = acc[ai][bj][m][1]; float z[8]; unpack8(zz[m][bj], z); float o[8];
; #pragma unroll
;                     for (int j = 0; j < 4; ++j) { o[j] = v0[j] * siluf_(z[j]); o[4 + j] = v1[j] * siluf_(z[4 + j]); }
;                     *(u32x4*)(O + (size_t)EPI_ROW * 1024 + EPI_COL(bj)) = pack8(o); } }
	v_cvt_pk_bf16_f32 v107, v107, v108
	v_cvt_pk_bf16_f32 v108, v110, v111
	v_add_u32_e32 v110, 16, v152
	v_ashrrev_i32_e32 v111, 31, v110
	v_mul_f32_e32 v113, v115, v122
	v_lshlrev_b64 v[110:111], 11, v[110:111]
	v_mul_f32_e32 v109, v109, v113
	v_lshl_add_u64 v[110:111], s[6:7], 0, v[110:111]
	v_cvt_pk_bf16_f32 v109, v112, v109
	v_lshl_add_u64 v[110:111], v[110:111], 0, v[150:151]
	v_lshlrev_b32_e32 v1, 16, v146
	global_store_dwordx4 v[110:111], v[106:109], off
	v_mul_f32_e32 v113, 0xbfb8aa3b, v1
	v_exp_f32_e32 v113, v113
	v_lshlrev_b32_e32 v109, 16, v148
	v_mul_f32_e32 v114, 0xbfb8aa3b, v109
	v_exp_f32_e32 v114, v114
	v_add_f32_e32 v113, 1.0, v113
	v_rcp_f32_e32 v113, v113
	v_and_b32_e32 v106, 0xffff0000, v146
	v_add_f32_e32 v114, 1.0, v114
	v_rcp_f32_e32 v114, v114
	v_and_b32_e32 v112, 0xffff0000, v148
	v_mul_f32_e32 v1, v113, v1
	v_mul_f32_e32 v1, v102, v1
	v_mul_f32_e32 v102, v114, v109
	v_mul_f32_e32 v109, 0xbfb8aa3b, v106
	v_mul_f32_e32 v113, 0xbfb8aa3b, v112
	v_exp_f32_e32 v109, v109
	v_exp_f32_e32 v113, v113
	v_lshlrev_b32_e32 v107, 16, v147
	v_mul_f32_e32 v102, v98, v102
	v_add_f32_e32 v98, 1.0, v109
	v_add_f32_e32 v109, 1.0, v113
	v_mul_f32_e32 v113, 0xbfb8aa3b, v107
	v_rcp_f32_e32 v98, v98
	v_exp_f32_e32 v113, v113
	v_rcp_f32_e32 v109, v109
	v_lshlrev_b32_e32 v115, 16, v149
	v_mul_f32_e32 v98, v98, v106
	v_add_f32_e32 v106, 1.0, v113
	v_rcp_f32_e32 v106, v106
	v_and_b32_e32 v108, 0xffff0000, v147
	v_mul_f32_e32 v98, v103, v98
	v_mul_f32_e32 v103, v109, v112
	v_mul_f32_e32 v109, 0xbfb8aa3b, v115
	v_and_b32_e32 v116, 0xffff0000, v149
	v_exp_f32_e32 v109, v109
	v_mul_f32_e32 v103, v99, v103
	v_mul_f32_e32 v99, v106, v107
	v_mul_f32_e32 v106, 0xbfb8aa3b, v108
	v_exp_f32_e32 v106, v106
	v_mul_f32_e32 v107, 0xbfb8aa3b, v116
	v_exp_f32_e32 v107, v107
	v_mul_f32_e32 v99, v104, v99
	v_add_f32_e32 v104, 1.0, v109
	v_rcp_f32_e32 v104, v104
	v_add_f32_e32 v106, 1.0, v106
	v_rcp_f32_e32 v106, v106
	v_add_f32_e32 v107, 1.0, v107
	v_rcp_f32_e32 v107, v107
	v_mul_f32_e32 v104, v104, v115
	v_mul_f32_e32 v104, v100, v104
	v_mul_f32_e32 v100, v106, v108
	v_mul_f32_e32 v100, v105, v100
	v_mul_f32_e32 v105, v107, v116
	v_mul_f32_e32 v101, v101, v105
	v_cvt_pk_bf16_f32 v98, v1, v98
	v_cvt_pk_bf16_f32 v99, v99, v100
	v_cvt_pk_bf16_f32 v100, v102, v103
	v_cvt_pk_bf16_f32 v101, v104, v101
	v_lshlrev_b32_e32 v1, 16, v142
	global_store_dwordx4 v[110:111], v[98:101], off offset:256
	v_mul_f32_e32 v103, 0xbfb8aa3b, v1
	v_exp_f32_e32 v103, v103
	v_lshlrev_b32_e32 v101, 16, v144
	v_mul_f32_e32 v104, 0xbfb8aa3b, v101
	v_exp_f32_e32 v104, v104
	v_add_f32_e32 v103, 1.0, v103
	v_rcp_f32_e32 v103, v103
	v_and_b32_e32 v98, 0xffff0000, v142
	v_add_f32_e32 v104, 1.0, v104
	v_rcp_f32_e32 v104, v104
	v_and_b32_e32 v102, 0xffff0000, v144
	v_mul_f32_e32 v1, v103, v1
	v_mul_f32_e32 v1, v94, v1
	v_mul_f32_e32 v94, v104, v101
	v_mul_f32_e32 v101, 0xbfb8aa3b, v98
	v_mul_f32_e32 v103, 0xbfb8aa3b, v102
	v_exp_f32_e32 v101, v101
	v_exp_f32_e32 v103, v103
	v_lshlrev_b32_e32 v99, 16, v143
	v_mul_f32_e32 v94, v90, v94
	v_add_f32_e32 v90, 1.0, v101
	v_add_f32_e32 v101, 1.0, v103
	v_mul_f32_e32 v103, 0xbfb8aa3b, v99
	v_rcp_f32_e32 v90, v90
	v_exp_f32_e32 v103, v103
	v_rcp_f32_e32 v101, v101
	v_lshlrev_b32_e32 v105, 16, v145
	v_mul_f32_e32 v90, v90, v98
	v_add_f32_e32 v98, 1.0, v103
	v_rcp_f32_e32 v98, v98
	v_and_b32_e32 v100, 0xffff0000, v143
	v_mul_f32_e32 v90, v95, v90
	v_mul_f32_e32 v95, v101, v102
	v_mul_f32_e32 v101, 0xbfb8aa3b, v105
	v_exp_f32_e32 v101, v101
	v_mul_f32_e32 v95, v91, v95
	v_mul_f32_e32 v91, v98, v99
	v_mul_f32_e32 v98, 0xbfb8aa3b, v100
	v_exp_f32_e32 v98, v98
	v_and_b32_e32 v106, 0xffff0000, v145
	v_mul_f32_e32 v91, v96, v91
	v_add_f32_e32 v96, 1.0, v101
	v_mul_f32_e32 v99, 0xbfb8aa3b, v106
	v_rcp_f32_e32 v96, v96
	v_exp_f32_e32 v99, v99
	v_add_f32_e32 v98, 1.0, v98
	v_rcp_f32_e32 v98, v98
	v_mul_f32_e32 v96, v96, v105
	v_add_f32_e32 v99, 1.0, v99
	v_rcp_f32_e32 v99, v99
	v_mul_f32_e32 v96, v92, v96
	v_mul_f32_e32 v92, v98, v100
	v_mul_f32_e32 v92, v97, v92
	v_cvt_pk_bf16_f32 v90, v1, v90
	v_cvt_pk_bf16_f32 v91, v91, v92
	v_cvt_pk_bf16_f32 v92, v94, v95
	v_add_u32_e32 v94, 32, v152
	v_ashrrev_i32_e32 v95, 31, v94
	v_mul_f32_e32 v97, v99, v106
	v_lshlrev_b64 v[94:95], 11, v[94:95]
	v_mul_f32_e32 v93, v93, v97
	v_lshl_add_u64 v[94:95], s[6:7], 0, v[94:95]
	v_cvt_pk_bf16_f32 v93, v96, v93
	v_lshl_add_u64 v[94:95], v[94:95], 0, v[150:151]
	v_lshlrev_b32_e32 v1, 16, v138
	global_store_dwordx4 v[94:95], v[90:93], off
	v_mul_f32_e32 v97, 0xbfb8aa3b, v1
	v_exp_f32_e32 v97, v97
	v_lshlrev_b32_e32 v93, 16, v140
	v_mul_f32_e32 v98, 0xbfb8aa3b, v93
	v_exp_f32_e32 v98, v98
	v_add_f32_e32 v97, 1.0, v97
	v_rcp_f32_e32 v97, v97
	v_and_b32_e32 v90, 0xffff0000, v138
	v_add_f32_e32 v98, 1.0, v98
	v_rcp_f32_e32 v98, v98
	v_and_b32_e32 v96, 0xffff0000, v140
	v_mul_f32_e32 v1, v97, v1
	v_mul_f32_e32 v1, v86, v1
	v_mul_f32_e32 v86, v98, v93
	v_mul_f32_e32 v93, 0xbfb8aa3b, v90
	v_mul_f32_e32 v97, 0xbfb8aa3b, v96
	v_exp_f32_e32 v93, v93
	v_exp_f32_e32 v97, v97
	v_lshlrev_b32_e32 v91, 16, v139
	v_mul_f32_e32 v86, v82, v86
	v_add_f32_e32 v82, 1.0, v93
	v_add_f32_e32 v93, 1.0, v97
	v_mul_f32_e32 v97, 0xbfb8aa3b, v91
	v_rcp_f32_e32 v82, v82
	v_exp_f32_e32 v97, v97
	v_rcp_f32_e32 v93, v93
	v_lshlrev_b32_e32 v99, 16, v141
	v_mul_f32_e32 v82, v82, v90
	v_add_f32_e32 v90, 1.0, v97
	v_rcp_f32_e32 v90, v90
	v_and_b32_e32 v92, 0xffff0000, v139
	v_mul_f32_e32 v82, v87, v82
	v_mul_f32_e32 v87, v93, v96
	v_mul_f32_e32 v93, 0xbfb8aa3b, v99
	v_and_b32_e32 v100, 0xffff0000, v141
	v_exp_f32_e32 v93, v93
	v_mul_f32_e32 v87, v83, v87
	v_mul_f32_e32 v83, v90, v91
	v_mul_f32_e32 v90, 0xbfb8aa3b, v92
; __device__ __forceinline__ float siluf_(float x) { return x * __builtin_amdgcn_rcpf(1.0f + __expf(-x)); }
; __device__ __forceinline__ u32x4 pack8(const float (&f)[8]) { u32x4 r; r[0] = cvt_pk_bf16(f[0], f[1]); r[1] = cvt_pk_bf16(f[2], f[3]); r[2] = cvt_pk_bf16(f[4], f[5]); r[3] = cvt_pk_bf16(f[6], f[7]); return r; }
;     __device__ __forceinline__ void operator()(EPI_ARGS) const {
;     ...
;         for (int ai = 0; ai < 2; ++ai) if (ai == 0 || !u.half) { u32x4 zz[4][2];
; #pragma unroll
;             for (int m = 0; m < 4; ++m)
; #pragma unroll
;                 for (int bj = 0; bj < 2; ++bj) zz[m][bj] = *(const u32x4*)(parts + E_PZC + (size_t)EPI_ROW * 1024 + EPI_COL(bj));
; #pragma unroll
;             for (int m = 0; m < 4; ++m)
; #pragma unroll
;                 for (int bj = 0; bj < 2; ++bj) { const f32x4 v0 = acc[ai][bj][m][0], v1 = acc[ai][bj][m][1]; float z[8]; unpack8(zz[m][bj], z); float o[8];
; #pragma unroll
;                     for (int j = 0; j < 4; ++j) { o[j] = v0[j] * siluf_(z[j]); o[4 + j] = v1[j] * siluf_(z[4 + j]); }
;                     *(u32x4*)(O + (size_t)EPI_ROW * 1024 + EPI_COL(bj)) = pack8(o); } }
	v_exp_f32_e32 v90, v90
	v_mul_f32_e32 v91, 0xbfb8aa3b, v100
	v_exp_f32_e32 v91, v91
	v_mul_f32_e32 v83, v88, v83
	v_add_f32_e32 v88, 1.0, v93
	v_rcp_f32_e32 v88, v88
	v_add_f32_e32 v90, 1.0, v90
	v_rcp_f32_e32 v90, v90
	v_add_f32_e32 v91, 1.0, v91
	v_rcp_f32_e32 v91, v91
	v_mul_f32_e32 v88, v88, v99
	v_mul_f32_e32 v88, v84, v88
	v_mul_f32_e32 v84, v90, v92
	v_mul_f32_e32 v84, v89, v84
	v_mul_f32_e32 v89, v91, v100
	v_mul_f32_e32 v85, v85, v89
	v_cvt_pk_bf16_f32 v82, v1, v82
	v_cvt_pk_bf16_f32 v83, v83, v84
	v_cvt_pk_bf16_f32 v84, v86, v87
	v_cvt_pk_bf16_f32 v85, v88, v85
	v_lshlrev_b32_e32 v1, 16, v134
	global_store_dwordx4 v[94:95], v[82:85], off offset:256
	v_mul_f32_e32 v87, 0xbfb8aa3b, v1
	v_exp_f32_e32 v87, v87
	v_lshlrev_b32_e32 v85, 16, v136
	v_mul_f32_e32 v88, 0xbfb8aa3b, v85
	v_exp_f32_e32 v88, v88
	v_add_f32_e32 v87, 1.0, v87
	v_rcp_f32_e32 v87, v87
	v_and_b32_e32 v82, 0xffff0000, v134
	v_add_f32_e32 v88, 1.0, v88
	v_rcp_f32_e32 v88, v88
	v_and_b32_e32 v86, 0xffff0000, v136
	v_mul_f32_e32 v1, v87, v1
	v_mul_f32_e32 v1, v78, v1
	v_mul_f32_e32 v78, v88, v85
	v_mul_f32_e32 v85, 0xbfb8aa3b, v82
	v_mul_f32_e32 v87, 0xbfb8aa3b, v86
	v_exp_f32_e32 v85, v85
	v_exp_f32_e32 v87, v87
	v_lshlrev_b32_e32 v83, 16, v135
	v_mul_f32_e32 v78, v74, v78
	v_add_f32_e32 v74, 1.0, v85
	v_add_f32_e32 v85, 1.0, v87
	v_mul_f32_e32 v87, 0xbfb8aa3b, v83
	v_rcp_f32_e32 v74, v74
	v_exp_f32_e32 v87, v87
	v_rcp_f32_e32 v85, v85
	v_lshlrev_b32_e32 v89, 16, v137
	v_mul_f32_e32 v74, v74, v82
	v_add_f32_e32 v82, 1.0, v87
	v_rcp_f32_e32 v82, v82
	v_and_b32_e32 v84, 0xffff0000, v135
	v_mul_f32_e32 v74, v79, v74
	v_mul_f32_e32 v79, v85, v86
	v_mul_f32_e32 v85, 0xbfb8aa3b, v89
	v_exp_f32_e32 v85, v85
	v_mul_f32_e32 v79, v75, v79
	v_mul_f32_e32 v75, v82, v83
	v_mul_f32_e32 v82, 0xbfb8aa3b, v84
	v_exp_f32_e32 v82, v82
	v_and_b32_e32 v90, 0xffff0000, v137
	v_mul_f32_e32 v75, v80, v75
	v_add_f32_e32 v80, 1.0, v85
	v_mul_f32_e32 v83, 0xbfb8aa3b, v90
	v_rcp_f32_e32 v80, v80
	v_exp_f32_e32 v83, v83
	v_add_f32_e32 v82, 1.0, v82
	v_rcp_f32_e32 v82, v82
	v_mul_f32_e32 v80, v80, v89
	v_add_f32_e32 v83, 1.0, v83
	v_rcp_f32_e32 v83, v83
	v_mul_f32_e32 v80, v76, v80
	v_mul_f32_e32 v76, v82, v84
	v_mul_f32_e32 v76, v81, v76
	v_cvt_pk_bf16_f32 v74, v1, v74
	v_cvt_pk_bf16_f32 v75, v75, v76
	v_cvt_pk_bf16_f32 v76, v78, v79
	v_add_u32_e32 v78, 48, v152
	v_ashrrev_i32_e32 v79, 31, v78
	v_mul_f32_e32 v81, v83, v90
	v_lshlrev_b64 v[78:79], 11, v[78:79]
	v_mul_f32_e32 v77, v77, v81
	v_lshl_add_u64 v[78:79], s[6:7], 0, v[78:79]
	v_cvt_pk_bf16_f32 v77, v80, v77
	v_lshl_add_u64 v[78:79], v[78:79], 0, v[150:151]
	v_lshlrev_b32_e32 v1, 16, v130
	global_store_dwordx4 v[78:79], v[74:77], off
	v_mul_f32_e32 v81, 0xbfb8aa3b, v1
	v_exp_f32_e32 v81, v81
	v_lshlrev_b32_e32 v77, 16, v132
	v_mul_f32_e32 v82, 0xbfb8aa3b, v77
	v_exp_f32_e32 v82, v82
	v_add_f32_e32 v81, 1.0, v81
	v_rcp_f32_e32 v81, v81
	v_and_b32_e32 v74, 0xffff0000, v130
	v_add_f32_e32 v82, 1.0, v82
	v_rcp_f32_e32 v82, v82
	v_and_b32_e32 v80, 0xffff0000, v132
	v_mul_f32_e32 v1, v81, v1
	v_mul_f32_e32 v1, v70, v1
	v_mul_f32_e32 v70, v82, v77
	v_mul_f32_e32 v77, 0xbfb8aa3b, v74
	v_mul_f32_e32 v81, 0xbfb8aa3b, v80
	v_exp_f32_e32 v77, v77
	v_exp_f32_e32 v81, v81
	v_lshlrev_b32_e32 v75, 16, v131
	v_mul_f32_e32 v70, v66, v70
	v_add_f32_e32 v66, 1.0, v77
	v_add_f32_e32 v77, 1.0, v81
	v_mul_f32_e32 v81, 0xbfb8aa3b, v75
	v_rcp_f32_e32 v66, v66
	v_exp_f32_e32 v81, v81
	v_rcp_f32_e32 v77, v77
	v_lshlrev_b32_e32 v83, 16, v133
	v_mul_f32_e32 v66, v66, v74
	v_add_f32_e32 v74, 1.0, v81
	v_rcp_f32_e32 v74, v74
	v_and_b32_e32 v76, 0xffff0000, v131
	v_mul_f32_e32 v66, v71, v66
	v_mul_f32_e32 v71, v77, v80
	v_mul_f32_e32 v77, 0xbfb8aa3b, v83
	v_exp_f32_e32 v77, v77
	v_mul_f32_e32 v71, v67, v71
	v_mul_f32_e32 v67, v74, v75
	v_mul_f32_e32 v74, 0xbfb8aa3b, v76
	v_exp_f32_e32 v74, v74
	v_and_b32_e32 v84, 0xffff0000, v133
	v_mul_f32_e32 v67, v72, v67
	v_add_f32_e32 v72, 1.0, v77
	v_rcp_f32_e32 v72, v72
	v_mul_f32_e32 v75, 0xbfb8aa3b, v84
	v_add_f32_e32 v74, 1.0, v74
	v_exp_f32_e32 v75, v75
	v_rcp_f32_e32 v74, v74
	v_mul_f32_e32 v72, v72, v83
	v_mul_f32_e32 v72, v68, v72
	v_add_f32_e32 v75, 1.0, v75
	v_mul_f32_e32 v68, v74, v76
	v_rcp_f32_e32 v75, v75
	v_mul_f32_e32 v68, v73, v68
	v_cvt_pk_bf16_f32 v66, v1, v66
	v_cvt_pk_bf16_f32 v67, v67, v68
	v_cvt_pk_bf16_f32 v68, v70, v71
	v_add_u32_e32 v70, 0x80, v152
	v_ashrrev_i32_e32 v71, 31, v70
	v_lshlrev_b64 v[104:105], 11, v[70:71]
	v_mul_f32_e32 v73, v75, v84
	v_lshl_add_u64 v[70:71], s[12:13], 0, v[104:105]
	v_mul_f32_e32 v69, v69, v73
	v_lshl_add_u64 v[70:71], v[70:71], 0, v[150:151]
	v_cvt_pk_bf16_f32 v69, v72, v69
	global_load_dwordx4 v[92:95], v[70:71], off
	s_nop 0
	global_store_dwordx4 v[78:79], v[66:69], off offset:256
	global_load_dwordx4 v[96:99], v[70:71], off offset:256
	s_waitcnt vmcnt(0)
; __device__ __forceinline__ float siluf_(float x) { return x * __builtin_amdgcn_rcpf(1.0f + __expf(-x)); }
; __device__ __forceinline__ u32x4 pack8(const float (&f)[8]) { u32x4 r; r[0] = cvt_pk_bf16(f[0], f[1]); r[1] = cvt_pk_bf16(f[2], f[3]); r[2] = cvt_pk_bf16(f[4], f[5]); r[3] = cvt_pk_bf16(f[6], f[7]); return r; }
;     __device__ __forceinline__ void operator()(EPI_ARGS) const {
;     ...
;         for (int ai = 0; ai < 2; ++ai) if (ai == 0 || !u.half) { u32x4 zz[4][2];
; #pragma unroll
;             for (int m = 0; m < 4; ++m)
; #pragma unroll
;                 for (int bj = 0; bj < 2; ++bj) zz[m][bj] = *(const u32x4*)(parts + E_PZC + (size_t)EPI_ROW * 1024 + EPI_COL(bj));
; #pragma unroll
;             for (int m = 0; m < 4; ++m)
; #pragma unroll
;                 for (int bj = 0; bj < 2; ++bj) { const f32x4 v0 = acc[ai][bj][m][0], v1 = acc[ai][bj][m][1]; float z[8]; unpack8(zz[m][bj], z); float o[8];
; #pragma unroll
;                     for (int j = 0; j < 4; ++j) { o[j] = v0[j] * siluf_(z[j]); o[4 + j] = v1[j] * siluf_(z[4 + j]); }
;                     *(u32x4*)(O + (size_t)EPI_ROW * 1024 + EPI_COL(bj)) = pack8(o); } }
	v_lshlrev_b32_e32 v1, 16, v92
	v_add_u32_e32 v66, 0x90, v152
	v_ashrrev_i32_e32 v67, 31, v66
	v_lshlrev_b64 v[90:91], 11, v[66:67]
	v_lshl_add_u64 v[66:67], s[12:13], 0, v[90:91]
	v_lshl_add_u64 v[66:67], v[66:67], 0, v[150:151]
	global_load_dwordx4 v[100:103], v[66:67], off
	global_load_dwordx4 v[82:85], v[66:67], off offset:256
	v_add_u32_e32 v66, 0xa0, v152
	v_ashrrev_i32_e32 v67, 31, v66
	v_lshlrev_b64 v[88:89], 11, v[66:67]
	v_lshl_add_u64 v[66:67], s[12:13], 0, v[88:89]
	v_lshl_add_u64 v[66:67], v[66:67], 0, v[150:151]
	global_load_dwordx4 v[78:81], v[66:67], off
	global_load_dwordx4 v[74:77], v[66:67], off offset:256
	v_add_u32_e32 v66, 0xb0, v152
	v_ashrrev_i32_e32 v67, 31, v66
	v_lshlrev_b64 v[86:87], 11, v[66:67]
	v_lshl_add_u64 v[66:67], s[12:13], 0, v[86:87]
	v_lshl_add_u64 v[106:107], v[66:67], 0, v[150:151]
	global_load_dwordx4 v[70:73], v[106:107], off
	global_load_dwordx4 v[66:69], v[106:107], off offset:256
	v_lshlrev_b32_e32 v107, 16, v94
	v_mul_f32_e32 v108, 0xbfb8aa3b, v1
	v_exp_f32_e32 v108, v108
	v_mul_f32_e32 v109, 0xbfb8aa3b, v107
	v_exp_f32_e32 v109, v109
	v_and_b32_e32 v92, 0xffff0000, v92
	v_add_f32_e32 v108, 1.0, v108
	v_rcp_f32_e32 v108, v108
	v_add_f32_e32 v109, 1.0, v109
	v_rcp_f32_e32 v109, v109
	v_and_b32_e32 v94, 0xffff0000, v94
	v_mul_f32_e32 v1, v108, v1
	v_mul_f32_e32 v1, v62, v1
	v_mul_f32_e32 v62, v109, v107
	v_mul_f32_e32 v107, 0xbfb8aa3b, v92
	v_mul_f32_e32 v108, 0xbfb8aa3b, v94
	v_exp_f32_e32 v107, v107
	v_exp_f32_e32 v108, v108
	v_lshlrev_b32_e32 v106, 16, v93
	v_mul_f32_e32 v62, v58, v62
	v_add_f32_e32 v58, 1.0, v107
	v_add_f32_e32 v107, 1.0, v108
	v_mul_f32_e32 v108, 0xbfb8aa3b, v106
	v_rcp_f32_e32 v58, v58
	v_exp_f32_e32 v108, v108
	v_rcp_f32_e32 v107, v107
	v_lshlrev_b32_e32 v110, 16, v95
	v_mul_f32_e32 v58, v58, v92
	v_add_f32_e32 v92, 1.0, v108
	v_mul_f32_e32 v58, v63, v58
	v_mul_f32_e32 v63, v107, v94
	v_rcp_f32_e32 v92, v92
	v_mul_f32_e32 v94, 0xbfb8aa3b, v110
	v_exp_f32_e32 v94, v94
	v_and_b32_e32 v93, 0xffff0000, v93
	v_and_b32_e32 v95, 0xffff0000, v95
	v_mul_f32_e32 v63, v59, v63
	v_mul_f32_e32 v59, v92, v106
	v_mul_f32_e32 v92, 0xbfb8aa3b, v93
	v_mul_f32_e32 v59, v64, v59
	v_add_f32_e32 v64, 1.0, v94
	v_exp_f32_e32 v92, v92
	v_mul_f32_e32 v94, 0xbfb8aa3b, v95
	v_exp_f32_e32 v94, v94
	v_rcp_f32_e32 v64, v64
	v_add_f32_e32 v92, 1.0, v92
	v_rcp_f32_e32 v92, v92
	v_add_f32_e32 v94, 1.0, v94
	v_rcp_f32_e32 v94, v94
	v_mul_f32_e32 v64, v64, v110
	v_mul_f32_e32 v64, v60, v64
	v_mul_f32_e32 v60, v92, v93
	v_mul_f32_e32 v60, v65, v60
	v_mul_f32_e32 v65, v94, v95
	v_mul_f32_e32 v61, v61, v65
	v_cvt_pk_bf16_f32 v58, v1, v58
	v_cvt_pk_bf16_f32 v59, v59, v60
	v_cvt_pk_bf16_f32 v60, v62, v63
	v_lshl_add_u64 v[62:63], s[6:7], 0, v[104:105]
	v_cvt_pk_bf16_f32 v61, v64, v61
	v_lshl_add_u64 v[62:63], v[62:63], 0, v[150:151]
	v_lshlrev_b32_e32 v1, 16, v96
	global_store_dwordx4 v[62:63], v[58:61], off
	v_mul_f32_e32 v65, 0xbfb8aa3b, v1
	v_exp_f32_e32 v65, v65
	v_lshlrev_b32_e32 v61, 16, v98
	v_mul_f32_e32 v92, 0xbfb8aa3b, v61
	v_exp_f32_e32 v92, v92
	v_add_f32_e32 v65, 1.0, v65
	v_rcp_f32_e32 v65, v65
	v_and_b32_e32 v58, 0xffff0000, v96
	v_add_f32_e32 v92, 1.0, v92
	v_rcp_f32_e32 v92, v92
	v_and_b32_e32 v64, 0xffff0000, v98
	v_mul_f32_e32 v1, v65, v1
	v_mul_f32_e32 v1, v54, v1
	v_mul_f32_e32 v54, v92, v61
	v_mul_f32_e32 v61, 0xbfb8aa3b, v58
	v_mul_f32_e32 v65, 0xbfb8aa3b, v64
	v_exp_f32_e32 v61, v61
	v_exp_f32_e32 v65, v65
	v_lshlrev_b32_e32 v59, 16, v97
	v_mul_f32_e32 v54, v50, v54
	v_add_f32_e32 v50, 1.0, v61
	v_add_f32_e32 v61, 1.0, v65
	v_mul_f32_e32 v65, 0xbfb8aa3b, v59
	v_rcp_f32_e32 v50, v50
	v_exp_f32_e32 v65, v65
	v_rcp_f32_e32 v61, v61
	v_lshlrev_b32_e32 v93, 16, v99
	v_mul_f32_e32 v50, v50, v58
	v_add_f32_e32 v58, 1.0, v65
	v_rcp_f32_e32 v58, v58
	v_and_b32_e32 v60, 0xffff0000, v97
	v_mul_f32_e32 v50, v55, v50
	v_mul_f32_e32 v55, v61, v64
	v_mul_f32_e32 v61, 0xbfb8aa3b, v93
	v_and_b32_e32 v94, 0xffff0000, v99
	v_exp_f32_e32 v61, v61
	v_mul_f32_e32 v55, v51, v55
	v_mul_f32_e32 v51, v58, v59
	v_mul_f32_e32 v58, 0xbfb8aa3b, v60
	v_exp_f32_e32 v58, v58
	v_mul_f32_e32 v59, 0xbfb8aa3b, v94
	v_exp_f32_e32 v59, v59
	v_mul_f32_e32 v51, v56, v51
	v_add_f32_e32 v56, 1.0, v61
	v_rcp_f32_e32 v56, v56
	v_add_f32_e32 v58, 1.0, v58
	v_rcp_f32_e32 v58, v58
	v_add_f32_e32 v59, 1.0, v59
	v_rcp_f32_e32 v59, v59
	v_mul_f32_e32 v56, v56, v93
	v_mul_f32_e32 v56, v52, v56
	v_mul_f32_e32 v52, v58, v60
	v_mul_f32_e32 v52, v57, v52
	v_mul_f32_e32 v57, v59, v94
	v_mul_f32_e32 v53, v53, v57
	v_cvt_pk_bf16_f32 v50, v1, v50
	v_cvt_pk_bf16_f32 v51, v51, v52
	v_cvt_pk_bf16_f32 v52, v54, v55
	v_cvt_pk_bf16_f32 v53, v56, v53
	s_waitcnt vmcnt(0)
; __device__ __forceinline__ float siluf_(float x) { return x * __builtin_amdgcn_rcpf(1.0f + __expf(-x)); }
; __device__ __forceinline__ u32x4 pack8(const float (&f)[8]) { u32x4 r; r[0] = cvt_pk_bf16(f[0], f[1]); r[1] = cvt_pk_bf16(f[2], f[3]); r[2] = cvt_pk_bf16(f[4], f[5]); r[3] = cvt_pk_bf16(f[6], f[7]); return r; }
;     __device__ __forceinline__ void operator()(EPI_ARGS) const {
;     ...
;         for (int ai = 0; ai < 2; ++ai) if (ai == 0 || !u.half) { u32x4 zz[4][2];
; #pragma unroll
;             for (int m = 0; m < 4; ++m)
; #pragma unroll
;                 for (int bj = 0; bj < 2; ++bj) zz[m][bj] = *(const u32x4*)(parts + E_PZC + (size_t)EPI_ROW * 1024 + EPI_COL(bj));
; #pragma unroll
;             for (int m = 0; m < 4; ++m)
; #pragma unroll
;                 for (int bj = 0; bj < 2; ++bj) { const f32x4 v0 = acc[ai][bj][m][0], v1 = acc[ai][bj][m][1]; float z[8]; unpack8(zz[m][bj], z); float o[8];
; #pragma unroll
;                     for (int j = 0; j < 4; ++j) { o[j] = v0[j] * siluf_(z[j]); o[4 + j] = v1[j] * siluf_(z[4 + j]); }
;                     *(u32x4*)(O + (size_t)EPI_ROW * 1024 + EPI_COL(bj)) = pack8(o); } }
	v_lshlrev_b32_e32 v1, 16, v100
	global_store_dwordx4 v[62:63], v[50:53], off offset:256
	v_mul_f32_e32 v55, 0xbfb8aa3b, v1
	v_exp_f32_e32 v55, v55
	v_lshlrev_b32_e32 v53, 16, v102
	v_mul_f32_e32 v56, 0xbfb8aa3b, v53
	v_exp_f32_e32 v56, v56
	v_add_f32_e32 v55, 1.0, v55
	v_rcp_f32_e32 v55, v55
	v_and_b32_e32 v50, 0xffff0000, v100
	v_add_f32_e32 v56, 1.0, v56
	v_rcp_f32_e32 v56, v56
	v_and_b32_e32 v54, 0xffff0000, v102
	v_mul_f32_e32 v1, v55, v1
	v_mul_f32_e32 v1, v46, v1
	v_mul_f32_e32 v46, v56, v53
	v_mul_f32_e32 v53, 0xbfb8aa3b, v50
	v_mul_f32_e32 v55, 0xbfb8aa3b, v54
	v_exp_f32_e32 v53, v53
	v_exp_f32_e32 v55, v55
	v_lshlrev_b32_e32 v51, 16, v101
	v_mul_f32_e32 v46, v42, v46
	v_add_f32_e32 v42, 1.0, v53
	v_add_f32_e32 v53, 1.0, v55
	v_mul_f32_e32 v55, 0xbfb8aa3b, v51
	v_rcp_f32_e32 v42, v42
	v_exp_f32_e32 v55, v55
	v_rcp_f32_e32 v53, v53
	v_lshlrev_b32_e32 v57, 16, v103
	v_mul_f32_e32 v42, v42, v50
	v_add_f32_e32 v50, 1.0, v55
	v_rcp_f32_e32 v50, v50
	v_and_b32_e32 v52, 0xffff0000, v101
	v_mul_f32_e32 v42, v47, v42
	v_mul_f32_e32 v47, v53, v54
	v_mul_f32_e32 v53, 0xbfb8aa3b, v57
	v_and_b32_e32 v58, 0xffff0000, v103
	v_exp_f32_e32 v53, v53
	v_mul_f32_e32 v47, v43, v47
	v_mul_f32_e32 v43, v50, v51
	v_mul_f32_e32 v50, 0xbfb8aa3b, v52
	v_exp_f32_e32 v50, v50
	v_mul_f32_e32 v51, 0xbfb8aa3b, v58
	v_exp_f32_e32 v51, v51
	v_mul_f32_e32 v43, v48, v43
	v_add_f32_e32 v48, 1.0, v53
	v_rcp_f32_e32 v48, v48
	v_add_f32_e32 v50, 1.0, v50
	v_rcp_f32_e32 v50, v50
	v_add_f32_e32 v51, 1.0, v51
	v_rcp_f32_e32 v51, v51
	v_mul_f32_e32 v48, v48, v57
	v_mul_f32_e32 v48, v44, v48
	v_mul_f32_e32 v44, v50, v52
	v_mul_f32_e32 v44, v49, v44
	v_mul_f32_e32 v49, v51, v58
	v_mul_f32_e32 v45, v45, v49
	v_cvt_pk_bf16_f32 v42, v1, v42
	v_cvt_pk_bf16_f32 v43, v43, v44
	v_cvt_pk_bf16_f32 v44, v46, v47
	v_lshl_add_u64 v[46:47], s[6:7], 0, v[90:91]
	v_cvt_pk_bf16_f32 v45, v48, v45
	v_lshl_add_u64 v[46:47], v[46:47], 0, v[150:151]
	v_lshlrev_b32_e32 v1, 16, v82
	global_store_dwordx4 v[46:47], v[42:45], off
	v_mul_f32_e32 v49, 0xbfb8aa3b, v1
	v_exp_f32_e32 v49, v49
	v_lshlrev_b32_e32 v45, 16, v84
	v_mul_f32_e32 v50, 0xbfb8aa3b, v45
	v_exp_f32_e32 v50, v50
	v_add_f32_e32 v49, 1.0, v49
	v_rcp_f32_e32 v49, v49
	v_and_b32_e32 v42, 0xffff0000, v82
	v_add_f32_e32 v50, 1.0, v50
	v_rcp_f32_e32 v50, v50
	v_and_b32_e32 v48, 0xffff0000, v84
	v_mul_f32_e32 v1, v49, v1
	v_mul_f32_e32 v1, v38, v1
	v_mul_f32_e32 v38, v50, v45
	v_mul_f32_e32 v45, 0xbfb8aa3b, v42
	v_mul_f32_e32 v49, 0xbfb8aa3b, v48
	v_exp_f32_e32 v45, v45
	v_exp_f32_e32 v49, v49
	v_lshlrev_b32_e32 v43, 16, v83
	v_mul_f32_e32 v38, v34, v38
	v_add_f32_e32 v34, 1.0, v45
	v_add_f32_e32 v45, 1.0, v49
	v_mul_f32_e32 v49, 0xbfb8aa3b, v43
	v_rcp_f32_e32 v34, v34
	v_exp_f32_e32 v49, v49
	v_rcp_f32_e32 v45, v45
	v_lshlrev_b32_e32 v51, 16, v85
	v_mul_f32_e32 v34, v34, v42
	v_add_f32_e32 v42, 1.0, v49
	v_rcp_f32_e32 v42, v42
	v_and_b32_e32 v44, 0xffff0000, v83
	v_mul_f32_e32 v34, v39, v34
	v_mul_f32_e32 v39, v45, v48
	v_mul_f32_e32 v45, 0xbfb8aa3b, v51
	v_and_b32_e32 v52, 0xffff0000, v85
	v_exp_f32_e32 v45, v45
	v_mul_f32_e32 v39, v35, v39
	v_mul_f32_e32 v35, v42, v43
	v_mul_f32_e32 v42, 0xbfb8aa3b, v44
	v_exp_f32_e32 v42, v42
	v_mul_f32_e32 v43, 0xbfb8aa3b, v52
	v_exp_f32_e32 v43, v43
	v_mul_f32_e32 v35, v40, v35
	v_add_f32_e32 v40, 1.0, v45
	v_rcp_f32_e32 v40, v40
	v_add_f32_e32 v42, 1.0, v42
	v_rcp_f32_e32 v42, v42
	v_add_f32_e32 v43, 1.0, v43
	v_rcp_f32_e32 v43, v43
	v_mul_f32_e32 v40, v40, v51
	v_mul_f32_e32 v40, v36, v40
	v_mul_f32_e32 v36, v42, v44
	v_mul_f32_e32 v36, v41, v36
	v_mul_f32_e32 v41, v43, v52
	v_mul_f32_e32 v37, v37, v41
	v_cvt_pk_bf16_f32 v34, v1, v34
	v_cvt_pk_bf16_f32 v35, v35, v36
	v_cvt_pk_bf16_f32 v36, v38, v39
	v_cvt_pk_bf16_f32 v37, v40, v37
	v_lshlrev_b32_e32 v1, 16, v78
	global_store_dwordx4 v[46:47], v[34:37], off offset:256
	v_mul_f32_e32 v39, 0xbfb8aa3b, v1
	v_exp_f32_e32 v39, v39
	v_lshlrev_b32_e32 v37, 16, v80
	v_mul_f32_e32 v40, 0xbfb8aa3b, v37
	v_exp_f32_e32 v40, v40
	v_add_f32_e32 v39, 1.0, v39
	v_rcp_f32_e32 v39, v39
	v_and_b32_e32 v34, 0xffff0000, v78
	v_add_f32_e32 v40, 1.0, v40
	v_rcp_f32_e32 v40, v40
	v_and_b32_e32 v38, 0xffff0000, v80
	v_mul_f32_e32 v1, v39, v1
	v_mul_f32_e32 v1, v30, v1
	v_mul_f32_e32 v30, v40, v37
	v_mul_f32_e32 v37, 0xbfb8aa3b, v34
	v_mul_f32_e32 v39, 0xbfb8aa3b, v38
	v_exp_f32_e32 v37, v37
	v_exp_f32_e32 v39, v39
	v_lshlrev_b32_e32 v35, 16, v79
	v_mul_f32_e32 v30, v26, v30
	v_add_f32_e32 v26, 1.0, v37
	v_add_f32_e32 v37, 1.0, v39
	v_mul_f32_e32 v39, 0xbfb8aa3b, v35
	v_rcp_f32_e32 v26, v26
	v_exp_f32_e32 v39, v39
	v_rcp_f32_e32 v37, v37
	v_lshlrev_b32_e32 v41, 16, v81
	v_mul_f32_e32 v26, v26, v34
	v_add_f32_e32 v34, 1.0, v39
	v_rcp_f32_e32 v34, v34
	v_and_b32_e32 v36, 0xffff0000, v79
	v_mul_f32_e32 v26, v31, v26
	v_mul_f32_e32 v31, v37, v38
	v_mul_f32_e32 v37, 0xbfb8aa3b, v41
	v_and_b32_e32 v42, 0xffff0000, v81
	v_exp_f32_e32 v37, v37
	v_mul_f32_e32 v31, v27, v31
	v_mul_f32_e32 v27, v34, v35
	v_mul_f32_e32 v34, 0xbfb8aa3b, v36
	v_exp_f32_e32 v34, v34
	v_mul_f32_e32 v35, 0xbfb8aa3b, v42
	v_exp_f32_e32 v35, v35
	v_mul_f32_e32 v27, v32, v27
	v_add_f32_e32 v32, 1.0, v37
	v_rcp_f32_e32 v32, v32
	v_add_f32_e32 v34, 1.0, v34
	v_rcp_f32_e32 v34, v34
	v_add_f32_e32 v35, 1.0, v35
	v_rcp_f32_e32 v35, v35
	v_mul_f32_e32 v32, v32, v41
	v_mul_f32_e32 v32, v28, v32
	v_mul_f32_e32 v28, v34, v36
	v_mul_f32_e32 v28, v33, v28
	v_mul_f32_e32 v33, v35, v42
	v_mul_f32_e32 v29, v29, v33
	v_cvt_pk_bf16_f32 v26, v1, v26
	v_cvt_pk_bf16_f32 v27, v27, v28
	v_cvt_pk_bf16_f32 v28, v30, v31
	v_lshl_add_u64 v[30:31], s[6:7], 0, v[88:89]
	v_cvt_pk_bf16_f32 v29, v32, v29
; __device__ __forceinline__ float siluf_(float x) { return x * __builtin_amdgcn_rcpf(1.0f + __expf(-x)); }
; __device__ __forceinline__ u32x4 pack8(const float (&f)[8]) { u32x4 r; r[0] = cvt_pk_bf16(f[0], f[1]); r[1] = cvt_pk_bf16(f[2], f[3]); r[2] = cvt_pk_bf16(f[4], f[5]); r[3] = cvt_pk_bf16(f[6], f[7]); return r; }
; #define PG8_WAIT_V(n) asm volatile("s_waitcnt vmcnt(" #n ")" ::: "memory")
; #define PG8_BAR __builtin_amdgcn_s_barrier()
; template <class Sched, class Epi>
; __device__ __forceinline__ void gemm_phase(LAS unsigned char* lds, const Sched& S, const Epi& E, const int K, const int lda, const int ldb) {
;     ...
;     PG8_WAIT_V(0);
;     if (wr == 0) PG8_BAR;
;     PG8_BAR;
;     __device__ __forceinline__ void operator()(EPI_ARGS) const {
;     ...
;             for (int m = 0; m < 4; ++m)
; #pragma unroll
;                 for (int bj = 0; bj < 2; ++bj) { const f32x4 v0 = acc[ai][bj][m][0], v1 = acc[ai][bj][m][1]; float z[8]; unpack8(zz[m][bj], z); float o[8];
; #pragma unroll
;                     for (int j = 0; j < 4; ++j) { o[j] = v0[j] * siluf_(z[j]); o[4 + j] = v1[j] * siluf_(z[4 + j]); }
;                     *(u32x4*)(O + (size_t)EPI_ROW * 1024 + EPI_COL(bj)) = pack8(o); } }
	v_lshl_add_u64 v[30:31], v[30:31], 0, v[150:151]
	v_lshlrev_b32_e32 v1, 16, v74
	global_store_dwordx4 v[30:31], v[26:29], off
	v_mul_f32_e32 v33, 0xbfb8aa3b, v1
	v_exp_f32_e32 v33, v33
	v_lshlrev_b32_e32 v29, 16, v76
	v_mul_f32_e32 v34, 0xbfb8aa3b, v29
	v_exp_f32_e32 v34, v34
	v_add_f32_e32 v33, 1.0, v33
	v_rcp_f32_e32 v33, v33
	v_and_b32_e32 v26, 0xffff0000, v74
	v_add_f32_e32 v34, 1.0, v34
	v_rcp_f32_e32 v34, v34
	v_and_b32_e32 v32, 0xffff0000, v76
	v_mul_f32_e32 v1, v33, v1
	v_mul_f32_e32 v1, v22, v1
	v_mul_f32_e32 v22, v34, v29
	v_mul_f32_e32 v29, 0xbfb8aa3b, v26
	v_mul_f32_e32 v33, 0xbfb8aa3b, v32
	v_exp_f32_e32 v29, v29
	v_exp_f32_e32 v33, v33
	v_lshlrev_b32_e32 v27, 16, v75
	v_mul_f32_e32 v22, v18, v22
	v_add_f32_e32 v18, 1.0, v29
	v_add_f32_e32 v29, 1.0, v33
	v_mul_f32_e32 v33, 0xbfb8aa3b, v27
	v_rcp_f32_e32 v18, v18
	v_exp_f32_e32 v33, v33
	v_rcp_f32_e32 v29, v29
	v_lshlrev_b32_e32 v35, 16, v77
	v_mul_f32_e32 v18, v18, v26
	v_add_f32_e32 v26, 1.0, v33
	v_rcp_f32_e32 v26, v26
	v_and_b32_e32 v28, 0xffff0000, v75
	v_mul_f32_e32 v18, v23, v18
	v_mul_f32_e32 v23, v29, v32
	v_mul_f32_e32 v29, 0xbfb8aa3b, v35
	v_and_b32_e32 v36, 0xffff0000, v77
	v_exp_f32_e32 v29, v29
	v_mul_f32_e32 v23, v19, v23
	v_mul_f32_e32 v19, v26, v27
	v_mul_f32_e32 v26, 0xbfb8aa3b, v28
	v_exp_f32_e32 v26, v26
	v_mul_f32_e32 v27, 0xbfb8aa3b, v36
	v_exp_f32_e32 v27, v27
	v_mul_f32_e32 v19, v24, v19
	v_add_f32_e32 v24, 1.0, v29
	v_rcp_f32_e32 v24, v24
	v_add_f32_e32 v26, 1.0, v26
	v_rcp_f32_e32 v26, v26
	v_add_f32_e32 v27, 1.0, v27
	v_rcp_f32_e32 v27, v27
	v_mul_f32_e32 v24, v24, v35
	v_mul_f32_e32 v24, v20, v24
	v_mul_f32_e32 v20, v26, v28
	v_mul_f32_e32 v20, v25, v20
	v_mul_f32_e32 v25, v27, v36
	v_mul_f32_e32 v21, v21, v25
	v_cvt_pk_bf16_f32 v18, v1, v18
	v_cvt_pk_bf16_f32 v19, v19, v20
	v_cvt_pk_bf16_f32 v20, v22, v23
	v_cvt_pk_bf16_f32 v21, v24, v21
	v_lshlrev_b32_e32 v1, 16, v70
	global_store_dwordx4 v[30:31], v[18:21], off offset:256
	v_mul_f32_e32 v23, 0xbfb8aa3b, v1
	v_exp_f32_e32 v23, v23
	v_lshlrev_b32_e32 v21, 16, v72
	v_mul_f32_e32 v24, 0xbfb8aa3b, v21
	v_exp_f32_e32 v24, v24
	v_add_f32_e32 v23, 1.0, v23
	v_rcp_f32_e32 v23, v23
	v_and_b32_e32 v18, 0xffff0000, v70
	v_add_f32_e32 v24, 1.0, v24
	v_rcp_f32_e32 v24, v24
	v_and_b32_e32 v22, 0xffff0000, v72
	v_mul_f32_e32 v1, v23, v1
	v_mul_f32_e32 v1, v14, v1
	v_mul_f32_e32 v14, v24, v21
	v_mul_f32_e32 v21, 0xbfb8aa3b, v18
	v_mul_f32_e32 v23, 0xbfb8aa3b, v22
	v_exp_f32_e32 v21, v21
	v_exp_f32_e32 v23, v23
	v_lshlrev_b32_e32 v19, 16, v71
	v_mul_f32_e32 v14, v10, v14
	v_add_f32_e32 v10, 1.0, v21
	v_add_f32_e32 v21, 1.0, v23
	v_mul_f32_e32 v23, 0xbfb8aa3b, v19
	v_rcp_f32_e32 v10, v10
	v_exp_f32_e32 v23, v23
	v_rcp_f32_e32 v21, v21
	v_lshlrev_b32_e32 v25, 16, v73
	v_mul_f32_e32 v10, v10, v18
	v_add_f32_e32 v18, 1.0, v23
	v_rcp_f32_e32 v18, v18
	v_and_b32_e32 v20, 0xffff0000, v71
	v_mul_f32_e32 v10, v15, v10
	v_mul_f32_e32 v15, v21, v22
	v_mul_f32_e32 v21, 0xbfb8aa3b, v25
	v_and_b32_e32 v26, 0xffff0000, v73
	v_exp_f32_e32 v21, v21
	v_mul_f32_e32 v15, v11, v15
	v_mul_f32_e32 v11, v18, v19
	v_mul_f32_e32 v18, 0xbfb8aa3b, v20
	v_exp_f32_e32 v18, v18
	v_mul_f32_e32 v19, 0xbfb8aa3b, v26
	v_exp_f32_e32 v19, v19
	v_mul_f32_e32 v11, v16, v11
	v_add_f32_e32 v16, 1.0, v21
	v_rcp_f32_e32 v16, v16
	v_add_f32_e32 v18, 1.0, v18
	v_rcp_f32_e32 v18, v18
	v_add_f32_e32 v19, 1.0, v19
	v_rcp_f32_e32 v19, v19
	v_mul_f32_e32 v16, v16, v25
	v_mul_f32_e32 v16, v12, v16
	v_mul_f32_e32 v12, v18, v20
	v_mul_f32_e32 v12, v17, v12
	v_mul_f32_e32 v17, v19, v26
	v_mul_f32_e32 v13, v13, v17
	v_cvt_pk_bf16_f32 v10, v1, v10
	v_cvt_pk_bf16_f32 v11, v11, v12
	v_cvt_pk_bf16_f32 v12, v14, v15
	v_lshl_add_u64 v[14:15], s[6:7], 0, v[86:87]
	v_cvt_pk_bf16_f32 v13, v16, v13
	v_lshl_add_u64 v[14:15], v[14:15], 0, v[150:151]
	v_lshlrev_b32_e32 v1, 16, v66
	global_store_dwordx4 v[14:15], v[10:13], off
	v_mul_f32_e32 v17, 0xbfb8aa3b, v1
	v_exp_f32_e32 v17, v17
	v_lshlrev_b32_e32 v13, 16, v68
	v_mul_f32_e32 v18, 0xbfb8aa3b, v13
	v_exp_f32_e32 v18, v18
	v_add_f32_e32 v17, 1.0, v17
	v_rcp_f32_e32 v17, v17
	v_and_b32_e32 v10, 0xffff0000, v66
	v_add_f32_e32 v18, 1.0, v18
	v_rcp_f32_e32 v18, v18
	v_and_b32_e32 v16, 0xffff0000, v68
	v_mul_f32_e32 v1, v17, v1
	v_mul_f32_e32 v1, v6, v1
	v_mul_f32_e32 v6, v18, v13
	v_mul_f32_e32 v13, 0xbfb8aa3b, v10
	v_mul_f32_e32 v17, 0xbfb8aa3b, v16
	v_exp_f32_e32 v13, v13
	v_exp_f32_e32 v17, v17
	v_lshlrev_b32_e32 v11, 16, v67
	v_mul_f32_e32 v6, v2, v6
	v_add_f32_e32 v2, 1.0, v13
	v_add_f32_e32 v13, 1.0, v17
	v_mul_f32_e32 v17, 0xbfb8aa3b, v11
	v_rcp_f32_e32 v2, v2
	v_exp_f32_e32 v17, v17
	v_rcp_f32_e32 v13, v13
	v_lshlrev_b32_e32 v19, 16, v69
	v_mul_f32_e32 v2, v2, v10
	v_add_f32_e32 v10, 1.0, v17
	v_rcp_f32_e32 v10, v10
	v_and_b32_e32 v12, 0xffff0000, v67
	v_mul_f32_e32 v2, v7, v2
	v_mul_f32_e32 v7, v13, v16
	v_mul_f32_e32 v13, 0xbfb8aa3b, v19
	v_and_b32_e32 v20, 0xffff0000, v69
	v_exp_f32_e32 v13, v13
	v_mul_f32_e32 v7, v3, v7
	v_mul_f32_e32 v3, v10, v11
	v_mul_f32_e32 v10, 0xbfb8aa3b, v12
	v_exp_f32_e32 v10, v10
	v_mul_f32_e32 v11, 0xbfb8aa3b, v20
	v_exp_f32_e32 v11, v11
	v_mul_f32_e32 v3, v8, v3
	v_add_f32_e32 v8, 1.0, v13
	v_rcp_f32_e32 v8, v8
	v_add_f32_e32 v10, 1.0, v10
	v_rcp_f32_e32 v10, v10
	v_add_f32_e32 v11, 1.0, v11
	v_rcp_f32_e32 v11, v11
	v_mul_f32_e32 v8, v8, v19
	v_mul_f32_e32 v8, v4, v8
	v_mul_f32_e32 v4, v10, v12
	v_mul_f32_e32 v4, v9, v4
	v_mul_f32_e32 v9, v11, v20
	v_mul_f32_e32 v5, v5, v9
	v_cvt_pk_bf16_f32 v2, v1, v2
	v_cvt_pk_bf16_f32 v3, v3, v4
	v_cvt_pk_bf16_f32 v4, v6, v7
	v_cvt_pk_bf16_f32 v5, v8, v5
	global_store_dwordx4 v[14:15], v[2:5], off offset:256
	s_waitcnt vmcnt(0)
	s_cbranch_scc0 .LBB0_1393
	s_barrier

; #define PG8_STAGE(bufoff, gbase, voff) do { _Pragma("unroll") for (int _i = 0; _i < 2; ++_i) \
;         __builtin_amdgcn_global_load_lds((const unsigned*)((const char*)(gbase) + (voff)[_i]), (LAS unsigned*)(lds + (bufoff) + ldsw + _i * 8192), 16, 0, 0); } while (0)
; #define PG8_LDA(dst, b, h) do { _Pragma("unroll") for (int m = 0; m < 4; ++m) _Pragma("unroll") for (int k = 0; k < 2; ++k) dst[m][k] = *(const LAS bf16x8*)(lds + PG8_SA(b, h) + aoff + m * 2048 + k * 1024); } while (0)
; #define PG8_LDB(dst, b, h) do { _Pragma("unroll") for (int n = 0; n < 2; ++n) _Pragma("unroll") for (int k = 0; k < 2; ++k) dst[n][k] = *(const LAS bf16x8*)(lds + PG8_SB(b, h) + boff + n * 2048 + k * 1024); } while (0)
; #define PG8_MMA(ai, bj, At, Bt) do { __builtin_amdgcn_s_setprio(1); _Pragma("unroll") for (int m = 0; m < 4; ++m) _Pragma("unroll") for (int n = 0; n < 2; ++n) _Pragma("unroll") for (int k = 0; k < 2; ++k) \
;         acc[ai][bj][m][n] = __builtin_amdgcn_mfma_f32_16x16x32_bf16(Bt[n][k], At[m][k], acc[ai][bj][m][n], 0, 0, 0); __builtin_amdgcn_s_setprio(0); } while (0)
; #define PG8_WAIT_L(n) asm volatile("s_waitcnt lgkmcnt(" #n ")" ::: "memory")
; #define PG8_BAR __builtin_amdgcn_s_barrier()
; #define PG8_SCHED __builtin_amdgcn_sched_barrier(0)
; template <class Sched, class Epi>
; __device__ __forceinline__ void gemm_phase(LAS unsigned char* lds, const Sched& S, const Epi& E, const int K, const int lda, const int ldb) {
;     ...
;             const bool last = (t == nt - 2);
;             const char* a1 = cA + (size_t)(t + 1) * kstep;
;             const char* a2 = last ? nA : cA + (size_t)(t + 2) * kstep; const char* b2 = last ? nB : cB + (size_t)(t + 2) * kstep;
;             const char* a3 = a2 + kstep; const char* b3 = b2 + kstep;
;             PG8_LDB(B0, 0, 0); PG8_SCHED; PG8_LDA(At, 0, 0); PG8_STAGE(PG8_SA(1, 1), a1 + hstepA, voffA);
;             PG8_WAIT_L(8); PG8_BAR; PG8_WAIT_L(0); PG8_MMA(0, 0, At, B0); PG8_BAR; PG8_SCHED;
;             PG8_LDB(B1, 0, 1); PG8_STAGE(PG8_SB(0, 0), b2, voffB);
;             PG8_BAR; PG8_WAIT_L(0); PG8_MMA(0, 1, At, B1); PG8_BAR;
;             PG8_LDA(At, 0, 1); PG8_STAGE(PG8_SA(0, 0), a2, voffA);
;             PG8_BAR; PG8_WAIT_L(0); if (!chalf) PG8_MMA(1, 0, At, B0); PG8_BAR; PG8_SCHED;
.Lal_1415:
.LBB0_1415:
	ds_read_b128 v[144:147], v155
	ds_read_b128 v[158:161], v155 offset:1024
	ds_read_b128 v[162:165], v155 offset:2048
	ds_read_b128 v[166:169], v155 offset:3072
	s_add_u32 s34, s28, 0xfffc0080
	s_addc_u32 s35, s29, -1
	s_cmp_eq_u32 s49, 12
	s_cselect_b32 s37, s25, s35
	s_cselect_b32 s36, s24, s34
	s_cselect_b32 s35, s27, s17
	s_cselect_b32 s34, s26, s15
	s_add_i32 m0, s23, 0xc000
	ds_read_b128 v[170:173], v156
	ds_read_b128 v[174:177], v156 offset:1024
	ds_read_b128 v[178:181], v156 offset:2048
	ds_read_b128 v[182:185], v156 offset:3072
	ds_read_b128 v[186:189], v156 offset:4096
	ds_read_b128 v[190:193], v156 offset:5120
	ds_read_b128 v[194:197], v156 offset:6144
	ds_read_b128 v[198:201], v156 offset:7168
	global_load_lds_dwordx4 v140, s[28:29]
	s_add_i32 m0, s23, 0xe000
	s_nop 0
	global_load_lds_dwordx4 v138, s[28:29]
	s_waitcnt lgkmcnt(8)
	s_barrier
	s_waitcnt lgkmcnt(0)
	s_setprio 1
	s_waitcnt lgkmcnt(0)
	v_mfma_f32_16x16x32_bf16 v[118:121], v[144:147], v[170:173], v[118:121]
	v_mfma_f32_16x16x32_bf16 v[114:117], v[162:165], v[170:173], v[114:117]
	v_mfma_f32_16x16x32_bf16 v[110:113], v[144:147], v[178:181], v[110:113]
	v_mfma_f32_16x16x32_bf16 v[106:109], v[162:165], v[178:181], v[106:109]
	v_mfma_f32_16x16x32_bf16 v[94:97], v[144:147], v[186:189], v[94:97]
	v_mfma_f32_16x16x32_bf16 v[90:93], v[162:165], v[186:189], v[90:93]
	v_mfma_f32_16x16x32_bf16 v[78:81], v[144:147], v[194:197], v[78:81]
	v_mfma_f32_16x16x32_bf16 v[74:77], v[162:165], v[194:197], v[74:77]
	v_mfma_f32_16x16x32_bf16 v[118:121], v[158:161], v[174:177], v[118:121]
	v_mfma_f32_16x16x32_bf16 v[114:117], v[166:169], v[174:177], v[114:117]
	v_mfma_f32_16x16x32_bf16 v[110:113], v[158:161], v[182:185], v[110:113]
	v_mfma_f32_16x16x32_bf16 v[106:109], v[166:169], v[182:185], v[106:109]
	v_mfma_f32_16x16x32_bf16 v[94:97], v[158:161], v[190:193], v[94:97]
	v_mfma_f32_16x16x32_bf16 v[90:93], v[166:169], v[190:193], v[90:93]
	v_mfma_f32_16x16x32_bf16 v[78:81], v[158:161], v[198:201], v[78:81]
	v_mfma_f32_16x16x32_bf16 v[74:77], v[166:169], v[198:201], v[74:77]
	s_setprio 0
	s_barrier
	s_add_i32 s50, s46, s38
	s_add_u32 s62, s34, s8
	s_addc_u32 s63, s35, s9
	s_mov_b32 m0, s50
	ds_read_b128 v[202:205], v157
	ds_read_b128 v[206:209], v157 offset:1024
	ds_read_b128 v[210:213], v157 offset:2048
	ds_read_b128 v[214:217], v157 offset:3072
	global_load_lds_dwordx4 v132, s[34:35]
	s_add_u32 s64, s34, s8
	s_addc_u32 s65, s35, s9
	s_add_i32 m0, s50, 0x2000
	s_nop 0
	global_load_lds_dwordx4 v136, s[34:35]
	s_barrier
	s_waitcnt lgkmcnt(0)
	s_setprio 1
	s_waitcnt lgkmcnt(0)
	v_mfma_f32_16x16x32_bf16 v[126:129], v[202:205], v[170:173], v[126:129]
	v_mfma_f32_16x16x32_bf16 v[122:125], v[210:213], v[170:173], v[122:125]
	v_mfma_f32_16x16x32_bf16 v[102:105], v[202:205], v[178:181], v[102:105]
	v_mfma_f32_16x16x32_bf16 v[98:101], v[210:213], v[178:181], v[98:101]
	v_mfma_f32_16x16x32_bf16 v[86:89], v[202:205], v[186:189], v[86:89]
	v_mfma_f32_16x16x32_bf16 v[82:85], v[210:213], v[186:189], v[82:85]
	v_mfma_f32_16x16x32_bf16 v[70:73], v[202:205], v[194:197], v[70:73]
	v_mfma_f32_16x16x32_bf16 v[66:69], v[210:213], v[194:197], v[66:69]
	v_mfma_f32_16x16x32_bf16 v[126:129], v[206:209], v[174:177], v[126:129]
	v_mfma_f32_16x16x32_bf16 v[122:125], v[214:217], v[174:177], v[122:125]
	v_mfma_f32_16x16x32_bf16 v[102:105], v[206:209], v[182:185], v[102:105]
	v_mfma_f32_16x16x32_bf16 v[98:101], v[214:217], v[182:185], v[98:101]
	v_mfma_f32_16x16x32_bf16 v[86:89], v[206:209], v[190:193], v[86:89]
	v_mfma_f32_16x16x32_bf16 v[82:85], v[214:217], v[190:193], v[82:85]
	v_mfma_f32_16x16x32_bf16 v[70:73], v[206:209], v[198:201], v[70:73]
	v_mfma_f32_16x16x32_bf16 v[66:69], v[214:217], v[198:201], v[66:69]
	s_setprio 0
	s_mov_b32 m0, s23
	s_add_u32 s66, s36, s8
	s_addc_u32 s67, s37, s9
	s_barrier
	ds_read_b128 v[170:173], v156 offset:16384
	ds_read_b128 v[174:177], v156 offset:17408
	ds_read_b128 v[178:181], v156 offset:18432
	ds_read_b128 v[182:185], v156 offset:19456
	ds_read_b128 v[186:189], v156 offset:20480
	ds_read_b128 v[190:193], v156 offset:21504
	ds_read_b128 v[194:197], v156 offset:22528
	ds_read_b128 v[198:201], v156 offset:23552
	global_load_lds_dwordx4 v130, s[36:37]
	s_add_u32 s68, s36, s8
	s_addc_u32 s69, s37, s9
	s_mov_b32 m0, s39
	s_nop 0
	global_load_lds_dwordx4 v134, s[36:37]
	s_barrier
	s_waitcnt lgkmcnt(0)
	s_setprio 1
	s_waitcnt lgkmcnt(0)
	v_mfma_f32_16x16x32_bf16 v[62:65], v[144:147], v[170:173], v[62:65]
	v_mfma_f32_16x16x32_bf16 v[58:61], v[162:165], v[170:173], v[58:61]
	v_mfma_f32_16x16x32_bf16 v[46:49], v[144:147], v[178:181], v[46:49]
	v_mfma_f32_16x16x32_bf16 v[42:45], v[162:165], v[178:181], v[42:45]
	v_mfma_f32_16x16x32_bf16 v[30:33], v[144:147], v[186:189], v[30:33]
	v_mfma_f32_16x16x32_bf16 v[26:29], v[162:165], v[186:189], v[26:29]
	v_mfma_f32_16x16x32_bf16 v[14:17], v[144:147], v[194:197], v[14:17]
	v_mfma_f32_16x16x32_bf16 v[10:13], v[162:165], v[194:197], v[10:13]
	v_mfma_f32_16x16x32_bf16 v[62:65], v[158:161], v[174:177], v[62:65]
	v_mfma_f32_16x16x32_bf16 v[58:61], v[166:169], v[174:177], v[58:61]
	v_mfma_f32_16x16x32_bf16 v[46:49], v[158:161], v[182:185], v[46:49]
	v_mfma_f32_16x16x32_bf16 v[42:45], v[166:169], v[182:185], v[42:45]
	v_mfma_f32_16x16x32_bf16 v[30:33], v[158:161], v[190:193], v[30:33]
	v_mfma_f32_16x16x32_bf16 v[26:29], v[166:169], v[190:193], v[26:29]
	v_mfma_f32_16x16x32_bf16 v[14:17], v[158:161], v[198:201], v[14:17]
	v_mfma_f32_16x16x32_bf16 v[10:13], v[166:169], v[198:201], v[10:13]
	s_setprio 0
	s_barrier
; #define PG8_STAGE(bufoff, gbase, voff) do { _Pragma("unroll") for (int _i = 0; _i < 2; ++_i) \
;         __builtin_amdgcn_global_load_lds((const unsigned*)((const char*)(gbase) + (voff)[_i]), (LAS unsigned*)(lds + (bufoff) + ldsw + _i * 8192), 16, 0, 0); } while (0)
; #define PG8_LDA(dst, b, h) do { _Pragma("unroll") for (int m = 0; m < 4; ++m) _Pragma("unroll") for (int k = 0; k < 2; ++k) dst[m][k] = *(const LAS bf16x8*)(lds + PG8_SA(b, h) + aoff + m * 2048 + k * 1024); } while (0)
; #define PG8_LDB(dst, b, h) do { _Pragma("unroll") for (int n = 0; n < 2; ++n) _Pragma("unroll") for (int k = 0; k < 2; ++k) dst[n][k] = *(const LAS bf16x8*)(lds + PG8_SB(b, h) + boff + n * 2048 + k * 1024); } while (0)
; #define PG8_MMA(ai, bj, At, Bt) do { __builtin_amdgcn_s_setprio(1); _Pragma("unroll") for (int m = 0; m < 4; ++m) _Pragma("unroll") for (int n = 0; n < 2; ++n) _Pragma("unroll") for (int k = 0; k < 2; ++k) \
;         acc[ai][bj][m][n] = __builtin_amdgcn_mfma_f32_16x16x32_bf16(Bt[n][k], At[m][k], acc[ai][bj][m][n], 0, 0, 0); __builtin_amdgcn_s_setprio(0); } while (0)
; #define PG8_WAIT_V(n) asm volatile("s_waitcnt vmcnt(" #n ")" ::: "memory")
; #define PG8_WAIT_L(n) asm volatile("s_waitcnt lgkmcnt(" #n ")" ::: "memory")
; #define PG8_BAR __builtin_amdgcn_s_barrier()
; #define PG8_SCHED __builtin_amdgcn_sched_barrier(0)
; template <class Sched, class Epi>
; __device__ __forceinline__ void gemm_phase(LAS unsigned char* lds, const Sched& S, const Epi& E, const int K, const int lda, const int ldb) {
;     ...
;             PG8_STAGE(PG8_SB(0, 1), b2 + hstepB, voffB);
;             PG8_WAIT_V(6); PG8_BAR; if (!chalf) PG8_MMA(1, 1, At, B1); PG8_BAR;
;             PG8_LDB(B0, 1, 0); PG8_SCHED; PG8_LDA(At, 1, 0); PG8_STAGE(PG8_SA(0, 1), a2 + hstepA, voffA);
;             PG8_WAIT_L(8); PG8_BAR; PG8_WAIT_L(0); PG8_MMA(0, 0, At, B0); PG8_BAR; PG8_SCHED;
;             PG8_LDB(B1, 1, 1); PG8_STAGE(PG8_SB(1, 0), b3, voffB);
;             PG8_BAR; PG8_WAIT_L(0); PG8_MMA(0, 1, At, B1); PG8_BAR;
;             PG8_LDA(At, 1, 1); PG8_STAGE(PG8_SA(1, 0), a3, voffA);
;             PG8_BAR; PG8_WAIT_L(0); if (!chalf) PG8_MMA(1, 0, At, B0); PG8_BAR; PG8_SCHED;
	s_add_u32 s50, s34, 0x40000
	s_addc_u32 s51, s35, 0
	s_add_i32 s52, s47, s38
	s_mov_b32 m0, s52
	s_nop 0
	global_load_lds_dwordx4 v132, s[50:51]
	s_add_i32 m0, s52, 0x2000
	s_nop 0
	global_load_lds_dwordx4 v136, s[50:51]
	s_waitcnt vmcnt(6)
	s_barrier
	s_setprio 1
	v_mfma_f32_16x16x32_bf16 v[54:57], v[202:205], v[170:173], v[54:57]
	v_mfma_f32_16x16x32_bf16 v[50:53], v[210:213], v[170:173], v[50:53]
	v_mfma_f32_16x16x32_bf16 v[38:41], v[202:205], v[178:181], v[38:41]
	v_mfma_f32_16x16x32_bf16 v[34:37], v[210:213], v[178:181], v[34:37]
	v_mfma_f32_16x16x32_bf16 v[22:25], v[202:205], v[186:189], v[22:25]
	v_mfma_f32_16x16x32_bf16 v[18:21], v[210:213], v[186:189], v[18:21]
	v_mfma_f32_16x16x32_bf16 v[6:9], v[202:205], v[194:197], v[6:9]
	v_mfma_f32_16x16x32_bf16 v[2:5], v[210:213], v[194:197], v[2:5]
	v_mfma_f32_16x16x32_bf16 v[54:57], v[206:209], v[174:177], v[54:57]
	v_mfma_f32_16x16x32_bf16 v[50:53], v[214:217], v[174:177], v[50:53]
	v_mfma_f32_16x16x32_bf16 v[38:41], v[206:209], v[182:185], v[38:41]
	v_mfma_f32_16x16x32_bf16 v[34:37], v[214:217], v[182:185], v[34:37]
	v_mfma_f32_16x16x32_bf16 v[22:25], v[206:209], v[190:193], v[22:25]
	v_mfma_f32_16x16x32_bf16 v[18:21], v[214:217], v[190:193], v[18:21]
	v_mfma_f32_16x16x32_bf16 v[6:9], v[206:209], v[198:201], v[6:9]
	v_mfma_f32_16x16x32_bf16 v[2:5], v[214:217], v[198:201], v[2:5]
	s_setprio 0
	s_add_i32 s50, 16, 0x18000
	v_add_u32_e32 v166, s50, v150
	s_barrier
	ds_read_b128 v[144:147], v166
	ds_read_b128 v[158:161], v166 offset:1024
	ds_read_b128 v[162:165], v166 offset:2048
	ds_read_b128 v[166:169], v166 offset:3072
	s_add_u32 s36, s36, 0x40000
	s_addc_u32 s37, s37, 0
	s_mov_b32 m0, s40
	ds_read_b128 v[170:173], v156 offset:32768
	ds_read_b128 v[174:177], v156 offset:33792
	ds_read_b128 v[178:181], v156 offset:34816
	ds_read_b128 v[182:185], v156 offset:35840
	ds_read_b128 v[186:189], v156 offset:36864
	ds_read_b128 v[190:193], v156 offset:37888
	ds_read_b128 v[194:197], v156 offset:38912
	ds_read_b128 v[198:201], v156 offset:39936
	global_load_lds_dwordx4 v130, s[36:37]
	s_mov_b32 m0, s41
	s_nop 0
	global_load_lds_dwordx4 v134, s[36:37]
	s_waitcnt lgkmcnt(8)
	s_barrier
	s_waitcnt lgkmcnt(0)
	s_setprio 1
	s_waitcnt lgkmcnt(0)
	v_mfma_f32_16x16x32_bf16 v[118:121], v[144:147], v[170:173], v[118:121]
	v_mfma_f32_16x16x32_bf16 v[114:117], v[162:165], v[170:173], v[114:117]
	v_mfma_f32_16x16x32_bf16 v[110:113], v[144:147], v[178:181], v[110:113]
	v_mfma_f32_16x16x32_bf16 v[106:109], v[162:165], v[178:181], v[106:109]
	v_mfma_f32_16x16x32_bf16 v[94:97], v[144:147], v[186:189], v[94:97]
	v_mfma_f32_16x16x32_bf16 v[90:93], v[162:165], v[186:189], v[90:93]
	v_mfma_f32_16x16x32_bf16 v[78:81], v[144:147], v[194:197], v[78:81]
	v_mfma_f32_16x16x32_bf16 v[74:77], v[162:165], v[194:197], v[74:77]
	v_mfma_f32_16x16x32_bf16 v[118:121], v[158:161], v[174:177], v[118:121]
	v_mfma_f32_16x16x32_bf16 v[114:117], v[166:169], v[174:177], v[114:117]
	v_mfma_f32_16x16x32_bf16 v[110:113], v[158:161], v[182:185], v[110:113]
	v_mfma_f32_16x16x32_bf16 v[106:109], v[166:169], v[182:185], v[106:109]
	v_mfma_f32_16x16x32_bf16 v[94:97], v[158:161], v[190:193], v[94:97]
	v_mfma_f32_16x16x32_bf16 v[90:93], v[166:169], v[190:193], v[90:93]
	v_mfma_f32_16x16x32_bf16 v[78:81], v[158:161], v[198:201], v[78:81]
	v_mfma_f32_16x16x32_bf16 v[74:77], v[166:169], v[198:201], v[74:77]
	s_setprio 0
	s_barrier
	s_add_i32 s36, 16, 0x1c000
	s_add_i32 s37, s50, s38
	v_add_u32_e32 v214, s36, v150
	s_mov_b32 m0, s37
	ds_read_b128 v[202:205], v214
	ds_read_b128 v[206:209], v214 offset:1024
	ds_read_b128 v[210:213], v214 offset:2048
	ds_read_b128 v[214:217], v214 offset:3072
	global_load_lds_dwordx4 v132, s[62:63]
	s_add_i32 m0, s37, 0x2000
	s_nop 0
	global_load_lds_dwordx4 v136, s[64:65]
	s_barrier
	s_waitcnt lgkmcnt(0)
	s_setprio 1
	s_waitcnt lgkmcnt(0)
	v_mfma_f32_16x16x32_bf16 v[126:129], v[202:205], v[170:173], v[126:129]
	v_mfma_f32_16x16x32_bf16 v[122:125], v[210:213], v[170:173], v[122:125]
	v_mfma_f32_16x16x32_bf16 v[102:105], v[202:205], v[178:181], v[102:105]
	v_mfma_f32_16x16x32_bf16 v[98:101], v[210:213], v[178:181], v[98:101]
	v_mfma_f32_16x16x32_bf16 v[86:89], v[202:205], v[186:189], v[86:89]
	v_mfma_f32_16x16x32_bf16 v[82:85], v[210:213], v[186:189], v[82:85]
	v_mfma_f32_16x16x32_bf16 v[70:73], v[202:205], v[194:197], v[70:73]
	v_mfma_f32_16x16x32_bf16 v[66:69], v[210:213], v[194:197], v[66:69]
	v_mfma_f32_16x16x32_bf16 v[126:129], v[206:209], v[174:177], v[126:129]
	v_mfma_f32_16x16x32_bf16 v[122:125], v[214:217], v[174:177], v[122:125]
	v_mfma_f32_16x16x32_bf16 v[102:105], v[206:209], v[182:185], v[102:105]
	v_mfma_f32_16x16x32_bf16 v[98:101], v[214:217], v[182:185], v[98:101]
	v_mfma_f32_16x16x32_bf16 v[86:89], v[206:209], v[190:193], v[86:89]
	v_mfma_f32_16x16x32_bf16 v[82:85], v[214:217], v[190:193], v[82:85]
	v_mfma_f32_16x16x32_bf16 v[70:73], v[206:209], v[198:201], v[70:73]
	v_mfma_f32_16x16x32_bf16 v[66:69], v[214:217], v[198:201], v[66:69]
	s_setprio 0
	s_mov_b32 m0, s42
	s_barrier
	ds_read_b128 v[170:173], v156 offset:49152
	ds_read_b128 v[174:177], v156 offset:50176
	ds_read_b128 v[178:181], v156 offset:51200
	ds_read_b128 v[182:185], v156 offset:52224
	ds_read_b128 v[186:189], v156 offset:53248
	ds_read_b128 v[190:193], v156 offset:54272
	ds_read_b128 v[194:197], v156 offset:55296
	ds_read_b128 v[198:201], v156 offset:56320
	global_load_lds_dwordx4 v130, s[66:67]
	s_mov_b32 m0, s43
	s_nop 0
	global_load_lds_dwordx4 v134, s[68:69]
	s_barrier
; __device__ __forceinline__ u32x4 pack8(const float (&f)[8]) { u32x4 r; r[0] = cvt_pk_bf16(f[0], f[1]); r[1] = cvt_pk_bf16(f[2], f[3]); r[2] = cvt_pk_bf16(f[4], f[5]); r[3] = cvt_pk_bf16(f[6], f[7]); return r; }
; #define PG8_STAGE(bufoff, gbase, voff) do { _Pragma("unroll") for (int _i = 0; _i < 2; ++_i) \
;         __builtin_amdgcn_global_load_lds((const unsigned*)((const char*)(gbase) + (voff)[_i]), (LAS unsigned*)(lds + (bufoff) + ldsw + _i * 8192), 16, 0, 0); } while (0)
; #define PG8_MMA(ai, bj, At, Bt) do { __builtin_amdgcn_s_setprio(1); _Pragma("unroll") for (int m = 0; m < 4; ++m) _Pragma("unroll") for (int n = 0; n < 2; ++n) _Pragma("unroll") for (int k = 0; k < 2; ++k) \
;         acc[ai][bj][m][n] = __builtin_amdgcn_mfma_f32_16x16x32_bf16(Bt[n][k], At[m][k], acc[ai][bj][m][n], 0, 0, 0); __builtin_amdgcn_s_setprio(0); } while (0)
; #define PG8_WAIT_V(n) asm volatile("s_waitcnt vmcnt(" #n ")" ::: "memory")
; #define PG8_WAIT_L(n) asm volatile("s_waitcnt lgkmcnt(" #n ")" ::: "memory")
; template <class Sched, class Epi>
; __device__ __forceinline__ void gemm_phase(LAS unsigned char* lds, const Sched& S, const Epi& E, const int K, const int lda, const int ldb) {
;     ...
;             PG8_BAR; PG8_WAIT_L(0); if (!chalf) PG8_MMA(1, 0, At, B0); PG8_BAR; PG8_SCHED;
;             PG8_STAGE(PG8_SB(1, 1), b3 + hstepB, voffB);
;             PG8_WAIT_V(6); PG8_BAR; if (!chalf) PG8_MMA(1, 1, At, B1); PG8_BAR;
;         }
;     __device__ __forceinline__ void operator()(EPI_ARGS) const {
;         const int col = u.pn * 128 + wc * 32 + 8 * fq;
; #pragma unroll
;         for (int ai = 0; ai < 2; ++ai) if (ai == 0 || !u.half) { u32x4 zz[4];
; #pragma unroll
;             for (int m = 0; m < 4; ++m) zz[m] = *(const u32x4*)(parts + E_PZB + (size_t)EPI_ROW * 1024 + col);
; #pragma unroll
;             for (int m = 0; m < 4; ++m) { float z[8]; unpack8(zz[m], z);
;                 const f32x4 a0 = acc[ai][0][m][0], a1 = acc[ai][0][m][1], b0 = acc[ai][1][m][0], b1 = acc[ai][1][m][1]; float o[8];
; #pragma unroll
;                 for (int j = 0; j < 4; ++j) { o[j] = a0[j] * z[j] * __builtin_amdgcn_rcpf((1.0f + __expf(-b0[j])) * (1.0f + __expf(-z[j]))); o[4 + j] = a1[j] * z[4 + j] * __builtin_amdgcn_rcpf((1.0f + __expf(-b1[j])) * (1.0f + __expf(-z[4 + j]))); }
;                 *(u32x4*)(O + (size_t)EPI_ROW * 1024 + col) = pack8(o); } }
	s_waitcnt lgkmcnt(0)
	s_setprio 1
	s_waitcnt lgkmcnt(0)
	v_mfma_f32_16x16x32_bf16 v[62:65], v[144:147], v[170:173], v[62:65]
	v_mfma_f32_16x16x32_bf16 v[58:61], v[162:165], v[170:173], v[58:61]
	v_mfma_f32_16x16x32_bf16 v[46:49], v[144:147], v[178:181], v[46:49]
	v_mfma_f32_16x16x32_bf16 v[42:45], v[162:165], v[178:181], v[42:45]
	v_mfma_f32_16x16x32_bf16 v[30:33], v[144:147], v[186:189], v[30:33]
	v_mfma_f32_16x16x32_bf16 v[26:29], v[162:165], v[186:189], v[26:29]
	v_mfma_f32_16x16x32_bf16 v[14:17], v[144:147], v[194:197], v[14:17]
	v_mfma_f32_16x16x32_bf16 v[10:13], v[162:165], v[194:197], v[10:13]
	v_mfma_f32_16x16x32_bf16 v[62:65], v[158:161], v[174:177], v[62:65]
	v_mfma_f32_16x16x32_bf16 v[58:61], v[166:169], v[174:177], v[58:61]
	v_mfma_f32_16x16x32_bf16 v[46:49], v[158:161], v[182:185], v[46:49]
	v_mfma_f32_16x16x32_bf16 v[42:45], v[166:169], v[182:185], v[42:45]
	v_mfma_f32_16x16x32_bf16 v[30:33], v[158:161], v[190:193], v[30:33]
	v_mfma_f32_16x16x32_bf16 v[26:29], v[166:169], v[190:193], v[26:29]
	v_mfma_f32_16x16x32_bf16 v[14:17], v[158:161], v[198:201], v[14:17]
	v_mfma_f32_16x16x32_bf16 v[10:13], v[166:169], v[198:201], v[10:13]
	s_setprio 0
	s_barrier
	s_add_u32 s34, s34, 0x40080
	s_addc_u32 s35, s35, 0
	s_add_i32 s36, s36, s38
	s_mov_b32 m0, s36
	s_nop 0
	global_load_lds_dwordx4 v132, s[34:35]
	s_add_i32 m0, s36, 0x2000
	s_nop 0
	global_load_lds_dwordx4 v136, s[34:35]
	s_waitcnt vmcnt(6)
	s_barrier
	s_setprio 1
	v_mfma_f32_16x16x32_bf16 v[54:57], v[202:205], v[170:173], v[54:57]
	v_mfma_f32_16x16x32_bf16 v[50:53], v[210:213], v[170:173], v[50:53]
	v_mfma_f32_16x16x32_bf16 v[38:41], v[202:205], v[178:181], v[38:41]
	v_mfma_f32_16x16x32_bf16 v[34:37], v[210:213], v[178:181], v[34:37]
	v_mfma_f32_16x16x32_bf16 v[22:25], v[202:205], v[186:189], v[22:25]
	v_mfma_f32_16x16x32_bf16 v[18:21], v[210:213], v[186:189], v[18:21]
	v_mfma_f32_16x16x32_bf16 v[6:9], v[202:205], v[194:197], v[6:9]
	v_mfma_f32_16x16x32_bf16 v[2:5], v[210:213], v[194:197], v[2:5]
	v_mfma_f32_16x16x32_bf16 v[54:57], v[206:209], v[174:177], v[54:57]
	v_mfma_f32_16x16x32_bf16 v[50:53], v[214:217], v[174:177], v[50:53]
	v_mfma_f32_16x16x32_bf16 v[38:41], v[206:209], v[182:185], v[38:41]
	v_mfma_f32_16x16x32_bf16 v[34:37], v[214:217], v[182:185], v[34:37]
	v_mfma_f32_16x16x32_bf16 v[22:25], v[206:209], v[190:193], v[22:25]
	v_mfma_f32_16x16x32_bf16 v[18:21], v[214:217], v[190:193], v[18:21]
	v_mfma_f32_16x16x32_bf16 v[6:9], v[206:209], v[198:201], v[6:9]
	v_mfma_f32_16x16x32_bf16 v[2:5], v[214:217], v[198:201], v[2:5]
	s_setprio 0
	s_add_i32 s49, s49, 2
	s_add_u32 s15, s15, 0x100
	s_addc_u32 s17, s17, 0
	s_add_u32 s28, s28, 0x100
	s_addc_u32 s29, s29, 0
	s_cmp_gt_u32 s49, 13
	s_barrier
	s_cbranch_scc0 .LBB0_1415
	v_lshl_or_b32 v144, s48, 7, v154
	v_ashrrev_i32_e32 v145, 31, v144
	v_add_u32_e32 v148, s22, v1
	v_lshlrev_b64 v[144:145], 1, v[144:145]
	v_ashrrev_i32_e32 v149, 31, v148
	v_lshl_add_u64 v[146:147], s[4:5], 0, v[144:145]
	v_lshlrev_b64 v[166:167], 11, v[148:149]
	v_lshl_add_u64 v[158:159], v[146:147], 0, v[166:167]
	global_load_dwordx4 v[158:161], v[158:159], off
	v_mul_f32_e32 v149, 0xbfb8aa3b, v122
	v_mul_f32_e32 v123, 0xbfb8aa3b, v123
	v_add_u32_e32 v122, 16, v148
	v_exp_f32_e32 v174, v123
	v_ashrrev_i32_e32 v123, 31, v122
	v_lshlrev_b64 v[122:123], 11, v[122:123]
	v_mul_f32_e32 v126, 0xbfb8aa3b, v126
	v_mul_f32_e32 v127, 0xbfb8aa3b, v127
	v_mul_f32_e32 v128, 0xbfb8aa3b, v128
	v_mul_f32_e32 v129, 0xbfb8aa3b, v129
	v_lshl_add_u64 v[122:123], v[146:147], 0, v[122:123]
	v_exp_f32_e32 v168, v126
	v_exp_f32_e32 v172, v127
	v_exp_f32_e32 v176, v128
	v_exp_f32_e32 v180, v129
	global_load_dwordx4 v[126:129], v[122:123], off
	v_mul_f32_e32 v163, 0xbfb8aa3b, v124
	v_mul_f32_e32 v125, 0xbfb8aa3b, v125
	v_add_u32_e32 v124, 32, v148
	v_add_u32_e32 v162, 48, v148
	v_exp_f32_e32 v178, v163
	v_exp_f32_e32 v182, v125
	v_ashrrev_i32_e32 v125, 31, v124
	v_ashrrev_i32_e32 v163, 31, v162
	v_lshlrev_b64 v[122:123], 11, v[124:125]
	v_lshlrev_b64 v[124:125], 11, v[162:163]
	v_lshl_add_u64 v[122:123], v[146:147], 0, v[122:123]
	v_lshl_add_u64 v[124:125], v[146:147], 0, v[124:125]
	global_load_dwordx4 v[162:165], v[122:123], off
	s_nop 0
	global_load_dwordx4 v[122:125], v[124:125], off
	v_exp_f32_e32 v170, v149
	v_mul_f32_e32 v102, 0xbfb8aa3b, v102
	v_mul_f32_e32 v98, 0xbfb8aa3b, v98
	v_mul_f32_e32 v100, 0xbfb8aa3b, v100
	v_mul_f32_e32 v86, 0xbfb8aa3b, v86
	v_mul_f32_e32 v82, 0xbfb8aa3b, v82
	v_mul_f32_e32 v84, 0xbfb8aa3b, v84
	v_mul_f32_e32 v70, 0xbfb8aa3b, v70
	v_mul_f32_e32 v66, 0xbfb8aa3b, v66
	v_mul_f32_e32 v68, 0xbfb8aa3b, v68
	v_mul_f32_e32 v54, 0xbfb8aa3b, v54
	v_mul_f32_e32 v50, 0xbfb8aa3b, v50
	v_mul_f32_e32 v52, 0xbfb8aa3b, v52
	v_mul_f32_e32 v38, 0xbfb8aa3b, v38
	v_mul_f32_e32 v34, 0xbfb8aa3b, v34
	v_mul_f32_e32 v36, 0xbfb8aa3b, v36
	v_mul_f32_e32 v22, 0xbfb8aa3b, v22
	v_mul_f32_e32 v18, 0xbfb8aa3b, v18
	v_mul_f32_e32 v20, 0xbfb8aa3b, v20
	v_mul_f32_e32 v6, 0xbfb8aa3b, v6
	v_mul_f32_e32 v2, 0xbfb8aa3b, v2
	v_mul_f32_e32 v4, 0xbfb8aa3b, v4
	s_and_b64 vcc, exec, s[12:13]
	s_mov_b32 s48, s14
	s_mov_b64 s[34:35], s[20:21]
	s_mov_b64 s[28:29], s[18:19]
	s_waitcnt vmcnt(0)
; __device__ __forceinline__ u32x4 pack8(const float (&f)[8]) { u32x4 r; r[0] = cvt_pk_bf16(f[0], f[1]); r[1] = cvt_pk_bf16(f[2], f[3]); r[2] = cvt_pk_bf16(f[4], f[5]); r[3] = cvt_pk_bf16(f[6], f[7]); return r; }
;     __device__ __forceinline__ void operator()(EPI_ARGS) const {
;     ...
;         for (int ai = 0; ai < 2; ++ai) if (ai == 0 || !u.half) { u32x4 zz[4];
; #pragma unroll
;             for (int m = 0; m < 4; ++m) zz[m] = *(const u32x4*)(parts + E_PZB + (size_t)EPI_ROW * 1024 + col);
; #pragma unroll
;             for (int m = 0; m < 4; ++m) { float z[8]; unpack8(zz[m], z);
;                 const f32x4 a0 = acc[ai][0][m][0], a1 = acc[ai][0][m][1], b0 = acc[ai][1][m][0], b1 = acc[ai][1][m][1]; float o[8];
; #pragma unroll
;                 for (int j = 0; j < 4; ++j) { o[j] = a0[j] * z[j] * __builtin_amdgcn_rcpf((1.0f + __expf(-b0[j])) * (1.0f + __expf(-z[j]))); o[4 + j] = a1[j] * z[4 + j] * __builtin_amdgcn_rcpf((1.0f + __expf(-b1[j])) * (1.0f + __expf(-z[4 + j]))); }
;                 *(u32x4*)(O + (size_t)EPI_ROW * 1024 + col) = pack8(o); } }
	v_lshlrev_b32_e32 v149, 16, v158
	v_and_b32_e32 v158, 0xffff0000, v158
	v_lshlrev_b32_e32 v169, 16, v159
	v_and_b32_e32 v184, 0xffff0000, v159
	v_lshlrev_b32_e32 v159, 16, v160
	v_and_b32_e32 v160, 0xffff0000, v160
	v_lshlrev_b32_e32 v171, 16, v161
	v_mul_f32_e32 v186, v118, v149
	v_mul_f32_e32 v118, 0xbfb8aa3b, v149
	v_mul_f32_e32 v149, v114, v159
	v_mul_f32_e32 v114, 0xbfb8aa3b, v159
	v_mul_f32_e32 v187, v119, v158
	v_mul_f32_e32 v119, 0xbfb8aa3b, v158
	v_mul_f32_e32 v188, v115, v160
	v_mul_f32_e32 v115, 0xbfb8aa3b, v160
	v_mul_f32_e32 v158, 0xbfb8aa3b, v169
	v_mul_f32_e32 v159, 0xbfb8aa3b, v171
	v_mul_f32_e32 v120, v120, v169
	v_mul_f32_e32 v116, v116, v171
	v_exp_f32_e32 v169, v118
	v_exp_f32_e32 v171, v114
	v_exp_f32_e32 v173, v119
	v_exp_f32_e32 v175, v115
	v_exp_f32_e32 v177, v158
	v_exp_f32_e32 v179, v159
	v_and_b32_e32 v185, 0xffff0000, v161
	v_mul_f32_e32 v160, 0xbfb8aa3b, v184
	v_mul_f32_e32 v161, 0xbfb8aa3b, v185
	v_exp_f32_e32 v181, v160
	v_exp_f32_e32 v183, v161
	v_pk_add_f32 v[114:115], v[168:169], 1.0 op_sel_hi:[1,0]
	v_pk_add_f32 v[118:119], v[170:171], 1.0 op_sel_hi:[1,0]
	v_pk_add_f32 v[158:159], v[172:173], 1.0 op_sel_hi:[1,0]
	v_pk_add_f32 v[160:161], v[174:175], 1.0 op_sel_hi:[1,0]
	v_pk_add_f32 v[168:169], v[176:177], 1.0 op_sel_hi:[1,0]
	v_pk_add_f32 v[170:171], v[178:179], 1.0 op_sel_hi:[1,0]
	v_mul_f32_e32 v114, v114, v115
	v_mul_f32_e32 v115, v118, v119
	v_mul_f32_e32 v118, v158, v159
	v_mul_f32_e32 v119, v160, v161
	v_mul_f32_e32 v158, v168, v169
	v_mul_f32_e32 v159, v170, v171
	v_rcp_f32_e32 v115, v115
	v_rcp_f32_e32 v118, v118
	v_rcp_f32_e32 v119, v119
	v_rcp_f32_e32 v158, v158
	v_rcp_f32_e32 v159, v159
	v_pk_add_f32 v[172:173], v[180:181], 1.0 op_sel_hi:[1,0]
	v_pk_add_f32 v[174:175], v[182:183], 1.0 op_sel_hi:[1,0]
	v_mul_f32_e32 v160, v172, v173
	v_rcp_f32_e32 v114, v114
	v_mul_f32_e32 v149, v149, v115
	v_mul_f32_e32 v115, v187, v118
	v_mul_f32_e32 v118, v188, v119
	v_mul_f32_e32 v119, v120, v158
	v_mul_f32_e32 v120, v116, v159
	v_mul_f32_e32 v116, v174, v175
	v_rcp_f32_e32 v160, v160
	v_rcp_f32_e32 v116, v116
	v_mul_f32_e32 v114, v186, v114
	v_mul_f32_e32 v121, v121, v184
	v_mul_f32_e32 v117, v117, v185
	v_mul_f32_e32 v121, v121, v160
	v_mul_f32_e32 v117, v117, v116
	v_cvt_pk_bf16_f32 v114, v114, v115
	v_cvt_pk_bf16_f32 v115, v119, v121
	v_cvt_pk_bf16_f32 v116, v149, v118
	v_lshl_add_u64 v[118:119], s[6:7], 0, v[166:167]
	v_lshl_add_u64 v[118:119], v[118:119], 0, v[144:145]
	v_cvt_pk_bf16_f32 v117, v120, v117
	global_store_dwordx4 v[118:119], v[114:117], off
	v_lshlrev_b32_e32 v118, 16, v126
	v_and_b32_e32 v119, 0xffff0000, v126
	v_lshlrev_b32_e32 v126, 16, v128
	v_exp_f32_e32 v114, v102
	v_mul_f32_e32 v102, 0xbfb8aa3b, v118
	v_exp_f32_e32 v115, v102
	v_exp_f32_e32 v116, v98
	v_mul_f32_e32 v98, 0xbfb8aa3b, v126
	v_exp_f32_e32 v117, v98
	v_pk_add_f32 v[114:115], v[114:115], 1.0 op_sel_hi:[1,0]
	v_mul_f32_e32 v110, v110, v118
	v_mul_f32_e32 v98, v114, v115
	v_pk_add_f32 v[114:115], v[116:117], 1.0 op_sel_hi:[1,0]
	v_rcp_f32_e32 v98, v98
	v_mul_f32_e32 v102, v114, v115
	v_rcp_f32_e32 v102, v102
	v_lshlrev_b32_e32 v120, 16, v127
	v_mul_f32_e32 v110, v110, v98
	v_mul_f32_e32 v98, v106, v126
	v_mul_f32_e32 v106, v98, v102
	v_mul_f32_e32 v98, 0xbfb8aa3b, v103
	v_and_b32_e32 v121, 0xffff0000, v127
	v_and_b32_e32 v127, 0xffff0000, v128
	v_exp_f32_e32 v102, v98
	v_mul_f32_e32 v98, 0xbfb8aa3b, v119
	v_exp_f32_e32 v103, v98
	v_mul_f32_e32 v98, 0xbfb8aa3b, v99
	v_mul_f32_e32 v99, 0xbfb8aa3b, v127
	v_exp_f32_e32 v98, v98
	v_exp_f32_e32 v99, v99
	v_pk_add_f32 v[102:103], v[102:103], 1.0 op_sel_hi:[1,0]
	v_lshlrev_b32_e32 v128, 16, v129
	v_mul_f32_e32 v102, v102, v103
	v_pk_add_f32 v[98:99], v[98:99], 1.0 op_sel_hi:[1,0]
	v_rcp_f32_e32 v102, v102
	v_mul_f32_e32 v98, v98, v99
	v_rcp_f32_e32 v98, v98
	v_mul_f32_e32 v99, v111, v119
	v_mul_f32_e32 v111, v99, v102
	v_mul_f32_e32 v99, v107, v127
	v_mul_f32_e32 v107, v99, v98
	v_mul_f32_e32 v98, 0xbfb8aa3b, v104
	v_mul_f32_e32 v99, 0xbfb8aa3b, v120
	v_exp_f32_e32 v98, v98
	v_exp_f32_e32 v99, v99
	v_exp_f32_e32 v102, v100
	v_mul_f32_e32 v100, 0xbfb8aa3b, v128
	v_exp_f32_e32 v103, v100
	v_pk_add_f32 v[98:99], v[98:99], 1.0 op_sel_hi:[1,0]
	v_and_b32_e32 v129, 0xffff0000, v129
	v_mul_f32_e32 v98, v98, v99
	v_rcp_f32_e32 v100, v98
	v_pk_add_f32 v[98:99], v[102:103], 1.0 op_sel_hi:[1,0]
	s_nop 0
	v_mul_f32_e32 v98, v98, v99
	v_rcp_f32_e32 v98, v98
	v_mul_f32_e32 v99, v112, v120
	v_mul_f32_e32 v102, v99, v100
	v_mul_f32_e32 v99, v108, v128
	v_mul_f32_e32 v103, v99, v98
	v_mul_f32_e32 v98, 0xbfb8aa3b, v105
	v_mul_f32_e32 v99, 0xbfb8aa3b, v121
	v_exp_f32_e32 v98, v98
	v_exp_f32_e32 v99, v99
	v_mul_f32_e32 v100, 0xbfb8aa3b, v101
	v_mul_f32_e32 v101, 0xbfb8aa3b, v129
	v_exp_f32_e32 v100, v100
	v_exp_f32_e32 v101, v101
	v_pk_add_f32 v[98:99], v[98:99], 1.0 op_sel_hi:[1,0]
	v_lshlrev_b32_e32 v108, 16, v165
	v_mul_f32_e32 v98, v98, v99
	v_rcp_f32_e32 v104, v98
	v_pk_add_f32 v[98:99], v[100:101], 1.0 op_sel_hi:[1,0]
	v_mul_f32_e32 v100, v109, v129
	v_mul_f32_e32 v98, v98, v99
	v_rcp_f32_e32 v98, v98
	v_mul_f32_e32 v99, v113, v121
	v_mul_f32_e32 v99, v99, v104
	v_lshlrev_b32_e32 v104, 16, v163
	v_mul_f32_e32 v101, v100, v98
	v_cvt_pk_bf16_f32 v98, v110, v111
	v_cvt_pk_bf16_f32 v99, v102, v99
	v_add_u32_e32 v102, s22, v151
	v_cvt_pk_bf16_f32 v100, v106, v107
	v_cvt_pk_bf16_f32 v101, v103, v101
	v_ashrrev_i32_e32 v103, 31, v102
	v_lshlrev_b64 v[102:103], 11, v[102:103]
	v_lshl_add_u64 v[102:103], s[6:7], 0, v[102:103]
	v_lshl_add_u64 v[102:103], v[102:103], 0, v[144:145]
	global_store_dwordx4 v[102:103], v[98:101], off
	v_lshlrev_b32_e32 v102, 16, v162
	v_lshlrev_b32_e32 v106, 16, v164
; __device__ __forceinline__ u32x4 pack8(const float (&f)[8]) { u32x4 r; r[0] = cvt_pk_bf16(f[0], f[1]); r[1] = cvt_pk_bf16(f[2], f[3]); r[2] = cvt_pk_bf16(f[4], f[5]); r[3] = cvt_pk_bf16(f[6], f[7]); return r; }
;     __device__ __forceinline__ void operator()(EPI_ARGS) const {
;     ...
;         for (int ai = 0; ai < 2; ++ai) if (ai == 0 || !u.half) { u32x4 zz[4];
; #pragma unroll
;             for (int m = 0; m < 4; ++m) zz[m] = *(const u32x4*)(parts + E_PZB + (size_t)EPI_ROW * 1024 + col);
; #pragma unroll
;             for (int m = 0; m < 4; ++m) { float z[8]; unpack8(zz[m], z);
;                 const f32x4 a0 = acc[ai][0][m][0], a1 = acc[ai][0][m][1], b0 = acc[ai][1][m][0], b1 = acc[ai][1][m][1]; float o[8];
; #pragma unroll
;                 for (int j = 0; j < 4; ++j) { o[j] = a0[j] * z[j] * __builtin_amdgcn_rcpf((1.0f + __expf(-b0[j])) * (1.0f + __expf(-z[j]))); o[4 + j] = a1[j] * z[4 + j] * __builtin_amdgcn_rcpf((1.0f + __expf(-b1[j])) * (1.0f + __expf(-z[4 + j]))); }
;                 *(u32x4*)(O + (size_t)EPI_ROW * 1024 + col) = pack8(o); } }
	v_exp_f32_e32 v98, v86
	v_mul_f32_e32 v86, 0xbfb8aa3b, v102
	v_exp_f32_e32 v99, v86
	v_exp_f32_e32 v100, v82
	v_mul_f32_e32 v82, 0xbfb8aa3b, v106
	v_exp_f32_e32 v101, v82
	v_pk_add_f32 v[98:99], v[98:99], 1.0 op_sel_hi:[1,0]
	v_mul_f32_e32 v94, v94, v102
	v_mul_f32_e32 v82, v98, v99
	v_pk_add_f32 v[98:99], v[100:101], 1.0 op_sel_hi:[1,0]
	v_rcp_f32_e32 v82, v82
	v_mul_f32_e32 v86, v98, v99
	v_rcp_f32_e32 v86, v86
	v_and_b32_e32 v103, 0xffff0000, v162
	v_mul_f32_e32 v94, v94, v82
	v_mul_f32_e32 v82, v90, v106
	v_mul_f32_e32 v90, v82, v86
	v_mul_f32_e32 v82, 0xbfb8aa3b, v87
	v_and_b32_e32 v107, 0xffff0000, v164
	v_exp_f32_e32 v86, v82
	v_mul_f32_e32 v82, 0xbfb8aa3b, v103
	v_exp_f32_e32 v87, v82
	v_mul_f32_e32 v82, 0xbfb8aa3b, v83
	v_mul_f32_e32 v83, 0xbfb8aa3b, v107
	v_exp_f32_e32 v82, v82
	v_exp_f32_e32 v83, v83
	v_pk_add_f32 v[86:87], v[86:87], 1.0 op_sel_hi:[1,0]
	v_and_b32_e32 v105, 0xffff0000, v163
	v_mul_f32_e32 v86, v86, v87
	v_pk_add_f32 v[82:83], v[82:83], 1.0 op_sel_hi:[1,0]
	v_rcp_f32_e32 v86, v86
	v_mul_f32_e32 v82, v82, v83
	v_rcp_f32_e32 v82, v82
	v_mul_f32_e32 v83, v95, v103
	v_mul_f32_e32 v95, v83, v86
	v_mul_f32_e32 v83, v91, v107
	v_mul_f32_e32 v91, v83, v82
	v_mul_f32_e32 v82, 0xbfb8aa3b, v88
	v_mul_f32_e32 v83, 0xbfb8aa3b, v104
	v_exp_f32_e32 v82, v82
	v_exp_f32_e32 v83, v83
	v_exp_f32_e32 v86, v84
	v_mul_f32_e32 v84, 0xbfb8aa3b, v108
	v_exp_f32_e32 v87, v84
	v_pk_add_f32 v[82:83], v[82:83], 1.0 op_sel_hi:[1,0]
	v_and_b32_e32 v109, 0xffff0000, v165
	v_mul_f32_e32 v82, v82, v83
	v_rcp_f32_e32 v84, v82
	v_pk_add_f32 v[82:83], v[86:87], 1.0 op_sel_hi:[1,0]
	s_nop 0
	v_mul_f32_e32 v82, v82, v83
	v_rcp_f32_e32 v82, v82
	v_mul_f32_e32 v83, v96, v104
	v_mul_f32_e32 v86, v83, v84
	v_mul_f32_e32 v83, v92, v108
	v_mul_f32_e32 v87, v83, v82
	v_mul_f32_e32 v82, 0xbfb8aa3b, v89
	v_mul_f32_e32 v83, 0xbfb8aa3b, v105
	v_exp_f32_e32 v82, v82
	v_exp_f32_e32 v83, v83
	v_mul_f32_e32 v84, 0xbfb8aa3b, v85
	v_mul_f32_e32 v85, 0xbfb8aa3b, v109
	v_exp_f32_e32 v84, v84
	v_exp_f32_e32 v85, v85
	v_pk_add_f32 v[82:83], v[82:83], 1.0 op_sel_hi:[1,0]
	v_lshlrev_b32_e32 v92, 16, v125
	v_mul_f32_e32 v82, v82, v83
	v_rcp_f32_e32 v88, v82
	v_pk_add_f32 v[82:83], v[84:85], 1.0 op_sel_hi:[1,0]
	v_mul_f32_e32 v84, v93, v109
	v_mul_f32_e32 v82, v82, v83
	v_rcp_f32_e32 v82, v82
	v_mul_f32_e32 v83, v97, v105
	v_mul_f32_e32 v83, v83, v88
	v_lshlrev_b32_e32 v88, 16, v123
	v_mul_f32_e32 v85, v84, v82
	v_cvt_pk_bf16_f32 v82, v94, v95
	v_cvt_pk_bf16_f32 v83, v86, v83
	v_add_u32_e32 v86, s22, v152
	v_cvt_pk_bf16_f32 v84, v90, v91
	v_cvt_pk_bf16_f32 v85, v87, v85
	v_ashrrev_i32_e32 v87, 31, v86
	v_lshlrev_b64 v[86:87], 11, v[86:87]
	v_lshl_add_u64 v[86:87], s[6:7], 0, v[86:87]
	v_lshl_add_u64 v[86:87], v[86:87], 0, v[144:145]
	global_store_dwordx4 v[86:87], v[82:85], off
	v_lshlrev_b32_e32 v86, 16, v122
	v_lshlrev_b32_e32 v90, 16, v124
	v_exp_f32_e32 v82, v70
	v_mul_f32_e32 v70, 0xbfb8aa3b, v86
	v_exp_f32_e32 v83, v70
	v_exp_f32_e32 v84, v66
	v_mul_f32_e32 v66, 0xbfb8aa3b, v90
	v_exp_f32_e32 v85, v66
	v_pk_add_f32 v[82:83], v[82:83], 1.0 op_sel_hi:[1,0]
	v_mul_f32_e32 v78, v78, v86
	v_mul_f32_e32 v66, v82, v83
	v_pk_add_f32 v[82:83], v[84:85], 1.0 op_sel_hi:[1,0]
	v_rcp_f32_e32 v66, v66
	v_mul_f32_e32 v70, v82, v83
	v_rcp_f32_e32 v70, v70
	v_and_b32_e32 v87, 0xffff0000, v122
	v_mul_f32_e32 v78, v78, v66
	v_mul_f32_e32 v66, v74, v90
	v_mul_f32_e32 v74, v66, v70
	v_mul_f32_e32 v66, 0xbfb8aa3b, v71
	v_and_b32_e32 v91, 0xffff0000, v124
	v_exp_f32_e32 v70, v66
	v_mul_f32_e32 v66, 0xbfb8aa3b, v87
	v_exp_f32_e32 v71, v66
	v_mul_f32_e32 v66, 0xbfb8aa3b, v67
	v_mul_f32_e32 v67, 0xbfb8aa3b, v91
	v_exp_f32_e32 v66, v66
	v_exp_f32_e32 v67, v67
	v_pk_add_f32 v[70:71], v[70:71], 1.0 op_sel_hi:[1,0]
	v_and_b32_e32 v89, 0xffff0000, v123
	v_mul_f32_e32 v70, v70, v71
	v_pk_add_f32 v[66:67], v[66:67], 1.0 op_sel_hi:[1,0]
	v_rcp_f32_e32 v70, v70
	v_mul_f32_e32 v66, v66, v67
	v_rcp_f32_e32 v66, v66
	v_mul_f32_e32 v67, v79, v87
	v_mul_f32_e32 v79, v67, v70
	v_mul_f32_e32 v67, v75, v91
	v_mul_f32_e32 v75, v67, v66
	v_mul_f32_e32 v66, 0xbfb8aa3b, v72
	v_mul_f32_e32 v67, 0xbfb8aa3b, v88
	v_exp_f32_e32 v66, v66
	v_exp_f32_e32 v67, v67
	v_exp_f32_e32 v70, v68
	v_mul_f32_e32 v68, 0xbfb8aa3b, v92
	v_exp_f32_e32 v71, v68
	v_pk_add_f32 v[66:67], v[66:67], 1.0 op_sel_hi:[1,0]
	v_and_b32_e32 v93, 0xffff0000, v125
	v_mul_f32_e32 v66, v66, v67
	v_rcp_f32_e32 v68, v66
	v_pk_add_f32 v[66:67], v[70:71], 1.0 op_sel_hi:[1,0]
	s_nop 0
	v_mul_f32_e32 v66, v66, v67
	v_rcp_f32_e32 v66, v66
	v_mul_f32_e32 v67, v80, v88
	v_mul_f32_e32 v70, v67, v68
	v_mul_f32_e32 v67, v76, v92
	v_mul_f32_e32 v71, v67, v66
	v_mul_f32_e32 v66, 0xbfb8aa3b, v73
	v_mul_f32_e32 v67, 0xbfb8aa3b, v89
	v_exp_f32_e32 v66, v66
	v_exp_f32_e32 v67, v67
	v_mul_f32_e32 v68, 0xbfb8aa3b, v69
	v_mul_f32_e32 v69, 0xbfb8aa3b, v93
	v_exp_f32_e32 v68, v68
	v_exp_f32_e32 v69, v69
	v_pk_add_f32 v[66:67], v[66:67], 1.0 op_sel_hi:[1,0]
	s_nop 0
	v_mul_f32_e32 v66, v66, v67
	v_rcp_f32_e32 v72, v66
	v_pk_add_f32 v[66:67], v[68:69], 1.0 op_sel_hi:[1,0]
	v_mul_f32_e32 v68, v77, v93
	v_mul_f32_e32 v66, v66, v67
	v_rcp_f32_e32 v66, v66
	v_mul_f32_e32 v67, v81, v89
	v_mul_f32_e32 v67, v67, v72
	v_mul_f32_e32 v69, v68, v66
	v_cvt_pk_bf16_f32 v66, v78, v79
	v_cvt_pk_bf16_f32 v67, v70, v67
	v_add_u32_e32 v70, s22, v153
	v_cvt_pk_bf16_f32 v68, v74, v75
	v_cvt_pk_bf16_f32 v69, v71, v69
	v_ashrrev_i32_e32 v71, 31, v70
	v_lshlrev_b64 v[70:71], 11, v[70:71]
	v_lshl_add_u64 v[70:71], s[6:7], 0, v[70:71]
	v_lshl_add_u64 v[70:71], v[70:71], 0, v[144:145]
	global_store_dwordx4 v[70:71], v[66:69], off
	s_mov_b32 s22, s16
	s_nop 0
	v_add_u32_e32 v66, 0x80, v148
	v_ashrrev_i32_e32 v67, 31, v66
	v_lshlrev_b64 v[88:89], 11, v[66:67]
	v_lshl_add_u64 v[66:67], v[146:147], 0, v[88:89]
	global_load_dwordx4 v[80:83], v[66:67], off
	v_add_u32_e32 v66, 0x90, v148
	v_ashrrev_i32_e32 v67, 31, v66
	v_lshlrev_b64 v[78:79], 11, v[66:67]
	v_lshl_add_u64 v[66:67], v[146:147], 0, v[78:79]
	global_load_dwordx4 v[84:87], v[66:67], off
	v_add_u32_e32 v66, 0xa0, v148
	v_ashrrev_i32_e32 v67, 31, v66
	v_lshlrev_b64 v[76:77], 11, v[66:67]
	v_add_u32_e32 v66, 0xb0, v148
	v_ashrrev_i32_e32 v67, 31, v66
	v_lshl_add_u64 v[90:91], v[146:147], 0, v[76:77]
	v_lshlrev_b64 v[74:75], 11, v[66:67]
	v_lshl_add_u64 v[92:93], v[146:147], 0, v[74:75]
	global_load_dwordx4 v[70:73], v[90:91], off
	global_load_dwordx4 v[66:69], v[92:93], off
	s_waitcnt vmcnt(0)
; __device__ __forceinline__ u32x4 pack8(const float (&f)[8]) { u32x4 r; r[0] = cvt_pk_bf16(f[0], f[1]); r[1] = cvt_pk_bf16(f[2], f[3]); r[2] = cvt_pk_bf16(f[4], f[5]); r[3] = cvt_pk_bf16(f[6], f[7]); return r; }
;     __device__ __forceinline__ void operator()(EPI_ARGS) const {
;     ...
;         for (int ai = 0; ai < 2; ++ai) if (ai == 0 || !u.half) { u32x4 zz[4];
; #pragma unroll
;             for (int m = 0; m < 4; ++m) zz[m] = *(const u32x4*)(parts + E_PZB + (size_t)EPI_ROW * 1024 + col);
; #pragma unroll
;             for (int m = 0; m < 4; ++m) { float z[8]; unpack8(zz[m], z);
;                 const f32x4 a0 = acc[ai][0][m][0], a1 = acc[ai][0][m][1], b0 = acc[ai][1][m][0], b1 = acc[ai][1][m][1]; float o[8];
; #pragma unroll
;                 for (int j = 0; j < 4; ++j) { o[j] = a0[j] * z[j] * __builtin_amdgcn_rcpf((1.0f + __expf(-b0[j])) * (1.0f + __expf(-z[j]))); o[4 + j] = a1[j] * z[4 + j] * __builtin_amdgcn_rcpf((1.0f + __expf(-b1[j])) * (1.0f + __expf(-z[4 + j]))); }
;                 *(u32x4*)(O + (size_t)EPI_ROW * 1024 + col) = pack8(o); } }
	v_lshlrev_b32_e32 v90, 16, v80
	v_and_b32_e32 v91, 0xffff0000, v80
	v_lshlrev_b32_e32 v94, 16, v82
	v_exp_f32_e32 v80, v54
	v_mul_f32_e32 v54, 0xbfb8aa3b, v90
	v_lshlrev_b32_e32 v92, 16, v81
	v_and_b32_e32 v93, 0xffff0000, v81
	v_and_b32_e32 v95, 0xffff0000, v82
	v_exp_f32_e32 v81, v54
	v_exp_f32_e32 v82, v50
	v_mul_f32_e32 v50, 0xbfb8aa3b, v94
	v_lshlrev_b32_e32 v96, 16, v83
	v_and_b32_e32 v97, 0xffff0000, v83
	v_exp_f32_e32 v83, v50
	v_pk_add_f32 v[80:81], v[80:81], 1.0 op_sel_hi:[1,0]
	v_mul_f32_e32 v62, v62, v90
	v_mul_f32_e32 v50, v80, v81
	v_pk_add_f32 v[80:81], v[82:83], 1.0 op_sel_hi:[1,0]
	v_rcp_f32_e32 v50, v50
	v_mul_f32_e32 v54, v80, v81
	v_rcp_f32_e32 v54, v54
	v_mul_f32_e32 v62, v62, v50
	v_mul_f32_e32 v50, v58, v94
	v_mul_f32_e32 v58, v50, v54
	v_mul_f32_e32 v50, 0xbfb8aa3b, v55
	v_exp_f32_e32 v54, v50
	v_mul_f32_e32 v50, 0xbfb8aa3b, v91
	v_exp_f32_e32 v55, v50
	v_mul_f32_e32 v50, 0xbfb8aa3b, v51
	v_mul_f32_e32 v51, 0xbfb8aa3b, v95
	v_exp_f32_e32 v50, v50
	v_exp_f32_e32 v51, v51
	v_pk_add_f32 v[54:55], v[54:55], 1.0 op_sel_hi:[1,0]
	v_pk_add_f32 v[50:51], v[50:51], 1.0 op_sel_hi:[1,0]
	v_mul_f32_e32 v54, v54, v55
	v_rcp_f32_e32 v54, v54
	v_mul_f32_e32 v50, v50, v51
	v_rcp_f32_e32 v50, v50
	v_mul_f32_e32 v51, v63, v91
	v_mul_f32_e32 v63, v51, v54
	v_mul_f32_e32 v51, v59, v95
	v_mul_f32_e32 v59, v51, v50
	v_mul_f32_e32 v50, 0xbfb8aa3b, v56
	v_mul_f32_e32 v51, 0xbfb8aa3b, v92
	v_exp_f32_e32 v50, v50
	v_exp_f32_e32 v51, v51
	v_exp_f32_e32 v54, v52
	v_mul_f32_e32 v52, 0xbfb8aa3b, v96
	v_exp_f32_e32 v55, v52
	v_pk_add_f32 v[50:51], v[50:51], 1.0 op_sel_hi:[1,0]
	s_nop 0
	v_mul_f32_e32 v50, v50, v51
	v_rcp_f32_e32 v52, v50
	v_pk_add_f32 v[50:51], v[54:55], 1.0 op_sel_hi:[1,0]
	s_nop 0
	v_mul_f32_e32 v50, v50, v51
	v_rcp_f32_e32 v50, v50
	v_mul_f32_e32 v51, v64, v92
	v_mul_f32_e32 v54, v51, v52
	v_mul_f32_e32 v51, v60, v96
	v_mul_f32_e32 v55, v51, v50
	v_mul_f32_e32 v50, 0xbfb8aa3b, v57
	v_mul_f32_e32 v51, 0xbfb8aa3b, v93
	v_exp_f32_e32 v50, v50
	v_exp_f32_e32 v51, v51
	v_mul_f32_e32 v52, 0xbfb8aa3b, v53
	v_mul_f32_e32 v53, 0xbfb8aa3b, v97
	v_exp_f32_e32 v52, v52
	v_exp_f32_e32 v53, v53
	v_pk_add_f32 v[50:51], v[50:51], 1.0 op_sel_hi:[1,0]
	v_lshlrev_b32_e32 v60, 16, v87
	v_mul_f32_e32 v50, v50, v51
	v_rcp_f32_e32 v56, v50
	v_pk_add_f32 v[50:51], v[52:53], 1.0 op_sel_hi:[1,0]
	v_mul_f32_e32 v52, v61, v97
	v_mul_f32_e32 v50, v50, v51
	v_rcp_f32_e32 v50, v50
	v_mul_f32_e32 v51, v65, v93
	v_mul_f32_e32 v51, v51, v56
	v_lshlrev_b32_e32 v56, 16, v85
	v_mul_f32_e32 v53, v52, v50
	v_cvt_pk_bf16_f32 v50, v62, v63
	v_cvt_pk_bf16_f32 v51, v54, v51
	v_cvt_pk_bf16_f32 v52, v58, v59
	v_cvt_pk_bf16_f32 v53, v55, v53
	v_lshl_add_u64 v[54:55], s[6:7], 0, v[88:89]
	v_lshl_add_u64 v[54:55], v[54:55], 0, v[144:145]
	global_store_dwordx4 v[54:55], v[50:53], off
	v_lshlrev_b32_e32 v54, 16, v84
	v_lshlrev_b32_e32 v58, 16, v86
	v_exp_f32_e32 v50, v38
	v_mul_f32_e32 v38, 0xbfb8aa3b, v54
	v_exp_f32_e32 v51, v38
	v_exp_f32_e32 v52, v34
	v_mul_f32_e32 v34, 0xbfb8aa3b, v58
	v_exp_f32_e32 v53, v34
	v_pk_add_f32 v[50:51], v[50:51], 1.0 op_sel_hi:[1,0]
	v_mul_f32_e32 v46, v46, v54
	v_mul_f32_e32 v34, v50, v51
	v_pk_add_f32 v[50:51], v[52:53], 1.0 op_sel_hi:[1,0]
	v_rcp_f32_e32 v34, v34
	v_mul_f32_e32 v38, v50, v51
	v_rcp_f32_e32 v38, v38
	v_and_b32_e32 v55, 0xffff0000, v84
	v_mul_f32_e32 v46, v46, v34
	v_mul_f32_e32 v34, v42, v58
	v_mul_f32_e32 v42, v34, v38
	v_mul_f32_e32 v34, 0xbfb8aa3b, v39
	v_and_b32_e32 v59, 0xffff0000, v86
	v_exp_f32_e32 v38, v34
	v_mul_f32_e32 v34, 0xbfb8aa3b, v55
	v_exp_f32_e32 v39, v34
	v_mul_f32_e32 v34, 0xbfb8aa3b, v35
	v_mul_f32_e32 v35, 0xbfb8aa3b, v59
	v_exp_f32_e32 v34, v34
	v_exp_f32_e32 v35, v35
	v_pk_add_f32 v[38:39], v[38:39], 1.0 op_sel_hi:[1,0]
	v_and_b32_e32 v57, 0xffff0000, v85
	v_mul_f32_e32 v38, v38, v39
	v_pk_add_f32 v[34:35], v[34:35], 1.0 op_sel_hi:[1,0]
	v_rcp_f32_e32 v38, v38
	v_mul_f32_e32 v34, v34, v35
	v_rcp_f32_e32 v34, v34
	v_mul_f32_e32 v35, v47, v55
	v_mul_f32_e32 v47, v35, v38
	v_mul_f32_e32 v35, v43, v59
	v_mul_f32_e32 v43, v35, v34
	v_mul_f32_e32 v34, 0xbfb8aa3b, v40
	v_mul_f32_e32 v35, 0xbfb8aa3b, v56
	v_exp_f32_e32 v34, v34
	v_exp_f32_e32 v35, v35
	v_exp_f32_e32 v38, v36
	v_mul_f32_e32 v36, 0xbfb8aa3b, v60
	v_exp_f32_e32 v39, v36
	v_pk_add_f32 v[34:35], v[34:35], 1.0 op_sel_hi:[1,0]
	v_and_b32_e32 v61, 0xffff0000, v87
	v_mul_f32_e32 v34, v34, v35
	v_rcp_f32_e32 v36, v34
	v_pk_add_f32 v[34:35], v[38:39], 1.0 op_sel_hi:[1,0]
	s_nop 0
	v_mul_f32_e32 v34, v34, v35
	v_rcp_f32_e32 v34, v34
	v_mul_f32_e32 v35, v48, v56
	v_mul_f32_e32 v38, v35, v36
	v_mul_f32_e32 v35, v44, v60
	v_mul_f32_e32 v39, v35, v34
	v_mul_f32_e32 v34, 0xbfb8aa3b, v41
	v_mul_f32_e32 v35, 0xbfb8aa3b, v57
	v_exp_f32_e32 v34, v34
	v_exp_f32_e32 v35, v35
	v_mul_f32_e32 v36, 0xbfb8aa3b, v37
	v_mul_f32_e32 v37, 0xbfb8aa3b, v61
	v_exp_f32_e32 v36, v36
	v_exp_f32_e32 v37, v37
	v_pk_add_f32 v[34:35], v[34:35], 1.0 op_sel_hi:[1,0]
	v_lshlrev_b32_e32 v44, 16, v73
	v_mul_f32_e32 v34, v34, v35
	v_rcp_f32_e32 v40, v34
	v_pk_add_f32 v[34:35], v[36:37], 1.0 op_sel_hi:[1,0]
	v_mul_f32_e32 v36, v45, v61
	v_mul_f32_e32 v34, v34, v35
	v_rcp_f32_e32 v34, v34
	v_mul_f32_e32 v35, v49, v57
	v_mul_f32_e32 v35, v35, v40
	v_lshlrev_b32_e32 v40, 16, v71
	v_mul_f32_e32 v37, v36, v34
	v_cvt_pk_bf16_f32 v34, v46, v47
	v_cvt_pk_bf16_f32 v35, v38, v35
	v_cvt_pk_bf16_f32 v36, v42, v43
	v_cvt_pk_bf16_f32 v37, v39, v37
	v_lshl_add_u64 v[38:39], s[6:7], 0, v[78:79]
; __device__ __forceinline__ u32x4 pack8(const float (&f)[8]) { u32x4 r; r[0] = cvt_pk_bf16(f[0], f[1]); r[1] = cvt_pk_bf16(f[2], f[3]); r[2] = cvt_pk_bf16(f[4], f[5]); r[3] = cvt_pk_bf16(f[6], f[7]); return r; }
; #define PG8_WAIT_V(n) asm volatile("s_waitcnt vmcnt(" #n ")" ::: "memory")
; #define PG8_BAR __builtin_amdgcn_s_barrier()
; template <class Sched, class Epi>
; __device__ __forceinline__ void gemm_phase(LAS unsigned char* lds, const Sched& S, const Epi& E, const int K, const int lda, const int ldb) {
;     ...
;         if (!has_next) break;
; #pragma unroll
;         for (int a = 0; a < 2; ++a)
; #pragma unroll
;             for (int b = 0; b < 2; ++b)
; #pragma unroll
;                 for (int m = 0; m < 4; ++m)
; #pragma unroll
;                     for (int n = 0; n < 2; ++n) acc[a][b][m][n] = (f32x4){0.f, 0.f, 0.f, 0.f};
;         cur = nxt; cA = nA; cB = nB; ++ui;
;     }
;     PG8_WAIT_V(0);
;     if (wr == 0) PG8_BAR;
;     PG8_BAR;
;     __device__ __forceinline__ void operator()(EPI_ARGS) const {
;     ...
;         for (int ai = 0; ai < 2; ++ai) if (ai == 0 || !u.half) { u32x4 zz[4];
; #pragma unroll
;             for (int m = 0; m < 4; ++m) zz[m] = *(const u32x4*)(parts + E_PZB + (size_t)EPI_ROW * 1024 + col);
; #pragma unroll
;             for (int m = 0; m < 4; ++m) { float z[8]; unpack8(zz[m], z);
;                 const f32x4 a0 = acc[ai][0][m][0], a1 = acc[ai][0][m][1], b0 = acc[ai][1][m][0], b1 = acc[ai][1][m][1]; float o[8];
; #pragma unroll
;                 for (int j = 0; j < 4; ++j) { o[j] = a0[j] * z[j] * __builtin_amdgcn_rcpf((1.0f + __expf(-b0[j])) * (1.0f + __expf(-z[j]))); o[4 + j] = a1[j] * z[4 + j] * __builtin_amdgcn_rcpf((1.0f + __expf(-b1[j])) * (1.0f + __expf(-z[4 + j]))); }
;                 *(u32x4*)(O + (size_t)EPI_ROW * 1024 + col) = pack8(o); } }
	v_lshl_add_u64 v[38:39], v[38:39], 0, v[144:145]
	global_store_dwordx4 v[38:39], v[34:37], off
	v_lshlrev_b32_e32 v38, 16, v70
	v_lshlrev_b32_e32 v42, 16, v72
	v_exp_f32_e32 v34, v22
	v_mul_f32_e32 v22, 0xbfb8aa3b, v38
	v_exp_f32_e32 v35, v22
	v_exp_f32_e32 v36, v18
	v_mul_f32_e32 v18, 0xbfb8aa3b, v42
	v_exp_f32_e32 v37, v18
	v_pk_add_f32 v[34:35], v[34:35], 1.0 op_sel_hi:[1,0]
	v_mul_f32_e32 v30, v30, v38
	v_mul_f32_e32 v18, v34, v35
	v_pk_add_f32 v[34:35], v[36:37], 1.0 op_sel_hi:[1,0]
	v_rcp_f32_e32 v18, v18
	v_mul_f32_e32 v22, v34, v35
	v_rcp_f32_e32 v22, v22
	v_and_b32_e32 v39, 0xffff0000, v70
	v_mul_f32_e32 v30, v30, v18
	v_mul_f32_e32 v18, v26, v42
	v_mul_f32_e32 v26, v18, v22
	v_mul_f32_e32 v18, 0xbfb8aa3b, v23
	v_and_b32_e32 v43, 0xffff0000, v72
	v_exp_f32_e32 v22, v18
	v_mul_f32_e32 v18, 0xbfb8aa3b, v39
	v_exp_f32_e32 v23, v18
	v_mul_f32_e32 v18, 0xbfb8aa3b, v19
	v_mul_f32_e32 v19, 0xbfb8aa3b, v43
	v_exp_f32_e32 v18, v18
	v_exp_f32_e32 v19, v19
	v_pk_add_f32 v[22:23], v[22:23], 1.0 op_sel_hi:[1,0]
	v_and_b32_e32 v41, 0xffff0000, v71
	v_mul_f32_e32 v22, v22, v23
	v_pk_add_f32 v[18:19], v[18:19], 1.0 op_sel_hi:[1,0]
	v_rcp_f32_e32 v22, v22
	v_mul_f32_e32 v18, v18, v19
	v_rcp_f32_e32 v18, v18
	v_mul_f32_e32 v19, v31, v39
	v_mul_f32_e32 v31, v19, v22
	v_mul_f32_e32 v19, v27, v43
	v_mul_f32_e32 v27, v19, v18
	v_mul_f32_e32 v18, 0xbfb8aa3b, v24
	v_mul_f32_e32 v19, 0xbfb8aa3b, v40
	v_exp_f32_e32 v18, v18
	v_exp_f32_e32 v19, v19
	v_exp_f32_e32 v22, v20
	v_mul_f32_e32 v20, 0xbfb8aa3b, v44
	v_exp_f32_e32 v23, v20
	v_pk_add_f32 v[18:19], v[18:19], 1.0 op_sel_hi:[1,0]
	v_and_b32_e32 v45, 0xffff0000, v73
	v_mul_f32_e32 v18, v18, v19
	v_rcp_f32_e32 v20, v18
	v_pk_add_f32 v[18:19], v[22:23], 1.0 op_sel_hi:[1,0]
	s_nop 0
	v_mul_f32_e32 v18, v18, v19
	v_rcp_f32_e32 v18, v18
	v_mul_f32_e32 v19, v32, v40
	v_mul_f32_e32 v22, v19, v20
	v_mul_f32_e32 v19, v28, v44
	v_mul_f32_e32 v23, v19, v18
	v_mul_f32_e32 v18, 0xbfb8aa3b, v25
	v_mul_f32_e32 v19, 0xbfb8aa3b, v41
	v_exp_f32_e32 v18, v18
	v_exp_f32_e32 v19, v19
	v_mul_f32_e32 v20, 0xbfb8aa3b, v21
	v_mul_f32_e32 v21, 0xbfb8aa3b, v45
	v_exp_f32_e32 v20, v20
	v_exp_f32_e32 v21, v21
	v_pk_add_f32 v[18:19], v[18:19], 1.0 op_sel_hi:[1,0]
	v_lshlrev_b32_e32 v28, 16, v69
	v_mul_f32_e32 v18, v18, v19
	v_rcp_f32_e32 v24, v18
	v_pk_add_f32 v[18:19], v[20:21], 1.0 op_sel_hi:[1,0]
	v_mul_f32_e32 v20, v29, v45
	v_mul_f32_e32 v18, v18, v19
	v_rcp_f32_e32 v18, v18
	v_mul_f32_e32 v19, v33, v41
	v_mul_f32_e32 v19, v19, v24
	v_lshlrev_b32_e32 v24, 16, v67
	v_mul_f32_e32 v21, v20, v18
	v_cvt_pk_bf16_f32 v18, v30, v31
	v_cvt_pk_bf16_f32 v19, v22, v19
	v_cvt_pk_bf16_f32 v20, v26, v27
	v_cvt_pk_bf16_f32 v21, v23, v21
	v_lshl_add_u64 v[22:23], s[6:7], 0, v[76:77]
	v_lshl_add_u64 v[22:23], v[22:23], 0, v[144:145]
	global_store_dwordx4 v[22:23], v[18:21], off
	v_lshlrev_b32_e32 v22, 16, v66
	v_lshlrev_b32_e32 v26, 16, v68
	v_exp_f32_e32 v18, v6
	v_mul_f32_e32 v6, 0xbfb8aa3b, v22
	v_exp_f32_e32 v19, v6
	v_exp_f32_e32 v20, v2
	v_mul_f32_e32 v2, 0xbfb8aa3b, v26
	v_exp_f32_e32 v21, v2
	v_pk_add_f32 v[18:19], v[18:19], 1.0 op_sel_hi:[1,0]
	v_mul_f32_e32 v14, v14, v22
	v_mul_f32_e32 v2, v18, v19
	v_pk_add_f32 v[18:19], v[20:21], 1.0 op_sel_hi:[1,0]
	v_rcp_f32_e32 v2, v2
	v_mul_f32_e32 v6, v18, v19
	v_rcp_f32_e32 v6, v6
	v_and_b32_e32 v23, 0xffff0000, v66
	v_mul_f32_e32 v14, v14, v2
	v_mul_f32_e32 v2, v10, v26
	v_mul_f32_e32 v10, v2, v6
	v_mul_f32_e32 v2, 0xbfb8aa3b, v7
	v_and_b32_e32 v27, 0xffff0000, v68
	v_exp_f32_e32 v6, v2
	v_mul_f32_e32 v2, 0xbfb8aa3b, v23
	v_exp_f32_e32 v7, v2
	v_mul_f32_e32 v2, 0xbfb8aa3b, v3
	v_mul_f32_e32 v3, 0xbfb8aa3b, v27
	v_exp_f32_e32 v2, v2
	v_exp_f32_e32 v3, v3
	v_pk_add_f32 v[6:7], v[6:7], 1.0 op_sel_hi:[1,0]
	v_and_b32_e32 v25, 0xffff0000, v67
	v_mul_f32_e32 v6, v6, v7
	v_pk_add_f32 v[2:3], v[2:3], 1.0 op_sel_hi:[1,0]
	v_rcp_f32_e32 v6, v6
	v_mul_f32_e32 v2, v2, v3
	v_rcp_f32_e32 v2, v2
	v_mul_f32_e32 v3, v15, v23
	v_mul_f32_e32 v15, v3, v6
	v_mul_f32_e32 v3, v11, v27
	v_mul_f32_e32 v11, v3, v2
	v_mul_f32_e32 v2, 0xbfb8aa3b, v8
	v_mul_f32_e32 v3, 0xbfb8aa3b, v24
	v_exp_f32_e32 v2, v2
	v_exp_f32_e32 v3, v3
	v_exp_f32_e32 v6, v4
	v_mul_f32_e32 v4, 0xbfb8aa3b, v28
	v_exp_f32_e32 v7, v4
	v_pk_add_f32 v[2:3], v[2:3], 1.0 op_sel_hi:[1,0]
	v_and_b32_e32 v29, 0xffff0000, v69
	v_mul_f32_e32 v2, v2, v3
	v_rcp_f32_e32 v4, v2
	v_pk_add_f32 v[2:3], v[6:7], 1.0 op_sel_hi:[1,0]
	s_nop 0
	v_mul_f32_e32 v2, v2, v3
	v_rcp_f32_e32 v2, v2
	v_mul_f32_e32 v3, v16, v24
	v_mul_f32_e32 v6, v3, v4
	v_mul_f32_e32 v3, v12, v28
	v_mul_f32_e32 v7, v3, v2
	v_mul_f32_e32 v2, 0xbfb8aa3b, v9
	v_mul_f32_e32 v3, 0xbfb8aa3b, v25
	v_exp_f32_e32 v2, v2
	v_exp_f32_e32 v3, v3
	v_mul_f32_e32 v4, 0xbfb8aa3b, v5
	v_mul_f32_e32 v5, 0xbfb8aa3b, v29
	v_exp_f32_e32 v4, v4
	v_exp_f32_e32 v5, v5
	v_pk_add_f32 v[2:3], v[2:3], 1.0 op_sel_hi:[1,0]
	s_nop 0
	v_mul_f32_e32 v2, v2, v3
	v_rcp_f32_e32 v8, v2
	v_pk_add_f32 v[2:3], v[4:5], 1.0 op_sel_hi:[1,0]
	v_mul_f32_e32 v4, v13, v29
	v_mul_f32_e32 v2, v2, v3
	v_rcp_f32_e32 v2, v2
	v_mul_f32_e32 v3, v17, v25
	v_mul_f32_e32 v3, v3, v8
	v_mul_f32_e32 v5, v4, v2
	v_cvt_pk_bf16_f32 v2, v14, v15
	v_cvt_pk_bf16_f32 v3, v6, v3
	v_cvt_pk_bf16_f32 v4, v10, v11
	v_cvt_pk_bf16_f32 v5, v7, v5
	v_lshl_add_u64 v[6:7], s[6:7], 0, v[74:75]
	v_lshl_add_u64 v[6:7], v[6:7], 0, v[144:145]
	global_store_dwordx4 v[6:7], v[2:5], off
	s_cbranch_vccz .LBB0_1408
	s_waitcnt vmcnt(0)
	s_cmpk_gt_u32 s2, 0xff
	s_cbranch_scc1 .LBB0_1419
	s_barrier

; #define PG8_STAGE(bufoff, gbase, voff) do { _Pragma("unroll") for (int _i = 0; _i < 2; ++_i) \
;         __builtin_amdgcn_global_load_lds((const unsigned*)((const char*)(gbase) + (voff)[_i]), (LAS unsigned*)(lds + (bufoff) + ldsw + _i * 8192), 16, 0, 0); } while (0)
; #define PG8_LDA(dst, b, h) do { _Pragma("unroll") for (int m = 0; m < 4; ++m) _Pragma("unroll") for (int k = 0; k < 2; ++k) dst[m][k] = *(const LAS bf16x8*)(lds + PG8_SA(b, h) + aoff + m * 2048 + k * 1024); } while (0)
; #define PG8_LDB(dst, b, h) do { _Pragma("unroll") for (int n = 0; n < 2; ++n) _Pragma("unroll") for (int k = 0; k < 2; ++k) dst[n][k] = *(const LAS bf16x8*)(lds + PG8_SB(b, h) + boff + n * 2048 + k * 1024); } while (0)
; #define PG8_MMA(ai, bj, At, Bt) do { __builtin_amdgcn_s_setprio(1); _Pragma("unroll") for (int m = 0; m < 4; ++m) _Pragma("unroll") for (int n = 0; n < 2; ++n) _Pragma("unroll") for (int k = 0; k < 2; ++k) \
;         acc[ai][bj][m][n] = __builtin_amdgcn_mfma_f32_16x16x32_bf16(Bt[n][k], At[m][k], acc[ai][bj][m][n], 0, 0, 0); __builtin_amdgcn_s_setprio(0); } while (0)
; #define PG8_WAIT_L(n) asm volatile("s_waitcnt lgkmcnt(" #n ")" ::: "memory")
; #define PG8_BAR __builtin_amdgcn_s_barrier()
; #define PG8_SCHED __builtin_amdgcn_sched_barrier(0)
; template <class Sched, class Epi>
; __device__ __forceinline__ void gemm_phase(LAS unsigned char* lds, const Sched& S, const Epi& E, const int K, const int lda, const int ldb) {
;     ...
;         for (int t = 0; t < nt; t += 2) {
;             const bool last = (t == nt - 2);
;             const char* a1 = cA + (size_t)(t + 1) * kstep;
;             const char* a2 = last ? nA : cA + (size_t)(t + 2) * kstep; const char* b2 = last ? nB : cB + (size_t)(t + 2) * kstep;
;             const char* a3 = a2 + kstep; const char* b3 = b2 + kstep;
;             PG8_LDB(B0, 0, 0); PG8_SCHED; PG8_LDA(At, 0, 0); PG8_STAGE(PG8_SA(1, 1), a1 + hstepA, voffA);
;             PG8_WAIT_L(8); PG8_BAR; PG8_WAIT_L(0); PG8_MMA(0, 0, At, B0); PG8_BAR; PG8_SCHED;
;     ...
; #pragma unroll
;         for (int a = 0; a < 2; ++a)
; #pragma unroll
;             for (int b = 0; b < 2; ++b)
; #pragma unroll
;                 for (int m = 0; m < 4; ++m)
; #pragma unroll
;                     for (int n = 0; n < 2; ++n) acc[a][b][m][n] = (f32x4){0.f, 0.f, 0.f, 0.f};
;         cur = nxt; cA = nA; cB = nB; ++ui;
.LBB0_1485:
	s_add_u32 s15, s26, 0x100
	s_addc_u32 s17, s27, 0
	s_add_u32 s6, s6, 0x40080
	v_mov_b32_e32 v2, 0
	s_addc_u32 s7, s7, 0
	s_mov_b32 s19, -2
	v_mov_b32_e32 v3, v2
	v_mov_b32_e32 v4, v2
	v_mov_b32_e32 v5, v2
	v_mov_b32_e32 v6, v2
	v_mov_b32_e32 v7, v2
	v_mov_b32_e32 v8, v2
	v_mov_b32_e32 v9, v2
	v_mov_b32_e32 v10, v2
	v_mov_b32_e32 v11, v2
	v_mov_b32_e32 v12, v2
	v_mov_b32_e32 v13, v2
	v_mov_b32_e32 v14, v2
	v_mov_b32_e32 v15, v2
	v_mov_b32_e32 v16, v2
	v_mov_b32_e32 v17, v2
	v_mov_b32_e32 v18, v2
	v_mov_b32_e32 v19, v2
	v_mov_b32_e32 v20, v2
	v_mov_b32_e32 v21, v2
	v_mov_b32_e32 v22, v2
	v_mov_b32_e32 v23, v2
	v_mov_b32_e32 v24, v2
	v_mov_b32_e32 v25, v2
	v_mov_b32_e32 v26, v2
	v_mov_b32_e32 v27, v2
	v_mov_b32_e32 v28, v2
	v_mov_b32_e32 v29, v2
	v_mov_b32_e32 v30, v2
	v_mov_b32_e32 v31, v2
	v_mov_b32_e32 v32, v2
	v_mov_b32_e32 v33, v2
	v_mov_b32_e32 v34, v2
	v_mov_b32_e32 v35, v2
	v_mov_b32_e32 v36, v2
	v_mov_b32_e32 v37, v2
	v_mov_b32_e32 v38, v2
	v_mov_b32_e32 v39, v2
	v_mov_b32_e32 v40, v2
	v_mov_b32_e32 v41, v2
	v_mov_b32_e32 v42, v2
	v_mov_b32_e32 v43, v2
	v_mov_b32_e32 v44, v2
	v_mov_b32_e32 v45, v2
	v_mov_b32_e32 v46, v2
	v_mov_b32_e32 v47, v2
	v_mov_b32_e32 v48, v2
	v_mov_b32_e32 v49, v2
	v_mov_b32_e32 v50, v2
	v_mov_b32_e32 v51, v2
	v_mov_b32_e32 v52, v2
	v_mov_b32_e32 v53, v2
	v_mov_b32_e32 v54, v2
	v_mov_b32_e32 v55, v2
	v_mov_b32_e32 v56, v2
	v_mov_b32_e32 v57, v2
	v_mov_b32_e32 v58, v2
	v_mov_b32_e32 v59, v2
	v_mov_b32_e32 v60, v2
	v_mov_b32_e32 v61, v2
	v_mov_b32_e32 v62, v2
	v_mov_b32_e32 v63, v2
	v_mov_b32_e32 v64, v2
	v_mov_b32_e32 v65, v2
	v_mov_b32_e32 v66, v2
	v_mov_b32_e32 v67, v2
	v_mov_b32_e32 v68, v2
	v_mov_b32_e32 v69, v2
	v_mov_b32_e32 v70, v2
	v_mov_b32_e32 v71, v2
	v_mov_b32_e32 v72, v2
	v_mov_b32_e32 v73, v2
	v_mov_b32_e32 v74, v2
	v_mov_b32_e32 v75, v2
	v_mov_b32_e32 v76, v2
	v_mov_b32_e32 v77, v2
	v_mov_b32_e32 v78, v2
	v_mov_b32_e32 v79, v2
	v_mov_b32_e32 v80, v2
	v_mov_b32_e32 v81, v2
	v_mov_b32_e32 v82, v2
	v_mov_b32_e32 v83, v2
	v_mov_b32_e32 v84, v2
	v_mov_b32_e32 v85, v2
	v_mov_b32_e32 v86, v2
	v_mov_b32_e32 v87, v2
	v_mov_b32_e32 v88, v2
	v_mov_b32_e32 v89, v2
	v_mov_b32_e32 v90, v2
	v_mov_b32_e32 v91, v2
	v_mov_b32_e32 v92, v2
	v_mov_b32_e32 v93, v2
	v_mov_b32_e32 v94, v2
	v_mov_b32_e32 v95, v2
	v_mov_b32_e32 v96, v2
	v_mov_b32_e32 v97, v2
	v_mov_b32_e32 v98, v2
	v_mov_b32_e32 v99, v2
	v_mov_b32_e32 v100, v2
	v_mov_b32_e32 v101, v2
	v_mov_b32_e32 v102, v2
	v_mov_b32_e32 v103, v2
	v_mov_b32_e32 v104, v2
	v_mov_b32_e32 v105, v2
	v_mov_b32_e32 v106, v2
	v_mov_b32_e32 v107, v2
	v_mov_b32_e32 v108, v2
	v_mov_b32_e32 v109, v2
	v_mov_b32_e32 v110, v2
	v_mov_b32_e32 v111, v2
	v_mov_b32_e32 v112, v2
	v_mov_b32_e32 v113, v2
	v_mov_b32_e32 v114, v2
	v_mov_b32_e32 v115, v2
	v_mov_b32_e32 v116, v2
	v_mov_b32_e32 v117, v2
	v_mov_b32_e32 v118, v2
	v_mov_b32_e32 v119, v2
	v_mov_b32_e32 v120, v2
	v_mov_b32_e32 v121, v2
	v_mov_b32_e32 v122, v2
	v_mov_b32_e32 v123, v2
	v_mov_b32_e32 v124, v2
	v_mov_b32_e32 v125, v2
	v_mov_b32_e32 v126, v2
	v_mov_b32_e32 v127, v2
	v_mov_b32_e32 v128, v2
	v_mov_b32_e32 v129, v2
	s_branch .Lal_1486
	.p2align 11
.Lal_1486:
.LBB0_1486:
	ds_read_b128 v[130:133], v233
	ds_read_b128 v[134:137], v233 offset:1024
	ds_read_b128 v[138:141], v233 offset:2048
	ds_read_b128 v[142:145], v233 offset:3072
	s_add_u32 s26, s6, 0xfffc0080
	s_addc_u32 s27, s7, -1
	s_cmp_eq_u32 s19, 12
	s_cselect_b32 s29, s21, s27
	s_cselect_b32 s28, s20, s26
	s_cselect_b32 s27, s23, s17
	s_cselect_b32 s26, s22, s15
	s_add_i32 m0, s31, 0xc000
	ds_read_b128 v[146:149], v234
	ds_read_b128 v[150:153], v234 offset:1024
	ds_read_b128 v[154:157], v234 offset:2048
	ds_read_b128 v[158:161], v234 offset:3072
	ds_read_b128 v[162:165], v234 offset:4096
	ds_read_b128 v[166:169], v234 offset:5120
	ds_read_b128 v[170:173], v234 offset:6144
	ds_read_b128 v[174:177], v234 offset:7168
	global_load_lds_dwordx4 v208, s[6:7]
	s_add_i32 m0, s31, 0xe000
	s_nop 0
	global_load_lds_dwordx4 v206, s[6:7]
	s_waitcnt lgkmcnt(8)
	s_barrier
	s_waitcnt lgkmcnt(0)
	s_setprio 1
	s_waitcnt lgkmcnt(0)
	v_mfma_f32_16x16x32_bf16 v[126:129], v[130:133], v[146:149], v[126:129]
	v_mfma_f32_16x16x32_bf16 v[122:125], v[138:141], v[146:149], v[122:125]
	v_mfma_f32_16x16x32_bf16 v[118:121], v[130:133], v[154:157], v[118:121]
	v_mfma_f32_16x16x32_bf16 v[114:117], v[138:141], v[154:157], v[114:117]
	v_mfma_f32_16x16x32_bf16 v[110:113], v[130:133], v[162:165], v[110:113]
	v_mfma_f32_16x16x32_bf16 v[106:109], v[138:141], v[162:165], v[106:109]
	v_mfma_f32_16x16x32_bf16 v[102:105], v[130:133], v[170:173], v[102:105]
	v_mfma_f32_16x16x32_bf16 v[98:101], v[138:141], v[170:173], v[98:101]
	v_mfma_f32_16x16x32_bf16 v[126:129], v[134:137], v[150:153], v[126:129]
	v_mfma_f32_16x16x32_bf16 v[122:125], v[142:145], v[150:153], v[122:125]
	v_mfma_f32_16x16x32_bf16 v[118:121], v[134:137], v[158:161], v[118:121]
	v_mfma_f32_16x16x32_bf16 v[114:117], v[142:145], v[158:161], v[114:117]
	v_mfma_f32_16x16x32_bf16 v[110:113], v[134:137], v[166:169], v[110:113]
	v_mfma_f32_16x16x32_bf16 v[106:109], v[142:145], v[166:169], v[106:109]
	v_mfma_f32_16x16x32_bf16 v[102:105], v[134:137], v[174:177], v[102:105]
	v_mfma_f32_16x16x32_bf16 v[98:101], v[142:145], v[174:177], v[98:101]
	s_setprio 0
	s_barrier
	s_add_i32 s49, s43, s25
	s_add_u32 s52, s26, s12
	s_addc_u32 s53, s27, s13
	s_mov_b32 m0, s49
	ds_read_b128 v[178:181], v235
	ds_read_b128 v[182:185], v235 offset:1024
	ds_read_b128 v[186:189], v235 offset:2048
	ds_read_b128 v[190:193], v235 offset:3072
	global_load_lds_dwordx4 v200, s[26:27]
	s_add_u32 s54, s26, s12
	s_addc_u32 s55, s27, s13
	s_add_i32 m0, s49, 0x2000
	s_nop 0
	global_load_lds_dwordx4 v204, s[26:27]
	s_barrier
; #define PG8_STAGE(bufoff, gbase, voff) do { _Pragma("unroll") for (int _i = 0; _i < 2; ++_i) \
;         __builtin_amdgcn_global_load_lds((const unsigned*)((const char*)(gbase) + (voff)[_i]), (LAS unsigned*)(lds + (bufoff) + ldsw + _i * 8192), 16, 0, 0); } while (0)
; #define PG8_LDA(dst, b, h) do { _Pragma("unroll") for (int m = 0; m < 4; ++m) _Pragma("unroll") for (int k = 0; k < 2; ++k) dst[m][k] = *(const LAS bf16x8*)(lds + PG8_SA(b, h) + aoff + m * 2048 + k * 1024); } while (0)
; #define PG8_LDB(dst, b, h) do { _Pragma("unroll") for (int n = 0; n < 2; ++n) _Pragma("unroll") for (int k = 0; k < 2; ++k) dst[n][k] = *(const LAS bf16x8*)(lds + PG8_SB(b, h) + boff + n * 2048 + k * 1024); } while (0)
; #define PG8_MMA(ai, bj, At, Bt) do { __builtin_amdgcn_s_setprio(1); _Pragma("unroll") for (int m = 0; m < 4; ++m) _Pragma("unroll") for (int n = 0; n < 2; ++n) _Pragma("unroll") for (int k = 0; k < 2; ++k) \
;         acc[ai][bj][m][n] = __builtin_amdgcn_mfma_f32_16x16x32_bf16(Bt[n][k], At[m][k], acc[ai][bj][m][n], 0, 0, 0); __builtin_amdgcn_s_setprio(0); } while (0)
; #define PG8_WAIT_V(n) asm volatile("s_waitcnt vmcnt(" #n ")" ::: "memory")
; #define PG8_WAIT_L(n) asm volatile("s_waitcnt lgkmcnt(" #n ")" ::: "memory")
; #define PG8_BAR __builtin_amdgcn_s_barrier()
; #define PG8_SCHED __builtin_amdgcn_sched_barrier(0)
; template <class Sched, class Epi>
; __device__ __forceinline__ void gemm_phase(LAS unsigned char* lds, const Sched& S, const Epi& E, const int K, const int lda, const int ldb) {
;     ...
;             PG8_LDB(B1, 0, 1); PG8_STAGE(PG8_SB(0, 0), b2, voffB);
;             PG8_BAR; PG8_WAIT_L(0); PG8_MMA(0, 1, At, B1); PG8_BAR;
;             PG8_LDA(At, 0, 1); PG8_STAGE(PG8_SA(0, 0), a2, voffA);
;             PG8_BAR; PG8_WAIT_L(0); if (!chalf) PG8_MMA(1, 0, At, B0); PG8_BAR; PG8_SCHED;
;             PG8_STAGE(PG8_SB(0, 1), b2 + hstepB, voffB);
;             PG8_WAIT_V(6); PG8_BAR; if (!chalf) PG8_MMA(1, 1, At, B1); PG8_BAR;
;             PG8_LDB(B0, 1, 0); PG8_SCHED; PG8_LDA(At, 1, 0); PG8_STAGE(PG8_SA(0, 1), a2 + hstepA, voffA);
;             PG8_WAIT_L(8); PG8_BAR; PG8_WAIT_L(0); PG8_MMA(0, 0, At, B0); PG8_BAR; PG8_SCHED;
;             PG8_LDB(B1, 1, 1); PG8_STAGE(PG8_SB(1, 0), b3, voffB);
;             PG8_BAR; PG8_WAIT_L(0); PG8_MMA(0, 1, At, B1); PG8_BAR;
	s_waitcnt lgkmcnt(0)
	s_setprio 1
	s_waitcnt lgkmcnt(0)
	v_mfma_f32_16x16x32_bf16 v[94:97], v[178:181], v[146:149], v[94:97]
	v_mfma_f32_16x16x32_bf16 v[90:93], v[186:189], v[146:149], v[90:93]
	v_mfma_f32_16x16x32_bf16 v[86:89], v[178:181], v[154:157], v[86:89]
	v_mfma_f32_16x16x32_bf16 v[82:85], v[186:189], v[154:157], v[82:85]
	v_mfma_f32_16x16x32_bf16 v[78:81], v[178:181], v[162:165], v[78:81]
	v_mfma_f32_16x16x32_bf16 v[74:77], v[186:189], v[162:165], v[74:77]
	v_mfma_f32_16x16x32_bf16 v[70:73], v[178:181], v[170:173], v[70:73]
	v_mfma_f32_16x16x32_bf16 v[66:69], v[186:189], v[170:173], v[66:69]
	v_mfma_f32_16x16x32_bf16 v[94:97], v[182:185], v[150:153], v[94:97]
	v_mfma_f32_16x16x32_bf16 v[90:93], v[190:193], v[150:153], v[90:93]
	v_mfma_f32_16x16x32_bf16 v[86:89], v[182:185], v[158:161], v[86:89]
	v_mfma_f32_16x16x32_bf16 v[82:85], v[190:193], v[158:161], v[82:85]
	v_mfma_f32_16x16x32_bf16 v[78:81], v[182:185], v[166:169], v[78:81]
	v_mfma_f32_16x16x32_bf16 v[74:77], v[190:193], v[166:169], v[74:77]
	v_mfma_f32_16x16x32_bf16 v[70:73], v[182:185], v[174:177], v[70:73]
	v_mfma_f32_16x16x32_bf16 v[66:69], v[190:193], v[174:177], v[66:69]
	s_setprio 0
	s_mov_b32 m0, s31
	s_add_u32 s56, s28, s12
	s_addc_u32 s57, s29, s13
	s_barrier
	ds_read_b128 v[146:149], v234 offset:16384
	ds_read_b128 v[150:153], v234 offset:17408
	ds_read_b128 v[154:157], v234 offset:18432
	ds_read_b128 v[158:161], v234 offset:19456
	ds_read_b128 v[162:165], v234 offset:20480
	ds_read_b128 v[166:169], v234 offset:21504
	ds_read_b128 v[170:173], v234 offset:22528
	ds_read_b128 v[174:177], v234 offset:23552
	global_load_lds_dwordx4 v198, s[28:29]
	s_add_u32 s58, s28, s12
	s_addc_u32 s59, s29, s13
	s_mov_b32 m0, s33
	s_nop 0
	global_load_lds_dwordx4 v202, s[28:29]
	s_barrier
	s_waitcnt lgkmcnt(0)
	s_setprio 1
	s_waitcnt lgkmcnt(0)
	v_mfma_f32_16x16x32_bf16 v[62:65], v[130:133], v[146:149], v[62:65]
	v_mfma_f32_16x16x32_bf16 v[58:61], v[138:141], v[146:149], v[58:61]
	v_mfma_f32_16x16x32_bf16 v[54:57], v[130:133], v[154:157], v[54:57]
	v_mfma_f32_16x16x32_bf16 v[50:53], v[138:141], v[154:157], v[50:53]
	v_mfma_f32_16x16x32_bf16 v[46:49], v[130:133], v[162:165], v[46:49]
	v_mfma_f32_16x16x32_bf16 v[42:45], v[138:141], v[162:165], v[42:45]
	v_mfma_f32_16x16x32_bf16 v[38:41], v[130:133], v[170:173], v[38:41]
	v_mfma_f32_16x16x32_bf16 v[34:37], v[138:141], v[170:173], v[34:37]
	v_mfma_f32_16x16x32_bf16 v[62:65], v[134:137], v[150:153], v[62:65]
	v_mfma_f32_16x16x32_bf16 v[58:61], v[142:145], v[150:153], v[58:61]
	v_mfma_f32_16x16x32_bf16 v[54:57], v[134:137], v[158:161], v[54:57]
	v_mfma_f32_16x16x32_bf16 v[50:53], v[142:145], v[158:161], v[50:53]
	v_mfma_f32_16x16x32_bf16 v[46:49], v[134:137], v[166:169], v[46:49]
	v_mfma_f32_16x16x32_bf16 v[42:45], v[142:145], v[166:169], v[42:45]
	v_mfma_f32_16x16x32_bf16 v[38:41], v[134:137], v[174:177], v[38:41]
	v_mfma_f32_16x16x32_bf16 v[34:37], v[142:145], v[174:177], v[34:37]
	s_setprio 0
	s_barrier
	s_add_u32 s50, s26, 0x40000
	s_addc_u32 s51, s27, 0
	s_add_i32 s49, s44, s25
	s_mov_b32 m0, s49
	s_nop 0
	global_load_lds_dwordx4 v200, s[50:51]
	s_add_i32 m0, s49, 0x2000
	s_nop 0
	global_load_lds_dwordx4 v204, s[50:51]
	s_waitcnt vmcnt(6)
	s_barrier
	s_setprio 1
	v_mfma_f32_16x16x32_bf16 v[30:33], v[178:181], v[146:149], v[30:33]
	v_mfma_f32_16x16x32_bf16 v[26:29], v[186:189], v[146:149], v[26:29]
	v_mfma_f32_16x16x32_bf16 v[22:25], v[178:181], v[154:157], v[22:25]
	v_mfma_f32_16x16x32_bf16 v[18:21], v[186:189], v[154:157], v[18:21]
	v_mfma_f32_16x16x32_bf16 v[14:17], v[178:181], v[162:165], v[14:17]
	v_mfma_f32_16x16x32_bf16 v[10:13], v[186:189], v[162:165], v[10:13]
	v_mfma_f32_16x16x32_bf16 v[6:9], v[178:181], v[170:173], v[6:9]
	v_mfma_f32_16x16x32_bf16 v[2:5], v[186:189], v[170:173], v[2:5]
	v_mfma_f32_16x16x32_bf16 v[30:33], v[182:185], v[150:153], v[30:33]
	v_mfma_f32_16x16x32_bf16 v[26:29], v[190:193], v[150:153], v[26:29]
	v_mfma_f32_16x16x32_bf16 v[22:25], v[182:185], v[158:161], v[22:25]
	v_mfma_f32_16x16x32_bf16 v[18:21], v[190:193], v[158:161], v[18:21]
	v_mfma_f32_16x16x32_bf16 v[14:17], v[182:185], v[166:169], v[14:17]
	v_mfma_f32_16x16x32_bf16 v[10:13], v[190:193], v[166:169], v[10:13]
	v_mfma_f32_16x16x32_bf16 v[6:9], v[182:185], v[174:177], v[6:9]
	v_mfma_f32_16x16x32_bf16 v[2:5], v[190:193], v[174:177], v[2:5]
	s_setprio 0
	s_add_i32 s49, 16, 0x18000
	v_add_u32_e32 v142, s49, v224
	s_barrier
	ds_read_b128 v[130:133], v142
	ds_read_b128 v[134:137], v142 offset:1024
	ds_read_b128 v[138:141], v142 offset:2048
	ds_read_b128 v[142:145], v142 offset:3072
	s_add_u32 s28, s28, 0x40000
	s_addc_u32 s29, s29, 0
	s_mov_b32 m0, s34
	ds_read_b128 v[146:149], v234 offset:32768
	ds_read_b128 v[150:153], v234 offset:33792
	ds_read_b128 v[154:157], v234 offset:34816
	ds_read_b128 v[158:161], v234 offset:35840
	ds_read_b128 v[162:165], v234 offset:36864
	ds_read_b128 v[166:169], v234 offset:37888
	ds_read_b128 v[170:173], v234 offset:38912
	ds_read_b128 v[174:177], v234 offset:39936
	global_load_lds_dwordx4 v198, s[28:29]
	s_mov_b32 m0, s35
	s_nop 0
	global_load_lds_dwordx4 v202, s[28:29]
	s_waitcnt lgkmcnt(8)
	s_barrier
; #define PG8_STAGE(bufoff, gbase, voff) do { _Pragma("unroll") for (int _i = 0; _i < 2; ++_i) \
;         __builtin_amdgcn_global_load_lds((const unsigned*)((const char*)(gbase) + (voff)[_i]), (LAS unsigned*)(lds + (bufoff) + ldsw + _i * 8192), 16, 0, 0); } while (0)
; #define PG8_LDA(dst, b, h) do { _Pragma("unroll") for (int m = 0; m < 4; ++m) _Pragma("unroll") for (int k = 0; k < 2; ++k) dst[m][k] = *(const LAS bf16x8*)(lds + PG8_SA(b, h) + aoff + m * 2048 + k * 1024); } while (0)
; #define PG8_MMA(ai, bj, At, Bt) do { __builtin_amdgcn_s_setprio(1); _Pragma("unroll") for (int m = 0; m < 4; ++m) _Pragma("unroll") for (int n = 0; n < 2; ++n) _Pragma("unroll") for (int k = 0; k < 2; ++k) \
;         acc[ai][bj][m][n] = __builtin_amdgcn_mfma_f32_16x16x32_bf16(Bt[n][k], At[m][k], acc[ai][bj][m][n], 0, 0, 0); __builtin_amdgcn_s_setprio(0); } while (0)
; #define PG8_WAIT_V(n) asm volatile("s_waitcnt vmcnt(" #n ")" ::: "memory")
; #define PG8_WAIT_L(n) asm volatile("s_waitcnt lgkmcnt(" #n ")" ::: "memory")
; #define PG8_BAR __builtin_amdgcn_s_barrier()
; #define PG8_SCHED __builtin_amdgcn_sched_barrier(0)
; template <class Sched, class Epi>
; __device__ __forceinline__ void gemm_phase(LAS unsigned char* lds, const Sched& S, const Epi& E, const int K, const int lda, const int ldb) {
;     ...
;             PG8_LDA(At, 1, 1); PG8_STAGE(PG8_SA(1, 0), a3, voffA);
;             PG8_BAR; PG8_WAIT_L(0); if (!chalf) PG8_MMA(1, 0, At, B0); PG8_BAR; PG8_SCHED;
;             PG8_STAGE(PG8_SB(1, 1), b3 + hstepB, voffB);
;             PG8_WAIT_V(6); PG8_BAR; if (!chalf) PG8_MMA(1, 1, At, B1); PG8_BAR;
;         }
;     __device__ __forceinline__ void operator()(EPI_ARGS) const {
;         const int br = u.z; const int nb = u.half ? 2 : 4;
;         u32x4 gg[2][4], pp[2][4];
	s_waitcnt lgkmcnt(0)
	s_setprio 1
	s_waitcnt lgkmcnt(0)
	v_mfma_f32_16x16x32_bf16 v[126:129], v[130:133], v[146:149], v[126:129]
	v_mfma_f32_16x16x32_bf16 v[122:125], v[138:141], v[146:149], v[122:125]
	v_mfma_f32_16x16x32_bf16 v[118:121], v[130:133], v[154:157], v[118:121]
	v_mfma_f32_16x16x32_bf16 v[114:117], v[138:141], v[154:157], v[114:117]
	v_mfma_f32_16x16x32_bf16 v[110:113], v[130:133], v[162:165], v[110:113]
	v_mfma_f32_16x16x32_bf16 v[106:109], v[138:141], v[162:165], v[106:109]
	v_mfma_f32_16x16x32_bf16 v[102:105], v[130:133], v[170:173], v[102:105]
	v_mfma_f32_16x16x32_bf16 v[98:101], v[138:141], v[170:173], v[98:101]
	v_mfma_f32_16x16x32_bf16 v[126:129], v[134:137], v[150:153], v[126:129]
	v_mfma_f32_16x16x32_bf16 v[122:125], v[142:145], v[150:153], v[122:125]
	v_mfma_f32_16x16x32_bf16 v[118:121], v[134:137], v[158:161], v[118:121]
	v_mfma_f32_16x16x32_bf16 v[114:117], v[142:145], v[158:161], v[114:117]
	v_mfma_f32_16x16x32_bf16 v[110:113], v[134:137], v[166:169], v[110:113]
	v_mfma_f32_16x16x32_bf16 v[106:109], v[142:145], v[166:169], v[106:109]
	v_mfma_f32_16x16x32_bf16 v[102:105], v[134:137], v[174:177], v[102:105]
	v_mfma_f32_16x16x32_bf16 v[98:101], v[142:145], v[174:177], v[98:101]
	s_setprio 0
	s_barrier
	s_add_i32 s28, 16, 0x1c000
	s_add_i32 s29, s49, s25
	v_add_u32_e32 v190, s28, v224
	s_mov_b32 m0, s29
	ds_read_b128 v[178:181], v190
	ds_read_b128 v[182:185], v190 offset:1024
	ds_read_b128 v[186:189], v190 offset:2048
	ds_read_b128 v[190:193], v190 offset:3072
	global_load_lds_dwordx4 v200, s[52:53]
	s_add_i32 m0, s29, 0x2000
	s_nop 0
	global_load_lds_dwordx4 v204, s[54:55]
	s_barrier
	s_waitcnt lgkmcnt(0)
	s_setprio 1
	s_waitcnt lgkmcnt(0)
	v_mfma_f32_16x16x32_bf16 v[94:97], v[178:181], v[146:149], v[94:97]
	v_mfma_f32_16x16x32_bf16 v[90:93], v[186:189], v[146:149], v[90:93]
	v_mfma_f32_16x16x32_bf16 v[86:89], v[178:181], v[154:157], v[86:89]
	v_mfma_f32_16x16x32_bf16 v[82:85], v[186:189], v[154:157], v[82:85]
	v_mfma_f32_16x16x32_bf16 v[78:81], v[178:181], v[162:165], v[78:81]
	v_mfma_f32_16x16x32_bf16 v[74:77], v[186:189], v[162:165], v[74:77]
	v_mfma_f32_16x16x32_bf16 v[70:73], v[178:181], v[170:173], v[70:73]
	v_mfma_f32_16x16x32_bf16 v[66:69], v[186:189], v[170:173], v[66:69]
	v_mfma_f32_16x16x32_bf16 v[94:97], v[182:185], v[150:153], v[94:97]
	v_mfma_f32_16x16x32_bf16 v[90:93], v[190:193], v[150:153], v[90:93]
	v_mfma_f32_16x16x32_bf16 v[86:89], v[182:185], v[158:161], v[86:89]
	v_mfma_f32_16x16x32_bf16 v[82:85], v[190:193], v[158:161], v[82:85]
	v_mfma_f32_16x16x32_bf16 v[78:81], v[182:185], v[166:169], v[78:81]
	v_mfma_f32_16x16x32_bf16 v[74:77], v[190:193], v[166:169], v[74:77]
	v_mfma_f32_16x16x32_bf16 v[70:73], v[182:185], v[174:177], v[70:73]
	v_mfma_f32_16x16x32_bf16 v[66:69], v[190:193], v[174:177], v[66:69]
	s_setprio 0
	s_mov_b32 m0, s39
	s_barrier
	ds_read_b128 v[146:149], v234 offset:49152
	ds_read_b128 v[150:153], v234 offset:50176
	ds_read_b128 v[154:157], v234 offset:51200
	ds_read_b128 v[158:161], v234 offset:52224
	ds_read_b128 v[162:165], v234 offset:53248
	ds_read_b128 v[166:169], v234 offset:54272
	ds_read_b128 v[170:173], v234 offset:55296
	ds_read_b128 v[174:177], v234 offset:56320
	global_load_lds_dwordx4 v198, s[56:57]
	s_mov_b32 m0, s40
	s_nop 0
	global_load_lds_dwordx4 v202, s[58:59]
	s_barrier
	s_waitcnt lgkmcnt(0)
	s_setprio 1
	s_waitcnt lgkmcnt(0)
	v_mfma_f32_16x16x32_bf16 v[62:65], v[130:133], v[146:149], v[62:65]
	v_mfma_f32_16x16x32_bf16 v[58:61], v[138:141], v[146:149], v[58:61]
	v_mfma_f32_16x16x32_bf16 v[54:57], v[130:133], v[154:157], v[54:57]
	v_mfma_f32_16x16x32_bf16 v[50:53], v[138:141], v[154:157], v[50:53]
	v_mfma_f32_16x16x32_bf16 v[46:49], v[130:133], v[162:165], v[46:49]
	v_mfma_f32_16x16x32_bf16 v[42:45], v[138:141], v[162:165], v[42:45]
	v_mfma_f32_16x16x32_bf16 v[38:41], v[130:133], v[170:173], v[38:41]
	v_mfma_f32_16x16x32_bf16 v[34:37], v[138:141], v[170:173], v[34:37]
	v_mfma_f32_16x16x32_bf16 v[62:65], v[134:137], v[150:153], v[62:65]
	v_mfma_f32_16x16x32_bf16 v[58:61], v[142:145], v[150:153], v[58:61]
	v_mfma_f32_16x16x32_bf16 v[54:57], v[134:137], v[158:161], v[54:57]
	v_mfma_f32_16x16x32_bf16 v[50:53], v[142:145], v[158:161], v[50:53]
	v_mfma_f32_16x16x32_bf16 v[46:49], v[134:137], v[166:169], v[46:49]
	v_mfma_f32_16x16x32_bf16 v[42:45], v[142:145], v[166:169], v[42:45]
	v_mfma_f32_16x16x32_bf16 v[38:41], v[134:137], v[174:177], v[38:41]
	v_mfma_f32_16x16x32_bf16 v[34:37], v[142:145], v[174:177], v[34:37]
	s_setprio 0
	s_barrier
	s_add_u32 s26, s26, 0x40080
	s_addc_u32 s27, s27, 0
	s_add_i32 s28, s28, s25
	s_mov_b32 m0, s28
	s_nop 0
	global_load_lds_dwordx4 v200, s[26:27]
	s_add_i32 m0, s28, 0x2000
	s_nop 0
	global_load_lds_dwordx4 v204, s[26:27]
	s_waitcnt vmcnt(6)
	s_barrier
	s_setprio 1
	v_mfma_f32_16x16x32_bf16 v[30:33], v[178:181], v[146:149], v[30:33]
	v_mfma_f32_16x16x32_bf16 v[26:29], v[186:189], v[146:149], v[26:29]
	v_mfma_f32_16x16x32_bf16 v[22:25], v[178:181], v[154:157], v[22:25]
	v_mfma_f32_16x16x32_bf16 v[18:21], v[186:189], v[154:157], v[18:21]
	v_mfma_f32_16x16x32_bf16 v[14:17], v[178:181], v[162:165], v[14:17]
	v_mfma_f32_16x16x32_bf16 v[10:13], v[186:189], v[162:165], v[10:13]
	v_mfma_f32_16x16x32_bf16 v[6:9], v[178:181], v[170:173], v[6:9]
	v_mfma_f32_16x16x32_bf16 v[2:5], v[186:189], v[170:173], v[2:5]
	v_mfma_f32_16x16x32_bf16 v[30:33], v[182:185], v[150:153], v[30:33]
	v_mfma_f32_16x16x32_bf16 v[26:29], v[190:193], v[150:153], v[26:29]
	v_mfma_f32_16x16x32_bf16 v[22:25], v[182:185], v[158:161], v[22:25]
	v_mfma_f32_16x16x32_bf16 v[18:21], v[190:193], v[158:161], v[18:21]
	v_mfma_f32_16x16x32_bf16 v[14:17], v[182:185], v[166:169], v[14:17]
	v_mfma_f32_16x16x32_bf16 v[10:13], v[190:193], v[166:169], v[10:13]
	v_mfma_f32_16x16x32_bf16 v[6:9], v[182:185], v[174:177], v[6:9]
	v_mfma_f32_16x16x32_bf16 v[2:5], v[190:193], v[174:177], v[2:5]
	s_setprio 0
	s_add_i32 s19, s19, 2
	s_add_u32 s15, s15, 0x100
	s_addc_u32 s17, s17, 0
	s_add_u32 s6, s6, 0x100
	s_addc_u32 s7, s7, 0
	s_cmp_gt_u32 s19, 13
	s_barrier
	s_cbranch_scc0 .LBB0_1486
	s_lshl_b32 s6, s48, 11
	s_ashr_i32 s7, s6, 31
	s_lshl_b64 s[26:27], s[6:7], 1
	v_lshl_or_b32 v134, s47, 8, v232
	s_add_u32 s6, s41, s26
	v_ashrrev_i32_e32 v135, 31, v134
	s_addc_u32 s7, s42, s27
	v_lshlrev_b64 v[212:213], 1, v[134:135]
	v_add_u32_e32 v130, s24, v1
	v_lshl_add_u64 v[216:217], s[6:7], 0, v[212:213]
	v_mad_i64_i32 v[132:133], s[6:7], v130, s45, v[216:217]
	global_load_dwordx4 v[194:197], v[132:133], off
	v_ashrrev_i32_e32 v131, 31, v130
	s_cmp_gt_i32 s48, 0
	v_lshl_add_u64 v[218:219], s[8:9], 0, v[212:213]
	v_lshlrev_b64 v[132:133], 12, v[130:131]
	s_cselect_b64 s[28:29], -1, 0
	s_cmp_lt_i32 s48, 1
	v_lshl_add_u64 v[136:137], v[218:219], 0, v[132:133]
	s_cbranch_scc1 .LBB0_1489
	global_load_dwordx4 v[190:193], v[136:137], off
	s_branch .LBB0_1490

; #define PG8_STAGE(bufoff, gbase, voff) do { _Pragma("unroll") for (int _i = 0; _i < 2; ++_i) \
;         __builtin_amdgcn_global_load_lds((const unsigned*)((const char*)(gbase) + (voff)[_i]), (LAS unsigned*)(lds + (bufoff) + ldsw + _i * 8192), 16, 0, 0); } while (0)
; #define PG8_LDA(dst, b, h) do { _Pragma("unroll") for (int m = 0; m < 4; ++m) _Pragma("unroll") for (int k = 0; k < 2; ++k) dst[m][k] = *(const LAS bf16x8*)(lds + PG8_SA(b, h) + aoff + m * 2048 + k * 1024); } while (0)
; #define PG8_LDB(dst, b, h) do { _Pragma("unroll") for (int n = 0; n < 2; ++n) _Pragma("unroll") for (int k = 0; k < 2; ++k) dst[n][k] = *(const LAS bf16x8*)(lds + PG8_SB(b, h) + boff + n * 2048 + k * 1024); } while (0)
; #define PG8_MMA(ai, bj, At, Bt) do { __builtin_amdgcn_s_setprio(1); _Pragma("unroll") for (int m = 0; m < 4; ++m) _Pragma("unroll") for (int n = 0; n < 2; ++n) _Pragma("unroll") for (int k = 0; k < 2; ++k) \
;         acc[ai][bj][m][n] = __builtin_amdgcn_mfma_f32_16x16x32_bf16(Bt[n][k], At[m][k], acc[ai][bj][m][n], 0, 0, 0); __builtin_amdgcn_s_setprio(0); } while (0)
; #define PG8_WAIT_L(n) asm volatile("s_waitcnt lgkmcnt(" #n ")" ::: "memory")
; #define PG8_BAR __builtin_amdgcn_s_barrier()
; #define PG8_SCHED __builtin_amdgcn_sched_barrier(0)
; template <class Sched, class Epi>
; __device__ __forceinline__ void gemm_phase(LAS unsigned char* lds, const Sched& S, const Epi& E, const int K, const int lda, const int ldb) {
;     ...
;         for (int t = 0; t < nt; t += 2) {
;             const bool last = (t == nt - 2);
;             const char* a1 = cA + (size_t)(t + 1) * kstep;
;             const char* a2 = last ? nA : cA + (size_t)(t + 2) * kstep; const char* b2 = last ? nB : cB + (size_t)(t + 2) * kstep;
;             const char* a3 = a2 + kstep; const char* b3 = b2 + kstep;
;             PG8_LDB(B0, 0, 0); PG8_SCHED; PG8_LDA(At, 0, 0); PG8_STAGE(PG8_SA(1, 1), a1 + hstepA, voffA);
;             PG8_WAIT_L(8); PG8_BAR; PG8_WAIT_L(0); PG8_MMA(0, 0, At, B0); PG8_BAR; PG8_SCHED;
;             PG8_LDB(B1, 0, 1); PG8_STAGE(PG8_SB(0, 0), b2, voffB);
;             PG8_BAR; PG8_WAIT_L(0); PG8_MMA(0, 1, At, B1); PG8_BAR;
;             PG8_LDA(At, 0, 1); PG8_STAGE(PG8_SA(0, 0), a2, voffA);
;             PG8_BAR; PG8_WAIT_L(0); if (!chalf) PG8_MMA(1, 0, At, B0); PG8_BAR; PG8_SCHED;
.Lal_1593:
.LBB0_1593:
	ds_read_b128 v[156:159], v153
	ds_read_b128 v[160:163], v153 offset:1024
	ds_read_b128 v[164:167], v153 offset:2048
	ds_read_b128 v[168:171], v153 offset:3072
	s_add_u32 s28, s26, 0xfff80080
	s_addc_u32 s29, s27, -1
	s_cmp_eq_u32 s46, 28
	s_cselect_b32 s35, s23, s29
	s_cselect_b32 s34, s22, s28
	s_cselect_b32 s29, s25, s17
	s_cselect_b32 s28, s24, s15
	s_add_i32 m0, s5, 0xc000
	ds_read_b128 v[172:175], v154
	ds_read_b128 v[176:179], v154 offset:1024
	ds_read_b128 v[180:183], v154 offset:2048
	ds_read_b128 v[184:187], v154 offset:3072
	ds_read_b128 v[188:191], v154 offset:4096
	ds_read_b128 v[192:195], v154 offset:5120
	ds_read_b128 v[196:199], v154 offset:6144
	ds_read_b128 v[200:203], v154 offset:7168
	global_load_lds_dwordx4 v140, s[26:27]
	s_add_i32 m0, s5, 0xe000
	s_nop 0
	global_load_lds_dwordx4 v138, s[26:27]
	s_waitcnt lgkmcnt(8)
	s_barrier
	s_waitcnt lgkmcnt(0)
	s_setprio 1
	s_waitcnt lgkmcnt(0)
	v_mfma_f32_16x16x32_bf16 v[126:129], v[156:159], v[172:175], v[126:129]
	v_mfma_f32_16x16x32_bf16 v[122:125], v[164:167], v[172:175], v[122:125]
	v_mfma_f32_16x16x32_bf16 v[114:117], v[156:159], v[180:183], v[114:117]
	v_mfma_f32_16x16x32_bf16 v[106:109], v[164:167], v[180:183], v[106:109]
	v_mfma_f32_16x16x32_bf16 v[98:101], v[156:159], v[188:191], v[98:101]
	v_mfma_f32_16x16x32_bf16 v[90:93], v[164:167], v[188:191], v[90:93]
	v_mfma_f32_16x16x32_bf16 v[82:85], v[156:159], v[196:199], v[82:85]
	v_mfma_f32_16x16x32_bf16 v[74:77], v[164:167], v[196:199], v[74:77]
	v_mfma_f32_16x16x32_bf16 v[126:129], v[160:163], v[176:179], v[126:129]
	v_mfma_f32_16x16x32_bf16 v[122:125], v[168:171], v[176:179], v[122:125]
	v_mfma_f32_16x16x32_bf16 v[114:117], v[160:163], v[184:187], v[114:117]
	v_mfma_f32_16x16x32_bf16 v[106:109], v[168:171], v[184:187], v[106:109]
	v_mfma_f32_16x16x32_bf16 v[98:101], v[160:163], v[192:195], v[98:101]
	v_mfma_f32_16x16x32_bf16 v[90:93], v[168:171], v[192:195], v[90:93]
	v_mfma_f32_16x16x32_bf16 v[82:85], v[160:163], v[200:203], v[82:85]
	v_mfma_f32_16x16x32_bf16 v[74:77], v[168:171], v[200:203], v[74:77]
	s_setprio 0
	s_barrier
	s_add_i32 s47, s43, s31
	s_add_u32 s52, s28, s8
	s_addc_u32 s53, s29, s9
	s_mov_b32 m0, s47
	ds_read_b128 v[204:207], v155
	ds_read_b128 v[208:211], v155 offset:1024
	ds_read_b128 v[212:215], v155 offset:2048
	ds_read_b128 v[216:219], v155 offset:3072
	global_load_lds_dwordx4 v132, s[28:29]
	s_add_u32 s54, s28, s8
	s_addc_u32 s55, s29, s9
	s_add_i32 m0, s47, 0x2000
	s_nop 0
	global_load_lds_dwordx4 v136, s[28:29]
	s_barrier
	s_waitcnt lgkmcnt(0)
	s_setprio 1
	s_waitcnt lgkmcnt(0)
	v_mfma_f32_16x16x32_bf16 v[118:121], v[204:207], v[172:175], v[118:121]
	v_mfma_f32_16x16x32_bf16 v[110:113], v[212:215], v[172:175], v[110:113]
	v_mfma_f32_16x16x32_bf16 v[102:105], v[204:207], v[180:183], v[102:105]
	v_mfma_f32_16x16x32_bf16 v[94:97], v[212:215], v[180:183], v[94:97]
	v_mfma_f32_16x16x32_bf16 v[86:89], v[204:207], v[188:191], v[86:89]
	v_mfma_f32_16x16x32_bf16 v[78:81], v[212:215], v[188:191], v[78:81]
	v_mfma_f32_16x16x32_bf16 v[70:73], v[204:207], v[196:199], v[70:73]
	v_mfma_f32_16x16x32_bf16 v[66:69], v[212:215], v[196:199], v[66:69]
	v_mfma_f32_16x16x32_bf16 v[118:121], v[208:211], v[176:179], v[118:121]
	v_mfma_f32_16x16x32_bf16 v[110:113], v[216:219], v[176:179], v[110:113]
	v_mfma_f32_16x16x32_bf16 v[102:105], v[208:211], v[184:187], v[102:105]
	v_mfma_f32_16x16x32_bf16 v[94:97], v[216:219], v[184:187], v[94:97]
	v_mfma_f32_16x16x32_bf16 v[86:89], v[208:211], v[192:195], v[86:89]
	v_mfma_f32_16x16x32_bf16 v[78:81], v[216:219], v[192:195], v[78:81]
	v_mfma_f32_16x16x32_bf16 v[70:73], v[208:211], v[200:203], v[70:73]
	v_mfma_f32_16x16x32_bf16 v[66:69], v[216:219], v[200:203], v[66:69]
	s_setprio 0
	s_mov_b32 m0, s5
	s_add_u32 s56, s34, s8
	s_addc_u32 s57, s35, s9
	s_barrier
	ds_read_b128 v[172:175], v154 offset:16384
	ds_read_b128 v[176:179], v154 offset:17408
	ds_read_b128 v[180:183], v154 offset:18432
	ds_read_b128 v[184:187], v154 offset:19456
	ds_read_b128 v[188:191], v154 offset:20480
	ds_read_b128 v[192:195], v154 offset:21504
	ds_read_b128 v[196:199], v154 offset:22528
	ds_read_b128 v[200:203], v154 offset:23552
	global_load_lds_dwordx4 v130, s[34:35]
	s_add_u32 s58, s34, s8
	s_addc_u32 s59, s35, s9
	s_mov_b32 m0, s33
	s_nop 0
	global_load_lds_dwordx4 v134, s[34:35]
	s_barrier
	s_waitcnt lgkmcnt(0)
	s_setprio 1
	s_waitcnt lgkmcnt(0)
	v_mfma_f32_16x16x32_bf16 v[62:65], v[156:159], v[172:175], v[62:65]
	v_mfma_f32_16x16x32_bf16 v[58:61], v[164:167], v[172:175], v[58:61]
	v_mfma_f32_16x16x32_bf16 v[54:57], v[156:159], v[180:183], v[54:57]
	v_mfma_f32_16x16x32_bf16 v[46:49], v[164:167], v[180:183], v[46:49]
	v_mfma_f32_16x16x32_bf16 v[38:41], v[156:159], v[188:191], v[38:41]
	v_mfma_f32_16x16x32_bf16 v[30:33], v[164:167], v[188:191], v[30:33]
	v_mfma_f32_16x16x32_bf16 v[22:25], v[156:159], v[196:199], v[22:25]
	v_mfma_f32_16x16x32_bf16 v[14:17], v[164:167], v[196:199], v[14:17]
	v_mfma_f32_16x16x32_bf16 v[62:65], v[160:163], v[176:179], v[62:65]
	v_mfma_f32_16x16x32_bf16 v[58:61], v[168:171], v[176:179], v[58:61]
	v_mfma_f32_16x16x32_bf16 v[54:57], v[160:163], v[184:187], v[54:57]
	v_mfma_f32_16x16x32_bf16 v[46:49], v[168:171], v[184:187], v[46:49]
	v_mfma_f32_16x16x32_bf16 v[38:41], v[160:163], v[192:195], v[38:41]
	v_mfma_f32_16x16x32_bf16 v[30:33], v[168:171], v[192:195], v[30:33]
	v_mfma_f32_16x16x32_bf16 v[22:25], v[160:163], v[200:203], v[22:25]
	v_mfma_f32_16x16x32_bf16 v[14:17], v[168:171], v[200:203], v[14:17]
	s_setprio 0
	s_barrier
; #define PG8_STAGE(bufoff, gbase, voff) do { _Pragma("unroll") for (int _i = 0; _i < 2; ++_i) \
;         __builtin_amdgcn_global_load_lds((const unsigned*)((const char*)(gbase) + (voff)[_i]), (LAS unsigned*)(lds + (bufoff) + ldsw + _i * 8192), 16, 0, 0); } while (0)
; #define PG8_LDA(dst, b, h) do { _Pragma("unroll") for (int m = 0; m < 4; ++m) _Pragma("unroll") for (int k = 0; k < 2; ++k) dst[m][k] = *(const LAS bf16x8*)(lds + PG8_SA(b, h) + aoff + m * 2048 + k * 1024); } while (0)
; #define PG8_LDB(dst, b, h) do { _Pragma("unroll") for (int n = 0; n < 2; ++n) _Pragma("unroll") for (int k = 0; k < 2; ++k) dst[n][k] = *(const LAS bf16x8*)(lds + PG8_SB(b, h) + boff + n * 2048 + k * 1024); } while (0)
; #define PG8_MMA(ai, bj, At, Bt) do { __builtin_amdgcn_s_setprio(1); _Pragma("unroll") for (int m = 0; m < 4; ++m) _Pragma("unroll") for (int n = 0; n < 2; ++n) _Pragma("unroll") for (int k = 0; k < 2; ++k) \
;         acc[ai][bj][m][n] = __builtin_amdgcn_mfma_f32_16x16x32_bf16(Bt[n][k], At[m][k], acc[ai][bj][m][n], 0, 0, 0); __builtin_amdgcn_s_setprio(0); } while (0)
; #define PG8_WAIT_V(n) asm volatile("s_waitcnt vmcnt(" #n ")" ::: "memory")
; #define PG8_WAIT_L(n) asm volatile("s_waitcnt lgkmcnt(" #n ")" ::: "memory")
; #define PG8_BAR __builtin_amdgcn_s_barrier()
; #define PG8_SCHED __builtin_amdgcn_sched_barrier(0)
; template <class Sched, class Epi>
; __device__ __forceinline__ void gemm_phase(LAS unsigned char* lds, const Sched& S, const Epi& E, const int K, const int lda, const int ldb) {
;     ...
;             PG8_STAGE(PG8_SB(0, 1), b2 + hstepB, voffB);
;             PG8_WAIT_V(6); PG8_BAR; if (!chalf) PG8_MMA(1, 1, At, B1); PG8_BAR;
;             PG8_LDB(B0, 1, 0); PG8_SCHED; PG8_LDA(At, 1, 0); PG8_STAGE(PG8_SA(0, 1), a2 + hstepA, voffA);
;             PG8_WAIT_L(8); PG8_BAR; PG8_WAIT_L(0); PG8_MMA(0, 0, At, B0); PG8_BAR; PG8_SCHED;
;             PG8_LDB(B1, 1, 1); PG8_STAGE(PG8_SB(1, 0), b3, voffB);
;             PG8_BAR; PG8_WAIT_L(0); PG8_MMA(0, 1, At, B1); PG8_BAR;
;             PG8_LDA(At, 1, 1); PG8_STAGE(PG8_SA(1, 0), a3, voffA);
;             PG8_BAR; PG8_WAIT_L(0); if (!chalf) PG8_MMA(1, 0, At, B0); PG8_BAR; PG8_SCHED;
	s_add_u32 s48, s28, 0x80000
	s_addc_u32 s49, s29, 0
	s_add_i32 s47, s44, s31
	s_mov_b32 m0, s47
	s_nop 0
	global_load_lds_dwordx4 v132, s[48:49]
	s_add_i32 m0, s47, 0x2000
	s_nop 0
	global_load_lds_dwordx4 v136, s[48:49]
	s_waitcnt vmcnt(6)
	s_barrier
	s_setprio 1
	v_mfma_f32_16x16x32_bf16 v[50:53], v[204:207], v[172:175], v[50:53]
	v_mfma_f32_16x16x32_bf16 v[42:45], v[212:215], v[172:175], v[42:45]
	v_mfma_f32_16x16x32_bf16 v[34:37], v[204:207], v[180:183], v[34:37]
	v_mfma_f32_16x16x32_bf16 v[26:29], v[212:215], v[180:183], v[26:29]
	v_mfma_f32_16x16x32_bf16 v[18:21], v[204:207], v[188:191], v[18:21]
	v_mfma_f32_16x16x32_bf16 v[10:13], v[212:215], v[188:191], v[10:13]
	v_mfma_f32_16x16x32_bf16 v[6:9], v[204:207], v[196:199], v[6:9]
	v_mfma_f32_16x16x32_bf16 v[2:5], v[212:215], v[196:199], v[2:5]
	v_mfma_f32_16x16x32_bf16 v[50:53], v[208:211], v[176:179], v[50:53]
	v_mfma_f32_16x16x32_bf16 v[42:45], v[216:219], v[176:179], v[42:45]
	v_mfma_f32_16x16x32_bf16 v[34:37], v[208:211], v[184:187], v[34:37]
	v_mfma_f32_16x16x32_bf16 v[26:29], v[216:219], v[184:187], v[26:29]
	v_mfma_f32_16x16x32_bf16 v[18:21], v[208:211], v[192:195], v[18:21]
	v_mfma_f32_16x16x32_bf16 v[10:13], v[216:219], v[192:195], v[10:13]
	v_mfma_f32_16x16x32_bf16 v[6:9], v[208:211], v[200:203], v[6:9]
	v_mfma_f32_16x16x32_bf16 v[2:5], v[216:219], v[200:203], v[2:5]
	s_setprio 0
	s_add_i32 s47, 16, 0x18000
	v_add_u32_e32 v168, s47, v144
	s_barrier
	ds_read_b128 v[156:159], v168
	ds_read_b128 v[160:163], v168 offset:1024
	ds_read_b128 v[164:167], v168 offset:2048
	ds_read_b128 v[168:171], v168 offset:3072
	s_add_u32 s34, s34, 0x80000
	s_addc_u32 s35, s35, 0
	s_mov_b32 m0, s36
	ds_read_b128 v[172:175], v154 offset:32768
	ds_read_b128 v[176:179], v154 offset:33792
	ds_read_b128 v[180:183], v154 offset:34816
	ds_read_b128 v[184:187], v154 offset:35840
	ds_read_b128 v[188:191], v154 offset:36864
	ds_read_b128 v[192:195], v154 offset:37888
	ds_read_b128 v[196:199], v154 offset:38912
	ds_read_b128 v[200:203], v154 offset:39936
	global_load_lds_dwordx4 v130, s[34:35]
	s_mov_b32 m0, s37
	s_nop 0
	global_load_lds_dwordx4 v134, s[34:35]
	s_waitcnt lgkmcnt(8)
	s_barrier
	s_waitcnt lgkmcnt(0)
	s_setprio 1
	s_waitcnt lgkmcnt(0)
	v_mfma_f32_16x16x32_bf16 v[126:129], v[156:159], v[172:175], v[126:129]
	v_mfma_f32_16x16x32_bf16 v[122:125], v[164:167], v[172:175], v[122:125]
	v_mfma_f32_16x16x32_bf16 v[114:117], v[156:159], v[180:183], v[114:117]
	v_mfma_f32_16x16x32_bf16 v[106:109], v[164:167], v[180:183], v[106:109]
	v_mfma_f32_16x16x32_bf16 v[98:101], v[156:159], v[188:191], v[98:101]
	v_mfma_f32_16x16x32_bf16 v[90:93], v[164:167], v[188:191], v[90:93]
	v_mfma_f32_16x16x32_bf16 v[82:85], v[156:159], v[196:199], v[82:85]
	v_mfma_f32_16x16x32_bf16 v[74:77], v[164:167], v[196:199], v[74:77]
	v_mfma_f32_16x16x32_bf16 v[126:129], v[160:163], v[176:179], v[126:129]
	v_mfma_f32_16x16x32_bf16 v[122:125], v[168:171], v[176:179], v[122:125]
	v_mfma_f32_16x16x32_bf16 v[114:117], v[160:163], v[184:187], v[114:117]
	v_mfma_f32_16x16x32_bf16 v[106:109], v[168:171], v[184:187], v[106:109]
	v_mfma_f32_16x16x32_bf16 v[98:101], v[160:163], v[192:195], v[98:101]
	v_mfma_f32_16x16x32_bf16 v[90:93], v[168:171], v[192:195], v[90:93]
	v_mfma_f32_16x16x32_bf16 v[82:85], v[160:163], v[200:203], v[82:85]
	v_mfma_f32_16x16x32_bf16 v[74:77], v[168:171], v[200:203], v[74:77]
	s_setprio 0
	s_barrier
	s_add_i32 s34, 16, 0x1c000
	s_add_i32 s35, s47, s31
	v_add_u32_e32 v216, s34, v144
	s_mov_b32 m0, s35
	ds_read_b128 v[204:207], v216
	ds_read_b128 v[208:211], v216 offset:1024
	ds_read_b128 v[212:215], v216 offset:2048
	ds_read_b128 v[216:219], v216 offset:3072
	global_load_lds_dwordx4 v132, s[52:53]
	s_add_i32 m0, s35, 0x2000
	s_nop 0
	global_load_lds_dwordx4 v136, s[54:55]
	s_barrier
	s_waitcnt lgkmcnt(0)
	s_setprio 1
	s_waitcnt lgkmcnt(0)
	v_mfma_f32_16x16x32_bf16 v[118:121], v[204:207], v[172:175], v[118:121]
	v_mfma_f32_16x16x32_bf16 v[110:113], v[212:215], v[172:175], v[110:113]
	v_mfma_f32_16x16x32_bf16 v[102:105], v[204:207], v[180:183], v[102:105]
	v_mfma_f32_16x16x32_bf16 v[94:97], v[212:215], v[180:183], v[94:97]
	v_mfma_f32_16x16x32_bf16 v[86:89], v[204:207], v[188:191], v[86:89]
	v_mfma_f32_16x16x32_bf16 v[78:81], v[212:215], v[188:191], v[78:81]
	v_mfma_f32_16x16x32_bf16 v[70:73], v[204:207], v[196:199], v[70:73]
	v_mfma_f32_16x16x32_bf16 v[66:69], v[212:215], v[196:199], v[66:69]
	v_mfma_f32_16x16x32_bf16 v[118:121], v[208:211], v[176:179], v[118:121]
	v_mfma_f32_16x16x32_bf16 v[110:113], v[216:219], v[176:179], v[110:113]
	v_mfma_f32_16x16x32_bf16 v[102:105], v[208:211], v[184:187], v[102:105]
	v_mfma_f32_16x16x32_bf16 v[94:97], v[216:219], v[184:187], v[94:97]
	v_mfma_f32_16x16x32_bf16 v[86:89], v[208:211], v[192:195], v[86:89]
	v_mfma_f32_16x16x32_bf16 v[78:81], v[216:219], v[192:195], v[78:81]
	v_mfma_f32_16x16x32_bf16 v[70:73], v[208:211], v[200:203], v[70:73]
	v_mfma_f32_16x16x32_bf16 v[66:69], v[216:219], v[200:203], v[66:69]
	s_setprio 0
	s_mov_b32 m0, s39
	s_barrier
	ds_read_b128 v[172:175], v154 offset:49152
	ds_read_b128 v[176:179], v154 offset:50176
	ds_read_b128 v[180:183], v154 offset:51200
	ds_read_b128 v[184:187], v154 offset:52224
	ds_read_b128 v[188:191], v154 offset:53248
	ds_read_b128 v[192:195], v154 offset:54272
	ds_read_b128 v[196:199], v154 offset:55296
	ds_read_b128 v[200:203], v154 offset:56320
	global_load_lds_dwordx4 v130, s[56:57]
	s_mov_b32 m0, s40
	s_nop 0
	global_load_lds_dwordx4 v134, s[58:59]
	s_barrier
; #define PG8_STAGE(bufoff, gbase, voff) do { _Pragma("unroll") for (int _i = 0; _i < 2; ++_i) \
;         __builtin_amdgcn_global_load_lds((const unsigned*)((const char*)(gbase) + (voff)[_i]), (LAS unsigned*)(lds + (bufoff) + ldsw + _i * 8192), 16, 0, 0); } while (0)
; #define PG8_MMA(ai, bj, At, Bt) do { __builtin_amdgcn_s_setprio(1); _Pragma("unroll") for (int m = 0; m < 4; ++m) _Pragma("unroll") for (int n = 0; n < 2; ++n) _Pragma("unroll") for (int k = 0; k < 2; ++k) \
;         acc[ai][bj][m][n] = __builtin_amdgcn_mfma_f32_16x16x32_bf16(Bt[n][k], At[m][k], acc[ai][bj][m][n], 0, 0, 0); __builtin_amdgcn_s_setprio(0); } while (0)
; #define PG8_WAIT_V(n) asm volatile("s_waitcnt vmcnt(" #n ")" ::: "memory")
; #define PG8_WAIT_L(n) asm volatile("s_waitcnt lgkmcnt(" #n ")" ::: "memory")
; #define PG8_BAR __builtin_amdgcn_s_barrier()
; #define PG8_SCHED __builtin_amdgcn_sched_barrier(0)
; template <class Sched, class Epi>
; __device__ __forceinline__ void gemm_phase(LAS unsigned char* lds, const Sched& S, const Epi& E, const int K, const int lda, const int ldb) {
;     ...
;             PG8_BAR; PG8_WAIT_L(0); if (!chalf) PG8_MMA(1, 0, At, B0); PG8_BAR; PG8_SCHED;
;             PG8_STAGE(PG8_SB(1, 1), b3 + hstepB, voffB);
;             PG8_WAIT_V(6); PG8_BAR; if (!chalf) PG8_MMA(1, 1, At, B1); PG8_BAR;
;         }
	s_waitcnt lgkmcnt(0)
	s_setprio 1
	s_waitcnt lgkmcnt(0)
	v_mfma_f32_16x16x32_bf16 v[62:65], v[156:159], v[172:175], v[62:65]
	v_mfma_f32_16x16x32_bf16 v[58:61], v[164:167], v[172:175], v[58:61]
	v_mfma_f32_16x16x32_bf16 v[54:57], v[156:159], v[180:183], v[54:57]
	v_mfma_f32_16x16x32_bf16 v[46:49], v[164:167], v[180:183], v[46:49]
	v_mfma_f32_16x16x32_bf16 v[38:41], v[156:159], v[188:191], v[38:41]
	v_mfma_f32_16x16x32_bf16 v[30:33], v[164:167], v[188:191], v[30:33]
	v_mfma_f32_16x16x32_bf16 v[22:25], v[156:159], v[196:199], v[22:25]
	v_mfma_f32_16x16x32_bf16 v[14:17], v[164:167], v[196:199], v[14:17]
	v_mfma_f32_16x16x32_bf16 v[62:65], v[160:163], v[176:179], v[62:65]
	v_mfma_f32_16x16x32_bf16 v[58:61], v[168:171], v[176:179], v[58:61]
	v_mfma_f32_16x16x32_bf16 v[54:57], v[160:163], v[184:187], v[54:57]
	v_mfma_f32_16x16x32_bf16 v[46:49], v[168:171], v[184:187], v[46:49]
	v_mfma_f32_16x16x32_bf16 v[38:41], v[160:163], v[192:195], v[38:41]
	v_mfma_f32_16x16x32_bf16 v[30:33], v[168:171], v[192:195], v[30:33]
	v_mfma_f32_16x16x32_bf16 v[22:25], v[160:163], v[200:203], v[22:25]
	v_mfma_f32_16x16x32_bf16 v[14:17], v[168:171], v[200:203], v[14:17]
	s_setprio 0
	s_barrier
	s_add_u32 s28, s28, 0x80080
	s_addc_u32 s29, s29, 0
	s_add_i32 s34, s34, s31
	s_mov_b32 m0, s34
	s_nop 0
	global_load_lds_dwordx4 v132, s[28:29]
	s_add_i32 m0, s34, 0x2000
	s_nop 0
	global_load_lds_dwordx4 v136, s[28:29]
	s_waitcnt vmcnt(6)
	s_barrier
	s_setprio 1
	v_mfma_f32_16x16x32_bf16 v[50:53], v[204:207], v[172:175], v[50:53]
	v_mfma_f32_16x16x32_bf16 v[42:45], v[212:215], v[172:175], v[42:45]
	v_mfma_f32_16x16x32_bf16 v[34:37], v[204:207], v[180:183], v[34:37]
	v_mfma_f32_16x16x32_bf16 v[26:29], v[212:215], v[180:183], v[26:29]
	v_mfma_f32_16x16x32_bf16 v[18:21], v[204:207], v[188:191], v[18:21]
	v_mfma_f32_16x16x32_bf16 v[10:13], v[212:215], v[188:191], v[10:13]
	v_mfma_f32_16x16x32_bf16 v[6:9], v[204:207], v[196:199], v[6:9]
	v_mfma_f32_16x16x32_bf16 v[2:5], v[212:215], v[196:199], v[2:5]
	v_mfma_f32_16x16x32_bf16 v[50:53], v[208:211], v[176:179], v[50:53]
	v_mfma_f32_16x16x32_bf16 v[42:45], v[216:219], v[176:179], v[42:45]
	v_mfma_f32_16x16x32_bf16 v[34:37], v[208:211], v[184:187], v[34:37]
	v_mfma_f32_16x16x32_bf16 v[26:29], v[216:219], v[184:187], v[26:29]
	v_mfma_f32_16x16x32_bf16 v[18:21], v[208:211], v[192:195], v[18:21]
	v_mfma_f32_16x16x32_bf16 v[10:13], v[216:219], v[192:195], v[10:13]
	v_mfma_f32_16x16x32_bf16 v[6:9], v[208:211], v[200:203], v[6:9]
	v_mfma_f32_16x16x32_bf16 v[2:5], v[216:219], v[200:203], v[2:5]
	s_setprio 0
	s_add_i32 s46, s46, 2
	s_add_u32 s15, s15, 0x100
	s_addc_u32 s17, s17, 0
	s_add_u32 s26, s26, 0x100
	s_addc_u32 s27, s27, 0
	s_cmp_gt_u32 s46, 29
	s_barrier
	s_cbranch_scc0 .LBB0_1593
; __device__ __forceinline__ unsigned cvt_pk_bf16(float lo, float hi) { unsigned r; asm volatile("v_cvt_pk_bf16_f32 %0, %1, %2" : "=v"(r) : "v"(lo), "v"(hi)); return r; }
; #define PG8_WAIT_V(n) asm volatile("s_waitcnt vmcnt(" #n ")" ::: "memory")
; #define PG8_BAR __builtin_amdgcn_s_barrier()
; #define EPI_FOR_ROWS _Pragma("unroll") for (int ai = 0; ai < 2; ++ai) if (ai == 0 || !u.half) _Pragma("unroll") for (int m = 0; m < 4; ++m)
; template <class Sched, class Epi>
; __device__ __forceinline__ void gemm_phase(LAS unsigned char* lds, const Sched& S, const Epi& E, const int K, const int lda, const int ldb) {
;     ...
;         E(acc, cur, wr, wc, fr, fq);
;         if (!has_next) break;
; #pragma unroll
;         for (int a = 0; a < 2; ++a)
; #pragma unroll
;             for (int b = 0; b < 2; ++b)
; #pragma unroll
;                 for (int m = 0; m < 4; ++m)
; #pragma unroll
;                     for (int n = 0; n < 2; ++n) acc[a][b][m][n] = (f32x4){0.f, 0.f, 0.f, 0.f};
;         cur = nxt; cA = nA; cB = nB; ++ui;
;     }
;     PG8_WAIT_V(0);
;     if (wr == 0) PG8_BAR;
;     PG8_BAR;
;     __device__ __forceinline__ void operator()(EPI_ARGS) const {
;         EPI_FOR_ROWS { bf16_t* rp = O + (size_t)EPI_ROW * ldc;
; #pragma unroll
;             for (int bj = 0; bj < 2; ++bj) { const f32x4 v0 = acc[ai][bj][m][0], v1 = acc[ai][bj][m][1]; u32x4 o;
;                 o[0] = cvt_pk_bf16(v0[0], v0[1]); o[1] = cvt_pk_bf16(v0[2], v0[3]); o[2] = cvt_pk_bf16(v1[0], v1[1]); o[3] = cvt_pk_bf16(v1[2], v1[3]);
;                 *(u32x4*)(rp + EPI_COL(bj)) = o; } }
	v_add_u32_e32 v156, s4, v1
	v_ashrrev_i32_e32 v157, 31, v156
	v_cvt_pk_bf16_f32 v126, v126, v127
	v_cvt_pk_bf16_f32 v127, v128, v129
	v_cvt_pk_bf16_f32 v128, v122, v123
	v_lshl_or_b32 v122, s45, 8, v152
	v_lshlrev_b64 v[156:157], 12, v[156:157]
	v_ashrrev_i32_e32 v123, 31, v122
	v_lshl_add_u64 v[156:157], s[6:7], 0, v[156:157]
	v_lshlrev_b64 v[122:123], 1, v[122:123]
	v_cvt_pk_bf16_f32 v129, v124, v125
	v_lshl_add_u64 v[124:125], v[156:157], 0, v[122:123]
	global_store_dwordx4 v[124:125], v[126:129], off
	v_cvt_pk_bf16_f32 v118, v118, v119
	v_cvt_pk_bf16_f32 v119, v120, v121
	v_cvt_pk_bf16_f32 v120, v110, v111
	v_add_u32_e32 v110, s4, v145
	v_ashrrev_i32_e32 v111, 31, v110
	v_lshlrev_b64 v[110:111], 12, v[110:111]
	v_cvt_pk_bf16_f32 v121, v112, v113
	global_store_dwordx4 v[124:125], v[118:121], off offset:256
	s_and_b64 vcc, exec, s[12:13]
	s_mov_b32 s45, s14
	v_lshl_add_u64 v[118:119], s[6:7], 0, v[110:111]
	v_cvt_pk_bf16_f32 v110, v114, v115
	v_cvt_pk_bf16_f32 v111, v116, v117
	v_cvt_pk_bf16_f32 v112, v106, v107
	v_lshl_add_u64 v[106:107], v[118:119], 0, v[122:123]
	v_cvt_pk_bf16_f32 v113, v108, v109
	global_store_dwordx4 v[106:107], v[110:113], off
	v_cvt_pk_bf16_f32 v102, v102, v103
	v_cvt_pk_bf16_f32 v103, v104, v105
	v_cvt_pk_bf16_f32 v104, v94, v95
	v_add_u32_e32 v94, s4, v146
	v_ashrrev_i32_e32 v95, 31, v94
	v_lshlrev_b64 v[94:95], 12, v[94:95]
	v_cvt_pk_bf16_f32 v105, v96, v97
	global_store_dwordx4 v[106:107], v[102:105], off offset:256
	s_mov_b64 s[28:29], s[20:21]
	s_mov_b64 s[26:27], s[18:19]
	v_lshl_add_u64 v[102:103], s[6:7], 0, v[94:95]
	v_cvt_pk_bf16_f32 v94, v98, v99
	v_cvt_pk_bf16_f32 v95, v100, v101
	v_cvt_pk_bf16_f32 v96, v90, v91
	v_lshl_add_u64 v[90:91], v[102:103], 0, v[122:123]
	v_cvt_pk_bf16_f32 v97, v92, v93
	global_store_dwordx4 v[90:91], v[94:97], off
	v_cvt_pk_bf16_f32 v86, v86, v87
	v_cvt_pk_bf16_f32 v87, v88, v89
	v_cvt_pk_bf16_f32 v88, v78, v79
	v_add_u32_e32 v78, s4, v147
	v_ashrrev_i32_e32 v79, 31, v78
	v_lshlrev_b64 v[78:79], 12, v[78:79]
	v_cvt_pk_bf16_f32 v89, v80, v81
	global_store_dwordx4 v[90:91], v[86:89], off offset:256
	s_nop 1
	v_lshl_add_u64 v[86:87], s[6:7], 0, v[78:79]
	v_cvt_pk_bf16_f32 v78, v82, v83
	v_cvt_pk_bf16_f32 v79, v84, v85
	v_cvt_pk_bf16_f32 v80, v74, v75
	v_lshl_add_u64 v[74:75], v[86:87], 0, v[122:123]
	v_cvt_pk_bf16_f32 v81, v76, v77
	global_store_dwordx4 v[74:75], v[78:81], off
	v_cvt_pk_bf16_f32 v70, v70, v71
	v_cvt_pk_bf16_f32 v71, v72, v73
	v_cvt_pk_bf16_f32 v72, v66, v67
	v_add_u32_e32 v66, s4, v148
	v_ashrrev_i32_e32 v67, 31, v66
	v_lshlrev_b64 v[66:67], 12, v[66:67]
	v_lshl_add_u64 v[66:67], s[6:7], 0, v[66:67]
	v_cvt_pk_bf16_f32 v73, v68, v69
	global_store_dwordx4 v[74:75], v[70:73], off offset:256
	v_cvt_pk_bf16_f32 v62, v62, v63
	v_cvt_pk_bf16_f32 v63, v64, v65
	v_cvt_pk_bf16_f32 v64, v58, v59
	v_lshl_add_u64 v[58:59], v[66:67], 0, v[122:123]
	v_cvt_pk_bf16_f32 v65, v60, v61
	global_store_dwordx4 v[58:59], v[62:65], off
	v_cvt_pk_bf16_f32 v50, v50, v51
	v_cvt_pk_bf16_f32 v51, v52, v53
	v_cvt_pk_bf16_f32 v52, v42, v43
	v_add_u32_e32 v42, s4, v149
	v_ashrrev_i32_e32 v43, 31, v42
	v_lshlrev_b64 v[42:43], 12, v[42:43]
	v_cvt_pk_bf16_f32 v53, v44, v45
	global_store_dwordx4 v[58:59], v[50:53], off offset:256
	s_nop 1
	v_lshl_add_u64 v[50:51], s[6:7], 0, v[42:43]
	v_cvt_pk_bf16_f32 v42, v54, v55
	v_cvt_pk_bf16_f32 v43, v56, v57
	v_cvt_pk_bf16_f32 v44, v46, v47
	v_lshl_add_u64 v[46:47], v[50:51], 0, v[122:123]
	v_cvt_pk_bf16_f32 v45, v48, v49
	global_store_dwordx4 v[46:47], v[42:45], off
	v_cvt_pk_bf16_f32 v34, v34, v35
	v_cvt_pk_bf16_f32 v35, v36, v37
	v_cvt_pk_bf16_f32 v36, v26, v27
	v_add_u32_e32 v26, s4, v150
	v_ashrrev_i32_e32 v27, 31, v26
	v_lshlrev_b64 v[26:27], 12, v[26:27]
	v_cvt_pk_bf16_f32 v37, v28, v29
	global_store_dwordx4 v[46:47], v[34:37], off offset:256
	s_nop 1
	v_lshl_add_u64 v[34:35], s[6:7], 0, v[26:27]
	v_cvt_pk_bf16_f32 v26, v38, v39
	v_cvt_pk_bf16_f32 v27, v40, v41
	v_cvt_pk_bf16_f32 v28, v30, v31
	v_lshl_add_u64 v[30:31], v[34:35], 0, v[122:123]
	v_cvt_pk_bf16_f32 v29, v32, v33
	global_store_dwordx4 v[30:31], v[26:29], off
	v_cvt_pk_bf16_f32 v18, v18, v19
	v_cvt_pk_bf16_f32 v19, v20, v21
	v_cvt_pk_bf16_f32 v20, v10, v11
	v_add_u32_e32 v10, s4, v151
	v_ashrrev_i32_e32 v11, 31, v10
	v_lshlrev_b64 v[10:11], 12, v[10:11]
	v_cvt_pk_bf16_f32 v21, v12, v13
	global_store_dwordx4 v[30:31], v[18:21], off offset:256
	s_mov_b32 s4, s16
	s_nop 0
	v_lshl_add_u64 v[18:19], s[6:7], 0, v[10:11]
	v_cvt_pk_bf16_f32 v10, v22, v23
	v_cvt_pk_bf16_f32 v11, v24, v25
	v_cvt_pk_bf16_f32 v12, v14, v15
	v_lshl_add_u64 v[14:15], v[18:19], 0, v[122:123]
	v_cvt_pk_bf16_f32 v13, v16, v17
	global_store_dwordx4 v[14:15], v[10:13], off
	v_cvt_pk_bf16_f32 v6, v6, v7
	v_cvt_pk_bf16_f32 v7, v8, v9
	v_cvt_pk_bf16_f32 v8, v2, v3
	v_cvt_pk_bf16_f32 v9, v4, v5
	global_store_dwordx4 v[14:15], v[6:9], off offset:256
	s_cbranch_vccz .LBB0_1586
	s_waitcnt vmcnt(0)
	s_cmpk_gt_u32 s1, 0xff
	s_cbranch_scc1 .LBB0_1597
	s_barrier
